# gemm_post_cluster_bookkeeping_after_the_barrier
# baseline (speedup 1.0000x reference)
.LBB0_150:
	ds_read_b128 v[152:155], v148
	ds_read_b128 v[156:159], v148 offset:1024
	ds_read_b128 v[160:163], v148 offset:2048
	ds_read_b128 v[164:167], v148 offset:3072
	s_add_u32 s40, s38, 0xfffc0080
	s_addc_u32 s41, s39, -1
	s_cmp_eq_u32 s75, 12
	s_cselect_b32 s43, s13, s41
	s_cselect_b32 s42, s37, s40
	s_cselect_b32 s41, s9, s74
	s_cselect_b32 s40, s72, s73
	v_lshl_add_u64 v[200:201], s[38:39], 0, v[136:137]
	s_add_i32 m0, s51, 0xc000
	ds_read_b128 v[168:171], v149
	ds_read_b128 v[172:175], v149 offset:1024
	ds_read_b128 v[176:179], v149 offset:2048
	ds_read_b128 v[180:183], v149 offset:3072
	ds_read_b128 v[184:187], v149 offset:4096
	ds_read_b128 v[188:191], v149 offset:5120
	ds_read_b128 v[192:195], v149 offset:6144
	ds_read_b128 v[196:199], v149 offset:7168
	global_load_lds_dwordx4 v[200:201], off
	v_lshl_add_u64 v[200:201], s[38:39], 0, v[138:139]
	s_add_i32 m0, s51, 0xe000
	s_nop 0
	global_load_lds_dwordx4 v[200:201], off
	s_waitcnt lgkmcnt(8)
	s_setprio 1
	s_barrier
	s_waitcnt lgkmcnt(0)
	v_mfma_f32_16x16x32_bf16 v[124:127], v[152:155], v[168:171], v[124:127]
	v_mfma_f32_16x16x32_bf16 v[120:123], v[160:163], v[168:171], v[120:123]
	v_mfma_f32_16x16x32_bf16 v[116:119], v[152:155], v[176:179], v[116:119]
	v_mfma_f32_16x16x32_bf16 v[112:115], v[160:163], v[176:179], v[112:115]
	v_mfma_f32_16x16x32_bf16 v[108:111], v[152:155], v[184:187], v[108:111]
	v_mfma_f32_16x16x32_bf16 v[104:107], v[160:163], v[184:187], v[104:107]
	v_mfma_f32_16x16x32_bf16 v[100:103], v[152:155], v[192:195], v[100:103]
	v_mfma_f32_16x16x32_bf16 v[96:99], v[160:163], v[192:195], v[96:99]
	v_mfma_f32_16x16x32_bf16 v[124:127], v[156:159], v[172:175], v[124:127]
	v_mfma_f32_16x16x32_bf16 v[120:123], v[164:167], v[172:175], v[120:123]
	v_mfma_f32_16x16x32_bf16 v[116:119], v[156:159], v[180:183], v[116:119]
	v_mfma_f32_16x16x32_bf16 v[112:115], v[164:167], v[180:183], v[112:115]
	v_mfma_f32_16x16x32_bf16 v[108:111], v[156:159], v[188:191], v[108:111]
	v_mfma_f32_16x16x32_bf16 v[104:107], v[164:167], v[188:191], v[104:107]
	v_mfma_f32_16x16x32_bf16 v[100:103], v[156:159], v[196:199], v[100:103]
	v_mfma_f32_16x16x32_bf16 v[96:99], v[164:167], v[196:199], v[96:99]
	s_barrier
	s_setprio 0
	s_add_i32 s76, s69, s48
	v_lshl_add_u64 v[208:209], s[40:41], 0, v[132:133]
	s_mov_b32 m0, s76
	ds_read_b128 v[200:203], v150
	ds_read_b128 v[204:207], v150 offset:1024
	ds_read_b128 v[212:215], v150 offset:2048
	ds_read_b128 v[216:219], v150 offset:3072
	global_load_lds_dwordx4 v[208:209], off
	v_lshl_add_u64 v[220:221], s[40:41], 0, v[128:129]
	s_add_i32 m0, s76, 0x2000
	s_nop 0
	global_load_lds_dwordx4 v[220:221], off
	s_setprio 1
	s_barrier
	s_waitcnt lgkmcnt(0)
	v_mfma_f32_16x16x32_bf16 v[76:79], v[200:203], v[168:171], v[76:79]
	v_mfma_f32_16x16x32_bf16 v[72:75], v[212:215], v[168:171], v[72:75]
	v_mfma_f32_16x16x32_bf16 v[60:63], v[200:203], v[176:179], v[60:63]
	v_mfma_f32_16x16x32_bf16 v[56:59], v[212:215], v[176:179], v[56:59]
	v_mfma_f32_16x16x32_bf16 v[44:47], v[200:203], v[184:187], v[44:47]
	v_mfma_f32_16x16x32_bf16 v[40:43], v[212:215], v[184:187], v[40:43]
	v_mfma_f32_16x16x32_bf16 v[36:39], v[200:203], v[192:195], v[36:39]
	v_mfma_f32_16x16x32_bf16 v[32:35], v[212:215], v[192:195], v[32:35]
	v_mfma_f32_16x16x32_bf16 v[76:79], v[204:207], v[172:175], v[76:79]
	v_mfma_f32_16x16x32_bf16 v[72:75], v[216:219], v[172:175], v[72:75]
	v_mfma_f32_16x16x32_bf16 v[60:63], v[204:207], v[180:183], v[60:63]
	v_mfma_f32_16x16x32_bf16 v[56:59], v[216:219], v[180:183], v[56:59]
	v_mfma_f32_16x16x32_bf16 v[44:47], v[204:207], v[188:191], v[44:47]
	v_mfma_f32_16x16x32_bf16 v[40:43], v[216:219], v[188:191], v[40:43]
	v_mfma_f32_16x16x32_bf16 v[36:39], v[204:207], v[196:199], v[36:39]
	v_mfma_f32_16x16x32_bf16 v[32:35], v[216:219], v[196:199], v[32:35]
	s_barrier
	s_setprio 0
	s_mov_b32 m0, s51
	v_lshl_add_u64 v[222:223], s[42:43], 0, v[134:135]
	ds_read_b128 v[168:171], v149 offset:16384
	ds_read_b128 v[172:175], v149 offset:17408
	ds_read_b128 v[176:179], v149 offset:18432
	ds_read_b128 v[180:183], v149 offset:19456
	ds_read_b128 v[184:187], v149 offset:20480
	ds_read_b128 v[188:191], v149 offset:21504
	ds_read_b128 v[192:195], v149 offset:22528
	ds_read_b128 v[196:199], v149 offset:23552
	global_load_lds_dwordx4 v[222:223], off
	v_lshl_add_u64 v[224:225], s[42:43], 0, v[130:131]
	s_mov_b32 m0, s54
	s_nop 0
	global_load_lds_dwordx4 v[224:225], off
	s_setprio 1
	s_barrier
	s_waitcnt lgkmcnt(0)
	v_mfma_f32_16x16x32_bf16 v[92:95], v[152:155], v[168:171], v[92:95]
	v_mfma_f32_16x16x32_bf16 v[88:91], v[160:163], v[168:171], v[88:91]
	v_mfma_f32_16x16x32_bf16 v[84:87], v[152:155], v[176:179], v[84:87]
	v_mfma_f32_16x16x32_bf16 v[80:83], v[160:163], v[176:179], v[80:83]
	v_mfma_f32_16x16x32_bf16 v[68:71], v[152:155], v[184:187], v[68:71]
	v_mfma_f32_16x16x32_bf16 v[64:67], v[160:163], v[184:187], v[64:67]
	v_mfma_f32_16x16x32_bf16 v[52:55], v[152:155], v[192:195], v[52:55]
	v_mfma_f32_16x16x32_bf16 v[48:51], v[160:163], v[192:195], v[48:51]
	v_mfma_f32_16x16x32_bf16 v[92:95], v[156:159], v[172:175], v[92:95]
	v_mfma_f32_16x16x32_bf16 v[88:91], v[164:167], v[172:175], v[88:91]
	v_mfma_f32_16x16x32_bf16 v[84:87], v[156:159], v[180:183], v[84:87]
	v_mfma_f32_16x16x32_bf16 v[80:83], v[164:167], v[180:183], v[80:83]
	v_mfma_f32_16x16x32_bf16 v[68:71], v[156:159], v[188:191], v[68:71]
	v_mfma_f32_16x16x32_bf16 v[64:67], v[164:167], v[188:191], v[64:67]
	v_mfma_f32_16x16x32_bf16 v[52:55], v[156:159], v[196:199], v[52:55]
	v_mfma_f32_16x16x32_bf16 v[48:51], v[164:167], v[196:199], v[48:51]
	s_barrier
	s_setprio 0
	s_add_u32 s76, s40, 0x40000
	s_addc_u32 s77, s41, 0
	s_add_i32 s78, s70, s48
	v_lshl_add_u64 v[152:153], s[76:77], 0, v[132:133]
	s_mov_b32 m0, s78
	s_nop 0
	global_load_lds_dwordx4 v[152:153], off
	v_lshl_add_u64 v[152:153], s[76:77], 0, v[128:129]
	s_add_i32 m0, s78, 0x2000
	s_nop 0
	global_load_lds_dwordx4 v[152:153], off
	s_waitcnt vmcnt(6)
	s_setprio 1
	s_barrier
	v_mfma_f32_16x16x32_bf16 v[28:31], v[200:203], v[168:171], v[28:31]
	v_mfma_f32_16x16x32_bf16 v[24:27], v[212:215], v[168:171], v[24:27]
	v_mfma_f32_16x16x32_bf16 v[20:23], v[200:203], v[176:179], v[20:23]
	v_mfma_f32_16x16x32_bf16 v[16:19], v[212:215], v[176:179], v[16:19]
	v_mfma_f32_16x16x32_bf16 v[12:15], v[200:203], v[184:187], v[12:15]
	v_mfma_f32_16x16x32_bf16 v[8:11], v[212:215], v[184:187], v[8:11]
	v_mfma_f32_16x16x32_bf16 v[4:7], v[200:203], v[192:195], v[4:7]
	v_mfma_f32_16x16x32_bf16 v[0:3], v[212:215], v[192:195], v[0:3]
	v_mfma_f32_16x16x32_bf16 v[28:31], v[204:207], v[172:175], v[28:31]
	v_mfma_f32_16x16x32_bf16 v[24:27], v[216:219], v[172:175], v[24:27]
	v_mfma_f32_16x16x32_bf16 v[20:23], v[204:207], v[180:183], v[20:23]
	v_mfma_f32_16x16x32_bf16 v[16:19], v[216:219], v[180:183], v[16:19]
	v_mfma_f32_16x16x32_bf16 v[12:15], v[204:207], v[188:191], v[12:15]
	v_mfma_f32_16x16x32_bf16 v[8:11], v[216:219], v[188:191], v[8:11]
	v_mfma_f32_16x16x32_bf16 v[4:7], v[204:207], v[196:199], v[4:7]
	v_mfma_f32_16x16x32_bf16 v[0:3], v[216:219], v[196:199], v[0:3]
	s_barrier
	s_setprio 0
	s_add_i32 s76, 0, 0x18000
	v_add_u32_e32 v151, s76, v146
	ds_read_b128 v[152:155], v151
	ds_read_b128 v[156:159], v151 offset:1024
	ds_read_b128 v[160:163], v151 offset:2048
	ds_read_b128 v[164:167], v151 offset:3072
	s_add_u32 s42, s42, 0x40000
	s_addc_u32 s43, s43, 0
	s_mov_b32 m0, s55
	v_lshl_add_u64 v[200:201], s[42:43], 0, v[134:135]
	ds_read_b128 v[168:171], v149 offset:32768
	ds_read_b128 v[172:175], v149 offset:33792
	ds_read_b128 v[176:179], v149 offset:34816
	ds_read_b128 v[180:183], v149 offset:35840
	ds_read_b128 v[184:187], v149 offset:36864
	ds_read_b128 v[188:191], v149 offset:37888
	ds_read_b128 v[192:195], v149 offset:38912
	ds_read_b128 v[196:199], v149 offset:39936
	global_load_lds_dwordx4 v[200:201], off
	v_lshl_add_u64 v[200:201], s[42:43], 0, v[130:131]
	s_mov_b32 m0, s62
	s_nop 0
	global_load_lds_dwordx4 v[200:201], off
	s_waitcnt lgkmcnt(8)
	s_setprio 1
	s_barrier
	s_waitcnt lgkmcnt(0)
	v_mfma_f32_16x16x32_bf16 v[124:127], v[152:155], v[168:171], v[124:127]
	v_mfma_f32_16x16x32_bf16 v[120:123], v[160:163], v[168:171], v[120:123]
	v_mfma_f32_16x16x32_bf16 v[116:119], v[152:155], v[176:179], v[116:119]
	v_mfma_f32_16x16x32_bf16 v[112:115], v[160:163], v[176:179], v[112:115]
	v_mfma_f32_16x16x32_bf16 v[108:111], v[152:155], v[184:187], v[108:111]
	v_mfma_f32_16x16x32_bf16 v[104:107], v[160:163], v[184:187], v[104:107]
	v_mfma_f32_16x16x32_bf16 v[100:103], v[152:155], v[192:195], v[100:103]
	v_mfma_f32_16x16x32_bf16 v[96:99], v[160:163], v[192:195], v[96:99]
	v_mfma_f32_16x16x32_bf16 v[124:127], v[156:159], v[172:175], v[124:127]
	v_mfma_f32_16x16x32_bf16 v[120:123], v[164:167], v[172:175], v[120:123]
	v_mfma_f32_16x16x32_bf16 v[116:119], v[156:159], v[180:183], v[116:119]
	v_mfma_f32_16x16x32_bf16 v[112:115], v[164:167], v[180:183], v[112:115]
	v_mfma_f32_16x16x32_bf16 v[108:111], v[156:159], v[188:191], v[108:111]
	v_mfma_f32_16x16x32_bf16 v[104:107], v[164:167], v[188:191], v[104:107]
	v_mfma_f32_16x16x32_bf16 v[100:103], v[156:159], v[196:199], v[100:103]
	v_mfma_f32_16x16x32_bf16 v[96:99], v[164:167], v[196:199], v[96:99]
	s_barrier
	s_setprio 0
	s_add_i32 s42, 0, 0x1c000
	s_add_i32 s43, s76, s48
	v_add_u32_e32 v151, s42, v146
	v_lshl_add_u64 v[208:209], v[208:209], 0, s[0:1]
	s_mov_b32 m0, s43
	ds_read_b128 v[200:203], v151
	ds_read_b128 v[204:207], v151 offset:1024
	ds_read_b128 v[212:215], v151 offset:2048
	ds_read_b128 v[216:219], v151 offset:3072
	global_load_lds_dwordx4 v[208:209], off
	v_lshl_add_u64 v[208:209], v[220:221], 0, s[0:1]
	s_add_i32 m0, s43, 0x2000
	s_nop 0
	global_load_lds_dwordx4 v[208:209], off
	s_setprio 1
	s_barrier
	s_waitcnt lgkmcnt(0)
	v_mfma_f32_16x16x32_bf16 v[76:79], v[200:203], v[168:171], v[76:79]
	v_mfma_f32_16x16x32_bf16 v[72:75], v[212:215], v[168:171], v[72:75]
	v_mfma_f32_16x16x32_bf16 v[60:63], v[200:203], v[176:179], v[60:63]
	v_mfma_f32_16x16x32_bf16 v[56:59], v[212:215], v[176:179], v[56:59]
	v_mfma_f32_16x16x32_bf16 v[44:47], v[200:203], v[184:187], v[44:47]
	v_mfma_f32_16x16x32_bf16 v[40:43], v[212:215], v[184:187], v[40:43]
	v_mfma_f32_16x16x32_bf16 v[36:39], v[200:203], v[192:195], v[36:39]
	v_mfma_f32_16x16x32_bf16 v[32:35], v[212:215], v[192:195], v[32:35]
	v_mfma_f32_16x16x32_bf16 v[76:79], v[204:207], v[172:175], v[76:79]
	v_mfma_f32_16x16x32_bf16 v[72:75], v[216:219], v[172:175], v[72:75]
	v_mfma_f32_16x16x32_bf16 v[60:63], v[204:207], v[180:183], v[60:63]
	v_mfma_f32_16x16x32_bf16 v[56:59], v[216:219], v[180:183], v[56:59]
	v_mfma_f32_16x16x32_bf16 v[44:47], v[204:207], v[188:191], v[44:47]
	v_mfma_f32_16x16x32_bf16 v[40:43], v[216:219], v[188:191], v[40:43]
	v_mfma_f32_16x16x32_bf16 v[36:39], v[204:207], v[196:199], v[36:39]
	v_mfma_f32_16x16x32_bf16 v[32:35], v[216:219], v[196:199], v[32:35]
	s_barrier
	s_setprio 0
	s_mov_b32 m0, s63
	v_lshl_add_u64 v[208:209], v[222:223], 0, s[0:1]
	ds_read_b128 v[168:171], v149 offset:49152
	ds_read_b128 v[172:175], v149 offset:50176
	ds_read_b128 v[176:179], v149 offset:51200
	ds_read_b128 v[180:183], v149 offset:52224
	ds_read_b128 v[184:187], v149 offset:53248
	ds_read_b128 v[188:191], v149 offset:54272
	ds_read_b128 v[192:195], v149 offset:55296
	ds_read_b128 v[196:199], v149 offset:56320
	global_load_lds_dwordx4 v[208:209], off
	v_lshl_add_u64 v[208:209], v[224:225], 0, s[0:1]
	s_mov_b32 m0, s64
	s_nop 0
	global_load_lds_dwordx4 v[208:209], off
	s_setprio 1
	s_barrier
	s_waitcnt lgkmcnt(0)
	v_mfma_f32_16x16x32_bf16 v[92:95], v[152:155], v[168:171], v[92:95]
	v_mfma_f32_16x16x32_bf16 v[88:91], v[160:163], v[168:171], v[88:91]
	v_mfma_f32_16x16x32_bf16 v[84:87], v[152:155], v[176:179], v[84:87]
	v_mfma_f32_16x16x32_bf16 v[80:83], v[160:163], v[176:179], v[80:83]
	v_mfma_f32_16x16x32_bf16 v[68:71], v[152:155], v[184:187], v[68:71]
	v_mfma_f32_16x16x32_bf16 v[64:67], v[160:163], v[184:187], v[64:67]
	v_mfma_f32_16x16x32_bf16 v[52:55], v[152:155], v[192:195], v[52:55]
	v_mfma_f32_16x16x32_bf16 v[48:51], v[160:163], v[192:195], v[48:51]
	v_mfma_f32_16x16x32_bf16 v[92:95], v[156:159], v[172:175], v[92:95]
	v_mfma_f32_16x16x32_bf16 v[88:91], v[164:167], v[172:175], v[88:91]
	v_mfma_f32_16x16x32_bf16 v[84:87], v[156:159], v[180:183], v[84:87]
	v_mfma_f32_16x16x32_bf16 v[80:83], v[164:167], v[180:183], v[80:83]
	v_mfma_f32_16x16x32_bf16 v[68:71], v[156:159], v[188:191], v[68:71]
	v_mfma_f32_16x16x32_bf16 v[64:67], v[164:167], v[188:191], v[64:67]
	v_mfma_f32_16x16x32_bf16 v[52:55], v[156:159], v[196:199], v[52:55]
	v_mfma_f32_16x16x32_bf16 v[48:51], v[164:167], v[196:199], v[48:51]
	s_barrier
	s_setprio 0
	s_add_u32 s40, s40, 0x40080
	s_addc_u32 s41, s41, 0
	s_add_i32 s42, s42, s48
	v_lshl_add_u64 v[152:153], s[40:41], 0, v[132:133]
	s_mov_b32 m0, s42
	s_nop 0
	global_load_lds_dwordx4 v[152:153], off
	v_lshl_add_u64 v[152:153], s[40:41], 0, v[128:129]
	s_add_i32 m0, s42, 0x2000
	s_nop 0
	global_load_lds_dwordx4 v[152:153], off
	s_waitcnt vmcnt(6)
	s_setprio 1
	s_barrier
	v_mfma_f32_16x16x32_bf16 v[28:31], v[200:203], v[168:171], v[28:31]
	v_mfma_f32_16x16x32_bf16 v[24:27], v[212:215], v[168:171], v[24:27]
	v_mfma_f32_16x16x32_bf16 v[20:23], v[200:203], v[176:179], v[20:23]
	v_mfma_f32_16x16x32_bf16 v[16:19], v[212:215], v[176:179], v[16:19]
	v_mfma_f32_16x16x32_bf16 v[12:15], v[200:203], v[184:187], v[12:15]
	v_mfma_f32_16x16x32_bf16 v[8:11], v[212:215], v[184:187], v[8:11]
	v_mfma_f32_16x16x32_bf16 v[4:7], v[200:203], v[192:195], v[4:7]
	v_mfma_f32_16x16x32_bf16 v[0:3], v[212:215], v[192:195], v[0:3]
	v_mfma_f32_16x16x32_bf16 v[28:31], v[204:207], v[172:175], v[28:31]
	v_mfma_f32_16x16x32_bf16 v[24:27], v[216:219], v[172:175], v[24:27]
	v_mfma_f32_16x16x32_bf16 v[20:23], v[204:207], v[180:183], v[20:23]
	v_mfma_f32_16x16x32_bf16 v[16:19], v[216:219], v[180:183], v[16:19]
	v_mfma_f32_16x16x32_bf16 v[12:15], v[204:207], v[188:191], v[12:15]
	v_mfma_f32_16x16x32_bf16 v[8:11], v[216:219], v[188:191], v[8:11]
	v_mfma_f32_16x16x32_bf16 v[4:7], v[204:207], v[196:199], v[4:7]
	v_mfma_f32_16x16x32_bf16 v[0:3], v[216:219], v[196:199], v[0:3]
	s_barrier
	s_setprio 0
	s_add_i32 s75, s75, 2
	s_add_u32 s38, s38, 0x100
	s_addc_u32 s39, s39, 0
	s_add_u32 s73, s73, 0x100
	s_addc_u32 s74, s74, 0
	s_cmp_gt_u32 s75, 13
	s_cbranch_scc0 .LBB0_150
	v_lshl_add_u32 v151, s36, 8, v144
	s_cmp_gt_i32 s71, 11
	s_mov_b64 s[36:37], -1
	s_cbranch_scc0 .LBB0_155
	s_and_saveexec_b64 s[36:37], s[2:3]
	s_cbranch_execz .LBB0_154
	v_lshl_or_b32 v152, v151, 8, v147
	v_readlane_b32 s38, v253, 59
	v_readlane_b32 s39, v253, 60
	v_or_b32_e32 v153, 0x1000, v152
	s_nop 3
	global_store_dwordx4 v153, v[116:119], s[38:39] nt
	v_or_b32_e32 v153, 0x2000, v152
	global_store_dwordx4 v153, v[108:111], s[38:39] nt
	v_or_b32_e32 v153, 0x3000, v152
	global_store_dwordx4 v153, v[100:103], s[38:39] nt
	v_add_u32_e32 v153, 0x8000, v152
	global_store_dwordx4 v153, v[92:95], s[38:39] nt
	v_add_u32_e32 v153, 0x9000, v152
	global_store_dwordx4 v153, v[84:87], s[38:39] nt
	v_add_u32_e32 v153, 0xa000, v152
	global_store_dwordx4 v153, v[68:71], s[38:39] nt
	v_add_u32_e32 v153, 0xb000, v152
	global_store_dwordx4 v153, v[52:55], s[38:39] nt
	v_or_b32_e32 v153, 16, v152
	global_store_dwordx4 v153, v[120:123], s[38:39] nt
	v_or_b32_e32 v153, 0x1010, v152
	global_store_dwordx4 v153, v[112:115], s[38:39] nt
	v_or_b32_e32 v153, 0x2010, v152
	global_store_dwordx4 v153, v[104:107], s[38:39] nt
	v_or_b32_e32 v153, 0x3010, v152
	global_store_dwordx4 v153, v[96:99], s[38:39] nt
	v_add_u32_e32 v153, 0x8010, v152
	global_store_dwordx4 v153, v[88:91], s[38:39] nt
	v_add_u32_e32 v153, 0x9010, v152
	global_store_dwordx4 v152, v[124:127], s[38:39] nt
	global_store_dwordx4 v153, v[80:83], s[38:39] nt
	v_add_u32_e32 v153, 0xa010, v152
	v_add_u32_e32 v152, 0xb010, v152
	global_store_dwordx4 v153, v[64:67], s[38:39] nt
	global_store_dwordx4 v152, v[48:51], s[38:39] nt

.LBB0_177:
	ds_read_b128 v[152:155], v149
	ds_read_b128 v[156:159], v149 offset:1024
	ds_read_b128 v[160:163], v149 offset:2048
	ds_read_b128 v[164:167], v149 offset:3072
	s_add_u32 s36, s34, 0xfffc0080
	s_addc_u32 s37, s35, -1
	s_cmp_eq_u32 s68, 12
	s_cselect_b32 s39, s9, s37
	s_cselect_b32 s38, s64, s36
	s_cselect_b32 s37, s3, s67
	s_cselect_b32 s36, s65, s66
	v_lshl_add_u64 v[144:145], s[34:35], 0, v[136:137]
	s_add_i32 m0, s13, 0xc000
	ds_read_b128 v[168:171], v150
	ds_read_b128 v[172:175], v150 offset:1024
	ds_read_b128 v[176:179], v150 offset:2048
	ds_read_b128 v[180:183], v150 offset:3072
	ds_read_b128 v[184:187], v150 offset:4096
	ds_read_b128 v[188:191], v150 offset:5120
	ds_read_b128 v[192:195], v150 offset:6144
	ds_read_b128 v[196:199], v150 offset:7168
	global_load_lds_dwordx4 v[144:145], off
	v_lshl_add_u64 v[144:145], s[34:35], 0, v[138:139]
	s_add_i32 m0, s13, 0xe000
	s_nop 0
	global_load_lds_dwordx4 v[144:145], off
	s_waitcnt lgkmcnt(8)
	s_setprio 1
	s_barrier
	s_waitcnt lgkmcnt(0)
	v_mfma_f32_16x16x32_bf16 v[124:127], v[152:155], v[168:171], v[124:127]
	v_mfma_f32_16x16x32_bf16 v[120:123], v[160:163], v[168:171], v[120:123]
	v_mfma_f32_16x16x32_bf16 v[112:115], v[152:155], v[176:179], v[112:115]
	v_mfma_f32_16x16x32_bf16 v[104:107], v[160:163], v[176:179], v[104:107]
	v_mfma_f32_16x16x32_bf16 v[96:99], v[152:155], v[184:187], v[96:99]
	v_mfma_f32_16x16x32_bf16 v[88:91], v[160:163], v[184:187], v[88:91]
	v_mfma_f32_16x16x32_bf16 v[80:83], v[152:155], v[192:195], v[80:83]
	v_mfma_f32_16x16x32_bf16 v[72:75], v[160:163], v[192:195], v[72:75]
	v_mfma_f32_16x16x32_bf16 v[124:127], v[156:159], v[172:175], v[124:127]
	v_mfma_f32_16x16x32_bf16 v[120:123], v[164:167], v[172:175], v[120:123]
	v_mfma_f32_16x16x32_bf16 v[112:115], v[156:159], v[180:183], v[112:115]
	v_mfma_f32_16x16x32_bf16 v[104:107], v[164:167], v[180:183], v[104:107]
	v_mfma_f32_16x16x32_bf16 v[96:99], v[156:159], v[188:191], v[96:99]
	v_mfma_f32_16x16x32_bf16 v[88:91], v[164:167], v[188:191], v[88:91]
	v_mfma_f32_16x16x32_bf16 v[80:83], v[156:159], v[196:199], v[80:83]
	v_mfma_f32_16x16x32_bf16 v[72:75], v[164:167], v[196:199], v[72:75]
	s_barrier
	s_setprio 0
	s_add_i32 s69, s55, s42
	v_lshl_add_u64 v[144:145], s[36:37], 0, v[130:131]
	s_mov_b32 m0, s69
	ds_read_b128 v[200:203], v151
	ds_read_b128 v[204:207], v151 offset:1024
	ds_read_b128 v[212:215], v151 offset:2048
	ds_read_b128 v[216:219], v151 offset:3072
	global_load_lds_dwordx4 v[144:145], off
	v_lshl_add_u64 v[208:209], s[36:37], 0, v[134:135]
	s_add_i32 m0, s69, 0x2000
	s_nop 0
	global_load_lds_dwordx4 v[208:209], off
	s_setprio 1
	s_barrier
	s_waitcnt lgkmcnt(0)
	v_mfma_f32_16x16x32_bf16 v[116:119], v[200:203], v[168:171], v[116:119]
	v_mfma_f32_16x16x32_bf16 v[108:111], v[212:215], v[168:171], v[108:111]
	v_mfma_f32_16x16x32_bf16 v[100:103], v[200:203], v[176:179], v[100:103]
	v_mfma_f32_16x16x32_bf16 v[92:95], v[212:215], v[176:179], v[92:95]
	v_mfma_f32_16x16x32_bf16 v[84:87], v[200:203], v[184:187], v[84:87]
	v_mfma_f32_16x16x32_bf16 v[76:79], v[212:215], v[184:187], v[76:79]
	v_mfma_f32_16x16x32_bf16 v[68:71], v[200:203], v[192:195], v[68:71]
	v_mfma_f32_16x16x32_bf16 v[64:67], v[212:215], v[192:195], v[64:67]
	v_mfma_f32_16x16x32_bf16 v[116:119], v[204:207], v[172:175], v[116:119]
	v_mfma_f32_16x16x32_bf16 v[108:111], v[216:219], v[172:175], v[108:111]
	v_mfma_f32_16x16x32_bf16 v[100:103], v[204:207], v[180:183], v[100:103]
	v_mfma_f32_16x16x32_bf16 v[92:95], v[216:219], v[180:183], v[92:95]
	v_mfma_f32_16x16x32_bf16 v[84:87], v[204:207], v[188:191], v[84:87]
	v_mfma_f32_16x16x32_bf16 v[76:79], v[216:219], v[188:191], v[76:79]
	v_mfma_f32_16x16x32_bf16 v[68:71], v[204:207], v[196:199], v[68:71]
	v_mfma_f32_16x16x32_bf16 v[64:67], v[216:219], v[196:199], v[64:67]
	s_barrier
	s_setprio 0
	s_mov_b32 m0, s13
	v_lshl_add_u64 v[220:221], s[38:39], 0, v[128:129]
	ds_read_b128 v[168:171], v150 offset:16384
	ds_read_b128 v[172:175], v150 offset:17408
	ds_read_b128 v[176:179], v150 offset:18432
	ds_read_b128 v[180:183], v150 offset:19456
	ds_read_b128 v[184:187], v150 offset:20480
	ds_read_b128 v[188:191], v150 offset:21504
	ds_read_b128 v[192:195], v150 offset:22528
	ds_read_b128 v[196:199], v150 offset:23552
	global_load_lds_dwordx4 v[220:221], off
	v_lshl_add_u64 v[222:223], s[38:39], 0, v[132:133]
	s_mov_b32 m0, s43
	s_nop 0
	global_load_lds_dwordx4 v[222:223], off
	s_setprio 1
	s_barrier
	s_waitcnt lgkmcnt(0)
	v_mfma_f32_16x16x32_bf16 v[60:63], v[152:155], v[168:171], v[60:63]
	v_mfma_f32_16x16x32_bf16 v[56:59], v[160:163], v[168:171], v[56:59]
	v_mfma_f32_16x16x32_bf16 v[52:55], v[152:155], v[176:179], v[52:55]
	v_mfma_f32_16x16x32_bf16 v[44:47], v[160:163], v[176:179], v[44:47]
	v_mfma_f32_16x16x32_bf16 v[36:39], v[152:155], v[184:187], v[36:39]
	v_mfma_f32_16x16x32_bf16 v[28:31], v[160:163], v[184:187], v[28:31]
	v_mfma_f32_16x16x32_bf16 v[20:23], v[152:155], v[192:195], v[20:23]
	v_mfma_f32_16x16x32_bf16 v[12:15], v[160:163], v[192:195], v[12:15]
	v_mfma_f32_16x16x32_bf16 v[60:63], v[156:159], v[172:175], v[60:63]
	v_mfma_f32_16x16x32_bf16 v[56:59], v[164:167], v[172:175], v[56:59]
	v_mfma_f32_16x16x32_bf16 v[52:55], v[156:159], v[180:183], v[52:55]
	v_mfma_f32_16x16x32_bf16 v[44:47], v[164:167], v[180:183], v[44:47]
	v_mfma_f32_16x16x32_bf16 v[36:39], v[156:159], v[188:191], v[36:39]
	v_mfma_f32_16x16x32_bf16 v[28:31], v[164:167], v[188:191], v[28:31]
	v_mfma_f32_16x16x32_bf16 v[20:23], v[156:159], v[196:199], v[20:23]
	v_mfma_f32_16x16x32_bf16 v[12:15], v[164:167], v[196:199], v[12:15]
	s_barrier
	s_setprio 0
	s_add_u32 s70, s36, 0x40000
	s_addc_u32 s71, s37, 0
	s_add_i32 s69, s62, s42
	v_lshl_add_u64 v[152:153], s[70:71], 0, v[130:131]
	s_mov_b32 m0, s69
	s_nop 0
	global_load_lds_dwordx4 v[152:153], off
	v_lshl_add_u64 v[152:153], s[70:71], 0, v[134:135]
	s_add_i32 m0, s69, 0x2000
	s_nop 0
	global_load_lds_dwordx4 v[152:153], off
	s_waitcnt vmcnt(6)
	s_setprio 1
	s_barrier
	v_mfma_f32_16x16x32_bf16 v[48:51], v[200:203], v[168:171], v[48:51]
	v_mfma_f32_16x16x32_bf16 v[40:43], v[212:215], v[168:171], v[40:43]
	v_mfma_f32_16x16x32_bf16 v[32:35], v[200:203], v[176:179], v[32:35]
	v_mfma_f32_16x16x32_bf16 v[24:27], v[212:215], v[176:179], v[24:27]
	v_mfma_f32_16x16x32_bf16 v[16:19], v[200:203], v[184:187], v[16:19]
	v_mfma_f32_16x16x32_bf16 v[8:11], v[212:215], v[184:187], v[8:11]
	v_mfma_f32_16x16x32_bf16 v[4:7], v[200:203], v[192:195], v[4:7]
	v_mfma_f32_16x16x32_bf16 v[0:3], v[212:215], v[192:195], v[0:3]
	v_mfma_f32_16x16x32_bf16 v[48:51], v[204:207], v[172:175], v[48:51]
	v_mfma_f32_16x16x32_bf16 v[40:43], v[216:219], v[172:175], v[40:43]
	v_mfma_f32_16x16x32_bf16 v[32:35], v[204:207], v[180:183], v[32:35]
	v_mfma_f32_16x16x32_bf16 v[24:27], v[216:219], v[180:183], v[24:27]
	v_mfma_f32_16x16x32_bf16 v[16:19], v[204:207], v[188:191], v[16:19]
	v_mfma_f32_16x16x32_bf16 v[8:11], v[216:219], v[188:191], v[8:11]
	v_mfma_f32_16x16x32_bf16 v[4:7], v[204:207], v[196:199], v[4:7]
	v_mfma_f32_16x16x32_bf16 v[0:3], v[216:219], v[196:199], v[0:3]
	s_barrier
	s_setprio 0
	s_add_i32 s69, 0, 0x18000
	v_add_u32_e32 v164, s69, v147
	ds_read_b128 v[152:155], v164
	ds_read_b128 v[156:159], v164 offset:1024
	ds_read_b128 v[160:163], v164 offset:2048
	ds_read_b128 v[164:167], v164 offset:3072
	s_add_u32 s38, s38, 0x40000
	s_addc_u32 s39, s39, 0
	s_mov_b32 m0, s48
	v_lshl_add_u64 v[200:201], s[38:39], 0, v[128:129]
	ds_read_b128 v[168:171], v150 offset:32768
	ds_read_b128 v[172:175], v150 offset:33792
	ds_read_b128 v[176:179], v150 offset:34816
	ds_read_b128 v[180:183], v150 offset:35840
	ds_read_b128 v[184:187], v150 offset:36864
	ds_read_b128 v[188:191], v150 offset:37888
	ds_read_b128 v[192:195], v150 offset:38912
	ds_read_b128 v[196:199], v150 offset:39936
	global_load_lds_dwordx4 v[200:201], off
	v_lshl_add_u64 v[200:201], s[38:39], 0, v[132:133]
	s_mov_b32 m0, s49
	s_nop 0
	global_load_lds_dwordx4 v[200:201], off
	s_waitcnt lgkmcnt(8)
	s_setprio 1
	s_barrier
	s_waitcnt lgkmcnt(0)
	v_mfma_f32_16x16x32_bf16 v[124:127], v[152:155], v[168:171], v[124:127]
	v_mfma_f32_16x16x32_bf16 v[120:123], v[160:163], v[168:171], v[120:123]
	v_mfma_f32_16x16x32_bf16 v[112:115], v[152:155], v[176:179], v[112:115]
	v_mfma_f32_16x16x32_bf16 v[104:107], v[160:163], v[176:179], v[104:107]
	v_mfma_f32_16x16x32_bf16 v[96:99], v[152:155], v[184:187], v[96:99]
	v_mfma_f32_16x16x32_bf16 v[88:91], v[160:163], v[184:187], v[88:91]
	v_mfma_f32_16x16x32_bf16 v[80:83], v[152:155], v[192:195], v[80:83]
	v_mfma_f32_16x16x32_bf16 v[72:75], v[160:163], v[192:195], v[72:75]
	v_mfma_f32_16x16x32_bf16 v[124:127], v[156:159], v[172:175], v[124:127]
	v_mfma_f32_16x16x32_bf16 v[120:123], v[164:167], v[172:175], v[120:123]
	v_mfma_f32_16x16x32_bf16 v[112:115], v[156:159], v[180:183], v[112:115]
	v_mfma_f32_16x16x32_bf16 v[104:107], v[164:167], v[180:183], v[104:107]
	v_mfma_f32_16x16x32_bf16 v[96:99], v[156:159], v[188:191], v[96:99]
	v_mfma_f32_16x16x32_bf16 v[88:91], v[164:167], v[188:191], v[88:91]
	v_mfma_f32_16x16x32_bf16 v[80:83], v[156:159], v[196:199], v[80:83]
	v_mfma_f32_16x16x32_bf16 v[72:75], v[164:167], v[196:199], v[72:75]
	s_barrier
	s_setprio 0
	s_add_i32 s38, 0, 0x1c000
	s_add_i32 s39, s69, s42
	v_add_u32_e32 v211, s38, v147
	v_lshl_add_u64 v[144:145], v[144:145], 0, s[0:1]
	s_mov_b32 m0, s39
	ds_read_b128 v[200:203], v211
	ds_read_b128 v[204:207], v211 offset:1024
	ds_read_b128 v[212:215], v211 offset:2048
	ds_read_b128 v[216:219], v211 offset:3072
	global_load_lds_dwordx4 v[144:145], off
	v_lshl_add_u64 v[144:145], v[208:209], 0, s[0:1]
	s_add_i32 m0, s39, 0x2000
	s_nop 0
	global_load_lds_dwordx4 v[144:145], off
	s_setprio 1
	s_barrier
	s_waitcnt lgkmcnt(0)
	v_mfma_f32_16x16x32_bf16 v[116:119], v[200:203], v[168:171], v[116:119]
	v_mfma_f32_16x16x32_bf16 v[108:111], v[212:215], v[168:171], v[108:111]
	v_mfma_f32_16x16x32_bf16 v[100:103], v[200:203], v[176:179], v[100:103]
	v_mfma_f32_16x16x32_bf16 v[92:95], v[212:215], v[176:179], v[92:95]
	v_mfma_f32_16x16x32_bf16 v[84:87], v[200:203], v[184:187], v[84:87]
	v_mfma_f32_16x16x32_bf16 v[76:79], v[212:215], v[184:187], v[76:79]
	v_mfma_f32_16x16x32_bf16 v[68:71], v[200:203], v[192:195], v[68:71]
	v_mfma_f32_16x16x32_bf16 v[64:67], v[212:215], v[192:195], v[64:67]
	v_mfma_f32_16x16x32_bf16 v[116:119], v[204:207], v[172:175], v[116:119]
	v_mfma_f32_16x16x32_bf16 v[108:111], v[216:219], v[172:175], v[108:111]
	v_mfma_f32_16x16x32_bf16 v[100:103], v[204:207], v[180:183], v[100:103]
	v_mfma_f32_16x16x32_bf16 v[92:95], v[216:219], v[180:183], v[92:95]
	v_mfma_f32_16x16x32_bf16 v[84:87], v[204:207], v[188:191], v[84:87]
	v_mfma_f32_16x16x32_bf16 v[76:79], v[216:219], v[188:191], v[76:79]
	v_mfma_f32_16x16x32_bf16 v[68:71], v[204:207], v[196:199], v[68:71]
	v_mfma_f32_16x16x32_bf16 v[64:67], v[216:219], v[196:199], v[64:67]
	s_barrier
	s_setprio 0
	s_mov_b32 m0, s51
	v_lshl_add_u64 v[144:145], v[220:221], 0, s[0:1]
	ds_read_b128 v[168:171], v150 offset:49152
	ds_read_b128 v[172:175], v150 offset:50176
	ds_read_b128 v[176:179], v150 offset:51200
	ds_read_b128 v[180:183], v150 offset:52224
	ds_read_b128 v[184:187], v150 offset:53248
	ds_read_b128 v[188:191], v150 offset:54272
	ds_read_b128 v[192:195], v150 offset:55296
	ds_read_b128 v[196:199], v150 offset:56320
	global_load_lds_dwordx4 v[144:145], off
	v_lshl_add_u64 v[144:145], v[222:223], 0, s[0:1]
	s_mov_b32 m0, s54
	s_nop 0
	global_load_lds_dwordx4 v[144:145], off
	s_setprio 1
	s_barrier
	s_waitcnt lgkmcnt(0)
	v_mfma_f32_16x16x32_bf16 v[60:63], v[152:155], v[168:171], v[60:63]
	v_mfma_f32_16x16x32_bf16 v[56:59], v[160:163], v[168:171], v[56:59]
	v_mfma_f32_16x16x32_bf16 v[52:55], v[152:155], v[176:179], v[52:55]
	v_mfma_f32_16x16x32_bf16 v[44:47], v[160:163], v[176:179], v[44:47]
	v_mfma_f32_16x16x32_bf16 v[36:39], v[152:155], v[184:187], v[36:39]
	v_mfma_f32_16x16x32_bf16 v[28:31], v[160:163], v[184:187], v[28:31]
	v_mfma_f32_16x16x32_bf16 v[20:23], v[152:155], v[192:195], v[20:23]
	v_mfma_f32_16x16x32_bf16 v[12:15], v[160:163], v[192:195], v[12:15]
	v_mfma_f32_16x16x32_bf16 v[60:63], v[156:159], v[172:175], v[60:63]
	v_mfma_f32_16x16x32_bf16 v[56:59], v[164:167], v[172:175], v[56:59]
	v_mfma_f32_16x16x32_bf16 v[52:55], v[156:159], v[180:183], v[52:55]
	v_mfma_f32_16x16x32_bf16 v[44:47], v[164:167], v[180:183], v[44:47]
	v_mfma_f32_16x16x32_bf16 v[36:39], v[156:159], v[188:191], v[36:39]
	v_mfma_f32_16x16x32_bf16 v[28:31], v[164:167], v[188:191], v[28:31]
	v_mfma_f32_16x16x32_bf16 v[20:23], v[156:159], v[196:199], v[20:23]
	v_mfma_f32_16x16x32_bf16 v[12:15], v[164:167], v[196:199], v[12:15]
	s_barrier
	s_setprio 0
	s_add_u32 s36, s36, 0x40080
	s_addc_u32 s37, s37, 0
	s_add_i32 s38, s38, s42
	v_lshl_add_u64 v[144:145], s[36:37], 0, v[130:131]
	s_mov_b32 m0, s38
	s_nop 0
	global_load_lds_dwordx4 v[144:145], off
	v_lshl_add_u64 v[144:145], s[36:37], 0, v[134:135]
	s_add_i32 m0, s38, 0x2000
	s_nop 0
	global_load_lds_dwordx4 v[144:145], off
	s_waitcnt vmcnt(6)
	s_setprio 1
	s_barrier
	v_mfma_f32_16x16x32_bf16 v[48:51], v[200:203], v[168:171], v[48:51]
	v_mfma_f32_16x16x32_bf16 v[40:43], v[212:215], v[168:171], v[40:43]
	v_mfma_f32_16x16x32_bf16 v[32:35], v[200:203], v[176:179], v[32:35]
	v_mfma_f32_16x16x32_bf16 v[24:27], v[212:215], v[176:179], v[24:27]
	v_mfma_f32_16x16x32_bf16 v[16:19], v[200:203], v[184:187], v[16:19]
	v_mfma_f32_16x16x32_bf16 v[8:11], v[212:215], v[184:187], v[8:11]
	v_mfma_f32_16x16x32_bf16 v[4:7], v[200:203], v[192:195], v[4:7]
	v_mfma_f32_16x16x32_bf16 v[0:3], v[212:215], v[192:195], v[0:3]
	v_mfma_f32_16x16x32_bf16 v[48:51], v[204:207], v[172:175], v[48:51]
	v_mfma_f32_16x16x32_bf16 v[40:43], v[216:219], v[172:175], v[40:43]
	v_mfma_f32_16x16x32_bf16 v[32:35], v[204:207], v[180:183], v[32:35]
	v_mfma_f32_16x16x32_bf16 v[24:27], v[216:219], v[180:183], v[24:27]
	v_mfma_f32_16x16x32_bf16 v[16:19], v[204:207], v[188:191], v[16:19]
	v_mfma_f32_16x16x32_bf16 v[8:11], v[216:219], v[188:191], v[8:11]
	v_mfma_f32_16x16x32_bf16 v[4:7], v[204:207], v[196:199], v[4:7]
	v_mfma_f32_16x16x32_bf16 v[0:3], v[216:219], v[196:199], v[0:3]
	s_barrier
	s_setprio 0
	s_add_i32 s68, s68, 2
	s_add_u32 s34, s34, 0x100
	s_addc_u32 s35, s35, 0
	s_add_u32 s66, s66, 0x100
	s_addc_u32 s67, s67, 0
	s_cmp_gt_u32 s68, 13
	s_cbranch_scc0 .LBB0_177
	v_lshl_add_u32 v152, s12, 8, v146
	v_ashrrev_i32_e32 v153, 31, v152
	v_lshl_or_b32 v144, s63, 8, v148
	v_readlane_b32 s34, v253, 61
	v_ashrrev_i32_e32 v145, 31, v144
	v_lshlrev_b64 v[154:155], 17, v[152:153]
	v_readlane_b32 s35, v253, 62
	v_lshlrev_b64 v[156:157], 1, v[144:145]
	v_cvt_pk_bf16_f32 v124, v124, v125
	v_cvt_pk_bf16_f32 v125, v126, v127
	v_cvt_pk_bf16_f32 v126, v120, v121
	s_nop 0
	v_lshl_add_u64 v[154:155], s[34:35], 0, v[154:155]
	v_lshl_add_u64 v[144:145], v[154:155], 0, v[156:157]
	v_cvt_pk_bf16_f32 v127, v122, v123
	global_store_dwordx4 v[144:145], v[124:127], off nt
	v_cvt_pk_bf16_f32 v116, v116, v117
	v_cvt_pk_bf16_f32 v117, v118, v119
	v_cvt_pk_bf16_f32 v118, v108, v109
	v_or_b32_e32 v108, 16, v152
	v_ashrrev_i32_e32 v109, 31, v108
	v_lshlrev_b64 v[108:109], 17, v[108:109]
	v_lshl_add_u64 v[108:109], s[34:35], 0, v[108:109]
	v_cvt_pk_bf16_f32 v119, v110, v111
	global_store_dwordx4 v[144:145], v[116:119], off offset:256 nt
	s_mov_b32 s3, 0x1000000
	s_mov_b32 s63, s2
	v_lshl_add_u64 v[116:117], v[108:109], 0, v[156:157]
	v_cvt_pk_bf16_f32 v108, v112, v113
	v_cvt_pk_bf16_f32 v109, v114, v115
	v_cvt_pk_bf16_f32 v110, v104, v105
	v_cvt_pk_bf16_f32 v111, v106, v107
	global_store_dwordx4 v[116:117], v[108:111], off nt
	v_cvt_pk_bf16_f32 v100, v100, v101
	v_cvt_pk_bf16_f32 v101, v102, v103
	v_cvt_pk_bf16_f32 v102, v92, v93
	v_or_b32_e32 v92, 32, v152
	v_ashrrev_i32_e32 v93, 31, v92
	v_lshlrev_b64 v[92:93], 17, v[92:93]
	v_lshl_add_u64 v[92:93], s[34:35], 0, v[92:93]
	v_cvt_pk_bf16_f32 v103, v94, v95
	global_store_dwordx4 v[116:117], v[100:103], off offset:256 nt
	s_mov_b32 s12, s8
	s_mov_b64 s[36:37], s[30:31]
	v_lshl_add_u64 v[100:101], v[92:93], 0, v[156:157]
	v_cvt_pk_bf16_f32 v92, v96, v97
	v_cvt_pk_bf16_f32 v93, v98, v99
	v_cvt_pk_bf16_f32 v94, v88, v89
	v_cvt_pk_bf16_f32 v95, v90, v91
	global_store_dwordx4 v[100:101], v[92:95], off nt
	v_cvt_pk_bf16_f32 v84, v84, v85
	v_cvt_pk_bf16_f32 v85, v86, v87
	v_cvt_pk_bf16_f32 v86, v76, v77
	v_or_b32_e32 v76, 48, v152
	v_ashrrev_i32_e32 v77, 31, v76
	v_lshlrev_b64 v[76:77], 17, v[76:77]
	v_lshl_add_u64 v[76:77], s[34:35], 0, v[76:77]
	v_cvt_pk_bf16_f32 v87, v78, v79
	global_store_dwordx4 v[100:101], v[84:87], off offset:256 nt
	s_mov_b64 s[34:35], 0x1000000
	s_nop 0
	v_lshl_add_u64 v[84:85], v[76:77], 0, v[156:157]
	v_cvt_pk_bf16_f32 v76, v80, v81
	v_cvt_pk_bf16_f32 v77, v82, v83
	v_cvt_pk_bf16_f32 v78, v72, v73
	v_cvt_pk_bf16_f32 v79, v74, v75
	global_store_dwordx4 v[84:85], v[76:79], off nt
	v_cvt_pk_bf16_f32 v68, v68, v69
	v_cvt_pk_bf16_f32 v69, v70, v71
	v_cvt_pk_bf16_f32 v70, v64, v65
	v_cvt_pk_bf16_f32 v71, v66, v67
	global_store_dwordx4 v[84:85], v[68:71], off offset:256 nt
	v_cvt_pk_bf16_f32 v60, v60, v61
	v_cvt_pk_bf16_f32 v61, v62, v63
	v_cvt_pk_bf16_f32 v62, v56, v57
	v_add_co_u32_e32 v56, vcc, s3, v144
	v_lshl_add_u64 v[64:65], v[144:145], 0, s[34:35]
	s_nop 0
	v_addc_co_u32_e32 v57, vcc, 0, v145, vcc
	s_mov_b32 s3, 0x1200000
	v_cvt_pk_bf16_f32 v63, v58, v59
	global_store_dwordx4 v[56:57], v[60:63], off nt
	v_cvt_pk_bf16_f32 v48, v48, v49
	v_cvt_pk_bf16_f32 v49, v50, v51
	v_cvt_pk_bf16_f32 v50, v40, v41
	v_cvt_pk_bf16_f32 v51, v42, v43
	global_store_dwordx4 v[64:65], v[48:51], off offset:256 nt
	s_mov_b64 s[34:35], 0x1200000
	v_cvt_pk_bf16_f32 v40, v52, v53
	v_cvt_pk_bf16_f32 v41, v54, v55
	v_cvt_pk_bf16_f32 v42, v44, v45
	v_add_co_u32_e32 v44, vcc, s3, v144
	v_lshl_add_u64 v[48:49], v[144:145], 0, s[34:35]
	s_nop 0
	v_addc_co_u32_e32 v45, vcc, 0, v145, vcc
	s_mov_b32 s3, 0x1400000
	v_cvt_pk_bf16_f32 v43, v46, v47
	global_store_dwordx4 v[44:45], v[40:43], off nt
	v_cvt_pk_bf16_f32 v32, v32, v33
	v_cvt_pk_bf16_f32 v33, v34, v35
	v_cvt_pk_bf16_f32 v34, v24, v25
	v_cvt_pk_bf16_f32 v35, v26, v27
	global_store_dwordx4 v[48:49], v[32:35], off offset:256 nt
	s_mov_b64 s[34:35], 0x1400000
	v_cvt_pk_bf16_f32 v24, v36, v37
	v_cvt_pk_bf16_f32 v25, v38, v39
	v_cvt_pk_bf16_f32 v26, v28, v29
	v_add_co_u32_e32 v28, vcc, s3, v144
	v_lshl_add_u64 v[32:33], v[144:145], 0, s[34:35]
	s_nop 0
	v_addc_co_u32_e32 v29, vcc, 0, v145, vcc
	s_mov_b32 s3, 0x1600000
	v_cvt_pk_bf16_f32 v27, v30, v31
	global_store_dwordx4 v[28:29], v[24:27], off nt
	v_cvt_pk_bf16_f32 v16, v16, v17
	v_cvt_pk_bf16_f32 v17, v18, v19
	v_cvt_pk_bf16_f32 v18, v8, v9
	v_cvt_pk_bf16_f32 v19, v10, v11
	global_store_dwordx4 v[32:33], v[16:19], off offset:256 nt
	v_cvt_pk_bf16_f32 v8, v20, v21
	v_cvt_pk_bf16_f32 v9, v22, v23
	v_cvt_pk_bf16_f32 v10, v12, v13
	v_add_co_u32_e32 v12, vcc, s3, v144
	s_mov_b64 s[34:35], 0x1600000
	s_nop 0
	v_addc_co_u32_e32 v13, vcc, 0, v145, vcc
	v_lshl_add_u64 v[16:17], v[144:145], 0, s[34:35]
	s_and_b64 vcc, exec, s[4:5]
	s_mov_b64 s[34:35], s[14:15]
	v_cvt_pk_bf16_f32 v11, v14, v15
	global_store_dwordx4 v[12:13], v[8:11], off nt
	v_cvt_pk_bf16_f32 v4, v4, v5
	v_cvt_pk_bf16_f32 v5, v6, v7
	v_cvt_pk_bf16_f32 v6, v0, v1
	v_cvt_pk_bf16_f32 v7, v2, v3
	global_store_dwordx4 v[16:17], v[4:7], off offset:256 nt
	s_cbranch_vccz .LBB0_170
	s_waitcnt vmcnt(0)
	s_cmpk_gt_u32 s40, 0xff
	s_cbranch_scc1 .LBB0_181
	s_barrier

.LBB0_200:
	s_add_u32 s48, s42, 0xfffc0080
	s_addc_u32 s49, s43, -1
	s_add_i32 s81, 0, 0x10000
	v_add_u32_e32 v140, s81, v144
	ds_read_b128 v[148:151], v140
	ds_read_b128 v[152:155], v140 offset:1024
	ds_read_b128 v[156:159], v140 offset:2048
	ds_read_b128 v[160:163], v140 offset:3072
	s_cmp_eq_u32 s80, 12
	s_cselect_b32 s51, s35, s49
	s_cselect_b32 s50, s76, s48
	s_cselect_b32 s49, s31, s79
	s_cselect_b32 s48, s77, s78
	v_lshl_add_u64 v[140:141], s[42:43], 0, v[136:137]
	s_add_i32 m0, s37, 0xc000
	ds_read_b128 v[164:167], v146
	ds_read_b128 v[168:171], v146 offset:1024
	ds_read_b128 v[172:175], v146 offset:2048
	ds_read_b128 v[176:179], v146 offset:3072
	ds_read_b128 v[180:183], v146 offset:4096
	ds_read_b128 v[184:187], v146 offset:5120
	ds_read_b128 v[188:191], v146 offset:6144
	ds_read_b128 v[192:195], v146 offset:7168
	global_load_lds_dwordx4 v[140:141], off
	v_lshl_add_u64 v[140:141], s[42:43], 0, v[138:139]
	s_add_i32 m0, s37, 0xe000
	s_nop 0
	global_load_lds_dwordx4 v[140:141], off
	s_waitcnt lgkmcnt(8)
	s_setprio 1
	s_barrier
	s_waitcnt lgkmcnt(0)
	v_mfma_f32_16x16x32_bf16 v[124:127], v[148:151], v[164:167], v[124:127]
	v_mfma_f32_16x16x32_bf16 v[120:123], v[156:159], v[164:167], v[120:123]
	v_mfma_f32_16x16x32_bf16 v[116:119], v[148:151], v[172:175], v[116:119]
	v_mfma_f32_16x16x32_bf16 v[108:111], v[156:159], v[172:175], v[108:111]
	v_mfma_f32_16x16x32_bf16 v[100:103], v[148:151], v[180:183], v[100:103]
	v_mfma_f32_16x16x32_bf16 v[92:95], v[156:159], v[180:183], v[92:95]
	v_mfma_f32_16x16x32_bf16 v[84:87], v[148:151], v[188:191], v[84:87]
	v_mfma_f32_16x16x32_bf16 v[76:79], v[156:159], v[188:191], v[76:79]
	v_mfma_f32_16x16x32_bf16 v[124:127], v[152:155], v[168:171], v[124:127]
	v_mfma_f32_16x16x32_bf16 v[120:123], v[160:163], v[168:171], v[120:123]
	v_mfma_f32_16x16x32_bf16 v[116:119], v[152:155], v[176:179], v[116:119]
	v_mfma_f32_16x16x32_bf16 v[108:111], v[160:163], v[176:179], v[108:111]
	v_mfma_f32_16x16x32_bf16 v[100:103], v[152:155], v[184:187], v[100:103]
	v_mfma_f32_16x16x32_bf16 v[92:95], v[160:163], v[184:187], v[92:95]
	v_mfma_f32_16x16x32_bf16 v[84:87], v[152:155], v[192:195], v[84:87]
	v_mfma_f32_16x16x32_bf16 v[76:79], v[160:163], v[192:195], v[76:79]
	s_barrier
	s_setprio 0
	s_add_i32 s84, 0, 0x14000
	v_add_u32_e32 v140, s84, v144
	s_add_i32 s81, s81, s69
	ds_read_b128 v[196:199], v140
	ds_read_b128 v[200:203], v140 offset:1024
	ds_read_b128 v[204:207], v140 offset:2048
	ds_read_b128 v[212:215], v140 offset:3072
	v_lshl_add_u64 v[140:141], s[48:49], 0, v[128:129]
	s_mov_b32 m0, s81
	v_lshl_add_u64 v[208:209], s[48:49], 0, v[134:135]
	global_load_lds_dwordx4 v[140:141], off
	s_add_i32 m0, s81, 0x2000
	s_nop 0
	global_load_lds_dwordx4 v[208:209], off
	s_setprio 1
	s_barrier
	s_waitcnt lgkmcnt(0)
	v_mfma_f32_16x16x32_bf16 v[112:115], v[196:199], v[164:167], v[112:115]
	v_mfma_f32_16x16x32_bf16 v[104:107], v[204:207], v[164:167], v[104:107]
	v_mfma_f32_16x16x32_bf16 v[96:99], v[196:199], v[172:175], v[96:99]
	v_mfma_f32_16x16x32_bf16 v[88:91], v[204:207], v[172:175], v[88:91]
	v_mfma_f32_16x16x32_bf16 v[80:83], v[196:199], v[180:183], v[80:83]
	v_mfma_f32_16x16x32_bf16 v[72:75], v[204:207], v[180:183], v[72:75]
	v_mfma_f32_16x16x32_bf16 v[68:71], v[196:199], v[188:191], v[68:71]
	v_mfma_f32_16x16x32_bf16 v[64:67], v[204:207], v[188:191], v[64:67]
	v_mfma_f32_16x16x32_bf16 v[112:115], v[200:203], v[168:171], v[112:115]
	v_mfma_f32_16x16x32_bf16 v[104:107], v[212:215], v[168:171], v[104:107]
	v_mfma_f32_16x16x32_bf16 v[96:99], v[200:203], v[176:179], v[96:99]
	v_mfma_f32_16x16x32_bf16 v[88:91], v[212:215], v[176:179], v[88:91]
	v_mfma_f32_16x16x32_bf16 v[80:83], v[200:203], v[184:187], v[80:83]
	v_mfma_f32_16x16x32_bf16 v[72:75], v[212:215], v[184:187], v[72:75]
	v_mfma_f32_16x16x32_bf16 v[68:71], v[200:203], v[192:195], v[68:71]
	v_mfma_f32_16x16x32_bf16 v[64:67], v[212:215], v[192:195], v[64:67]
	s_barrier
	s_setprio 0
	s_mov_b32 m0, s37
	v_lshl_add_u64 v[216:217], s[50:51], 0, v[130:131]
	ds_read_b128 v[164:167], v146 offset:16384
	ds_read_b128 v[168:171], v146 offset:17408
	ds_read_b128 v[172:175], v146 offset:18432
	ds_read_b128 v[176:179], v146 offset:19456
	ds_read_b128 v[180:183], v146 offset:20480
	ds_read_b128 v[184:187], v146 offset:21504
	ds_read_b128 v[188:191], v146 offset:22528
	ds_read_b128 v[192:195], v146 offset:23552
	global_load_lds_dwordx4 v[216:217], off
	v_lshl_add_u64 v[218:219], s[50:51], 0, v[132:133]
	s_mov_b32 m0, s70
	s_nop 0
	global_load_lds_dwordx4 v[218:219], off
	s_setprio 1
	s_barrier
	s_waitcnt lgkmcnt(0)
	v_mfma_f32_16x16x32_bf16 v[60:63], v[148:151], v[164:167], v[60:63]
	v_mfma_f32_16x16x32_bf16 v[56:59], v[156:159], v[164:167], v[56:59]
	v_mfma_f32_16x16x32_bf16 v[52:55], v[148:151], v[172:175], v[52:55]
	v_mfma_f32_16x16x32_bf16 v[44:47], v[156:159], v[172:175], v[44:47]
	v_mfma_f32_16x16x32_bf16 v[36:39], v[148:151], v[180:183], v[36:39]
	v_mfma_f32_16x16x32_bf16 v[28:31], v[156:159], v[180:183], v[28:31]
	v_mfma_f32_16x16x32_bf16 v[20:23], v[148:151], v[188:191], v[20:23]
	v_mfma_f32_16x16x32_bf16 v[12:15], v[156:159], v[188:191], v[12:15]
	v_mfma_f32_16x16x32_bf16 v[60:63], v[152:155], v[168:171], v[60:63]
	v_mfma_f32_16x16x32_bf16 v[56:59], v[160:163], v[168:171], v[56:59]
	v_mfma_f32_16x16x32_bf16 v[52:55], v[152:155], v[176:179], v[52:55]
	v_mfma_f32_16x16x32_bf16 v[44:47], v[160:163], v[176:179], v[44:47]
	v_mfma_f32_16x16x32_bf16 v[36:39], v[152:155], v[184:187], v[36:39]
	v_mfma_f32_16x16x32_bf16 v[28:31], v[160:163], v[184:187], v[28:31]
	v_mfma_f32_16x16x32_bf16 v[20:23], v[152:155], v[192:195], v[20:23]
	v_mfma_f32_16x16x32_bf16 v[12:15], v[160:163], v[192:195], v[12:15]
	s_barrier
	s_setprio 0
	s_add_u32 s82, s48, 0x40000
	s_addc_u32 s83, s49, 0
	s_add_i32 s81, s84, s69
	v_lshl_add_u64 v[148:149], s[82:83], 0, v[128:129]
	s_mov_b32 m0, s81
	s_nop 0
	global_load_lds_dwordx4 v[148:149], off
	v_lshl_add_u64 v[148:149], s[82:83], 0, v[134:135]
	s_add_i32 m0, s81, 0x2000
	s_nop 0
	global_load_lds_dwordx4 v[148:149], off
	s_waitcnt vmcnt(6)
	s_setprio 1
	s_barrier
	v_mfma_f32_16x16x32_bf16 v[48:51], v[196:199], v[164:167], v[48:51]
	v_mfma_f32_16x16x32_bf16 v[40:43], v[204:207], v[164:167], v[40:43]
	v_mfma_f32_16x16x32_bf16 v[32:35], v[196:199], v[172:175], v[32:35]
	v_mfma_f32_16x16x32_bf16 v[24:27], v[204:207], v[172:175], v[24:27]
	v_mfma_f32_16x16x32_bf16 v[16:19], v[196:199], v[180:183], v[16:19]
	v_mfma_f32_16x16x32_bf16 v[8:11], v[204:207], v[180:183], v[8:11]
	v_mfma_f32_16x16x32_bf16 v[4:7], v[196:199], v[188:191], v[4:7]
	v_mfma_f32_16x16x32_bf16 v[0:3], v[204:207], v[188:191], v[0:3]
	v_mfma_f32_16x16x32_bf16 v[48:51], v[200:203], v[168:171], v[48:51]
	v_mfma_f32_16x16x32_bf16 v[40:43], v[212:215], v[168:171], v[40:43]
	v_mfma_f32_16x16x32_bf16 v[32:35], v[200:203], v[176:179], v[32:35]
	v_mfma_f32_16x16x32_bf16 v[24:27], v[212:215], v[176:179], v[24:27]
	v_mfma_f32_16x16x32_bf16 v[16:19], v[200:203], v[184:187], v[16:19]
	v_mfma_f32_16x16x32_bf16 v[8:11], v[212:215], v[184:187], v[8:11]
	v_mfma_f32_16x16x32_bf16 v[4:7], v[200:203], v[192:195], v[4:7]
	v_mfma_f32_16x16x32_bf16 v[0:3], v[212:215], v[192:195], v[0:3]
	s_barrier
	s_setprio 0
	s_add_i32 s81, 0, 0x18000
	v_add_u32_e32 v147, s81, v144
	ds_read_b128 v[148:151], v147
	ds_read_b128 v[152:155], v147 offset:1024
	ds_read_b128 v[156:159], v147 offset:2048
	ds_read_b128 v[160:163], v147 offset:3072
	s_add_u32 s50, s50, 0x40000
	s_addc_u32 s51, s51, 0
	s_mov_b32 m0, s71
	v_lshl_add_u64 v[196:197], s[50:51], 0, v[130:131]
	ds_read_b128 v[164:167], v146 offset:32768
	ds_read_b128 v[168:171], v146 offset:33792
	ds_read_b128 v[172:175], v146 offset:34816
	ds_read_b128 v[176:179], v146 offset:35840
	ds_read_b128 v[180:183], v146 offset:36864
	ds_read_b128 v[184:187], v146 offset:37888
	ds_read_b128 v[188:191], v146 offset:38912
	ds_read_b128 v[192:195], v146 offset:39936
	global_load_lds_dwordx4 v[196:197], off
	v_lshl_add_u64 v[196:197], s[50:51], 0, v[132:133]
	s_mov_b32 m0, s72
	s_nop 0
	global_load_lds_dwordx4 v[196:197], off
	s_waitcnt lgkmcnt(8)
	s_setprio 1
	s_barrier
	s_waitcnt lgkmcnt(0)
	v_mfma_f32_16x16x32_bf16 v[124:127], v[148:151], v[164:167], v[124:127]
	v_mfma_f32_16x16x32_bf16 v[120:123], v[156:159], v[164:167], v[120:123]
	v_mfma_f32_16x16x32_bf16 v[116:119], v[148:151], v[172:175], v[116:119]
	v_mfma_f32_16x16x32_bf16 v[108:111], v[156:159], v[172:175], v[108:111]
	v_mfma_f32_16x16x32_bf16 v[100:103], v[148:151], v[180:183], v[100:103]
	v_mfma_f32_16x16x32_bf16 v[92:95], v[156:159], v[180:183], v[92:95]
	v_mfma_f32_16x16x32_bf16 v[84:87], v[148:151], v[188:191], v[84:87]
	v_mfma_f32_16x16x32_bf16 v[76:79], v[156:159], v[188:191], v[76:79]
	v_mfma_f32_16x16x32_bf16 v[124:127], v[152:155], v[168:171], v[124:127]
	v_mfma_f32_16x16x32_bf16 v[120:123], v[160:163], v[168:171], v[120:123]
	v_mfma_f32_16x16x32_bf16 v[116:119], v[152:155], v[176:179], v[116:119]
	v_mfma_f32_16x16x32_bf16 v[108:111], v[160:163], v[176:179], v[108:111]
	v_mfma_f32_16x16x32_bf16 v[100:103], v[152:155], v[184:187], v[100:103]
	v_mfma_f32_16x16x32_bf16 v[92:95], v[160:163], v[184:187], v[92:95]
	v_mfma_f32_16x16x32_bf16 v[84:87], v[152:155], v[192:195], v[84:87]
	v_mfma_f32_16x16x32_bf16 v[76:79], v[160:163], v[192:195], v[76:79]
	s_barrier
	s_setprio 0
	s_add_i32 s50, 0, 0x1c000
	s_add_i32 s51, s81, s69
	v_add_u32_e32 v147, s50, v144
	v_lshl_add_u64 v[140:141], v[140:141], 0, s[2:3]
	s_mov_b32 m0, s51
	ds_read_b128 v[196:199], v147
	ds_read_b128 v[200:203], v147 offset:1024
	ds_read_b128 v[204:207], v147 offset:2048
	ds_read_b128 v[212:215], v147 offset:3072
	global_load_lds_dwordx4 v[140:141], off
	v_lshl_add_u64 v[140:141], v[208:209], 0, s[2:3]
	s_add_i32 m0, s51, 0x2000
	s_nop 0
	global_load_lds_dwordx4 v[140:141], off
	s_setprio 1
	s_barrier
	s_waitcnt lgkmcnt(0)
	v_mfma_f32_16x16x32_bf16 v[112:115], v[196:199], v[164:167], v[112:115]
	v_mfma_f32_16x16x32_bf16 v[104:107], v[204:207], v[164:167], v[104:107]
	v_mfma_f32_16x16x32_bf16 v[96:99], v[196:199], v[172:175], v[96:99]
	v_mfma_f32_16x16x32_bf16 v[88:91], v[204:207], v[172:175], v[88:91]
	v_mfma_f32_16x16x32_bf16 v[80:83], v[196:199], v[180:183], v[80:83]
	v_mfma_f32_16x16x32_bf16 v[72:75], v[204:207], v[180:183], v[72:75]
	v_mfma_f32_16x16x32_bf16 v[68:71], v[196:199], v[188:191], v[68:71]
	v_mfma_f32_16x16x32_bf16 v[64:67], v[204:207], v[188:191], v[64:67]
	v_mfma_f32_16x16x32_bf16 v[112:115], v[200:203], v[168:171], v[112:115]
	v_mfma_f32_16x16x32_bf16 v[104:107], v[212:215], v[168:171], v[104:107]
	v_mfma_f32_16x16x32_bf16 v[96:99], v[200:203], v[176:179], v[96:99]
	v_mfma_f32_16x16x32_bf16 v[88:91], v[212:215], v[176:179], v[88:91]
	v_mfma_f32_16x16x32_bf16 v[80:83], v[200:203], v[184:187], v[80:83]
	v_mfma_f32_16x16x32_bf16 v[72:75], v[212:215], v[184:187], v[72:75]
	v_mfma_f32_16x16x32_bf16 v[68:71], v[200:203], v[192:195], v[68:71]
	v_mfma_f32_16x16x32_bf16 v[64:67], v[212:215], v[192:195], v[64:67]
	s_barrier
	s_setprio 0
	s_mov_b32 m0, s0
	v_lshl_add_u64 v[140:141], v[216:217], 0, s[2:3]
	ds_read_b128 v[164:167], v146 offset:49152
	ds_read_b128 v[168:171], v146 offset:50176
	ds_read_b128 v[172:175], v146 offset:51200
	ds_read_b128 v[176:179], v146 offset:52224
	ds_read_b128 v[180:183], v146 offset:53248
	ds_read_b128 v[184:187], v146 offset:54272
	ds_read_b128 v[188:191], v146 offset:55296
	ds_read_b128 v[192:195], v146 offset:56320
	global_load_lds_dwordx4 v[140:141], off
	v_lshl_add_u64 v[140:141], v[218:219], 0, s[2:3]
	s_mov_b32 m0, s73
	s_nop 0
	global_load_lds_dwordx4 v[140:141], off
	s_setprio 1
	s_barrier
	s_waitcnt lgkmcnt(0)
	v_mfma_f32_16x16x32_bf16 v[60:63], v[148:151], v[164:167], v[60:63]
	v_mfma_f32_16x16x32_bf16 v[56:59], v[156:159], v[164:167], v[56:59]
	v_mfma_f32_16x16x32_bf16 v[52:55], v[148:151], v[172:175], v[52:55]
	v_mfma_f32_16x16x32_bf16 v[44:47], v[156:159], v[172:175], v[44:47]
	v_mfma_f32_16x16x32_bf16 v[36:39], v[148:151], v[180:183], v[36:39]
	v_mfma_f32_16x16x32_bf16 v[28:31], v[156:159], v[180:183], v[28:31]
	v_mfma_f32_16x16x32_bf16 v[20:23], v[148:151], v[188:191], v[20:23]
	v_mfma_f32_16x16x32_bf16 v[12:15], v[156:159], v[188:191], v[12:15]
	v_mfma_f32_16x16x32_bf16 v[60:63], v[152:155], v[168:171], v[60:63]
	v_mfma_f32_16x16x32_bf16 v[56:59], v[160:163], v[168:171], v[56:59]
	v_mfma_f32_16x16x32_bf16 v[52:55], v[152:155], v[176:179], v[52:55]
	v_mfma_f32_16x16x32_bf16 v[44:47], v[160:163], v[176:179], v[44:47]
	v_mfma_f32_16x16x32_bf16 v[36:39], v[152:155], v[184:187], v[36:39]
	v_mfma_f32_16x16x32_bf16 v[28:31], v[160:163], v[184:187], v[28:31]
	v_mfma_f32_16x16x32_bf16 v[20:23], v[152:155], v[192:195], v[20:23]
	v_mfma_f32_16x16x32_bf16 v[12:15], v[160:163], v[192:195], v[12:15]
	s_barrier
	s_setprio 0
	s_add_u32 s48, s48, 0x40080
	s_addc_u32 s49, s49, 0
	s_add_i32 s50, s50, s69
	v_lshl_add_u64 v[140:141], s[48:49], 0, v[128:129]
	s_mov_b32 m0, s50
	s_nop 0
	global_load_lds_dwordx4 v[140:141], off
	v_lshl_add_u64 v[140:141], s[48:49], 0, v[134:135]
	s_add_i32 m0, s50, 0x2000
	s_nop 0
	global_load_lds_dwordx4 v[140:141], off
	s_waitcnt vmcnt(6)
	s_setprio 1
	s_barrier
	v_mfma_f32_16x16x32_bf16 v[48:51], v[196:199], v[164:167], v[48:51]
	v_mfma_f32_16x16x32_bf16 v[40:43], v[204:207], v[164:167], v[40:43]
	v_mfma_f32_16x16x32_bf16 v[32:35], v[196:199], v[172:175], v[32:35]
	v_mfma_f32_16x16x32_bf16 v[24:27], v[204:207], v[172:175], v[24:27]
	v_mfma_f32_16x16x32_bf16 v[16:19], v[196:199], v[180:183], v[16:19]
	v_mfma_f32_16x16x32_bf16 v[8:11], v[204:207], v[180:183], v[8:11]
	v_mfma_f32_16x16x32_bf16 v[4:7], v[196:199], v[188:191], v[4:7]
	v_mfma_f32_16x16x32_bf16 v[0:3], v[204:207], v[188:191], v[0:3]
	v_mfma_f32_16x16x32_bf16 v[48:51], v[200:203], v[168:171], v[48:51]
	v_mfma_f32_16x16x32_bf16 v[40:43], v[212:215], v[168:171], v[40:43]
	v_mfma_f32_16x16x32_bf16 v[32:35], v[200:203], v[176:179], v[32:35]
	v_mfma_f32_16x16x32_bf16 v[24:27], v[212:215], v[176:179], v[24:27]
	v_mfma_f32_16x16x32_bf16 v[16:19], v[200:203], v[184:187], v[16:19]
	v_mfma_f32_16x16x32_bf16 v[8:11], v[212:215], v[184:187], v[8:11]
	v_mfma_f32_16x16x32_bf16 v[4:7], v[200:203], v[192:195], v[4:7]
	v_mfma_f32_16x16x32_bf16 v[0:3], v[212:215], v[192:195], v[0:3]
	s_barrier
	s_setprio 0
	s_add_i32 s80, s80, 2
	s_add_u32 s42, s42, 0x100
	s_addc_u32 s43, s43, 0
	s_add_u32 s78, s78, 0x100
	s_addc_u32 s79, s79, 0
	s_cmp_gt_u32 s80, 13
	s_cbranch_scc0 .LBB0_200
	v_lshl_add_u32 v148, s36, 8, v143
	v_ashrrev_i32_e32 v149, 31, v148
	v_lshl_or_b32 v140, s75, 8, v145
	v_ashrrev_i32_e32 v141, 31, v140
	v_lshlrev_b64 v[150:151], 10, v[148:149]
	v_lshl_add_u64 v[150:151], s[14:15], 0, v[150:151]
	v_lshlrev_b64 v[152:153], 1, v[140:141]
	v_lshl_add_u64 v[140:141], v[150:151], 0, v[152:153]
	v_cvt_pk_bf16_f32 v124, v124, v125
	v_cvt_pk_bf16_f32 v125, v126, v127
	v_cvt_pk_bf16_f32 v126, v120, v121
	v_cvt_pk_bf16_f32 v127, v122, v123
	global_store_dwordx4 v[140:141], v[124:127], off nt
	v_cvt_pk_bf16_f32 v112, v112, v113
	v_cvt_pk_bf16_f32 v113, v114, v115
	v_cvt_pk_bf16_f32 v114, v104, v105
	v_or_b32_e32 v104, 16, v148
	v_ashrrev_i32_e32 v105, 31, v104
	v_lshlrev_b64 v[104:105], 10, v[104:105]
	v_lshl_add_u64 v[104:105], s[14:15], 0, v[104:105]
	v_cvt_pk_bf16_f32 v115, v106, v107
	global_store_dwordx4 v[140:141], v[112:115], off offset:256 nt
	s_mov_b32 s31, 0x20000
	s_mov_b64 s[42:43], 0x20000
	v_lshl_add_u64 v[112:113], v[104:105], 0, v[152:153]
	v_cvt_pk_bf16_f32 v104, v116, v117
	v_cvt_pk_bf16_f32 v105, v118, v119
	v_cvt_pk_bf16_f32 v106, v108, v109
	v_cvt_pk_bf16_f32 v107, v110, v111
	global_store_dwordx4 v[112:113], v[104:107], off nt
	v_cvt_pk_bf16_f32 v96, v96, v97
	v_cvt_pk_bf16_f32 v97, v98, v99
	v_cvt_pk_bf16_f32 v98, v88, v89
	v_or_b32_e32 v88, 32, v148
	v_ashrrev_i32_e32 v89, 31, v88
	v_lshlrev_b64 v[88:89], 10, v[88:89]
	v_lshl_add_u64 v[88:89], s[14:15], 0, v[88:89]
	v_cvt_pk_bf16_f32 v99, v90, v91
	global_store_dwordx4 v[112:113], v[96:99], off offset:256 nt
	s_mov_b32 s75, s30
	s_mov_b32 s36, s34
	v_lshl_add_u64 v[96:97], v[88:89], 0, v[152:153]
	v_cvt_pk_bf16_f32 v88, v100, v101
	v_cvt_pk_bf16_f32 v89, v102, v103
	v_cvt_pk_bf16_f32 v90, v92, v93
	v_cvt_pk_bf16_f32 v91, v94, v95
	global_store_dwordx4 v[96:97], v[88:91], off nt
	v_cvt_pk_bf16_f32 v80, v80, v81
	v_cvt_pk_bf16_f32 v81, v82, v83
	v_cvt_pk_bf16_f32 v82, v72, v73
	v_or_b32_e32 v72, 48, v148
	v_ashrrev_i32_e32 v73, 31, v72
	v_lshlrev_b64 v[72:73], 10, v[72:73]
	v_lshl_add_u64 v[72:73], s[14:15], 0, v[72:73]
	v_cvt_pk_bf16_f32 v83, v74, v75
	global_store_dwordx4 v[96:97], v[80:83], off offset:256 nt
	s_mov_b64 s[48:49], s[40:41]
	s_nop 0
	v_lshl_add_u64 v[80:81], v[72:73], 0, v[152:153]
	v_cvt_pk_bf16_f32 v72, v84, v85
	v_cvt_pk_bf16_f32 v73, v86, v87
	v_cvt_pk_bf16_f32 v74, v76, v77
	v_cvt_pk_bf16_f32 v75, v78, v79
	global_store_dwordx4 v[80:81], v[72:75], off nt
	v_cvt_pk_bf16_f32 v68, v68, v69
	v_cvt_pk_bf16_f32 v69, v70, v71
	v_cvt_pk_bf16_f32 v70, v64, v65
	v_cvt_pk_bf16_f32 v71, v66, v67
	global_store_dwordx4 v[80:81], v[68:71], off offset:256 nt
	v_cvt_pk_bf16_f32 v60, v60, v61
	v_cvt_pk_bf16_f32 v61, v62, v63
	v_cvt_pk_bf16_f32 v62, v56, v57
	v_add_co_u32_e32 v56, vcc, s31, v140
	v_lshl_add_u64 v[64:65], v[140:141], 0, s[42:43]
	s_nop 0
	v_addc_co_u32_e32 v57, vcc, 0, v141, vcc
	s_mov_b32 s31, 0x24000
	v_cvt_pk_bf16_f32 v63, v58, v59
	global_store_dwordx4 v[56:57], v[60:63], off nt
	v_cvt_pk_bf16_f32 v48, v48, v49
	v_cvt_pk_bf16_f32 v49, v50, v51
	v_cvt_pk_bf16_f32 v50, v40, v41
	v_cvt_pk_bf16_f32 v51, v42, v43
	global_store_dwordx4 v[64:65], v[48:51], off offset:256 nt
	s_mov_b64 s[42:43], 0x24000
	v_cvt_pk_bf16_f32 v40, v52, v53
	v_cvt_pk_bf16_f32 v41, v54, v55
	v_cvt_pk_bf16_f32 v42, v44, v45
	v_add_co_u32_e32 v44, vcc, s31, v140
	v_lshl_add_u64 v[48:49], v[140:141], 0, s[42:43]
	s_nop 0
	v_addc_co_u32_e32 v45, vcc, 0, v141, vcc
	s_mov_b32 s31, 0x28000
	v_cvt_pk_bf16_f32 v43, v46, v47
	global_store_dwordx4 v[44:45], v[40:43], off nt
	v_cvt_pk_bf16_f32 v32, v32, v33
	v_cvt_pk_bf16_f32 v33, v34, v35
	v_cvt_pk_bf16_f32 v34, v24, v25
	v_cvt_pk_bf16_f32 v35, v26, v27
	global_store_dwordx4 v[48:49], v[32:35], off offset:256 nt
	s_mov_b64 s[42:43], 0x28000
	v_cvt_pk_bf16_f32 v24, v36, v37
	v_cvt_pk_bf16_f32 v25, v38, v39
	v_cvt_pk_bf16_f32 v26, v28, v29
	v_add_co_u32_e32 v28, vcc, s31, v140
	v_lshl_add_u64 v[32:33], v[140:141], 0, s[42:43]
	s_nop 0
	v_addc_co_u32_e32 v29, vcc, 0, v141, vcc
	s_mov_b32 s31, 0x2c000
	v_cvt_pk_bf16_f32 v27, v30, v31
	global_store_dwordx4 v[28:29], v[24:27], off nt
	v_cvt_pk_bf16_f32 v16, v16, v17
	v_cvt_pk_bf16_f32 v17, v18, v19
	v_cvt_pk_bf16_f32 v18, v8, v9
	v_cvt_pk_bf16_f32 v19, v10, v11
	global_store_dwordx4 v[32:33], v[16:19], off offset:256 nt
	v_cvt_pk_bf16_f32 v8, v20, v21
	v_cvt_pk_bf16_f32 v9, v22, v23
	v_cvt_pk_bf16_f32 v10, v12, v13
	v_add_co_u32_e32 v12, vcc, s31, v140
	s_mov_b64 s[42:43], 0x2c000
	s_nop 0
	v_addc_co_u32_e32 v13, vcc, 0, v141, vcc
	v_lshl_add_u64 v[16:17], v[140:141], 0, s[42:43]
	s_and_b64 vcc, exec, s[28:29]
	s_mov_b64 s[42:43], s[38:39]
	v_cvt_pk_bf16_f32 v11, v14, v15
	global_store_dwordx4 v[12:13], v[8:11], off nt
	v_cvt_pk_bf16_f32 v4, v4, v5
	v_cvt_pk_bf16_f32 v5, v6, v7
	v_cvt_pk_bf16_f32 v6, v0, v1
	v_cvt_pk_bf16_f32 v7, v2, v3
	global_store_dwordx4 v[16:17], v[4:7], off offset:256 nt
	s_cbranch_vccz .LBB0_193
	s_waitcnt vmcnt(0)
	s_cmpk_gt_u32 s65, 0xff
	s_cbranch_scc1 .LBB0_204
	s_barrier

.LBB0_220:
	s_add_u32 s40, s38, 0xfffc0080
	s_addc_u32 s41, s39, -1
	s_add_i32 s76, 0, 0x10000
	v_add_u32_e32 v140, s76, v144
	ds_read_b128 v[148:151], v140
	ds_read_b128 v[152:155], v140 offset:1024
	ds_read_b128 v[156:159], v140 offset:2048
	ds_read_b128 v[160:163], v140 offset:3072
	s_cmp_eq_u32 s75, 12
	s_cselect_b32 s43, s29, s41
	s_cselect_b32 s42, s71, s40
	s_cselect_b32 s41, s15, s74
	s_cselect_b32 s40, s72, s73
	v_lshl_add_u64 v[140:141], s[38:39], 0, v[136:137]
	s_add_i32 m0, s31, 0xc000
	ds_read_b128 v[164:167], v146
	ds_read_b128 v[168:171], v146 offset:1024
	ds_read_b128 v[172:175], v146 offset:2048
	ds_read_b128 v[176:179], v146 offset:3072
	ds_read_b128 v[180:183], v146 offset:4096
	ds_read_b128 v[184:187], v146 offset:5120
	ds_read_b128 v[188:191], v146 offset:6144
	ds_read_b128 v[192:195], v146 offset:7168
	global_load_lds_dwordx4 v[140:141], off
	v_lshl_add_u64 v[140:141], s[38:39], 0, v[138:139]
	s_add_i32 m0, s31, 0xe000
	s_nop 0
	global_load_lds_dwordx4 v[140:141], off
	s_waitcnt lgkmcnt(8)
	s_setprio 1
	s_barrier
	s_waitcnt lgkmcnt(0)
	v_mfma_f32_16x16x32_bf16 v[124:127], v[148:151], v[164:167], v[124:127]
	v_mfma_f32_16x16x32_bf16 v[120:123], v[156:159], v[164:167], v[120:123]
	v_mfma_f32_16x16x32_bf16 v[116:119], v[148:151], v[172:175], v[116:119]
	v_mfma_f32_16x16x32_bf16 v[108:111], v[156:159], v[172:175], v[108:111]
	v_mfma_f32_16x16x32_bf16 v[100:103], v[148:151], v[180:183], v[100:103]
	v_mfma_f32_16x16x32_bf16 v[92:95], v[156:159], v[180:183], v[92:95]
	v_mfma_f32_16x16x32_bf16 v[84:87], v[148:151], v[188:191], v[84:87]
	v_mfma_f32_16x16x32_bf16 v[76:79], v[156:159], v[188:191], v[76:79]
	v_mfma_f32_16x16x32_bf16 v[124:127], v[152:155], v[168:171], v[124:127]
	v_mfma_f32_16x16x32_bf16 v[120:123], v[160:163], v[168:171], v[120:123]
	v_mfma_f32_16x16x32_bf16 v[116:119], v[152:155], v[176:179], v[116:119]
	v_mfma_f32_16x16x32_bf16 v[108:111], v[160:163], v[176:179], v[108:111]
	v_mfma_f32_16x16x32_bf16 v[100:103], v[152:155], v[184:187], v[100:103]
	v_mfma_f32_16x16x32_bf16 v[92:95], v[160:163], v[184:187], v[92:95]
	v_mfma_f32_16x16x32_bf16 v[84:87], v[152:155], v[192:195], v[84:87]
	v_mfma_f32_16x16x32_bf16 v[76:79], v[160:163], v[192:195], v[76:79]
	s_barrier
	s_setprio 0
	s_add_i32 s78, 0, 0x14000
	v_add_u32_e32 v140, s78, v144
	s_add_i32 s76, s76, s64
	ds_read_b128 v[196:199], v140
	ds_read_b128 v[200:203], v140 offset:1024
	ds_read_b128 v[204:207], v140 offset:2048
	ds_read_b128 v[212:215], v140 offset:3072
	v_lshl_add_u64 v[140:141], s[40:41], 0, v[128:129]
	s_mov_b32 m0, s76
	v_lshl_add_u64 v[208:209], s[40:41], 0, v[134:135]
	global_load_lds_dwordx4 v[140:141], off
	s_add_i32 m0, s76, 0x2000
	s_nop 0
	global_load_lds_dwordx4 v[208:209], off
	s_setprio 1
	s_barrier
	s_waitcnt lgkmcnt(0)
	v_mfma_f32_16x16x32_bf16 v[112:115], v[196:199], v[164:167], v[112:115]
	v_mfma_f32_16x16x32_bf16 v[104:107], v[204:207], v[164:167], v[104:107]
	v_mfma_f32_16x16x32_bf16 v[96:99], v[196:199], v[172:175], v[96:99]
	v_mfma_f32_16x16x32_bf16 v[88:91], v[204:207], v[172:175], v[88:91]
	v_mfma_f32_16x16x32_bf16 v[80:83], v[196:199], v[180:183], v[80:83]
	v_mfma_f32_16x16x32_bf16 v[72:75], v[204:207], v[180:183], v[72:75]
	v_mfma_f32_16x16x32_bf16 v[68:71], v[196:199], v[188:191], v[68:71]
	v_mfma_f32_16x16x32_bf16 v[64:67], v[204:207], v[188:191], v[64:67]
	v_mfma_f32_16x16x32_bf16 v[112:115], v[200:203], v[168:171], v[112:115]
	v_mfma_f32_16x16x32_bf16 v[104:107], v[212:215], v[168:171], v[104:107]
	v_mfma_f32_16x16x32_bf16 v[96:99], v[200:203], v[176:179], v[96:99]
	v_mfma_f32_16x16x32_bf16 v[88:91], v[212:215], v[176:179], v[88:91]
	v_mfma_f32_16x16x32_bf16 v[80:83], v[200:203], v[184:187], v[80:83]
	v_mfma_f32_16x16x32_bf16 v[72:75], v[212:215], v[184:187], v[72:75]
	v_mfma_f32_16x16x32_bf16 v[68:71], v[200:203], v[192:195], v[68:71]
	v_mfma_f32_16x16x32_bf16 v[64:67], v[212:215], v[192:195], v[64:67]
	s_barrier
	s_setprio 0
	s_mov_b32 m0, s31
	v_lshl_add_u64 v[216:217], s[42:43], 0, v[130:131]
	ds_read_b128 v[164:167], v146 offset:16384
	ds_read_b128 v[168:171], v146 offset:17408
	ds_read_b128 v[172:175], v146 offset:18432
	ds_read_b128 v[176:179], v146 offset:19456
	ds_read_b128 v[180:183], v146 offset:20480
	ds_read_b128 v[184:187], v146 offset:21504
	ds_read_b128 v[188:191], v146 offset:22528
	ds_read_b128 v[192:195], v146 offset:23552
	global_load_lds_dwordx4 v[216:217], off
	v_lshl_add_u64 v[218:219], s[42:43], 0, v[132:133]
	s_mov_b32 m0, s65
	s_nop 0
	global_load_lds_dwordx4 v[218:219], off
	s_setprio 1
	s_barrier
	s_waitcnt lgkmcnt(0)
	v_mfma_f32_16x16x32_bf16 v[60:63], v[148:151], v[164:167], v[60:63]
	v_mfma_f32_16x16x32_bf16 v[56:59], v[156:159], v[164:167], v[56:59]
	v_mfma_f32_16x16x32_bf16 v[52:55], v[148:151], v[172:175], v[52:55]
	v_mfma_f32_16x16x32_bf16 v[44:47], v[156:159], v[172:175], v[44:47]
	v_mfma_f32_16x16x32_bf16 v[36:39], v[148:151], v[180:183], v[36:39]
	v_mfma_f32_16x16x32_bf16 v[28:31], v[156:159], v[180:183], v[28:31]
	v_mfma_f32_16x16x32_bf16 v[20:23], v[148:151], v[188:191], v[20:23]
	v_mfma_f32_16x16x32_bf16 v[12:15], v[156:159], v[188:191], v[12:15]
	v_mfma_f32_16x16x32_bf16 v[60:63], v[152:155], v[168:171], v[60:63]
	v_mfma_f32_16x16x32_bf16 v[56:59], v[160:163], v[168:171], v[56:59]
	v_mfma_f32_16x16x32_bf16 v[52:55], v[152:155], v[176:179], v[52:55]
	v_mfma_f32_16x16x32_bf16 v[44:47], v[160:163], v[176:179], v[44:47]
	v_mfma_f32_16x16x32_bf16 v[36:39], v[152:155], v[184:187], v[36:39]
	v_mfma_f32_16x16x32_bf16 v[28:31], v[160:163], v[184:187], v[28:31]
	v_mfma_f32_16x16x32_bf16 v[20:23], v[152:155], v[192:195], v[20:23]
	v_mfma_f32_16x16x32_bf16 v[12:15], v[160:163], v[192:195], v[12:15]
	s_barrier
	s_setprio 0
	s_add_u32 s76, s40, 0x40000
	s_addc_u32 s77, s41, 0
	s_add_i32 s78, s78, s64
	v_lshl_add_u64 v[148:149], s[76:77], 0, v[128:129]
	s_mov_b32 m0, s78
	s_nop 0
	global_load_lds_dwordx4 v[148:149], off
	v_lshl_add_u64 v[148:149], s[76:77], 0, v[134:135]
	s_add_i32 m0, s78, 0x2000
	s_nop 0
	global_load_lds_dwordx4 v[148:149], off
	s_waitcnt vmcnt(6)
	s_setprio 1
	s_barrier
	v_mfma_f32_16x16x32_bf16 v[48:51], v[196:199], v[164:167], v[48:51]
	v_mfma_f32_16x16x32_bf16 v[40:43], v[204:207], v[164:167], v[40:43]
	v_mfma_f32_16x16x32_bf16 v[32:35], v[196:199], v[172:175], v[32:35]
	v_mfma_f32_16x16x32_bf16 v[24:27], v[204:207], v[172:175], v[24:27]
	v_mfma_f32_16x16x32_bf16 v[16:19], v[196:199], v[180:183], v[16:19]
	v_mfma_f32_16x16x32_bf16 v[8:11], v[204:207], v[180:183], v[8:11]
	v_mfma_f32_16x16x32_bf16 v[4:7], v[196:199], v[188:191], v[4:7]
	v_mfma_f32_16x16x32_bf16 v[0:3], v[204:207], v[188:191], v[0:3]
	v_mfma_f32_16x16x32_bf16 v[48:51], v[200:203], v[168:171], v[48:51]
	v_mfma_f32_16x16x32_bf16 v[40:43], v[212:215], v[168:171], v[40:43]
	v_mfma_f32_16x16x32_bf16 v[32:35], v[200:203], v[176:179], v[32:35]
	v_mfma_f32_16x16x32_bf16 v[24:27], v[212:215], v[176:179], v[24:27]
	v_mfma_f32_16x16x32_bf16 v[16:19], v[200:203], v[184:187], v[16:19]
	v_mfma_f32_16x16x32_bf16 v[8:11], v[212:215], v[184:187], v[8:11]
	v_mfma_f32_16x16x32_bf16 v[4:7], v[200:203], v[192:195], v[4:7]
	v_mfma_f32_16x16x32_bf16 v[0:3], v[212:215], v[192:195], v[0:3]
	s_barrier
	s_setprio 0
	s_add_i32 s76, 0, 0x18000
	v_add_u32_e32 v147, s76, v144
	ds_read_b128 v[148:151], v147
	ds_read_b128 v[152:155], v147 offset:1024
	ds_read_b128 v[156:159], v147 offset:2048
	ds_read_b128 v[160:163], v147 offset:3072
	s_add_u32 s42, s42, 0x40000
	s_addc_u32 s43, s43, 0
	s_mov_b32 m0, s66
	v_lshl_add_u64 v[196:197], s[42:43], 0, v[130:131]
	ds_read_b128 v[164:167], v146 offset:32768
	ds_read_b128 v[168:171], v146 offset:33792
	ds_read_b128 v[172:175], v146 offset:34816
	ds_read_b128 v[176:179], v146 offset:35840
	ds_read_b128 v[180:183], v146 offset:36864
	ds_read_b128 v[184:187], v146 offset:37888
	ds_read_b128 v[188:191], v146 offset:38912
	ds_read_b128 v[192:195], v146 offset:39936
	global_load_lds_dwordx4 v[196:197], off
	v_lshl_add_u64 v[196:197], s[42:43], 0, v[132:133]
	s_mov_b32 m0, s67
	s_nop 0
	global_load_lds_dwordx4 v[196:197], off
	s_waitcnt lgkmcnt(8)
	s_setprio 1
	s_barrier
	s_waitcnt lgkmcnt(0)
	v_mfma_f32_16x16x32_bf16 v[124:127], v[148:151], v[164:167], v[124:127]
	v_mfma_f32_16x16x32_bf16 v[120:123], v[156:159], v[164:167], v[120:123]
	v_mfma_f32_16x16x32_bf16 v[116:119], v[148:151], v[172:175], v[116:119]
	v_mfma_f32_16x16x32_bf16 v[108:111], v[156:159], v[172:175], v[108:111]
	v_mfma_f32_16x16x32_bf16 v[100:103], v[148:151], v[180:183], v[100:103]
	v_mfma_f32_16x16x32_bf16 v[92:95], v[156:159], v[180:183], v[92:95]
	v_mfma_f32_16x16x32_bf16 v[84:87], v[148:151], v[188:191], v[84:87]
	v_mfma_f32_16x16x32_bf16 v[76:79], v[156:159], v[188:191], v[76:79]
	v_mfma_f32_16x16x32_bf16 v[124:127], v[152:155], v[168:171], v[124:127]
	v_mfma_f32_16x16x32_bf16 v[120:123], v[160:163], v[168:171], v[120:123]
	v_mfma_f32_16x16x32_bf16 v[116:119], v[152:155], v[176:179], v[116:119]
	v_mfma_f32_16x16x32_bf16 v[108:111], v[160:163], v[176:179], v[108:111]
	v_mfma_f32_16x16x32_bf16 v[100:103], v[152:155], v[184:187], v[100:103]
	v_mfma_f32_16x16x32_bf16 v[92:95], v[160:163], v[184:187], v[92:95]
	v_mfma_f32_16x16x32_bf16 v[84:87], v[152:155], v[192:195], v[84:87]
	v_mfma_f32_16x16x32_bf16 v[76:79], v[160:163], v[192:195], v[76:79]
	s_barrier
	s_setprio 0
	s_add_i32 s42, 0, 0x1c000
	s_add_i32 s43, s76, s64
	v_add_u32_e32 v147, s42, v144
	v_lshl_add_u64 v[140:141], v[140:141], 0, s[2:3]
	s_mov_b32 m0, s43
	ds_read_b128 v[196:199], v147
	ds_read_b128 v[200:203], v147 offset:1024
	ds_read_b128 v[204:207], v147 offset:2048
	ds_read_b128 v[212:215], v147 offset:3072
	global_load_lds_dwordx4 v[140:141], off
	v_lshl_add_u64 v[140:141], v[208:209], 0, s[2:3]
	s_add_i32 m0, s43, 0x2000
	s_nop 0
	global_load_lds_dwordx4 v[140:141], off
	s_setprio 1
	s_barrier
	s_waitcnt lgkmcnt(0)
	v_mfma_f32_16x16x32_bf16 v[112:115], v[196:199], v[164:167], v[112:115]
	v_mfma_f32_16x16x32_bf16 v[104:107], v[204:207], v[164:167], v[104:107]
	v_mfma_f32_16x16x32_bf16 v[96:99], v[196:199], v[172:175], v[96:99]
	v_mfma_f32_16x16x32_bf16 v[88:91], v[204:207], v[172:175], v[88:91]
	v_mfma_f32_16x16x32_bf16 v[80:83], v[196:199], v[180:183], v[80:83]
	v_mfma_f32_16x16x32_bf16 v[72:75], v[204:207], v[180:183], v[72:75]
	v_mfma_f32_16x16x32_bf16 v[68:71], v[196:199], v[188:191], v[68:71]
	v_mfma_f32_16x16x32_bf16 v[64:67], v[204:207], v[188:191], v[64:67]
	v_mfma_f32_16x16x32_bf16 v[112:115], v[200:203], v[168:171], v[112:115]
	v_mfma_f32_16x16x32_bf16 v[104:107], v[212:215], v[168:171], v[104:107]
	v_mfma_f32_16x16x32_bf16 v[96:99], v[200:203], v[176:179], v[96:99]
	v_mfma_f32_16x16x32_bf16 v[88:91], v[212:215], v[176:179], v[88:91]
	v_mfma_f32_16x16x32_bf16 v[80:83], v[200:203], v[184:187], v[80:83]
	v_mfma_f32_16x16x32_bf16 v[72:75], v[212:215], v[184:187], v[72:75]
	v_mfma_f32_16x16x32_bf16 v[68:71], v[200:203], v[192:195], v[68:71]
	v_mfma_f32_16x16x32_bf16 v[64:67], v[212:215], v[192:195], v[64:67]
	s_barrier
	s_setprio 0
	s_mov_b32 m0, s0
	v_lshl_add_u64 v[140:141], v[216:217], 0, s[2:3]
	ds_read_b128 v[164:167], v146 offset:49152
	ds_read_b128 v[168:171], v146 offset:50176
	ds_read_b128 v[172:175], v146 offset:51200
	ds_read_b128 v[176:179], v146 offset:52224
	ds_read_b128 v[180:183], v146 offset:53248
	ds_read_b128 v[184:187], v146 offset:54272
	ds_read_b128 v[188:191], v146 offset:55296
	ds_read_b128 v[192:195], v146 offset:56320
	global_load_lds_dwordx4 v[140:141], off
	v_lshl_add_u64 v[140:141], v[218:219], 0, s[2:3]
	s_mov_b32 m0, s68
	s_nop 0
	global_load_lds_dwordx4 v[140:141], off
	s_setprio 1
	s_barrier
	s_waitcnt lgkmcnt(0)
	v_mfma_f32_16x16x32_bf16 v[60:63], v[148:151], v[164:167], v[60:63]
	v_mfma_f32_16x16x32_bf16 v[56:59], v[156:159], v[164:167], v[56:59]
	v_mfma_f32_16x16x32_bf16 v[52:55], v[148:151], v[172:175], v[52:55]
	v_mfma_f32_16x16x32_bf16 v[44:47], v[156:159], v[172:175], v[44:47]
	v_mfma_f32_16x16x32_bf16 v[36:39], v[148:151], v[180:183], v[36:39]
	v_mfma_f32_16x16x32_bf16 v[28:31], v[156:159], v[180:183], v[28:31]
	v_mfma_f32_16x16x32_bf16 v[20:23], v[148:151], v[188:191], v[20:23]
	v_mfma_f32_16x16x32_bf16 v[12:15], v[156:159], v[188:191], v[12:15]
	v_mfma_f32_16x16x32_bf16 v[60:63], v[152:155], v[168:171], v[60:63]
	v_mfma_f32_16x16x32_bf16 v[56:59], v[160:163], v[168:171], v[56:59]
	v_mfma_f32_16x16x32_bf16 v[52:55], v[152:155], v[176:179], v[52:55]
	v_mfma_f32_16x16x32_bf16 v[44:47], v[160:163], v[176:179], v[44:47]
	v_mfma_f32_16x16x32_bf16 v[36:39], v[152:155], v[184:187], v[36:39]
	v_mfma_f32_16x16x32_bf16 v[28:31], v[160:163], v[184:187], v[28:31]
	v_mfma_f32_16x16x32_bf16 v[20:23], v[152:155], v[192:195], v[20:23]
	v_mfma_f32_16x16x32_bf16 v[12:15], v[160:163], v[192:195], v[12:15]
	s_barrier
	s_setprio 0
	s_add_u32 s40, s40, 0x40080
	s_addc_u32 s41, s41, 0
	s_add_i32 s42, s42, s64
	v_lshl_add_u64 v[140:141], s[40:41], 0, v[128:129]
	s_mov_b32 m0, s42
	s_nop 0
	global_load_lds_dwordx4 v[140:141], off
	v_lshl_add_u64 v[140:141], s[40:41], 0, v[134:135]
	s_add_i32 m0, s42, 0x2000
	s_nop 0
	global_load_lds_dwordx4 v[140:141], off
	s_waitcnt vmcnt(6)
	s_setprio 1
	s_barrier
	v_mfma_f32_16x16x32_bf16 v[48:51], v[196:199], v[164:167], v[48:51]
	v_mfma_f32_16x16x32_bf16 v[40:43], v[204:207], v[164:167], v[40:43]
	v_mfma_f32_16x16x32_bf16 v[32:35], v[196:199], v[172:175], v[32:35]
	v_mfma_f32_16x16x32_bf16 v[24:27], v[204:207], v[172:175], v[24:27]
	v_mfma_f32_16x16x32_bf16 v[16:19], v[196:199], v[180:183], v[16:19]
	v_mfma_f32_16x16x32_bf16 v[8:11], v[204:207], v[180:183], v[8:11]
	v_mfma_f32_16x16x32_bf16 v[4:7], v[196:199], v[188:191], v[4:7]
	v_mfma_f32_16x16x32_bf16 v[0:3], v[204:207], v[188:191], v[0:3]
	v_mfma_f32_16x16x32_bf16 v[48:51], v[200:203], v[168:171], v[48:51]
	v_mfma_f32_16x16x32_bf16 v[40:43], v[212:215], v[168:171], v[40:43]
	v_mfma_f32_16x16x32_bf16 v[32:35], v[200:203], v[176:179], v[32:35]
	v_mfma_f32_16x16x32_bf16 v[24:27], v[212:215], v[176:179], v[24:27]
	v_mfma_f32_16x16x32_bf16 v[16:19], v[200:203], v[184:187], v[16:19]
	v_mfma_f32_16x16x32_bf16 v[8:11], v[212:215], v[184:187], v[8:11]
	v_mfma_f32_16x16x32_bf16 v[4:7], v[200:203], v[192:195], v[4:7]
	v_mfma_f32_16x16x32_bf16 v[0:3], v[212:215], v[192:195], v[0:3]
	s_barrier
	s_setprio 0
	s_add_i32 s75, s75, 2
	s_add_u32 s38, s38, 0x100
	s_addc_u32 s39, s39, 0
	s_add_u32 s73, s73, 0x100
	s_addc_u32 s74, s74, 0
	s_cmp_gt_u32 s75, 13
	s_cbranch_scc0 .LBB0_220
	v_lshl_add_u32 v148, s30, 8, v143
	v_ashrrev_i32_e32 v149, 31, v148
	v_lshl_or_b32 v140, s70, 8, v145
	v_ashrrev_i32_e32 v141, 31, v140
	v_lshlrev_b64 v[150:151], 13, v[148:149]
	v_lshl_add_u64 v[150:151], s[8:9], 0, v[150:151]
	v_lshlrev_b64 v[152:153], 1, v[140:141]
	v_lshl_add_u64 v[140:141], v[150:151], 0, v[152:153]
	v_cvt_pk_bf16_f32 v124, v124, v125
	v_cvt_pk_bf16_f32 v125, v126, v127
	v_cvt_pk_bf16_f32 v126, v120, v121
	v_cvt_pk_bf16_f32 v127, v122, v123
	global_store_dwordx4 v[140:141], v[124:127], off nt
	v_cvt_pk_bf16_f32 v112, v112, v113
	v_cvt_pk_bf16_f32 v113, v114, v115
	v_cvt_pk_bf16_f32 v114, v104, v105
	v_or_b32_e32 v104, 16, v148
	v_ashrrev_i32_e32 v105, 31, v104
	v_lshlrev_b64 v[104:105], 13, v[104:105]
	v_lshl_add_u64 v[104:105], s[8:9], 0, v[104:105]
	v_cvt_pk_bf16_f32 v115, v106, v107
	global_store_dwordx4 v[140:141], v[112:115], off offset:256 nt
	s_mov_b32 s15, 0x100000
	s_mov_b64 s[38:39], 0x100000
	v_lshl_add_u64 v[112:113], v[104:105], 0, v[152:153]
	v_cvt_pk_bf16_f32 v104, v116, v117
	v_cvt_pk_bf16_f32 v105, v118, v119
	v_cvt_pk_bf16_f32 v106, v108, v109
	v_cvt_pk_bf16_f32 v107, v110, v111
	global_store_dwordx4 v[112:113], v[104:107], off nt
	v_cvt_pk_bf16_f32 v96, v96, v97
	v_cvt_pk_bf16_f32 v97, v98, v99
	v_cvt_pk_bf16_f32 v98, v88, v89
	v_or_b32_e32 v88, 32, v148
	v_ashrrev_i32_e32 v89, 31, v88
	v_lshlrev_b64 v[88:89], 13, v[88:89]
	v_lshl_add_u64 v[88:89], s[8:9], 0, v[88:89]
	v_cvt_pk_bf16_f32 v99, v90, v91
	global_store_dwordx4 v[112:113], v[96:99], off offset:256 nt
	s_mov_b32 s70, s14
	s_mov_b32 s30, s28
	v_lshl_add_u64 v[96:97], v[88:89], 0, v[152:153]
	v_cvt_pk_bf16_f32 v88, v100, v101
	v_cvt_pk_bf16_f32 v89, v102, v103
	v_cvt_pk_bf16_f32 v90, v92, v93
	v_cvt_pk_bf16_f32 v91, v94, v95
	global_store_dwordx4 v[96:97], v[88:91], off nt
	v_cvt_pk_bf16_f32 v80, v80, v81
	v_cvt_pk_bf16_f32 v81, v82, v83
	v_cvt_pk_bf16_f32 v82, v72, v73
	v_or_b32_e32 v72, 48, v148
	v_ashrrev_i32_e32 v73, 31, v72
	v_lshlrev_b64 v[72:73], 13, v[72:73]
	v_lshl_add_u64 v[72:73], s[8:9], 0, v[72:73]
	v_cvt_pk_bf16_f32 v83, v74, v75
	global_store_dwordx4 v[96:97], v[80:83], off offset:256 nt
	s_mov_b64 s[40:41], s[36:37]
	s_nop 0
	v_lshl_add_u64 v[80:81], v[72:73], 0, v[152:153]
	v_cvt_pk_bf16_f32 v72, v84, v85
	v_cvt_pk_bf16_f32 v73, v86, v87
	v_cvt_pk_bf16_f32 v74, v76, v77
	v_cvt_pk_bf16_f32 v75, v78, v79
	global_store_dwordx4 v[80:81], v[72:75], off nt
	v_cvt_pk_bf16_f32 v68, v68, v69
	v_cvt_pk_bf16_f32 v69, v70, v71
	v_cvt_pk_bf16_f32 v70, v64, v65
	v_cvt_pk_bf16_f32 v71, v66, v67
	global_store_dwordx4 v[80:81], v[68:71], off offset:256 nt
	v_cvt_pk_bf16_f32 v60, v60, v61
	v_cvt_pk_bf16_f32 v61, v62, v63
	v_cvt_pk_bf16_f32 v62, v56, v57
	v_add_co_u32_e32 v56, vcc, s15, v140
	v_lshl_add_u64 v[64:65], v[140:141], 0, s[38:39]
	s_nop 0
	v_addc_co_u32_e32 v57, vcc, 0, v141, vcc
	s_mov_b32 s15, 0x120000
	v_cvt_pk_bf16_f32 v63, v58, v59
	global_store_dwordx4 v[56:57], v[60:63], off nt
	v_cvt_pk_bf16_f32 v48, v48, v49
	v_cvt_pk_bf16_f32 v49, v50, v51
	v_cvt_pk_bf16_f32 v50, v40, v41
	v_cvt_pk_bf16_f32 v51, v42, v43
	global_store_dwordx4 v[64:65], v[48:51], off offset:256 nt
	s_mov_b64 s[38:39], 0x120000
	v_cvt_pk_bf16_f32 v40, v52, v53
	v_cvt_pk_bf16_f32 v41, v54, v55
	v_cvt_pk_bf16_f32 v42, v44, v45
	v_add_co_u32_e32 v44, vcc, s15, v140
	v_lshl_add_u64 v[48:49], v[140:141], 0, s[38:39]
	s_nop 0
	v_addc_co_u32_e32 v45, vcc, 0, v141, vcc
	s_mov_b32 s15, 0x140000
	v_cvt_pk_bf16_f32 v43, v46, v47
	global_store_dwordx4 v[44:45], v[40:43], off nt
	v_cvt_pk_bf16_f32 v32, v32, v33
	v_cvt_pk_bf16_f32 v33, v34, v35
	v_cvt_pk_bf16_f32 v34, v24, v25
	v_cvt_pk_bf16_f32 v35, v26, v27
	global_store_dwordx4 v[48:49], v[32:35], off offset:256 nt
	s_mov_b64 s[38:39], 0x140000
	v_cvt_pk_bf16_f32 v24, v36, v37
	v_cvt_pk_bf16_f32 v25, v38, v39
	v_cvt_pk_bf16_f32 v26, v28, v29
	v_add_co_u32_e32 v28, vcc, s15, v140
	v_lshl_add_u64 v[32:33], v[140:141], 0, s[38:39]
	s_nop 0
	v_addc_co_u32_e32 v29, vcc, 0, v141, vcc
	s_mov_b32 s15, 0x160000
	v_cvt_pk_bf16_f32 v27, v30, v31
	global_store_dwordx4 v[28:29], v[24:27], off nt
	v_cvt_pk_bf16_f32 v16, v16, v17
	v_cvt_pk_bf16_f32 v17, v18, v19
	v_cvt_pk_bf16_f32 v18, v8, v9
	v_cvt_pk_bf16_f32 v19, v10, v11
	global_store_dwordx4 v[32:33], v[16:19], off offset:256 nt
	v_cvt_pk_bf16_f32 v8, v20, v21
	v_cvt_pk_bf16_f32 v9, v22, v23
	v_cvt_pk_bf16_f32 v10, v12, v13
	v_add_co_u32_e32 v12, vcc, s15, v140
	s_mov_b64 s[38:39], 0x160000
	s_nop 0
	v_addc_co_u32_e32 v13, vcc, 0, v141, vcc
	v_lshl_add_u64 v[16:17], v[140:141], 0, s[38:39]
	s_and_b64 vcc, exec, s[12:13]
	s_mov_b64 s[38:39], s[34:35]
	v_cvt_pk_bf16_f32 v11, v14, v15
	global_store_dwordx4 v[12:13], v[8:11], off nt
	v_cvt_pk_bf16_f32 v4, v4, v5
	v_cvt_pk_bf16_f32 v5, v6, v7
	v_cvt_pk_bf16_f32 v6, v0, v1
	v_cvt_pk_bf16_f32 v7, v2, v3
	global_store_dwordx4 v[16:17], v[4:7], off offset:256 nt
	s_cbranch_vccz .LBB0_213
	s_waitcnt vmcnt(0)
	s_cmpk_gt_u32 s49, 0xff
	s_cbranch_scc1 .LBB0_183
	s_barrier
	s_branch .LBB0_183

.LBB0_262:
	ds_read_b128 v[128:131], v157
	ds_read_b128 v[132:135], v157 offset:1024
	ds_read_b128 v[160:163], v157 offset:2048
	ds_read_b128 v[164:167], v157 offset:3072
	s_add_u32 s34, s30, 0xfffc0080
	s_addc_u32 s35, s31, -1
	s_cmp_eq_u32 s59, 28
	s_cselect_b32 s37, s1, s35
	s_cselect_b32 s36, s2, s34
	s_cselect_b32 s35, s13, s58
	s_cselect_b32 s34, s15, s55
	v_lshl_add_u64 v[152:153], s[30:31], 0, v[148:149]
	s_add_i32 m0, s40, 0xc000
	ds_read_b128 v[168:171], v158
	ds_read_b128 v[172:175], v158 offset:1024
	ds_read_b128 v[176:179], v158 offset:2048
	ds_read_b128 v[180:183], v158 offset:3072
	ds_read_b128 v[184:187], v158 offset:4096
	ds_read_b128 v[188:191], v158 offset:5120
	ds_read_b128 v[192:195], v158 offset:6144
	ds_read_b128 v[196:199], v158 offset:7168
	global_load_lds_dwordx4 v[152:153], off
	v_lshl_add_u64 v[152:153], s[30:31], 0, v[150:151]
	s_add_i32 m0, s40, 0xe000
	s_nop 0
	global_load_lds_dwordx4 v[152:153], off
	s_waitcnt lgkmcnt(8)
	s_setprio 1
	s_barrier
	s_waitcnt lgkmcnt(0)
	v_mfma_f32_16x16x32_bf16 v[124:127], v[128:131], v[168:171], v[124:127]
	v_mfma_f32_16x16x32_bf16 v[100:103], v[160:163], v[168:171], v[100:103]
	v_mfma_f32_16x16x32_bf16 v[116:119], v[128:131], v[176:179], v[116:119]
	v_mfma_f32_16x16x32_bf16 v[96:99], v[160:163], v[176:179], v[96:99]
	v_mfma_f32_16x16x32_bf16 v[92:95], v[128:131], v[184:187], v[92:95]
	v_mfma_f32_16x16x32_bf16 v[72:75], v[160:163], v[184:187], v[72:75]
	v_mfma_f32_16x16x32_bf16 v[84:87], v[128:131], v[192:195], v[84:87]
	v_mfma_f32_16x16x32_bf16 v[60:63], v[160:163], v[192:195], v[60:63]
	v_mfma_f32_16x16x32_bf16 v[124:127], v[132:135], v[172:175], v[124:127]
	v_mfma_f32_16x16x32_bf16 v[100:103], v[164:167], v[172:175], v[100:103]
	v_mfma_f32_16x16x32_bf16 v[116:119], v[132:135], v[180:183], v[116:119]
	v_mfma_f32_16x16x32_bf16 v[96:99], v[164:167], v[180:183], v[96:99]
	v_mfma_f32_16x16x32_bf16 v[92:95], v[132:135], v[188:191], v[92:95]
	v_mfma_f32_16x16x32_bf16 v[72:75], v[164:167], v[188:191], v[72:75]
	v_mfma_f32_16x16x32_bf16 v[84:87], v[132:135], v[196:199], v[84:87]
	v_mfma_f32_16x16x32_bf16 v[60:63], v[164:167], v[196:199], v[60:63]
	s_barrier
	s_setprio 0
	s_add_i32 s60, s51, s39
	v_lshl_add_u64 v[152:153], s[34:35], 0, v[138:139]
	s_mov_b32 m0, s60
	ds_read_b128 v[200:203], v159
	ds_read_b128 v[204:207], v159 offset:1024
	ds_read_b128 v[212:215], v159 offset:2048
	ds_read_b128 v[216:219], v159 offset:3072
	global_load_lds_dwordx4 v[152:153], off
	v_lshl_add_u64 v[208:209], s[34:35], 0, v[142:143]
	s_add_i32 m0, s60, 0x2000
	s_nop 0
	global_load_lds_dwordx4 v[208:209], off
	s_setprio 1
	s_barrier
	s_waitcnt lgkmcnt(0)
	v_mfma_f32_16x16x32_bf16 v[120:123], v[200:203], v[168:171], v[120:123]
	v_mfma_f32_16x16x32_bf16 v[108:111], v[212:215], v[168:171], v[108:111]
	v_mfma_f32_16x16x32_bf16 v[112:115], v[200:203], v[176:179], v[112:115]
	v_mfma_f32_16x16x32_bf16 v[104:107], v[212:215], v[176:179], v[104:107]
	v_mfma_f32_16x16x32_bf16 v[88:91], v[200:203], v[184:187], v[88:91]
	v_mfma_f32_16x16x32_bf16 v[80:83], v[212:215], v[184:187], v[80:83]
	v_mfma_f32_16x16x32_bf16 v[76:79], v[200:203], v[192:195], v[76:79]
	v_mfma_f32_16x16x32_bf16 v[68:71], v[212:215], v[192:195], v[68:71]
	v_mfma_f32_16x16x32_bf16 v[120:123], v[204:207], v[172:175], v[120:123]
	v_mfma_f32_16x16x32_bf16 v[108:111], v[216:219], v[172:175], v[108:111]
	v_mfma_f32_16x16x32_bf16 v[112:115], v[204:207], v[180:183], v[112:115]
	v_mfma_f32_16x16x32_bf16 v[104:107], v[216:219], v[180:183], v[104:107]
	v_mfma_f32_16x16x32_bf16 v[88:91], v[204:207], v[188:191], v[88:91]
	v_mfma_f32_16x16x32_bf16 v[80:83], v[216:219], v[188:191], v[80:83]
	v_mfma_f32_16x16x32_bf16 v[76:79], v[204:207], v[196:199], v[76:79]
	v_mfma_f32_16x16x32_bf16 v[68:71], v[216:219], v[196:199], v[68:71]
	s_barrier
	s_setprio 0
	s_mov_b32 m0, s40
	v_lshl_add_u64 v[220:221], s[36:37], 0, v[136:137]
	ds_read_b128 v[168:171], v158 offset:16384
	ds_read_b128 v[172:175], v158 offset:17408
	ds_read_b128 v[176:179], v158 offset:18432
	ds_read_b128 v[180:183], v158 offset:19456
	ds_read_b128 v[184:187], v158 offset:20480
	ds_read_b128 v[188:191], v158 offset:21504
	ds_read_b128 v[192:195], v158 offset:22528
	ds_read_b128 v[196:199], v158 offset:23552
	global_load_lds_dwordx4 v[220:221], off
	v_lshl_add_u64 v[222:223], s[36:37], 0, v[140:141]
	s_mov_b32 m0, s41
	s_nop 0
	global_load_lds_dwordx4 v[222:223], off
	s_setprio 1
	s_barrier
	s_waitcnt lgkmcnt(0)
	v_mfma_f32_16x16x32_bf16 v[64:67], v[128:131], v[168:171], v[64:67]
	v_mfma_f32_16x16x32_bf16 v[48:51], v[160:163], v[168:171], v[48:51]
	v_mfma_f32_16x16x32_bf16 v[44:47], v[128:131], v[176:179], v[44:47]
	v_mfma_f32_16x16x32_bf16 v[32:35], v[160:163], v[176:179], v[32:35]
	v_mfma_f32_16x16x32_bf16 v[28:31], v[128:131], v[184:187], v[28:31]
	v_mfma_f32_16x16x32_bf16 v[16:19], v[160:163], v[184:187], v[16:19]
	v_mfma_f32_16x16x32_bf16 v[12:15], v[128:131], v[192:195], v[12:15]
	v_mfma_f32_16x16x32_bf16 v[0:3], v[160:163], v[192:195], v[0:3]
	v_mfma_f32_16x16x32_bf16 v[64:67], v[132:135], v[172:175], v[64:67]
	v_mfma_f32_16x16x32_bf16 v[48:51], v[164:167], v[172:175], v[48:51]
	v_mfma_f32_16x16x32_bf16 v[44:47], v[132:135], v[180:183], v[44:47]
	v_mfma_f32_16x16x32_bf16 v[32:35], v[164:167], v[180:183], v[32:35]
	v_mfma_f32_16x16x32_bf16 v[28:31], v[132:135], v[188:191], v[28:31]
	v_mfma_f32_16x16x32_bf16 v[16:19], v[164:167], v[188:191], v[16:19]
	v_mfma_f32_16x16x32_bf16 v[12:15], v[132:135], v[196:199], v[12:15]
	v_mfma_f32_16x16x32_bf16 v[0:3], v[164:167], v[196:199], v[0:3]
	s_barrier
	s_setprio 0
	s_add_u32 s60, s34, 0x80000
	s_addc_u32 s61, s35, 0
	s_add_i32 s62, s53, s39
	v_lshl_add_u64 v[128:129], s[60:61], 0, v[138:139]
	s_mov_b32 m0, s62
	s_nop 0
	global_load_lds_dwordx4 v[128:129], off
	v_lshl_add_u64 v[128:129], s[60:61], 0, v[142:143]
	s_add_i32 m0, s62, 0x2000
	s_nop 0
	global_load_lds_dwordx4 v[128:129], off
	s_waitcnt vmcnt(6)
	s_setprio 1
	s_barrier
	v_mfma_f32_16x16x32_bf16 v[56:59], v[200:203], v[168:171], v[56:59]
	v_mfma_f32_16x16x32_bf16 v[52:55], v[212:215], v[168:171], v[52:55]
	v_mfma_f32_16x16x32_bf16 v[40:43], v[200:203], v[176:179], v[40:43]
	v_mfma_f32_16x16x32_bf16 v[36:39], v[212:215], v[176:179], v[36:39]
	v_mfma_f32_16x16x32_bf16 v[24:27], v[200:203], v[184:187], v[24:27]
	v_mfma_f32_16x16x32_bf16 v[20:23], v[212:215], v[184:187], v[20:23]
	v_mfma_f32_16x16x32_bf16 v[8:11], v[200:203], v[192:195], v[8:11]
	v_mfma_f32_16x16x32_bf16 v[4:7], v[212:215], v[192:195], v[4:7]
	v_mfma_f32_16x16x32_bf16 v[56:59], v[204:207], v[172:175], v[56:59]
	v_mfma_f32_16x16x32_bf16 v[52:55], v[216:219], v[172:175], v[52:55]
	v_mfma_f32_16x16x32_bf16 v[40:43], v[204:207], v[180:183], v[40:43]
	v_mfma_f32_16x16x32_bf16 v[36:39], v[216:219], v[180:183], v[36:39]
	v_mfma_f32_16x16x32_bf16 v[24:27], v[204:207], v[188:191], v[24:27]
	v_mfma_f32_16x16x32_bf16 v[20:23], v[216:219], v[188:191], v[20:23]
	v_mfma_f32_16x16x32_bf16 v[8:11], v[204:207], v[196:199], v[8:11]
	v_mfma_f32_16x16x32_bf16 v[4:7], v[216:219], v[196:199], v[4:7]
	s_barrier
	s_setprio 0
	s_add_i32 s60, 0, 0x18000
	v_add_u32_e32 v164, s60, v156
	ds_read_b128 v[128:131], v164
	ds_read_b128 v[132:135], v164 offset:1024
	ds_read_b128 v[160:163], v164 offset:2048
	ds_read_b128 v[164:167], v164 offset:3072
	s_add_u32 s36, s36, 0x40000
	s_addc_u32 s37, s37, 0
	s_mov_b32 m0, s42
	v_lshl_add_u64 v[200:201], s[36:37], 0, v[136:137]
	ds_read_b128 v[168:171], v158 offset:32768
	ds_read_b128 v[172:175], v158 offset:33792
	ds_read_b128 v[176:179], v158 offset:34816
	ds_read_b128 v[180:183], v158 offset:35840
	ds_read_b128 v[184:187], v158 offset:36864
	ds_read_b128 v[188:191], v158 offset:37888
	ds_read_b128 v[192:195], v158 offset:38912
	ds_read_b128 v[196:199], v158 offset:39936
	global_load_lds_dwordx4 v[200:201], off
	v_lshl_add_u64 v[200:201], s[36:37], 0, v[140:141]
	s_mov_b32 m0, s43
	s_nop 0
	global_load_lds_dwordx4 v[200:201], off
	s_waitcnt lgkmcnt(8)
	s_setprio 1
	s_barrier
	s_waitcnt lgkmcnt(0)
	v_mfma_f32_16x16x32_bf16 v[124:127], v[128:131], v[168:171], v[124:127]
	v_mfma_f32_16x16x32_bf16 v[100:103], v[160:163], v[168:171], v[100:103]
	v_mfma_f32_16x16x32_bf16 v[116:119], v[128:131], v[176:179], v[116:119]
	v_mfma_f32_16x16x32_bf16 v[96:99], v[160:163], v[176:179], v[96:99]
	v_mfma_f32_16x16x32_bf16 v[92:95], v[128:131], v[184:187], v[92:95]
	v_mfma_f32_16x16x32_bf16 v[72:75], v[160:163], v[184:187], v[72:75]
	v_mfma_f32_16x16x32_bf16 v[84:87], v[128:131], v[192:195], v[84:87]
	v_mfma_f32_16x16x32_bf16 v[60:63], v[160:163], v[192:195], v[60:63]
	v_mfma_f32_16x16x32_bf16 v[124:127], v[132:135], v[172:175], v[124:127]
	v_mfma_f32_16x16x32_bf16 v[100:103], v[164:167], v[172:175], v[100:103]
	v_mfma_f32_16x16x32_bf16 v[116:119], v[132:135], v[180:183], v[116:119]
	v_mfma_f32_16x16x32_bf16 v[96:99], v[164:167], v[180:183], v[96:99]
	v_mfma_f32_16x16x32_bf16 v[92:95], v[132:135], v[188:191], v[92:95]
	v_mfma_f32_16x16x32_bf16 v[72:75], v[164:167], v[188:191], v[72:75]
	v_mfma_f32_16x16x32_bf16 v[84:87], v[132:135], v[196:199], v[84:87]
	v_mfma_f32_16x16x32_bf16 v[60:63], v[164:167], v[196:199], v[60:63]
	s_barrier
	s_setprio 0
	s_add_i32 s36, 0, 0x1c000
	s_add_i32 s37, s60, s39
	v_add_u32_e32 v211, s36, v156
	v_lshl_add_u64 v[152:153], v[152:153], 0, s[4:5]
	s_mov_b32 m0, s37
	ds_read_b128 v[200:203], v211
	ds_read_b128 v[204:207], v211 offset:1024
	ds_read_b128 v[212:215], v211 offset:2048
	ds_read_b128 v[216:219], v211 offset:3072
	global_load_lds_dwordx4 v[152:153], off
	v_lshl_add_u64 v[152:153], v[208:209], 0, s[4:5]
	s_add_i32 m0, s37, 0x2000
	s_nop 0
	global_load_lds_dwordx4 v[152:153], off
	s_setprio 1
	s_barrier
	s_waitcnt lgkmcnt(0)
	v_mfma_f32_16x16x32_bf16 v[120:123], v[200:203], v[168:171], v[120:123]
	v_mfma_f32_16x16x32_bf16 v[108:111], v[212:215], v[168:171], v[108:111]
	v_mfma_f32_16x16x32_bf16 v[112:115], v[200:203], v[176:179], v[112:115]
	v_mfma_f32_16x16x32_bf16 v[104:107], v[212:215], v[176:179], v[104:107]
	v_mfma_f32_16x16x32_bf16 v[88:91], v[200:203], v[184:187], v[88:91]
	v_mfma_f32_16x16x32_bf16 v[80:83], v[212:215], v[184:187], v[80:83]
	v_mfma_f32_16x16x32_bf16 v[76:79], v[200:203], v[192:195], v[76:79]
	v_mfma_f32_16x16x32_bf16 v[68:71], v[212:215], v[192:195], v[68:71]
	v_mfma_f32_16x16x32_bf16 v[120:123], v[204:207], v[172:175], v[120:123]
	v_mfma_f32_16x16x32_bf16 v[108:111], v[216:219], v[172:175], v[108:111]
	v_mfma_f32_16x16x32_bf16 v[112:115], v[204:207], v[180:183], v[112:115]
	v_mfma_f32_16x16x32_bf16 v[104:107], v[216:219], v[180:183], v[104:107]
	v_mfma_f32_16x16x32_bf16 v[88:91], v[204:207], v[188:191], v[88:91]
	v_mfma_f32_16x16x32_bf16 v[80:83], v[216:219], v[188:191], v[80:83]
	v_mfma_f32_16x16x32_bf16 v[76:79], v[204:207], v[196:199], v[76:79]
	v_mfma_f32_16x16x32_bf16 v[68:71], v[216:219], v[196:199], v[68:71]
	s_barrier
	s_setprio 0
	s_mov_b32 m0, s48
	v_lshl_add_u64 v[152:153], v[220:221], 0, s[4:5]
	ds_read_b128 v[168:171], v158 offset:49152
	ds_read_b128 v[172:175], v158 offset:50176
	ds_read_b128 v[176:179], v158 offset:51200
	ds_read_b128 v[180:183], v158 offset:52224
	ds_read_b128 v[184:187], v158 offset:53248
	ds_read_b128 v[188:191], v158 offset:54272
	ds_read_b128 v[192:195], v158 offset:55296
	ds_read_b128 v[196:199], v158 offset:56320
	global_load_lds_dwordx4 v[152:153], off
	v_lshl_add_u64 v[152:153], v[222:223], 0, s[4:5]
	s_mov_b32 m0, s49
	s_nop 0
	global_load_lds_dwordx4 v[152:153], off
	s_setprio 1
	s_barrier
	s_waitcnt lgkmcnt(0)
	v_mfma_f32_16x16x32_bf16 v[64:67], v[128:131], v[168:171], v[64:67]
	v_mfma_f32_16x16x32_bf16 v[48:51], v[160:163], v[168:171], v[48:51]
	v_mfma_f32_16x16x32_bf16 v[44:47], v[128:131], v[176:179], v[44:47]
	v_mfma_f32_16x16x32_bf16 v[32:35], v[160:163], v[176:179], v[32:35]
	v_mfma_f32_16x16x32_bf16 v[28:31], v[128:131], v[184:187], v[28:31]
	v_mfma_f32_16x16x32_bf16 v[16:19], v[160:163], v[184:187], v[16:19]
	v_mfma_f32_16x16x32_bf16 v[12:15], v[128:131], v[192:195], v[12:15]
	v_mfma_f32_16x16x32_bf16 v[0:3], v[160:163], v[192:195], v[0:3]
	v_mfma_f32_16x16x32_bf16 v[64:67], v[132:135], v[172:175], v[64:67]
	v_mfma_f32_16x16x32_bf16 v[48:51], v[164:167], v[172:175], v[48:51]
	v_mfma_f32_16x16x32_bf16 v[44:47], v[132:135], v[180:183], v[44:47]
	v_mfma_f32_16x16x32_bf16 v[32:35], v[164:167], v[180:183], v[32:35]
	v_mfma_f32_16x16x32_bf16 v[28:31], v[132:135], v[188:191], v[28:31]
	v_mfma_f32_16x16x32_bf16 v[16:19], v[164:167], v[188:191], v[16:19]
	v_mfma_f32_16x16x32_bf16 v[12:15], v[132:135], v[196:199], v[12:15]
	v_mfma_f32_16x16x32_bf16 v[0:3], v[164:167], v[196:199], v[0:3]
	s_barrier
	s_setprio 0
	s_add_u32 s34, s34, 0x80080
	s_addc_u32 s35, s35, 0
	s_add_i32 s36, s36, s39
	v_lshl_add_u64 v[128:129], s[34:35], 0, v[138:139]
	s_mov_b32 m0, s36
	s_nop 0
	global_load_lds_dwordx4 v[128:129], off
	v_lshl_add_u64 v[128:129], s[34:35], 0, v[142:143]
	s_add_i32 m0, s36, 0x2000
	s_nop 0
	global_load_lds_dwordx4 v[128:129], off
	s_waitcnt vmcnt(6)
	s_setprio 1
	s_barrier
	v_mfma_f32_16x16x32_bf16 v[56:59], v[200:203], v[168:171], v[56:59]
	v_mfma_f32_16x16x32_bf16 v[52:55], v[212:215], v[168:171], v[52:55]
	v_mfma_f32_16x16x32_bf16 v[40:43], v[200:203], v[176:179], v[40:43]
	v_mfma_f32_16x16x32_bf16 v[36:39], v[212:215], v[176:179], v[36:39]
	v_mfma_f32_16x16x32_bf16 v[24:27], v[200:203], v[184:187], v[24:27]
	v_mfma_f32_16x16x32_bf16 v[20:23], v[212:215], v[184:187], v[20:23]
	v_mfma_f32_16x16x32_bf16 v[8:11], v[200:203], v[192:195], v[8:11]
	v_mfma_f32_16x16x32_bf16 v[4:7], v[212:215], v[192:195], v[4:7]
	v_mfma_f32_16x16x32_bf16 v[56:59], v[204:207], v[172:175], v[56:59]
	v_mfma_f32_16x16x32_bf16 v[52:55], v[216:219], v[172:175], v[52:55]
	v_mfma_f32_16x16x32_bf16 v[40:43], v[204:207], v[180:183], v[40:43]
	v_mfma_f32_16x16x32_bf16 v[36:39], v[216:219], v[180:183], v[36:39]
	v_mfma_f32_16x16x32_bf16 v[24:27], v[204:207], v[188:191], v[24:27]
	v_mfma_f32_16x16x32_bf16 v[20:23], v[216:219], v[188:191], v[20:23]
	v_mfma_f32_16x16x32_bf16 v[8:11], v[204:207], v[196:199], v[8:11]
	v_mfma_f32_16x16x32_bf16 v[4:7], v[216:219], v[196:199], v[4:7]
	s_barrier
	s_setprio 0
	s_add_i32 s59, s59, 2
	s_add_u32 s30, s30, 0x100
	s_addc_u32 s31, s31, 0
	s_add_u32 s55, s55, 0x100
	s_addc_u32 s58, s58, 0
	s_cmp_gt_u32 s59, 29
	s_cbranch_scc0 .LBB0_262
	s_cmp_gt_i32 s0, 31
	s_cselect_b64 vcc, -1, 0
	s_and_b64 s[30:31], vcc, exec
	s_cselect_b32 s2, 0x200, 0
	v_lshl_add_u64 v[128:129], v[144:145], 0, s[2:3]
	global_load_dwordx4 v[132:135], v[128:129], off
	s_nop 0
	global_load_dwordx4 v[128:131], v[128:129], off offset:16
	v_cndmask_b32_e32 v121, v125, v121, vcc
	v_cndmask_b32_e32 v120, v124, v120, vcc
	v_cndmask_b32_e32 v101, v101, v109, vcc
	v_cndmask_b32_e32 v100, v100, v108, vcc
	v_cndmask_b32_e32 v123, v127, v123, vcc
	v_cndmask_b32_e32 v122, v126, v122, vcc
	v_cndmask_b32_e32 v103, v103, v111, vcc
	v_cndmask_b32_e32 v102, v102, v110, vcc
	v_cndmask_b32_e32 v111, v119, v115, vcc
	v_cndmask_b32_e32 v110, v118, v114, vcc
	v_cndmask_b32_e32 v99, v99, v107, vcc
	v_cndmask_b32_e32 v98, v98, v106, vcc
	v_cndmask_b32_e32 v109, v117, v113, vcc
	v_cndmask_b32_e32 v108, v116, v112, vcc
	v_cndmask_b32_e32 v89, v93, v89, vcc
	v_cndmask_b32_e32 v88, v92, v88, vcc
	v_cndmask_b32_e32 v73, v73, v81, vcc
	v_cndmask_b32_e32 v72, v72, v80, vcc
	v_cndmask_b32_e32 v105, v97, v105, vcc
	v_cndmask_b32_e32 v104, v96, v104, vcc
	v_cndmask_b32_e32 v74, v74, v82, vcc
	v_lshl_add_u32 v152, s0, 8, v155
	v_ashrrev_i32_e32 v153, 31, v152
	v_lshlrev_b64 v[162:163], 8, v[152:153]
	v_cndmask_b32_e32 v75, v75, v83, vcc
	v_lshl_add_u64 v[96:97], v[146:147], 0, v[162:163]
	v_cndmask_b32_e32 v91, v95, v91, vcc
	v_cndmask_b32_e32 v90, v94, v90, vcc
	v_or_b32_e32 v160, 16, v152
	v_ashrrev_i32_e32 v161, 31, v160
	v_lshlrev_b64 v[106:107], 8, v[160:161]
	v_cndmask_b32_e32 v61, v61, v69, vcc
	v_cndmask_b32_e32 v60, v60, v68, vcc
	v_cndmask_b32_e32 v57, v65, v57, vcc
	v_cndmask_b32_e32 v56, v64, v56, vcc
	v_cndmask_b32_e32 v49, v49, v53, vcc
	v_cndmask_b32_e32 v48, v48, v52, vcc
	v_cndmask_b32_e32 v62, v62, v70, vcc
	v_cndmask_b32_e32 v50, v50, v54, vcc
	v_cndmask_b32_e32 v41, v45, v41, vcc
	v_cndmask_b32_e32 v40, v44, v40, vcc
	v_cndmask_b32_e32 v33, v33, v37, vcc
	v_cndmask_b32_e32 v32, v32, v36, vcc
	v_cndmask_b32_e32 v25, v29, v25, vcc
	v_cndmask_b32_e32 v24, v28, v24, vcc
	v_cndmask_b32_e32 v17, v17, v21, vcc
	v_cndmask_b32_e32 v16, v16, v20, vcc
	v_cndmask_b32_e32 v34, v34, v38, vcc
	v_cndmask_b32_e32 v18, v18, v22, vcc
	v_cndmask_b32_e32 v9, v13, v9, vcc
	v_cndmask_b32_e32 v8, v12, v8, vcc
	v_cndmask_b32_e32 v1, v1, v5, vcc
	v_cndmask_b32_e32 v0, v0, v4, vcc
	v_cndmask_b32_e32 v63, v63, v71, vcc
	v_cndmask_b32_e32 v51, v51, v55, vcc
	v_cndmask_b32_e32 v2, v2, v6, vcc
	v_cndmask_b32_e32 v35, v35, v39, vcc
	v_cndmask_b32_e32 v59, v67, v59, vcc
	v_cndmask_b32_e32 v58, v66, v58, vcc
	v_cndmask_b32_e32 v19, v19, v23, vcc
	v_cndmask_b32_e32 v43, v47, v43, vcc
	v_cndmask_b32_e32 v42, v46, v42, vcc
	v_cndmask_b32_e32 v3, v3, v7, vcc
	v_cndmask_b32_e32 v27, v31, v27, vcc
	v_cndmask_b32_e32 v26, v30, v26, vcc
	v_cndmask_b32_e32 v11, v15, v11, vcc
	v_cndmask_b32_e32 v10, v14, v10, vcc
	s_mov_b32 s0, 0x9000
	s_mov_b64 s[34:35], s[28:29]
	s_mov_b64 s[30:31], s[26:27]
	s_waitcnt vmcnt(0)
	v_pk_add_f32 v[114:115], v[120:121], v[132:133]
	v_pk_add_f32 v[100:101], v[100:101], v[128:129]
	v_pk_add_f32 v[112:113], v[122:123], v[134:135]
	v_pk_add_f32 v[102:103], v[102:103], v[130:131]
	v_pk_add_f32 v[116:117], v[98:99], v[130:131]
	v_mul_f32_e32 v98, 0xbfb8aa3b, v114
	v_mul_f32_e32 v99, 0xbfb8aa3b, v100
	v_mul_f32_e32 v118, 0xbfb8aa3b, v115
	v_mul_f32_e32 v119, 0xbfb8aa3b, v101
	v_mul_f32_e32 v120, 0xbfb8aa3b, v112
	v_mul_f32_e32 v121, 0xbfb8aa3b, v102
	v_mul_f32_e32 v122, 0xbfb8aa3b, v113
	v_mul_f32_e32 v123, 0xbfb8aa3b, v103
	v_exp_f32_e32 v98, v98
	v_exp_f32_e32 v99, v99
	v_exp_f32_e32 v118, v118
	v_exp_f32_e32 v119, v119
	v_exp_f32_e32 v120, v120
	v_exp_f32_e32 v121, v121
	v_exp_f32_e32 v122, v122
	v_exp_f32_e32 v123, v123
	v_pk_add_f32 v[88:89], v[88:89], v[132:133]
	v_pk_add_f32 v[72:73], v[72:73], v[128:129]
	v_add_f32_e32 v98, 1.0, v98
	v_add_f32_e32 v99, 1.0, v99
	v_add_f32_e32 v118, 1.0, v118
	v_add_f32_e32 v119, 1.0, v119
	v_mul_f32_e32 v80, 0xbfb8aa3b, v88
	v_mul_f32_e32 v81, 0xbfb8aa3b, v72
	v_mul_f32_e32 v82, 0xbfb8aa3b, v89
	v_pk_add_f32 v[104:105], v[104:105], v[128:129]
	v_add_f32_e32 v120, 1.0, v120
	v_add_f32_e32 v121, 1.0, v121
	v_add_f32_e32 v122, 1.0, v122
	v_add_f32_e32 v123, 1.0, v123
	v_rcp_f32_e32 v98, v98
	v_rcp_f32_e32 v99, v99
	v_rcp_f32_e32 v118, v118
	v_rcp_f32_e32 v119, v119
	v_exp_f32_e32 v80, v80
	v_exp_f32_e32 v81, v81
	v_exp_f32_e32 v82, v82
	v_mul_f32_e32 v127, 0xbfb8aa3b, v105
	v_rcp_f32_e32 v120, v120
	v_rcp_f32_e32 v121, v121
	v_rcp_f32_e32 v122, v122
	v_rcp_f32_e32 v123, v123
	v_exp_f32_e32 v127, v127
	v_mul_f32_e32 v98, v114, v98
	v_mul_f32_e32 v100, v100, v99
	v_mul_f32_e32 v99, v115, v118
	v_mul_f32_e32 v101, v101, v119
	v_add_f32_e32 v80, 1.0, v80
	v_add_f32_e32 v81, 1.0, v81
	v_add_f32_e32 v82, 1.0, v82
	v_mul_f32_e32 v83, 0xbfb8aa3b, v73
	v_pk_add_f32 v[110:111], v[110:111], v[134:135]
	v_mul_f32_e32 v112, v112, v120
	v_mul_f32_e32 v102, v102, v121
	v_mul_f32_e32 v113, v113, v122
	v_mul_f32_e32 v103, v103, v123
	v_cvt_pk_bf16_f32 v98, v98, v99
	v_cvt_pk_bf16_f32 v99, v112, v113
	v_cvt_pk_bf16_f32 v100, v100, v101
	v_cvt_pk_bf16_f32 v101, v102, v103
	v_rcp_f32_e32 v80, v80
	v_rcp_f32_e32 v81, v81
	v_rcp_f32_e32 v82, v82
	v_exp_f32_e32 v83, v83
	global_store_dwordx4 v[96:97], v[98:101], off
	v_pk_add_f32 v[90:91], v[90:91], v[134:135]
	v_pk_add_f32 v[74:75], v[74:75], v[130:131]
	v_add_f32_e32 v99, 1.0, v127
	v_mul_f32_e32 v100, 0xbfb8aa3b, v110
	v_mul_f32_e32 v101, 0xbfb8aa3b, v116
	v_rcp_f32_e32 v99, v99
	v_exp_f32_e32 v100, v100
	v_exp_f32_e32 v101, v101
	v_pk_add_f32 v[108:109], v[108:109], v[132:133]
	v_mul_f32_e32 v88, v88, v80
	v_mul_f32_e32 v92, v72, v81
	v_mul_f32_e32 v72, v89, v82
	v_add_f32_e32 v80, 1.0, v83
	v_mul_f32_e32 v81, 0xbfb8aa3b, v90
	v_mul_f32_e32 v82, 0xbfb8aa3b, v74
	v_mul_f32_e32 v126, 0xbfb8aa3b, v109
	v_rcp_f32_e32 v80, v80
	v_exp_f32_e32 v81, v81
	v_exp_f32_e32 v82, v82
	v_mul_f32_e32 v124, 0xbfb8aa3b, v108
	v_exp_f32_e32 v126, v126
	v_mul_f32_e32 v105, v105, v99
	v_add_f32_e32 v99, 1.0, v100
	v_add_f32_e32 v100, 1.0, v101
	v_mul_f32_e32 v101, 0xbfb8aa3b, v111
	v_mul_f32_e32 v102, 0xbfb8aa3b, v117
	v_mul_f32_e32 v125, 0xbfb8aa3b, v104
	v_exp_f32_e32 v124, v124
	v_exp_f32_e32 v101, v101
	v_exp_f32_e32 v102, v102
	v_exp_f32_e32 v125, v125
	v_mul_f32_e32 v83, v73, v80
	v_add_f32_e32 v73, 1.0, v81
	v_add_f32_e32 v80, 1.0, v82
	v_mul_f32_e32 v81, 0xbfb8aa3b, v91
	v_mul_f32_e32 v82, 0xbfb8aa3b, v75
	v_add_f32_e32 v126, 1.0, v126
	v_exp_f32_e32 v81, v81
	v_exp_f32_e32 v82, v82
	v_add_f32_e32 v124, 1.0, v124
	v_rcp_f32_e32 v126, v126
	v_add_f32_e32 v101, 1.0, v101
	v_add_f32_e32 v102, 1.0, v102
	v_add_f32_e32 v125, 1.0, v125
	v_rcp_f32_e32 v124, v124
	v_rcp_f32_e32 v99, v99
	v_rcp_f32_e32 v100, v100
	v_rcp_f32_e32 v101, v101
	v_rcp_f32_e32 v102, v102
	v_rcp_f32_e32 v125, v125
	v_add_f32_e32 v81, 1.0, v81
	v_add_f32_e32 v82, 1.0, v82
	v_mul_f32_e32 v98, v109, v126
	v_rcp_f32_e32 v73, v73
	v_rcp_f32_e32 v80, v80
	v_rcp_f32_e32 v81, v81
	v_rcp_f32_e32 v82, v82
	v_mul_f32_e32 v108, v108, v124
	v_mul_f32_e32 v99, v110, v99
	v_mul_f32_e32 v109, v116, v100
	v_mul_f32_e32 v100, v111, v101
	v_mul_f32_e32 v101, v117, v102
	v_lshl_add_u64 v[102:103], v[146:147], 0, v[106:107]
	v_cvt_pk_bf16_f32 v98, v108, v98
	v_mul_f32_e32 v104, v104, v125
	v_cvt_pk_bf16_f32 v99, v99, v100
	v_cvt_pk_bf16_f32 v100, v104, v105
	v_cvt_pk_bf16_f32 v101, v109, v101
	global_store_dwordx4 v[102:103], v[98:101], off
	v_mul_f32_e32 v73, v90, v73
	v_mul_f32_e32 v89, v74, v80
	v_or_b32_e32 v98, 32, v152
	v_ashrrev_i32_e32 v99, 31, v98
	v_lshlrev_b64 v[98:99], 8, v[98:99]
	v_mul_f32_e32 v74, v91, v81
	v_mul_f32_e32 v75, v75, v82
	v_lshl_add_u64 v[80:81], v[146:147], 0, v[98:99]
	v_cvt_pk_bf16_f32 v72, v88, v72
	v_cvt_pk_bf16_f32 v73, v73, v74
	v_cvt_pk_bf16_f32 v74, v92, v83
	v_cvt_pk_bf16_f32 v75, v89, v75
	global_store_dwordx4 v[80:81], v[72:75], off
	v_pk_add_f32 v[60:61], v[60:61], v[128:129]
	v_pk_add_f32 v[56:57], v[56:57], v[132:133]
	v_cndmask_b32_e32 v75, v85, v77, vcc
	v_cndmask_b32_e32 v74, v84, v76, vcc
	v_pk_add_f32 v[74:75], v[74:75], v[132:133]
	v_mul_f32_e32 v69, 0xbfb8aa3b, v60
	v_mul_f32_e32 v68, 0xbfb8aa3b, v74
	v_mul_f32_e32 v70, 0xbfb8aa3b, v75
	v_pk_add_f32 v[48:49], v[48:49], v[128:129]
	v_exp_f32_e32 v68, v68
	v_exp_f32_e32 v69, v69
	v_exp_f32_e32 v70, v70
	v_mul_f32_e32 v52, 0xbfb8aa3b, v56
	v_mul_f32_e32 v53, 0xbfb8aa3b, v48
	v_mul_f32_e32 v54, 0xbfb8aa3b, v57
	v_exp_f32_e32 v52, v52
	v_exp_f32_e32 v53, v53
	v_exp_f32_e32 v54, v54
	v_pk_add_f32 v[40:41], v[40:41], v[132:133]
	v_pk_add_f32 v[32:33], v[32:33], v[128:129]
	v_mul_f32_e32 v36, 0xbfb8aa3b, v40
	v_mul_f32_e32 v37, 0xbfb8aa3b, v32
	v_mul_f32_e32 v38, 0xbfb8aa3b, v41
	v_pk_add_f32 v[24:25], v[24:25], v[132:133]
	v_pk_add_f32 v[16:17], v[16:17], v[128:129]
	v_exp_f32_e32 v36, v36
	v_exp_f32_e32 v37, v37
	v_exp_f32_e32 v38, v38
	v_mul_f32_e32 v20, 0xbfb8aa3b, v24
	v_mul_f32_e32 v21, 0xbfb8aa3b, v16
	v_mul_f32_e32 v22, 0xbfb8aa3b, v25
	v_add_f32_e32 v68, 1.0, v68
	v_add_f32_e32 v69, 1.0, v69
	v_add_f32_e32 v70, 1.0, v70
	v_mul_f32_e32 v71, 0xbfb8aa3b, v61
	v_exp_f32_e32 v20, v20
	v_exp_f32_e32 v21, v21
	v_exp_f32_e32 v22, v22
	v_pk_add_f32 v[8:9], v[8:9], v[132:133]
	v_pk_add_f32 v[0:1], v[0:1], v[128:129]
	v_rcp_f32_e32 v68, v68
	v_rcp_f32_e32 v69, v69
	v_rcp_f32_e32 v70, v70
	v_exp_f32_e32 v71, v71
	v_add_f32_e32 v52, 1.0, v52
	v_add_f32_e32 v53, 1.0, v53
	v_add_f32_e32 v54, 1.0, v54
	v_mul_f32_e32 v55, 0xbfb8aa3b, v49
	v_mul_f32_e32 v4, 0xbfb8aa3b, v8
	v_mul_f32_e32 v5, 0xbfb8aa3b, v0
	v_mul_f32_e32 v6, 0xbfb8aa3b, v9
	v_rcp_f32_e32 v52, v52
	v_rcp_f32_e32 v53, v53
	v_rcp_f32_e32 v54, v54
	v_exp_f32_e32 v55, v55
	v_exp_f32_e32 v4, v4
	v_exp_f32_e32 v5, v5
	v_exp_f32_e32 v6, v6
	v_cndmask_b32_e32 v77, v87, v79, vcc
	v_cndmask_b32_e32 v76, v86, v78, vcc
	v_add_f32_e32 v36, 1.0, v36
	v_add_f32_e32 v37, 1.0, v37
	v_add_f32_e32 v38, 1.0, v38
	v_mul_f32_e32 v39, 0xbfb8aa3b, v33
	v_pk_add_f32 v[76:77], v[76:77], v[134:135]
	v_pk_add_f32 v[62:63], v[62:63], v[130:131]
	v_rcp_f32_e32 v36, v36
	v_rcp_f32_e32 v37, v37
	v_rcp_f32_e32 v38, v38
	v_exp_f32_e32 v39, v39
	v_add_f32_e32 v20, 1.0, v20
	v_add_f32_e32 v21, 1.0, v21
	v_add_f32_e32 v22, 1.0, v22
	v_mul_f32_e32 v23, 0xbfb8aa3b, v17
	v_mul_f32_e32 v74, v74, v68
	v_mul_f32_e32 v78, v60, v69
	v_mul_f32_e32 v60, v75, v70
	v_add_f32_e32 v68, 1.0, v71
	v_mul_f32_e32 v69, 0xbfb8aa3b, v76
	v_mul_f32_e32 v70, 0xbfb8aa3b, v62
	v_pk_add_f32 v[58:59], v[58:59], v[134:135]
	v_pk_add_f32 v[50:51], v[50:51], v[130:131]
	v_rcp_f32_e32 v20, v20
	v_rcp_f32_e32 v21, v21
	v_rcp_f32_e32 v22, v22
	v_exp_f32_e32 v23, v23
	v_rcp_f32_e32 v68, v68
	v_exp_f32_e32 v69, v69
	v_exp_f32_e32 v70, v70
	v_mul_f32_e32 v52, v56, v52
	v_mul_f32_e32 v53, v48, v53
	v_mul_f32_e32 v48, v57, v54
	v_add_f32_e32 v54, 1.0, v55
	v_mul_f32_e32 v55, 0xbfb8aa3b, v58
	v_mul_f32_e32 v56, 0xbfb8aa3b, v50
	v_add_f32_e32 v4, 1.0, v4
	v_add_f32_e32 v5, 1.0, v5
	v_add_f32_e32 v6, 1.0, v6
	v_mul_f32_e32 v7, 0xbfb8aa3b, v1
	v_rcp_f32_e32 v54, v54
	v_exp_f32_e32 v55, v55
	v_exp_f32_e32 v56, v56
	v_pk_add_f32 v[42:43], v[42:43], v[134:135]
	v_pk_add_f32 v[34:35], v[34:35], v[130:131]
	v_rcp_f32_e32 v4, v4
	v_rcp_f32_e32 v5, v5
	v_rcp_f32_e32 v6, v6
	v_exp_f32_e32 v7, v7
	v_mul_f32_e32 v36, v40, v36
	v_mul_f32_e32 v37, v32, v37
	v_mul_f32_e32 v32, v41, v38
	v_add_f32_e32 v38, 1.0, v39
	v_mul_f32_e32 v39, 0xbfb8aa3b, v42
	v_mul_f32_e32 v40, 0xbfb8aa3b, v34
	v_pk_add_f32 v[26:27], v[26:27], v[134:135]
	v_pk_add_f32 v[18:19], v[18:19], v[130:131]
	v_rcp_f32_e32 v38, v38
	v_exp_f32_e32 v39, v39
	v_exp_f32_e32 v40, v40
	v_mul_f32_e32 v20, v24, v20
	v_mul_f32_e32 v21, v16, v21
	v_mul_f32_e32 v16, v25, v22
	v_add_f32_e32 v22, 1.0, v23
	v_mul_f32_e32 v23, 0xbfb8aa3b, v26
	v_mul_f32_e32 v24, 0xbfb8aa3b, v18
	v_mul_f32_e32 v71, v61, v68
	v_add_f32_e32 v61, 1.0, v69
	v_add_f32_e32 v68, 1.0, v70
	v_mul_f32_e32 v69, 0xbfb8aa3b, v77
	v_mul_f32_e32 v70, 0xbfb8aa3b, v63
	v_rcp_f32_e32 v22, v22
	v_exp_f32_e32 v23, v23
	v_exp_f32_e32 v24, v24
	v_pk_add_f32 v[10:11], v[10:11], v[134:135]
	v_pk_add_f32 v[2:3], v[2:3], v[130:131]
	v_exp_f32_e32 v69, v69
	v_exp_f32_e32 v70, v70
	v_mul_f32_e32 v54, v49, v54
	v_add_f32_e32 v49, 1.0, v55
	v_add_f32_e32 v55, 1.0, v56
	v_mul_f32_e32 v56, 0xbfb8aa3b, v59
	v_mul_f32_e32 v4, v8, v4
	v_mul_f32_e32 v5, v0, v5
	v_mul_f32_e32 v0, v9, v6
	v_add_f32_e32 v6, 1.0, v7
	v_mul_f32_e32 v7, 0xbfb8aa3b, v10
	v_mul_f32_e32 v8, 0xbfb8aa3b, v2
	v_exp_f32_e32 v56, v56
	v_rcp_f32_e32 v6, v6
	v_exp_f32_e32 v7, v7
	v_exp_f32_e32 v8, v8
	v_mul_f32_e32 v57, 0xbfb8aa3b, v51
	v_mul_f32_e32 v38, v33, v38
	v_add_f32_e32 v33, 1.0, v39
	v_add_f32_e32 v39, 1.0, v40
	v_mul_f32_e32 v40, 0xbfb8aa3b, v43
	v_mul_f32_e32 v41, 0xbfb8aa3b, v35
	v_exp_f32_e32 v57, v57
	v_exp_f32_e32 v40, v40
	v_exp_f32_e32 v41, v41
	v_mul_f32_e32 v22, v17, v22
	v_add_f32_e32 v17, 1.0, v23
	v_add_f32_e32 v23, 1.0, v24
	v_mul_f32_e32 v24, 0xbfb8aa3b, v27
	v_add_f32_e32 v69, 1.0, v69
	v_add_f32_e32 v70, 1.0, v70
	v_exp_f32_e32 v24, v24
	v_mul_f32_e32 v25, 0xbfb8aa3b, v19
	v_rcp_f32_e32 v61, v61
	v_rcp_f32_e32 v68, v68
	v_rcp_f32_e32 v69, v69
	v_rcp_f32_e32 v70, v70
	v_add_f32_e32 v56, 1.0, v56
	v_exp_f32_e32 v25, v25
	v_mul_f32_e32 v6, v1, v6
	v_add_f32_e32 v1, 1.0, v7
	v_add_f32_e32 v7, 1.0, v8
	v_mul_f32_e32 v8, 0xbfb8aa3b, v11
	v_or_b32_e32 v72, 48, v152
	v_rcp_f32_e32 v49, v49
	v_rcp_f32_e32 v55, v55
	v_rcp_f32_e32 v56, v56
	v_exp_f32_e32 v8, v8
	v_ashrrev_i32_e32 v73, 31, v72
	v_add_f32_e32 v57, 1.0, v57
	v_add_f32_e32 v40, 1.0, v40
	v_add_f32_e32 v41, 1.0, v41
	v_mul_f32_e32 v9, 0xbfb8aa3b, v3
	v_lshlrev_b64 v[72:73], 8, v[72:73]
	v_rcp_f32_e32 v57, v57
	v_rcp_f32_e32 v33, v33
	v_rcp_f32_e32 v39, v39
	v_rcp_f32_e32 v40, v40
	v_rcp_f32_e32 v41, v41
	v_add_f32_e32 v24, 1.0, v24
	v_exp_f32_e32 v9, v9
	v_mul_f32_e32 v61, v76, v61
	v_mul_f32_e32 v75, v62, v68
	v_mul_f32_e32 v62, v77, v69
	v_mul_f32_e32 v63, v63, v70
	v_lshl_add_u64 v[68:69], v[146:147], 0, v[72:73]
	v_rcp_f32_e32 v17, v17
	v_rcp_f32_e32 v23, v23
	v_rcp_f32_e32 v24, v24
	v_add_f32_e32 v25, 1.0, v25
	v_cvt_pk_bf16_f32 v60, v74, v60
	v_cvt_pk_bf16_f32 v61, v61, v62
	v_cvt_pk_bf16_f32 v62, v78, v71
	v_cvt_pk_bf16_f32 v63, v75, v63
	global_store_dwordx4 v[68:69], v[60:63], off
	v_mul_f32_e32 v49, v58, v49
	v_mul_f32_e32 v55, v50, v55
	v_mul_f32_e32 v50, v59, v56
	v_cvt_pk_bf16_f32 v48, v52, v48
	v_add_co_u32_e64 v52, s[0:1], s0, v96
	v_rcp_f32_e32 v25, v25
	v_add_f32_e32 v8, 1.0, v8
	v_cvt_pk_bf16_f32 v49, v49, v50
	v_cvt_pk_bf16_f32 v50, v53, v54
	v_addc_co_u32_e64 v53, s[0:1], 0, v97, s[0:1]
	v_rcp_f32_e32 v1, v1
	v_rcp_f32_e32 v7, v7
	v_rcp_f32_e32 v8, v8
	v_mul_f32_e32 v51, v51, v57
	v_mul_f32_e32 v33, v42, v33
	v_mul_f32_e32 v39, v34, v39
	v_mul_f32_e32 v34, v43, v40
	v_mul_f32_e32 v35, v35, v41
	s_mov_b32 s0, 0xa000
	v_add_f32_e32 v9, 1.0, v9
	v_cvt_pk_bf16_f32 v51, v55, v51
	global_store_dwordx4 v[52:53], v[48:51], off offset:-4096
	v_cvt_pk_bf16_f32 v32, v36, v32
	v_cvt_pk_bf16_f32 v33, v33, v34
	v_cvt_pk_bf16_f32 v34, v37, v38
	v_cvt_pk_bf16_f32 v35, v39, v35
	global_store_dwordx4 v[52:53], v[32:35], off
	v_mul_f32_e32 v17, v26, v17
	v_mul_f32_e32 v23, v18, v23
	v_mul_f32_e32 v18, v27, v24
	v_cvt_pk_bf16_f32 v16, v20, v16
	v_add_co_u32_e64 v20, s[0:1], s0, v96
	v_rcp_f32_e32 v9, v9
	v_mul_f32_e32 v19, v19, v25
	v_cvt_pk_bf16_f32 v17, v17, v18
	v_cvt_pk_bf16_f32 v18, v21, v22
	v_addc_co_u32_e64 v21, s[0:1], 0, v97, s[0:1]
	v_cvt_pk_bf16_f32 v19, v23, v19
	global_store_dwordx4 v[20:21], v[16:19], off
	v_mul_f32_e32 v1, v10, v1
	v_mul_f32_e32 v7, v2, v7
	v_mul_f32_e32 v2, v11, v8
	v_cvt_pk_bf16_f32 v0, v4, v0
	v_add_co_u32_e32 v4, vcc, 0xb000, v96
	v_cvt_pk_bf16_f32 v1, v1, v2
	v_cvt_pk_bf16_f32 v2, v5, v6
	v_mul_f32_e32 v3, v3, v9
	s_nop 0
	v_addc_co_u32_e32 v5, vcc, 0, v97, vcc
	s_and_b64 vcc, exec, s[8:9]
	s_mov_b32 s0, s14
	v_cvt_pk_bf16_f32 v3, v7, v3
	global_store_dwordx4 v[4:5], v[0:3], off
	s_cbranch_vccz .LBB0_255
	s_waitcnt vmcnt(0)
	s_cmpk_gt_u32 s33, 0xff
	s_cbranch_scc1 .LBB0_266
	s_barrier

.LBB0_654:
	ds_read_b128 v[144:147], v157
	ds_read_b128 v[148:151], v157 offset:1024
	ds_read_b128 v[160:163], v157 offset:2048
	ds_read_b128 v[164:167], v157 offset:3072
	s_add_u32 s24, s22, 0xfffc0080
	s_addc_u32 s25, s23, -1
	s_cmp_eq_u32 s49, 12
	s_cselect_b32 s27, s13, s25
	s_cselect_b32 s26, s19, s24
	s_cselect_b32 s25, s3, s48
	s_cselect_b32 s24, s42, s43
	v_lshl_add_u64 v[152:153], s[22:23], 0, v[136:137]
	s_add_i32 m0, s21, 0xc000
	ds_read_b128 v[168:171], v158
	ds_read_b128 v[176:179], v158 offset:1024
	ds_read_b128 v[180:183], v158 offset:2048
	ds_read_b128 v[184:187], v158 offset:3072
	ds_read_b128 v[188:191], v158 offset:4096
	ds_read_b128 v[192:195], v158 offset:5120
	ds_read_b128 v[196:199], v158 offset:6144
	ds_read_b128 v[200:203], v158 offset:7168
	global_load_lds_dwordx4 v[152:153], off
	v_lshl_add_u64 v[152:153], s[22:23], 0, v[138:139]
	s_add_i32 m0, s21, 0xe000
	s_nop 0
	global_load_lds_dwordx4 v[152:153], off
	s_waitcnt lgkmcnt(8)
	s_setprio 1
	s_barrier
	s_waitcnt lgkmcnt(0)
	v_mfma_f32_16x16x32_bf16 v[124:127], v[144:147], v[168:171], v[124:127]
	v_mfma_f32_16x16x32_bf16 v[120:123], v[160:163], v[168:171], v[120:123]
	v_mfma_f32_16x16x32_bf16 v[116:119], v[144:147], v[180:183], v[116:119]
	v_mfma_f32_16x16x32_bf16 v[112:115], v[160:163], v[180:183], v[112:115]
	v_mfma_f32_16x16x32_bf16 v[96:99], v[144:147], v[188:191], v[96:99]
	v_mfma_f32_16x16x32_bf16 v[88:91], v[160:163], v[188:191], v[88:91]
	v_mfma_f32_16x16x32_bf16 v[80:83], v[144:147], v[196:199], v[80:83]
	v_mfma_f32_16x16x32_bf16 v[72:75], v[160:163], v[196:199], v[72:75]
	v_mfma_f32_16x16x32_bf16 v[124:127], v[148:151], v[176:179], v[124:127]
	v_mfma_f32_16x16x32_bf16 v[120:123], v[164:167], v[176:179], v[120:123]
	v_mfma_f32_16x16x32_bf16 v[116:119], v[148:151], v[184:187], v[116:119]
	v_mfma_f32_16x16x32_bf16 v[112:115], v[164:167], v[184:187], v[112:115]
	v_mfma_f32_16x16x32_bf16 v[96:99], v[148:151], v[192:195], v[96:99]
	v_mfma_f32_16x16x32_bf16 v[88:91], v[164:167], v[192:195], v[88:91]
	v_mfma_f32_16x16x32_bf16 v[80:83], v[148:151], v[200:203], v[80:83]
	v_mfma_f32_16x16x32_bf16 v[72:75], v[164:167], v[200:203], v[72:75]
	s_barrier
	s_setprio 0
	s_add_i32 s50, s40, s29
	v_lshl_add_u64 v[152:153], s[24:25], 0, v[130:131]
	s_mov_b32 m0, s50
	ds_read_b128 v[204:207], v159
	ds_read_b128 v[212:215], v159 offset:1024
	ds_read_b128 v[216:219], v159 offset:2048
	ds_read_b128 v[220:223], v159 offset:3072
	global_load_lds_dwordx4 v[152:153], off
	v_lshl_add_u64 v[172:173], s[24:25], 0, v[134:135]
	s_add_i32 m0, s50, 0x2000
	s_nop 0
	global_load_lds_dwordx4 v[172:173], off
	s_setprio 1
	s_barrier
	s_waitcnt lgkmcnt(0)
	v_mfma_f32_16x16x32_bf16 v[108:111], v[204:207], v[168:171], v[108:111]
	v_mfma_f32_16x16x32_bf16 v[104:107], v[216:219], v[168:171], v[104:107]
	v_mfma_f32_16x16x32_bf16 v[100:103], v[204:207], v[180:183], v[100:103]
	v_mfma_f32_16x16x32_bf16 v[92:95], v[216:219], v[180:183], v[92:95]
	v_mfma_f32_16x16x32_bf16 v[84:87], v[204:207], v[188:191], v[84:87]
	v_mfma_f32_16x16x32_bf16 v[76:79], v[216:219], v[188:191], v[76:79]
	v_mfma_f32_16x16x32_bf16 v[68:71], v[204:207], v[196:199], v[68:71]
	v_mfma_f32_16x16x32_bf16 v[64:67], v[216:219], v[196:199], v[64:67]
	v_mfma_f32_16x16x32_bf16 v[108:111], v[212:215], v[176:179], v[108:111]
	v_mfma_f32_16x16x32_bf16 v[104:107], v[220:223], v[176:179], v[104:107]
	v_mfma_f32_16x16x32_bf16 v[100:103], v[212:215], v[184:187], v[100:103]
	v_mfma_f32_16x16x32_bf16 v[92:95], v[220:223], v[184:187], v[92:95]
	v_mfma_f32_16x16x32_bf16 v[84:87], v[212:215], v[192:195], v[84:87]
	v_mfma_f32_16x16x32_bf16 v[76:79], v[220:223], v[192:195], v[76:79]
	v_mfma_f32_16x16x32_bf16 v[68:71], v[212:215], v[200:203], v[68:71]
	v_mfma_f32_16x16x32_bf16 v[64:67], v[220:223], v[200:203], v[64:67]
	s_barrier
	s_setprio 0
	s_mov_b32 m0, s21
	v_lshl_add_u64 v[208:209], s[26:27], 0, v[128:129]
	ds_read_b128 v[168:171], v158 offset:16384
	ds_read_b128 v[176:179], v158 offset:17408
	ds_read_b128 v[180:183], v158 offset:18432
	ds_read_b128 v[184:187], v158 offset:19456
	ds_read_b128 v[188:191], v158 offset:20480
	ds_read_b128 v[192:195], v158 offset:21504
	ds_read_b128 v[196:199], v158 offset:22528
	ds_read_b128 v[200:203], v158 offset:23552
	global_load_lds_dwordx4 v[208:209], off
	v_lshl_add_u64 v[224:225], s[26:27], 0, v[132:133]
	s_mov_b32 m0, s30
	s_nop 0
	global_load_lds_dwordx4 v[224:225], off
	s_setprio 1
	s_barrier
	s_waitcnt lgkmcnt(0)
	v_mfma_f32_16x16x32_bf16 v[60:63], v[144:147], v[168:171], v[60:63]
	v_mfma_f32_16x16x32_bf16 v[56:59], v[160:163], v[168:171], v[56:59]
	v_mfma_f32_16x16x32_bf16 v[52:55], v[144:147], v[180:183], v[52:55]
	v_mfma_f32_16x16x32_bf16 v[48:51], v[160:163], v[180:183], v[48:51]
	v_mfma_f32_16x16x32_bf16 v[32:35], v[144:147], v[188:191], v[32:35]
	v_mfma_f32_16x16x32_bf16 v[24:27], v[160:163], v[188:191], v[24:27]
	v_mfma_f32_16x16x32_bf16 v[16:19], v[144:147], v[196:199], v[16:19]
	v_mfma_f32_16x16x32_bf16 v[8:11], v[160:163], v[196:199], v[8:11]
	v_mfma_f32_16x16x32_bf16 v[60:63], v[148:151], v[176:179], v[60:63]
	v_mfma_f32_16x16x32_bf16 v[56:59], v[164:167], v[176:179], v[56:59]
	v_mfma_f32_16x16x32_bf16 v[52:55], v[148:151], v[184:187], v[52:55]
	v_mfma_f32_16x16x32_bf16 v[48:51], v[164:167], v[184:187], v[48:51]
	v_mfma_f32_16x16x32_bf16 v[32:35], v[148:151], v[192:195], v[32:35]
	v_mfma_f32_16x16x32_bf16 v[24:27], v[164:167], v[192:195], v[24:27]
	v_mfma_f32_16x16x32_bf16 v[16:19], v[148:151], v[200:203], v[16:19]
	v_mfma_f32_16x16x32_bf16 v[8:11], v[164:167], v[200:203], v[8:11]
	s_barrier
	s_setprio 0
	s_add_u32 s50, s24, 0x40000
	s_addc_u32 s51, s25, 0
	s_add_i32 s52, s41, s29
	v_lshl_add_u64 v[144:145], s[50:51], 0, v[130:131]
	s_mov_b32 m0, s52
	s_nop 0
	global_load_lds_dwordx4 v[144:145], off
	v_lshl_add_u64 v[144:145], s[50:51], 0, v[134:135]
	s_add_i32 m0, s52, 0x2000
	s_nop 0
	global_load_lds_dwordx4 v[144:145], off
	s_waitcnt vmcnt(6)
	s_setprio 1
	s_barrier
	v_mfma_f32_16x16x32_bf16 v[44:47], v[204:207], v[168:171], v[44:47]
	v_mfma_f32_16x16x32_bf16 v[40:43], v[216:219], v[168:171], v[40:43]
	v_mfma_f32_16x16x32_bf16 v[36:39], v[204:207], v[180:183], v[36:39]
	v_mfma_f32_16x16x32_bf16 v[28:31], v[216:219], v[180:183], v[28:31]
	v_mfma_f32_16x16x32_bf16 v[20:23], v[204:207], v[188:191], v[20:23]
	v_mfma_f32_16x16x32_bf16 v[12:15], v[216:219], v[188:191], v[12:15]
	v_mfma_f32_16x16x32_bf16 v[4:7], v[204:207], v[196:199], v[4:7]
	v_mfma_f32_16x16x32_bf16 v[0:3], v[216:219], v[196:199], v[0:3]
	v_mfma_f32_16x16x32_bf16 v[44:47], v[212:215], v[176:179], v[44:47]
	v_mfma_f32_16x16x32_bf16 v[40:43], v[220:223], v[176:179], v[40:43]
	v_mfma_f32_16x16x32_bf16 v[36:39], v[212:215], v[184:187], v[36:39]
	v_mfma_f32_16x16x32_bf16 v[28:31], v[220:223], v[184:187], v[28:31]
	v_mfma_f32_16x16x32_bf16 v[20:23], v[212:215], v[192:195], v[20:23]
	v_mfma_f32_16x16x32_bf16 v[12:15], v[220:223], v[192:195], v[12:15]
	v_mfma_f32_16x16x32_bf16 v[4:7], v[212:215], v[200:203], v[4:7]
	v_mfma_f32_16x16x32_bf16 v[0:3], v[220:223], v[200:203], v[0:3]
	s_barrier
	s_setprio 0
	s_add_i32 s50, 0, 0x18000
	v_add_u32_e32 v164, s50, v155
	ds_read_b128 v[144:147], v164
	ds_read_b128 v[148:151], v164 offset:1024
	ds_read_b128 v[160:163], v164 offset:2048
	ds_read_b128 v[164:167], v164 offset:3072
	s_add_u32 s26, s26, 0x40000
	s_addc_u32 s27, s27, 0
	s_mov_b32 m0, s31
	v_lshl_add_u64 v[204:205], s[26:27], 0, v[128:129]
	ds_read_b128 v[168:171], v158 offset:32768
	ds_read_b128 v[176:179], v158 offset:33792
	ds_read_b128 v[180:183], v158 offset:34816
	ds_read_b128 v[184:187], v158 offset:35840
	ds_read_b128 v[188:191], v158 offset:36864
	ds_read_b128 v[192:195], v158 offset:37888
	ds_read_b128 v[196:199], v158 offset:38912
	ds_read_b128 v[200:203], v158 offset:39936
	global_load_lds_dwordx4 v[204:205], off
	v_lshl_add_u64 v[204:205], s[26:27], 0, v[132:133]
	s_mov_b32 m0, s33
	s_nop 0
	global_load_lds_dwordx4 v[204:205], off
	s_waitcnt lgkmcnt(8)
	s_setprio 1
	s_barrier
	s_waitcnt lgkmcnt(0)
	v_mfma_f32_16x16x32_bf16 v[124:127], v[144:147], v[168:171], v[124:127]
	v_mfma_f32_16x16x32_bf16 v[120:123], v[160:163], v[168:171], v[120:123]
	v_mfma_f32_16x16x32_bf16 v[116:119], v[144:147], v[180:183], v[116:119]
	v_mfma_f32_16x16x32_bf16 v[112:115], v[160:163], v[180:183], v[112:115]
	v_mfma_f32_16x16x32_bf16 v[96:99], v[144:147], v[188:191], v[96:99]
	v_mfma_f32_16x16x32_bf16 v[88:91], v[160:163], v[188:191], v[88:91]
	v_mfma_f32_16x16x32_bf16 v[80:83], v[144:147], v[196:199], v[80:83]
	v_mfma_f32_16x16x32_bf16 v[72:75], v[160:163], v[196:199], v[72:75]
	v_mfma_f32_16x16x32_bf16 v[124:127], v[148:151], v[176:179], v[124:127]
	v_mfma_f32_16x16x32_bf16 v[120:123], v[164:167], v[176:179], v[120:123]
	v_mfma_f32_16x16x32_bf16 v[116:119], v[148:151], v[184:187], v[116:119]
	v_mfma_f32_16x16x32_bf16 v[112:115], v[164:167], v[184:187], v[112:115]
	v_mfma_f32_16x16x32_bf16 v[96:99], v[148:151], v[192:195], v[96:99]
	v_mfma_f32_16x16x32_bf16 v[88:91], v[164:167], v[192:195], v[88:91]
	v_mfma_f32_16x16x32_bf16 v[80:83], v[148:151], v[200:203], v[80:83]
	v_mfma_f32_16x16x32_bf16 v[72:75], v[164:167], v[200:203], v[72:75]
	s_barrier
	s_setprio 0
	s_add_i32 s26, 0, 0x1c000
	s_add_i32 s27, s50, s29
	v_add_u32_e32 v175, s26, v155
	v_lshl_add_u64 v[152:153], v[152:153], 0, s[0:1]
	s_mov_b32 m0, s27
	ds_read_b128 v[204:207], v175
	ds_read_b128 v[212:215], v175 offset:1024
	ds_read_b128 v[216:219], v175 offset:2048
	ds_read_b128 v[220:223], v175 offset:3072
	global_load_lds_dwordx4 v[152:153], off
	v_lshl_add_u64 v[152:153], v[172:173], 0, s[0:1]
	s_add_i32 m0, s27, 0x2000
	s_nop 0
	global_load_lds_dwordx4 v[152:153], off
	s_setprio 1
	s_barrier
	s_waitcnt lgkmcnt(0)
	v_mfma_f32_16x16x32_bf16 v[108:111], v[204:207], v[168:171], v[108:111]
	v_mfma_f32_16x16x32_bf16 v[104:107], v[216:219], v[168:171], v[104:107]
	v_mfma_f32_16x16x32_bf16 v[100:103], v[204:207], v[180:183], v[100:103]
	v_mfma_f32_16x16x32_bf16 v[92:95], v[216:219], v[180:183], v[92:95]
	v_mfma_f32_16x16x32_bf16 v[84:87], v[204:207], v[188:191], v[84:87]
	v_mfma_f32_16x16x32_bf16 v[76:79], v[216:219], v[188:191], v[76:79]
	v_mfma_f32_16x16x32_bf16 v[68:71], v[204:207], v[196:199], v[68:71]
	v_mfma_f32_16x16x32_bf16 v[64:67], v[216:219], v[196:199], v[64:67]
	v_mfma_f32_16x16x32_bf16 v[108:111], v[212:215], v[176:179], v[108:111]
	v_mfma_f32_16x16x32_bf16 v[104:107], v[220:223], v[176:179], v[104:107]
	v_mfma_f32_16x16x32_bf16 v[100:103], v[212:215], v[184:187], v[100:103]
	v_mfma_f32_16x16x32_bf16 v[92:95], v[220:223], v[184:187], v[92:95]
	v_mfma_f32_16x16x32_bf16 v[84:87], v[212:215], v[192:195], v[84:87]
	v_mfma_f32_16x16x32_bf16 v[76:79], v[220:223], v[192:195], v[76:79]
	v_mfma_f32_16x16x32_bf16 v[68:71], v[212:215], v[200:203], v[68:71]
	v_mfma_f32_16x16x32_bf16 v[64:67], v[220:223], v[200:203], v[64:67]
	s_barrier
	s_setprio 0
	s_mov_b32 m0, s35
	v_lshl_add_u64 v[152:153], v[208:209], 0, s[0:1]
	ds_read_b128 v[168:171], v158 offset:49152
	ds_read_b128 v[176:179], v158 offset:50176
	ds_read_b128 v[180:183], v158 offset:51200
	ds_read_b128 v[184:187], v158 offset:52224
	ds_read_b128 v[188:191], v158 offset:53248
	ds_read_b128 v[192:195], v158 offset:54272
	ds_read_b128 v[196:199], v158 offset:55296
	ds_read_b128 v[200:203], v158 offset:56320
	global_load_lds_dwordx4 v[152:153], off
	v_lshl_add_u64 v[152:153], v[224:225], 0, s[0:1]
	s_mov_b32 m0, s36
	s_nop 0
	global_load_lds_dwordx4 v[152:153], off
	s_setprio 1
	s_barrier
	s_waitcnt lgkmcnt(0)
	v_mfma_f32_16x16x32_bf16 v[60:63], v[144:147], v[168:171], v[60:63]
	v_mfma_f32_16x16x32_bf16 v[56:59], v[160:163], v[168:171], v[56:59]
	v_mfma_f32_16x16x32_bf16 v[52:55], v[144:147], v[180:183], v[52:55]
	v_mfma_f32_16x16x32_bf16 v[48:51], v[160:163], v[180:183], v[48:51]
	v_mfma_f32_16x16x32_bf16 v[32:35], v[144:147], v[188:191], v[32:35]
	v_mfma_f32_16x16x32_bf16 v[24:27], v[160:163], v[188:191], v[24:27]
	v_mfma_f32_16x16x32_bf16 v[16:19], v[144:147], v[196:199], v[16:19]
	v_mfma_f32_16x16x32_bf16 v[8:11], v[160:163], v[196:199], v[8:11]
	v_mfma_f32_16x16x32_bf16 v[60:63], v[148:151], v[176:179], v[60:63]
	v_mfma_f32_16x16x32_bf16 v[56:59], v[164:167], v[176:179], v[56:59]
	v_mfma_f32_16x16x32_bf16 v[52:55], v[148:151], v[184:187], v[52:55]
	v_mfma_f32_16x16x32_bf16 v[48:51], v[164:167], v[184:187], v[48:51]
	v_mfma_f32_16x16x32_bf16 v[32:35], v[148:151], v[192:195], v[32:35]
	v_mfma_f32_16x16x32_bf16 v[24:27], v[164:167], v[192:195], v[24:27]
	v_mfma_f32_16x16x32_bf16 v[16:19], v[148:151], v[200:203], v[16:19]
	v_mfma_f32_16x16x32_bf16 v[8:11], v[164:167], v[200:203], v[8:11]
	s_barrier
	s_setprio 0
	s_add_u32 s24, s24, 0x40080
	s_addc_u32 s25, s25, 0
	s_add_i32 s26, s26, s29
	v_lshl_add_u64 v[144:145], s[24:25], 0, v[130:131]
	s_mov_b32 m0, s26
	s_nop 0
	global_load_lds_dwordx4 v[144:145], off
	v_lshl_add_u64 v[144:145], s[24:25], 0, v[134:135]
	s_add_i32 m0, s26, 0x2000
	s_nop 0
	global_load_lds_dwordx4 v[144:145], off
	s_waitcnt vmcnt(6)
	s_setprio 1
	s_barrier
	v_mfma_f32_16x16x32_bf16 v[44:47], v[204:207], v[168:171], v[44:47]
	v_mfma_f32_16x16x32_bf16 v[40:43], v[216:219], v[168:171], v[40:43]
	v_mfma_f32_16x16x32_bf16 v[36:39], v[204:207], v[180:183], v[36:39]
	v_mfma_f32_16x16x32_bf16 v[28:31], v[216:219], v[180:183], v[28:31]
	v_mfma_f32_16x16x32_bf16 v[20:23], v[204:207], v[188:191], v[20:23]
	v_mfma_f32_16x16x32_bf16 v[12:15], v[216:219], v[188:191], v[12:15]
	v_mfma_f32_16x16x32_bf16 v[4:7], v[204:207], v[196:199], v[4:7]
	v_mfma_f32_16x16x32_bf16 v[0:3], v[216:219], v[196:199], v[0:3]
	v_mfma_f32_16x16x32_bf16 v[44:47], v[212:215], v[176:179], v[44:47]
	v_mfma_f32_16x16x32_bf16 v[40:43], v[220:223], v[176:179], v[40:43]
	v_mfma_f32_16x16x32_bf16 v[36:39], v[212:215], v[184:187], v[36:39]
	v_mfma_f32_16x16x32_bf16 v[28:31], v[220:223], v[184:187], v[28:31]
	v_mfma_f32_16x16x32_bf16 v[20:23], v[212:215], v[192:195], v[20:23]
	v_mfma_f32_16x16x32_bf16 v[12:15], v[220:223], v[192:195], v[12:15]
	v_mfma_f32_16x16x32_bf16 v[4:7], v[212:215], v[200:203], v[4:7]
	v_mfma_f32_16x16x32_bf16 v[0:3], v[220:223], v[200:203], v[0:3]
	s_barrier
	s_setprio 0
	s_add_i32 s49, s49, 2
	s_add_u32 s22, s22, 0x100
	s_addc_u32 s23, s23, 0
	s_add_u32 s43, s43, 0x100
	s_addc_u32 s48, s48, 0
	s_cmp_gt_u32 s49, 13
	s_cbranch_scc0 .LBB0_654
	v_lshl_add_u32 v148, s18, 8, v154
	v_lshl_or_b32 v144, s20, 8, v156
	v_readlane_b32 s48, v253, 12
	v_ashrrev_i32_e32 v145, 31, v144
	v_ashrrev_i32_e32 v149, 31, v148
	v_readlane_b32 s49, v253, 13
	v_lshlrev_b64 v[150:151], 12, v[148:149]
	v_or_b32_e32 v172, 16, v148
	v_lshl_add_u64 v[146:147], v[144:145], 2, s[48:49]
	v_lshl_add_u64 v[150:151], v[146:147], 0, v[150:151]
	v_ashrrev_i32_e32 v173, 31, v172
	global_load_dwordx4 v[160:163], v[150:151], off
	global_load_dwordx4 v[164:167], v[150:151], off offset:16
	global_load_dwordx4 v[168:171], v[150:151], off offset:512
	global_load_dwordx4 v[176:179], v[150:151], off offset:528
	v_lshlrev_b64 v[150:151], 12, v[172:173]
	v_or_b32_e32 v152, 32, v148
	v_lshl_add_u64 v[150:151], v[146:147], 0, v[150:151]
	v_ashrrev_i32_e32 v153, 31, v152
	global_load_dwordx4 v[180:183], v[150:151], off
	global_load_dwordx4 v[184:187], v[150:151], off offset:16
	global_load_dwordx4 v[188:191], v[150:151], off offset:512
	global_load_dwordx4 v[192:195], v[150:151], off offset:528
	v_lshlrev_b64 v[150:151], 12, v[152:153]
	v_lshl_add_u64 v[208:209], v[146:147], 0, v[150:151]
	v_or_b32_e32 v150, 48, v148
	global_load_dwordx4 v[196:199], v[208:209], off
	global_load_dwordx4 v[200:203], v[208:209], off offset:16
	v_ashrrev_i32_e32 v151, 31, v150
	v_lshlrev_b64 v[204:205], 11, v[148:149]
	v_lshlrev_b64 v[216:217], 12, v[150:151]
	v_lshl_add_u64 v[218:219], s[10:11], 0, v[204:205]
	global_load_dwordx4 v[204:207], v[208:209], off offset:528
	global_load_dwordx4 v[212:215], v[208:209], off offset:512
	v_lshlrev_b64 v[144:145], 1, v[144:145]
	v_lshl_add_u64 v[208:209], v[146:147], 0, v[216:217]
	v_lshl_add_u64 v[232:233], v[218:219], 0, v[144:145]
	global_load_dwordx4 v[216:219], v[208:209], off offset:16
	global_load_dwordx4 v[220:223], v[208:209], off
	global_load_dwordx4 v[224:227], v[208:209], off offset:528
	global_load_dwordx4 v[228:231], v[208:209], off offset:512
	v_lshlrev_b64 v[172:173], 11, v[172:173]
	v_lshl_add_u64 v[172:173], s[10:11], 0, v[172:173]
	v_lshl_add_u64 v[172:173], v[172:173], 0, v[144:145]
	v_readlane_b32 s50, v253, 14
	v_readlane_b32 s51, v253, 15
	v_readlane_b32 s52, v253, 16
	v_readlane_b32 s53, v253, 17
	v_readlane_b32 s54, v253, 18
	v_readlane_b32 s55, v253, 19
	v_readlane_b32 s56, v253, 20
	v_readlane_b32 s57, v253, 21
	v_readlane_b32 s58, v253, 22
	v_readlane_b32 s59, v253, 23
	v_readlane_b32 s60, v253, 24
	v_readlane_b32 s61, v253, 25
	v_readlane_b32 s62, v253, 26
	v_readlane_b32 s63, v253, 27
	s_waitcnt vmcnt(0)
	v_pk_add_f32 v[126:127], v[126:127], v[162:163]
	v_pk_add_f32 v[124:125], v[124:125], v[160:161]
	v_pk_add_f32 v[160:161], v[122:123], v[166:167]
	v_pk_add_f32 v[162:163], v[120:121], v[164:165]
	v_pk_add_f32 v[164:165], v[110:111], v[170:171]
	v_pk_add_f32 v[166:167], v[108:109], v[168:169]
	v_pk_add_f32 v[168:169], v[106:107], v[178:179]
	v_cvt_pk_bf16_f32 v120, v124, v125
	v_cvt_pk_bf16_f32 v121, v126, v127
	v_cvt_pk_bf16_f32 v122, v162, v163
	v_cvt_pk_bf16_f32 v123, v160, v161
	v_pk_add_f32 v[106:107], v[112:113], v[184:185]
	global_store_dwordx4 v[232:233], v[120:123], off
	v_cvt_pk_bf16_f32 v112, v166, v167
	v_cvt_pk_bf16_f32 v113, v164, v165
	v_pk_add_f32 v[170:171], v[104:105], v[176:177]
	v_pk_add_f32 v[108:109], v[118:119], v[182:183]
	v_pk_add_f32 v[110:111], v[116:117], v[180:181]
	v_pk_add_f32 v[104:105], v[114:115], v[186:187]
	v_cvt_pk_bf16_f32 v114, v170, v171
	v_cvt_pk_bf16_f32 v115, v168, v169
	global_store_dwordx4 v[232:233], v[112:115], off offset:256
	v_mul_f32_e32 v175, v125, v125
	v_mul_f32_e32 v176, v127, v127
	v_cvt_pk_bf16_f32 v112, v110, v111
	v_cvt_pk_bf16_f32 v113, v108, v109
	v_mul_f32_e32 v125, v167, v167
	v_mul_f32_e32 v127, v165, v165
	v_cvt_pk_bf16_f32 v114, v106, v107
	v_cvt_pk_bf16_f32 v115, v104, v105
	global_store_dwordx4 v[172:173], v[112:115], off
	v_mul_f32_e32 v177, v163, v163
	v_mul_f32_e32 v178, v161, v161
	v_pk_add_f32 v[112:113], v[100:101], v[188:189]
	v_pk_add_f32 v[100:101], v[92:93], v[192:193]
	v_pk_add_f32 v[92:93], v[98:99], v[198:199]
	v_lshlrev_b64 v[98:99], 11, v[152:153]
	v_mul_f32_e32 v161, v171, v171
	v_fmac_f32_e32 v175, v124, v124
	v_fmac_f32_e32 v176, v126, v126
	v_fmac_f32_e32 v125, v166, v166
	v_fmac_f32_e32 v127, v164, v164
	v_lshl_add_u64 v[98:99], s[10:11], 0, v[98:99]
	v_mul_f32_e32 v163, v169, v169
	v_fmac_f32_e32 v177, v162, v162
	v_fmac_f32_e32 v161, v170, v170
	v_add_f32_e32 v116, v175, v176
	v_add_f32_e32 v117, v125, v127
	v_lshl_add_u64 v[118:119], v[98:99], 0, v[144:145]
	v_pk_add_f32 v[98:99], v[84:85], v[212:213]
	v_pk_add_f32 v[84:85], v[76:77], v[204:205]
	v_pk_add_f32 v[76:77], v[82:83], v[222:223]
	v_lshlrev_b64 v[82:83], 11, v[150:151]
	v_fmac_f32_e32 v178, v160, v160
	v_fmac_f32_e32 v163, v168, v168
	v_add_f32_e32 v116, v116, v177
	v_add_f32_e32 v117, v117, v161
	v_lshl_add_u64 v[82:83], s[10:11], 0, v[82:83]
	v_add_f32_e32 v116, v178, v116
	v_add_f32_e32 v117, v163, v117
	v_cvt_pk_bf16_f32 v114, v112, v113
	v_lshl_add_u64 v[122:123], v[82:83], 0, v[144:145]
	v_pk_add_f32 v[82:83], v[68:69], v[228:229]
	v_pk_add_f32 v[68:69], v[64:65], v[224:225]
	v_and_b32_e32 v65, 64, v174
	v_add_f32_e32 v120, v116, v117
	v_pk_add_f32 v[102:103], v[102:103], v[190:191]
	v_pk_add_f32 v[94:95], v[94:95], v[194:195]
	v_cvt_pk_bf16_f32 v115, v102, v103
	v_cvt_pk_bf16_f32 v116, v100, v101
	v_pk_add_f32 v[96:97], v[96:97], v[196:197]
	v_cvt_pk_bf16_f32 v117, v94, v95
	global_store_dwordx4 v[172:173], v[114:117], off offset:256
	v_xor_b32_e32 v64, 16, v174
	v_add_u32_e32 v65, 64, v65
	v_cvt_pk_bf16_f32 v114, v96, v97
	v_pk_add_f32 v[90:91], v[90:91], v[202:203]
	v_pk_add_f32 v[88:89], v[88:89], v[200:201]
	v_cvt_pk_bf16_f32 v115, v92, v93
	v_cmp_lt_i32_e32 vcc, v64, v65
	v_cvt_pk_bf16_f32 v116, v88, v89
	v_cvt_pk_bf16_f32 v117, v90, v91
	global_store_dwordx4 v[118:119], v[114:117], off
	v_pk_add_f32 v[86:87], v[86:87], v[214:215]
	v_pk_add_f32 v[78:79], v[78:79], v[206:207]
	v_cvt_pk_bf16_f32 v114, v98, v99
	v_cvt_pk_bf16_f32 v115, v86, v87
	v_cvt_pk_bf16_f32 v116, v84, v85
	v_pk_add_f32 v[80:81], v[80:81], v[220:221]
	v_cvt_pk_bf16_f32 v117, v78, v79
	global_store_dwordx4 v[118:119], v[114:117], off offset:256
	v_cndmask_b32_e32 v64, v174, v64, vcc
	v_pk_add_f32 v[74:75], v[74:75], v[218:219]
	v_cvt_pk_bf16_f32 v114, v80, v81
	v_pk_add_f32 v[72:73], v[72:73], v[216:217]
	v_cvt_pk_bf16_f32 v115, v76, v77
	v_pk_add_f32 v[70:71], v[70:71], v[230:231]
	v_cvt_pk_bf16_f32 v116, v72, v73
	v_cvt_pk_bf16_f32 v117, v74, v75
	global_store_dwordx4 v[122:123], v[114:117], off
	v_pk_add_f32 v[66:67], v[66:67], v[226:227]
	v_cvt_pk_bf16_f32 v118, v82, v83
	v_cvt_pk_bf16_f32 v119, v70, v71
	s_nop 0
	v_lshlrev_b32_e32 v114, 2, v64
	ds_bpermute_b32 v64, v114, v120
	v_xor_b32_e32 v115, 32, v174
	v_cmp_lt_i32_e32 vcc, v115, v65
	s_waitcnt lgkmcnt(0)
	v_add_f32_e32 v116, v120, v64
	v_cndmask_b32_e32 v65, v174, v115, vcc
	v_lshlrev_b32_e32 v115, 2, v65
	ds_bpermute_b32 v117, v115, v116
	v_lshl_add_u64 v[64:65], v[148:149], 2, s[66:67]
	v_cvt_pk_bf16_f32 v120, v68, v69
	v_cvt_pk_bf16_f32 v121, v66, v67
	global_store_dwordx4 v[122:123], v[118:121], off offset:256
	s_and_saveexec_b64 s[18:19], s[6:7]
	s_cbranch_execz .LBB0_657
	s_waitcnt lgkmcnt(0)
	v_add_f32_e32 v116, v116, v117
	global_atomic_add_f32 v[64:65], v116, off

.LBB0_712:
	ds_read_b128 v[144:147], v151
	ds_read_b128 v[156:159], v151 offset:1024
	ds_read_b128 v[160:163], v151 offset:2048
	ds_read_b128 v[164:167], v151 offset:3072
	s_add_u32 s26, s2, 0xfffc0080
	s_addc_u32 s27, s3, -1
	s_cmp_eq_u32 s56, 12
	s_cselect_b32 s29, s21, s27
	s_cselect_b32 s28, s52, s26
	s_cselect_b32 s27, s19, s55
	s_cselect_b32 s26, s53, s54
	v_lshl_add_u64 v[172:173], s[2:3], 0, v[136:137]
	s_add_i32 m0, s34, 0xc000
	ds_read_b128 v[168:171], v152
	ds_read_b128 v[176:179], v152 offset:1024
	ds_read_b128 v[180:183], v152 offset:2048
	ds_read_b128 v[184:187], v152 offset:3072
	ds_read_b128 v[188:191], v152 offset:4096
	ds_read_b128 v[192:195], v152 offset:5120
	ds_read_b128 v[196:199], v152 offset:6144
	ds_read_b128 v[200:203], v152 offset:7168
	global_load_lds_dwordx4 v[172:173], off
	v_lshl_add_u64 v[172:173], s[2:3], 0, v[138:139]
	s_add_i32 m0, s34, 0xe000
	s_nop 0
	global_load_lds_dwordx4 v[172:173], off
	s_waitcnt lgkmcnt(8)
	s_setprio 1
	s_barrier
	s_waitcnt lgkmcnt(0)
	v_mfma_f32_16x16x32_bf16 v[124:127], v[144:147], v[168:171], v[124:127]
	v_mfma_f32_16x16x32_bf16 v[120:123], v[160:163], v[168:171], v[120:123]
	v_mfma_f32_16x16x32_bf16 v[116:119], v[144:147], v[180:183], v[116:119]
	v_mfma_f32_16x16x32_bf16 v[112:115], v[160:163], v[180:183], v[112:115]
	v_mfma_f32_16x16x32_bf16 v[104:107], v[144:147], v[188:191], v[104:107]
	v_mfma_f32_16x16x32_bf16 v[96:99], v[160:163], v[188:191], v[96:99]
	v_mfma_f32_16x16x32_bf16 v[76:79], v[144:147], v[196:199], v[76:79]
	v_mfma_f32_16x16x32_bf16 v[72:75], v[160:163], v[196:199], v[72:75]
	v_mfma_f32_16x16x32_bf16 v[124:127], v[156:159], v[176:179], v[124:127]
	v_mfma_f32_16x16x32_bf16 v[120:123], v[164:167], v[176:179], v[120:123]
	v_mfma_f32_16x16x32_bf16 v[116:119], v[156:159], v[184:187], v[116:119]
	v_mfma_f32_16x16x32_bf16 v[112:115], v[164:167], v[184:187], v[112:115]
	v_mfma_f32_16x16x32_bf16 v[104:107], v[156:159], v[192:195], v[104:107]
	v_mfma_f32_16x16x32_bf16 v[96:99], v[164:167], v[192:195], v[96:99]
	v_mfma_f32_16x16x32_bf16 v[76:79], v[156:159], v[200:203], v[76:79]
	v_mfma_f32_16x16x32_bf16 v[72:75], v[164:167], v[200:203], v[72:75]
	s_barrier
	s_setprio 0
	s_add_i32 s57, s43, s33
	v_lshl_add_u64 v[172:173], s[26:27], 0, v[130:131]
	s_mov_b32 m0, s57
	ds_read_b128 v[204:207], v153
	ds_read_b128 v[212:215], v153 offset:1024
	ds_read_b128 v[216:219], v153 offset:2048
	ds_read_b128 v[220:223], v153 offset:3072
	global_load_lds_dwordx4 v[172:173], off
	v_lshl_add_u64 v[208:209], s[26:27], 0, v[134:135]
	s_add_i32 m0, s57, 0x2000
	s_nop 0
	global_load_lds_dwordx4 v[208:209], off
	s_setprio 1
	s_barrier
	s_waitcnt lgkmcnt(0)
	v_mfma_f32_16x16x32_bf16 v[108:111], v[204:207], v[168:171], v[108:111]
	v_mfma_f32_16x16x32_bf16 v[100:103], v[216:219], v[168:171], v[100:103]
	v_mfma_f32_16x16x32_bf16 v[92:95], v[204:207], v[180:183], v[92:95]
	v_mfma_f32_16x16x32_bf16 v[88:91], v[216:219], v[180:183], v[88:91]
	v_mfma_f32_16x16x32_bf16 v[84:87], v[204:207], v[188:191], v[84:87]
	v_mfma_f32_16x16x32_bf16 v[80:83], v[216:219], v[188:191], v[80:83]
	v_mfma_f32_16x16x32_bf16 v[68:71], v[204:207], v[196:199], v[68:71]
	v_mfma_f32_16x16x32_bf16 v[64:67], v[216:219], v[196:199], v[64:67]
	v_mfma_f32_16x16x32_bf16 v[108:111], v[212:215], v[176:179], v[108:111]
	v_mfma_f32_16x16x32_bf16 v[100:103], v[220:223], v[176:179], v[100:103]
	v_mfma_f32_16x16x32_bf16 v[92:95], v[212:215], v[184:187], v[92:95]
	v_mfma_f32_16x16x32_bf16 v[88:91], v[220:223], v[184:187], v[88:91]
	v_mfma_f32_16x16x32_bf16 v[84:87], v[212:215], v[192:195], v[84:87]
	v_mfma_f32_16x16x32_bf16 v[80:83], v[220:223], v[192:195], v[80:83]
	v_mfma_f32_16x16x32_bf16 v[68:71], v[212:215], v[200:203], v[68:71]
	v_mfma_f32_16x16x32_bf16 v[64:67], v[220:223], v[200:203], v[64:67]
	s_barrier
	s_setprio 0
	s_mov_b32 m0, s34
	v_lshl_add_u64 v[224:225], s[28:29], 0, v[128:129]
	ds_read_b128 v[168:171], v152 offset:16384
	ds_read_b128 v[176:179], v152 offset:17408
	ds_read_b128 v[180:183], v152 offset:18432
	ds_read_b128 v[184:187], v152 offset:19456
	ds_read_b128 v[188:191], v152 offset:20480
	ds_read_b128 v[192:195], v152 offset:21504
	ds_read_b128 v[196:199], v152 offset:22528
	ds_read_b128 v[200:203], v152 offset:23552
	global_load_lds_dwordx4 v[224:225], off
	v_lshl_add_u64 v[226:227], s[28:29], 0, v[132:133]
	s_mov_b32 m0, s35
	s_nop 0
	global_load_lds_dwordx4 v[226:227], off
	s_setprio 1
	s_barrier
	s_waitcnt lgkmcnt(0)
	v_mfma_f32_16x16x32_bf16 v[60:63], v[144:147], v[168:171], v[60:63]
	v_mfma_f32_16x16x32_bf16 v[56:59], v[160:163], v[168:171], v[56:59]
	v_mfma_f32_16x16x32_bf16 v[44:47], v[144:147], v[180:183], v[44:47]
	v_mfma_f32_16x16x32_bf16 v[40:43], v[160:163], v[180:183], v[40:43]
	v_mfma_f32_16x16x32_bf16 v[28:31], v[144:147], v[188:191], v[28:31]
	v_mfma_f32_16x16x32_bf16 v[24:27], v[160:163], v[188:191], v[24:27]
	v_mfma_f32_16x16x32_bf16 v[12:15], v[144:147], v[196:199], v[12:15]
	v_mfma_f32_16x16x32_bf16 v[8:11], v[160:163], v[196:199], v[8:11]
	v_mfma_f32_16x16x32_bf16 v[60:63], v[156:159], v[176:179], v[60:63]
	v_mfma_f32_16x16x32_bf16 v[56:59], v[164:167], v[176:179], v[56:59]
	v_mfma_f32_16x16x32_bf16 v[44:47], v[156:159], v[184:187], v[44:47]
	v_mfma_f32_16x16x32_bf16 v[40:43], v[164:167], v[184:187], v[40:43]
	v_mfma_f32_16x16x32_bf16 v[28:31], v[156:159], v[192:195], v[28:31]
	v_mfma_f32_16x16x32_bf16 v[24:27], v[164:167], v[192:195], v[24:27]
	v_mfma_f32_16x16x32_bf16 v[12:15], v[156:159], v[200:203], v[12:15]
	v_mfma_f32_16x16x32_bf16 v[8:11], v[164:167], v[200:203], v[8:11]
	s_barrier
	s_setprio 0
	s_add_u32 s58, s26, 0x40000
	s_addc_u32 s59, s27, 0
	s_add_i32 s57, s48, s33
	v_lshl_add_u64 v[144:145], s[58:59], 0, v[130:131]
	s_mov_b32 m0, s57
	s_nop 0
	global_load_lds_dwordx4 v[144:145], off
	v_lshl_add_u64 v[144:145], s[58:59], 0, v[134:135]
	s_add_i32 m0, s57, 0x2000
	s_nop 0
	global_load_lds_dwordx4 v[144:145], off
	s_waitcnt vmcnt(6)
	s_setprio 1
	s_barrier
	v_mfma_f32_16x16x32_bf16 v[52:55], v[204:207], v[168:171], v[52:55]
	v_mfma_f32_16x16x32_bf16 v[48:51], v[216:219], v[168:171], v[48:51]
	v_mfma_f32_16x16x32_bf16 v[36:39], v[204:207], v[180:183], v[36:39]
	v_mfma_f32_16x16x32_bf16 v[32:35], v[216:219], v[180:183], v[32:35]
	v_mfma_f32_16x16x32_bf16 v[20:23], v[204:207], v[188:191], v[20:23]
	v_mfma_f32_16x16x32_bf16 v[16:19], v[216:219], v[188:191], v[16:19]
	v_mfma_f32_16x16x32_bf16 v[4:7], v[204:207], v[196:199], v[4:7]
	v_mfma_f32_16x16x32_bf16 v[0:3], v[216:219], v[196:199], v[0:3]
	v_mfma_f32_16x16x32_bf16 v[52:55], v[212:215], v[176:179], v[52:55]
	v_mfma_f32_16x16x32_bf16 v[48:51], v[220:223], v[176:179], v[48:51]
	v_mfma_f32_16x16x32_bf16 v[36:39], v[212:215], v[184:187], v[36:39]
	v_mfma_f32_16x16x32_bf16 v[32:35], v[220:223], v[184:187], v[32:35]
	v_mfma_f32_16x16x32_bf16 v[20:23], v[212:215], v[192:195], v[20:23]
	v_mfma_f32_16x16x32_bf16 v[16:19], v[220:223], v[192:195], v[16:19]
	v_mfma_f32_16x16x32_bf16 v[4:7], v[212:215], v[200:203], v[4:7]
	v_mfma_f32_16x16x32_bf16 v[0:3], v[220:223], v[200:203], v[0:3]
	s_barrier
	s_setprio 0
	s_add_i32 s57, 0, 0x18000
	v_add_u32_e32 v155, s57, v149
	ds_read_b128 v[144:147], v155
	ds_read_b128 v[156:159], v155 offset:1024
	ds_read_b128 v[160:163], v155 offset:2048
	ds_read_b128 v[164:167], v155 offset:3072
	s_add_u32 s28, s28, 0x40000
	s_addc_u32 s29, s29, 0
	s_mov_b32 m0, s36
	v_lshl_add_u64 v[204:205], s[28:29], 0, v[128:129]
	ds_read_b128 v[168:171], v152 offset:32768
	ds_read_b128 v[176:179], v152 offset:33792
	ds_read_b128 v[180:183], v152 offset:34816
	ds_read_b128 v[184:187], v152 offset:35840
	ds_read_b128 v[188:191], v152 offset:36864
	ds_read_b128 v[192:195], v152 offset:37888
	ds_read_b128 v[196:199], v152 offset:38912
	ds_read_b128 v[200:203], v152 offset:39936
	global_load_lds_dwordx4 v[204:205], off
	v_lshl_add_u64 v[204:205], s[28:29], 0, v[132:133]
	s_mov_b32 m0, s37
	s_nop 0
	global_load_lds_dwordx4 v[204:205], off
	s_waitcnt lgkmcnt(8)
	s_setprio 1
	s_barrier
	s_waitcnt lgkmcnt(0)
	v_mfma_f32_16x16x32_bf16 v[124:127], v[144:147], v[168:171], v[124:127]
	v_mfma_f32_16x16x32_bf16 v[120:123], v[160:163], v[168:171], v[120:123]
	v_mfma_f32_16x16x32_bf16 v[116:119], v[144:147], v[180:183], v[116:119]
	v_mfma_f32_16x16x32_bf16 v[112:115], v[160:163], v[180:183], v[112:115]
	v_mfma_f32_16x16x32_bf16 v[104:107], v[144:147], v[188:191], v[104:107]
	v_mfma_f32_16x16x32_bf16 v[96:99], v[160:163], v[188:191], v[96:99]
	v_mfma_f32_16x16x32_bf16 v[76:79], v[144:147], v[196:199], v[76:79]
	v_mfma_f32_16x16x32_bf16 v[72:75], v[160:163], v[196:199], v[72:75]
	v_mfma_f32_16x16x32_bf16 v[124:127], v[156:159], v[176:179], v[124:127]
	v_mfma_f32_16x16x32_bf16 v[120:123], v[164:167], v[176:179], v[120:123]
	v_mfma_f32_16x16x32_bf16 v[116:119], v[156:159], v[184:187], v[116:119]
	v_mfma_f32_16x16x32_bf16 v[112:115], v[164:167], v[184:187], v[112:115]
	v_mfma_f32_16x16x32_bf16 v[104:107], v[156:159], v[192:195], v[104:107]
	v_mfma_f32_16x16x32_bf16 v[96:99], v[164:167], v[192:195], v[96:99]
	v_mfma_f32_16x16x32_bf16 v[76:79], v[156:159], v[200:203], v[76:79]
	v_mfma_f32_16x16x32_bf16 v[72:75], v[164:167], v[200:203], v[72:75]
	s_barrier
	s_setprio 0
	s_add_i32 s28, 0, 0x1c000
	s_add_i32 s29, s57, s33
	v_add_u32_e32 v155, s28, v149
	v_lshl_add_u64 v[172:173], v[172:173], 0, s[8:9]
	s_mov_b32 m0, s29
	ds_read_b128 v[204:207], v155
	ds_read_b128 v[212:215], v155 offset:1024
	ds_read_b128 v[216:219], v155 offset:2048
	ds_read_b128 v[220:223], v155 offset:3072
	global_load_lds_dwordx4 v[172:173], off
	v_lshl_add_u64 v[172:173], v[208:209], 0, s[8:9]
	s_add_i32 m0, s29, 0x2000
	s_nop 0
	global_load_lds_dwordx4 v[172:173], off
	s_setprio 1
	s_barrier
	s_waitcnt lgkmcnt(0)
	v_mfma_f32_16x16x32_bf16 v[108:111], v[204:207], v[168:171], v[108:111]
	v_mfma_f32_16x16x32_bf16 v[100:103], v[216:219], v[168:171], v[100:103]
	v_mfma_f32_16x16x32_bf16 v[92:95], v[204:207], v[180:183], v[92:95]
	v_mfma_f32_16x16x32_bf16 v[88:91], v[216:219], v[180:183], v[88:91]
	v_mfma_f32_16x16x32_bf16 v[84:87], v[204:207], v[188:191], v[84:87]
	v_mfma_f32_16x16x32_bf16 v[80:83], v[216:219], v[188:191], v[80:83]
	v_mfma_f32_16x16x32_bf16 v[68:71], v[204:207], v[196:199], v[68:71]
	v_mfma_f32_16x16x32_bf16 v[64:67], v[216:219], v[196:199], v[64:67]
	v_mfma_f32_16x16x32_bf16 v[108:111], v[212:215], v[176:179], v[108:111]
	v_mfma_f32_16x16x32_bf16 v[100:103], v[220:223], v[176:179], v[100:103]
	v_mfma_f32_16x16x32_bf16 v[92:95], v[212:215], v[184:187], v[92:95]
	v_mfma_f32_16x16x32_bf16 v[88:91], v[220:223], v[184:187], v[88:91]
	v_mfma_f32_16x16x32_bf16 v[84:87], v[212:215], v[192:195], v[84:87]
	v_mfma_f32_16x16x32_bf16 v[80:83], v[220:223], v[192:195], v[80:83]
	v_mfma_f32_16x16x32_bf16 v[68:71], v[212:215], v[200:203], v[68:71]
	v_mfma_f32_16x16x32_bf16 v[64:67], v[220:223], v[200:203], v[64:67]
	s_barrier
	s_setprio 0
	s_mov_b32 m0, s39
	v_lshl_add_u64 v[172:173], v[224:225], 0, s[8:9]
	ds_read_b128 v[168:171], v152 offset:49152
	ds_read_b128 v[176:179], v152 offset:50176
	ds_read_b128 v[180:183], v152 offset:51200
	ds_read_b128 v[184:187], v152 offset:52224
	ds_read_b128 v[188:191], v152 offset:53248
	ds_read_b128 v[192:195], v152 offset:54272
	ds_read_b128 v[196:199], v152 offset:55296
	ds_read_b128 v[200:203], v152 offset:56320
	global_load_lds_dwordx4 v[172:173], off
	v_lshl_add_u64 v[172:173], v[226:227], 0, s[8:9]
	s_mov_b32 m0, s40
	s_nop 0
	global_load_lds_dwordx4 v[172:173], off
	s_setprio 1
	s_barrier
	s_waitcnt lgkmcnt(0)
	v_mfma_f32_16x16x32_bf16 v[60:63], v[144:147], v[168:171], v[60:63]
	v_mfma_f32_16x16x32_bf16 v[56:59], v[160:163], v[168:171], v[56:59]
	v_mfma_f32_16x16x32_bf16 v[44:47], v[144:147], v[180:183], v[44:47]
	v_mfma_f32_16x16x32_bf16 v[40:43], v[160:163], v[180:183], v[40:43]
	v_mfma_f32_16x16x32_bf16 v[28:31], v[144:147], v[188:191], v[28:31]
	v_mfma_f32_16x16x32_bf16 v[24:27], v[160:163], v[188:191], v[24:27]
	v_mfma_f32_16x16x32_bf16 v[12:15], v[144:147], v[196:199], v[12:15]
	v_mfma_f32_16x16x32_bf16 v[8:11], v[160:163], v[196:199], v[8:11]
	v_mfma_f32_16x16x32_bf16 v[60:63], v[156:159], v[176:179], v[60:63]
	v_mfma_f32_16x16x32_bf16 v[56:59], v[164:167], v[176:179], v[56:59]
	v_mfma_f32_16x16x32_bf16 v[44:47], v[156:159], v[184:187], v[44:47]
	v_mfma_f32_16x16x32_bf16 v[40:43], v[164:167], v[184:187], v[40:43]
	v_mfma_f32_16x16x32_bf16 v[28:31], v[156:159], v[192:195], v[28:31]
	v_mfma_f32_16x16x32_bf16 v[24:27], v[164:167], v[192:195], v[24:27]
	v_mfma_f32_16x16x32_bf16 v[12:15], v[156:159], v[200:203], v[12:15]
	v_mfma_f32_16x16x32_bf16 v[8:11], v[164:167], v[200:203], v[8:11]
	s_barrier
	s_setprio 0
	s_add_u32 s26, s26, 0x40080
	s_addc_u32 s27, s27, 0
	s_add_i32 s28, s28, s33
	v_lshl_add_u64 v[144:145], s[26:27], 0, v[130:131]
	s_mov_b32 m0, s28
	s_nop 0
	global_load_lds_dwordx4 v[144:145], off
	v_lshl_add_u64 v[144:145], s[26:27], 0, v[134:135]
	s_add_i32 m0, s28, 0x2000
	s_nop 0
	global_load_lds_dwordx4 v[144:145], off
	s_waitcnt vmcnt(6)
	s_setprio 1
	s_barrier
	v_mfma_f32_16x16x32_bf16 v[52:55], v[204:207], v[168:171], v[52:55]
	v_mfma_f32_16x16x32_bf16 v[48:51], v[216:219], v[168:171], v[48:51]
	v_mfma_f32_16x16x32_bf16 v[36:39], v[204:207], v[180:183], v[36:39]
	v_mfma_f32_16x16x32_bf16 v[32:35], v[216:219], v[180:183], v[32:35]
	v_mfma_f32_16x16x32_bf16 v[20:23], v[204:207], v[188:191], v[20:23]
	v_mfma_f32_16x16x32_bf16 v[16:19], v[216:219], v[188:191], v[16:19]
	v_mfma_f32_16x16x32_bf16 v[4:7], v[204:207], v[196:199], v[4:7]
	v_mfma_f32_16x16x32_bf16 v[0:3], v[216:219], v[196:199], v[0:3]
	v_mfma_f32_16x16x32_bf16 v[52:55], v[212:215], v[176:179], v[52:55]
	v_mfma_f32_16x16x32_bf16 v[48:51], v[220:223], v[176:179], v[48:51]
	v_mfma_f32_16x16x32_bf16 v[36:39], v[212:215], v[184:187], v[36:39]
	v_mfma_f32_16x16x32_bf16 v[32:35], v[220:223], v[184:187], v[32:35]
	v_mfma_f32_16x16x32_bf16 v[20:23], v[212:215], v[192:195], v[20:23]
	v_mfma_f32_16x16x32_bf16 v[16:19], v[220:223], v[192:195], v[16:19]
	v_mfma_f32_16x16x32_bf16 v[4:7], v[212:215], v[200:203], v[4:7]
	v_mfma_f32_16x16x32_bf16 v[0:3], v[220:223], v[200:203], v[0:3]
	s_barrier
	s_setprio 0
	s_add_i32 s56, s56, 2
	s_add_u32 s2, s2, 0x100
	s_addc_u32 s3, s3, 0
	s_add_u32 s54, s54, 0x100
	s_addc_u32 s55, s55, 0
	s_cmp_gt_u32 s56, 13
	s_cbranch_scc0 .LBB0_712
	v_lshl_add_u32 v146, s0, 8, v148
	v_ashrrev_i32_e32 v147, 31, v146
	v_lshl_add_u64 v[144:145], v[146:147], 2, s[66:67]
	global_load_dword v155, v[144:145], off
	global_load_dword v164, v[144:145], off offset:64
	global_load_dword v165, v[144:145], off offset:128
	global_load_dword v166, v[144:145], off offset:192
	global_load_dword v167, v[144:145], off offset:512
	global_load_dword v168, v[144:145], off offset:576
	global_load_dword v169, v[144:145], off offset:640
	global_load_dword v170, v[144:145], off offset:704
	v_lshl_or_b32 v144, s1, 8, v150
	v_ashrrev_i32_e32 v145, 31, v144
	v_lshlrev_b64 v[160:161], 10, v[146:147]
	v_lshlrev_b64 v[162:163], 1, v[144:145]
	v_lshl_add_u64 v[144:145], s[92:93], 0, v[160:161]
	v_or_b32_e32 v156, 16, v146
	v_ashrrev_i32_e32 v157, 31, v156
	v_or_b32_e32 v158, 32, v146
	v_lshlrev_b64 v[156:157], 10, v[156:157]
	v_lshl_add_u64 v[144:145], v[144:145], 0, v[162:163]
	v_ashrrev_i32_e32 v159, 31, v158
	v_lshl_add_u64 v[156:157], s[92:93], 0, v[156:157]
	v_lshlrev_b64 v[158:159], 10, v[158:159]
	v_lshl_add_u64 v[156:157], v[156:157], 0, v[162:163]
	v_lshl_add_u64 v[158:159], s[92:93], 0, v[158:159]
	v_lshl_add_u64 v[158:159], v[158:159], 0, v[162:163]
	s_mov_b64 s[26:27], s[24:25]
	s_waitcnt vmcnt(0)
	v_fmamk_f32 v147, v155, 0x3a800000, v154
	v_fmamk_f32 v155, v164, 0x3a800000, v154
	v_fmamk_f32 v160, v165, 0x3a800000, v154
	v_mul_f32_e32 v161, 0x4b800000, v147
	v_mul_f32_e32 v164, 0x4b800000, v155
	v_cmp_gt_f32_e32 vcc, s49, v147
	v_cmp_gt_f32_e64 s[0:1], s49, v155
	v_mul_f32_e32 v165, 0x4b800000, v160
	v_cndmask_b32_e32 v147, v147, v161, vcc
	v_cndmask_b32_e64 v155, v155, v164, s[0:1]
	v_cmp_gt_f32_e64 s[2:3], s49, v160
	v_rsq_f32_e32 v147, v147
	v_rsq_f32_e32 v155, v155
	v_cndmask_b32_e64 v160, v160, v165, s[2:3]
	v_rsq_f32_e32 v160, v160
	v_mul_f32_e32 v161, 0x45800000, v147
	v_mul_f32_e32 v164, 0x45800000, v155
	v_cndmask_b32_e32 v147, v147, v161, vcc
	v_mul_f32_e32 v165, 0x45800000, v160
	v_cndmask_b32_e64 v155, v155, v164, s[0:1]
	v_cndmask_b32_e64 v161, v160, v165, s[2:3]
	v_mul_f32_e32 v160, 0x3e0293ee, v147
	v_mul_f32_e32 v164, 0x3e0293ee, v155
	v_fmamk_f32 v171, v166, 0x3a800000, v154
	v_mul_f32_e32 v166, 0x3e0293ee, v161
	v_pk_mul_f32 v[126:127], v[126:127], v[160:161] op_sel_hi:[1,0]
	v_pk_mul_f32 v[124:125], v[124:125], v[160:161] op_sel_hi:[1,0]
	v_pk_mul_f32 v[122:123], v[122:123], v[160:161] op_sel_hi:[1,0]
	v_pk_mul_f32 v[120:121], v[120:121], v[160:161] op_sel_hi:[1,0]
	v_pk_mul_f32 v[110:111], v[110:111], v[160:161] op_sel_hi:[1,0]
	v_pk_mul_f32 v[108:109], v[108:109], v[160:161] op_sel_hi:[1,0]
	v_pk_mul_f32 v[102:103], v[102:103], v[160:161] op_sel_hi:[1,0]
	v_pk_mul_f32 v[100:101], v[100:101], v[160:161] op_sel_hi:[1,0]
	v_pk_mul_f32 v[118:119], v[118:119], v[164:165] op_sel_hi:[1,0]
	v_pk_mul_f32 v[116:117], v[116:117], v[164:165] op_sel_hi:[1,0]
	v_pk_mul_f32 v[114:115], v[114:115], v[164:165] op_sel_hi:[1,0]
	v_pk_mul_f32 v[112:113], v[112:113], v[164:165] op_sel_hi:[1,0]
	v_pk_mul_f32 v[94:95], v[94:95], v[164:165] op_sel_hi:[1,0]
	v_pk_mul_f32 v[92:93], v[92:93], v[164:165] op_sel_hi:[1,0]
	v_pk_mul_f32 v[160:161], v[90:91], v[164:165] op_sel_hi:[1,0]
	v_pk_mul_f32 v[164:165], v[88:89], v[164:165] op_sel_hi:[1,0]
	v_cvt_pk_bf16_f32 v88, v124, v125
	v_cvt_pk_bf16_f32 v89, v126, v127
	v_cvt_pk_bf16_f32 v90, v120, v121
	v_cvt_pk_bf16_f32 v91, v122, v123
	global_store_dwordx4 v[144:145], v[88:91], off
	v_fmamk_f32 v167, v167, 0x3a800000, v154
	v_pk_mul_f32 v[106:107], v[106:107], v[166:167] op_sel_hi:[1,0]
	v_cvt_pk_bf16_f32 v88, v108, v109
	v_cvt_pk_bf16_f32 v89, v110, v111
	v_cvt_pk_bf16_f32 v90, v100, v101
	v_cvt_pk_bf16_f32 v91, v102, v103
	global_store_dwordx4 v[144:145], v[88:91], off offset:256
	v_pk_mul_f32 v[104:105], v[104:105], v[166:167] op_sel_hi:[1,0]
	v_pk_mul_f32 v[98:99], v[98:99], v[166:167] op_sel_hi:[1,0]
	v_cvt_pk_bf16_f32 v88, v116, v117
	v_cvt_pk_bf16_f32 v89, v118, v119
	v_cvt_pk_bf16_f32 v90, v112, v113
	v_cvt_pk_bf16_f32 v91, v114, v115
	global_store_dwordx4 v[156:157], v[88:91], off
	v_pk_mul_f32 v[96:97], v[96:97], v[166:167] op_sel_hi:[1,0]
	v_pk_mul_f32 v[86:87], v[86:87], v[166:167] op_sel_hi:[1,0]
	v_cvt_pk_bf16_f32 v88, v92, v93
	v_cvt_pk_bf16_f32 v89, v94, v95
	v_cvt_pk_bf16_f32 v90, v164, v165
	v_cvt_pk_bf16_f32 v91, v160, v161
	global_store_dwordx4 v[156:157], v[88:91], off offset:256
	v_pk_mul_f32 v[84:85], v[84:85], v[166:167] op_sel_hi:[1,0]
	v_cmp_gt_f32_e32 vcc, s49, v171
	v_cvt_pk_bf16_f32 v88, v104, v105
	v_cvt_pk_bf16_f32 v89, v106, v107
	v_cvt_pk_bf16_f32 v90, v96, v97
	v_cvt_pk_bf16_f32 v91, v98, v99
	global_store_dwordx4 v[158:159], v[88:91], off
	s_mov_b64 s[0:1], 0x20000
	v_fmamk_f32 v168, v168, 0x3a800000, v154
	v_pk_mul_f32 v[88:89], v[82:83], v[166:167] op_sel_hi:[1,0]
	v_pk_mul_f32 v[82:83], v[80:81], v[166:167] op_sel_hi:[1,0]
	v_cvt_pk_bf16_f32 v80, v84, v85
	v_cvt_pk_bf16_f32 v81, v86, v87
	v_fmamk_f32 v169, v169, 0x3a800000, v154
	v_cvt_pk_bf16_f32 v82, v82, v83
	v_cvt_pk_bf16_f32 v83, v88, v89
	global_store_dwordx4 v[158:159], v[80:83], off offset:256
	v_fmamk_f32 v170, v170, 0x3a800000, v154
	s_mov_b64 s[2:3], s[22:23]
	v_mul_f32_e32 v82, 0x4b800000, v171
	v_cndmask_b32_e32 v82, v171, v82, vcc
	v_rsq_f32_e32 v82, v82
	v_or_b32_e32 v80, 48, v146
	v_ashrrev_i32_e32 v81, 31, v80
	v_lshlrev_b64 v[80:81], 10, v[80:81]
	v_mul_f32_e32 v83, 0x45800000, v82
	v_cndmask_b32_e32 v82, v82, v83, vcc
	v_lshl_add_u64 v[80:81], s[92:93], 0, v[80:81]
	v_mul_f32_e32 v82, 0x3e0293ee, v82
	v_lshl_add_u64 v[80:81], v[80:81], 0, v[162:163]
	v_pk_mul_f32 v[78:79], v[78:79], v[82:83] op_sel_hi:[1,0]
	v_pk_mul_f32 v[76:77], v[76:77], v[82:83] op_sel_hi:[1,0]
	v_pk_mul_f32 v[84:85], v[74:75], v[82:83] op_sel_hi:[1,0]
	v_pk_mul_f32 v[74:75], v[72:73], v[82:83] op_sel_hi:[1,0]
	v_cvt_pk_bf16_f32 v72, v76, v77
	v_cvt_pk_bf16_f32 v73, v78, v79
	v_pk_mul_f32 v[70:71], v[70:71], v[82:83] op_sel_hi:[1,0]
	v_cvt_pk_bf16_f32 v74, v74, v75
	v_cvt_pk_bf16_f32 v75, v84, v85
	global_store_dwordx4 v[80:81], v[72:75], off
	v_pk_mul_f32 v[68:69], v[68:69], v[82:83] op_sel_hi:[1,0]
	v_cmp_gt_f32_e32 vcc, s49, v167
	v_pk_mul_f32 v[72:73], v[66:67], v[82:83] op_sel_hi:[1,0]
	v_pk_mul_f32 v[66:67], v[64:65], v[82:83] op_sel_hi:[1,0]
	v_cvt_pk_bf16_f32 v64, v68, v69
	v_cvt_pk_bf16_f32 v65, v70, v71
	s_nop 0
	v_cvt_pk_bf16_f32 v66, v66, v67
	v_mul_f32_e32 v67, 0x4b800000, v167
	v_cndmask_b32_e32 v67, v167, v67, vcc
	v_rsq_f32_e32 v68, v67
	v_cvt_pk_bf16_f32 v67, v72, v73
	global_store_dwordx4 v[80:81], v[64:67], off offset:256
	s_nop 1
	v_mul_f32_e32 v66, 0x45800000, v68
	v_cndmask_b32_e32 v66, v68, v66, vcc
	v_mul_f32_e32 v66, 0x3e0293ee, v66
	v_lshl_add_u64 v[64:65], v[144:145], 0, s[0:1]
	v_pk_mul_f32 v[60:61], v[60:61], v[66:67] op_sel_hi:[1,0]
	s_mov_b32 s0, 0x20000
	v_pk_mul_f32 v[68:69], v[58:59], v[66:67] op_sel_hi:[1,0]
	v_pk_mul_f32 v[58:59], v[56:57], v[66:67] op_sel_hi:[1,0]
	v_cvt_pk_bf16_f32 v56, v60, v61
	v_add_co_u32_e32 v60, vcc, s0, v144
	v_pk_mul_f32 v[62:63], v[62:63], v[66:67] op_sel_hi:[1,0]
	s_nop 0
	v_addc_co_u32_e32 v61, vcc, 0, v145, vcc
	v_cvt_pk_bf16_f32 v57, v62, v63
	v_cvt_pk_bf16_f32 v58, v58, v59
	v_cvt_pk_bf16_f32 v59, v68, v69
	global_store_dwordx4 v[60:61], v[56:59], off
	v_pk_mul_f32 v[54:55], v[54:55], v[66:67] op_sel_hi:[1,0]
	v_pk_mul_f32 v[52:53], v[52:53], v[66:67] op_sel_hi:[1,0]
	v_pk_mul_f32 v[56:57], v[50:51], v[66:67] op_sel_hi:[1,0]
	v_pk_mul_f32 v[50:51], v[48:49], v[66:67] op_sel_hi:[1,0]
	v_cvt_pk_bf16_f32 v48, v52, v53
	v_cvt_pk_bf16_f32 v49, v54, v55
	v_cmp_gt_f32_e32 vcc, s49, v168
	v_cvt_pk_bf16_f32 v50, v50, v51
	v_mul_f32_e32 v51, 0x4b800000, v168
	s_mov_b64 s[0:1], 0x24000
	v_cndmask_b32_e32 v51, v168, v51, vcc
	v_rsq_f32_e32 v52, v51
	v_cvt_pk_bf16_f32 v51, v56, v57
	global_store_dwordx4 v[64:65], v[48:51], off offset:256
	s_nop 1
	v_mul_f32_e32 v50, 0x45800000, v52
	v_cndmask_b32_e32 v50, v52, v50, vcc
	v_mul_f32_e32 v50, 0x3e0293ee, v50
	v_lshl_add_u64 v[48:49], v[144:145], 0, s[0:1]
	v_pk_mul_f32 v[44:45], v[44:45], v[50:51] op_sel_hi:[1,0]
	s_mov_b32 s0, 0x24000
	v_pk_mul_f32 v[52:53], v[42:43], v[50:51] op_sel_hi:[1,0]
	v_pk_mul_f32 v[42:43], v[40:41], v[50:51] op_sel_hi:[1,0]
	v_cvt_pk_bf16_f32 v40, v44, v45
	v_add_co_u32_e32 v44, vcc, s0, v144
	v_pk_mul_f32 v[46:47], v[46:47], v[50:51] op_sel_hi:[1,0]
	s_nop 0
	v_addc_co_u32_e32 v45, vcc, 0, v145, vcc
	v_cvt_pk_bf16_f32 v41, v46, v47
	v_cvt_pk_bf16_f32 v42, v42, v43
	v_cvt_pk_bf16_f32 v43, v52, v53
	global_store_dwordx4 v[44:45], v[40:43], off
	v_pk_mul_f32 v[38:39], v[38:39], v[50:51] op_sel_hi:[1,0]
	v_pk_mul_f32 v[36:37], v[36:37], v[50:51] op_sel_hi:[1,0]
	v_pk_mul_f32 v[40:41], v[34:35], v[50:51] op_sel_hi:[1,0]
	v_pk_mul_f32 v[34:35], v[32:33], v[50:51] op_sel_hi:[1,0]
	v_cvt_pk_bf16_f32 v32, v36, v37
	v_cvt_pk_bf16_f32 v33, v38, v39
	v_cmp_gt_f32_e32 vcc, s49, v169
	v_cvt_pk_bf16_f32 v34, v34, v35
	v_mul_f32_e32 v35, 0x4b800000, v169
	s_mov_b32 s1, s18
	v_cndmask_b32_e32 v35, v169, v35, vcc
	v_rsq_f32_e32 v36, v35
	v_cvt_pk_bf16_f32 v35, v40, v41
	global_store_dwordx4 v[48:49], v[32:35], off offset:256
	s_mov_b32 s0, s20
	s_nop 0
	v_mul_f32_e32 v34, 0x45800000, v36
	v_cndmask_b32_e32 v34, v36, v34, vcc
	v_mul_f32_e32 v34, 0x3e0293ee, v34
	v_pk_mul_f32 v[28:29], v[28:29], v[34:35] op_sel_hi:[1,0]
	v_pk_mul_f32 v[36:37], v[26:27], v[34:35] op_sel_hi:[1,0]
	v_pk_mul_f32 v[26:27], v[24:25], v[34:35] op_sel_hi:[1,0]
	v_cvt_pk_bf16_f32 v24, v28, v29
	v_add_co_u32_e32 v28, vcc, s50, v144
	v_pk_mul_f32 v[30:31], v[30:31], v[34:35] op_sel_hi:[1,0]
	s_nop 0
	v_addc_co_u32_e32 v29, vcc, 0, v145, vcc
	v_cvt_pk_bf16_f32 v25, v30, v31
	v_cvt_pk_bf16_f32 v26, v26, v27
	v_cvt_pk_bf16_f32 v27, v36, v37
	global_store_dwordx4 v[28:29], v[24:27], off
	v_pk_mul_f32 v[22:23], v[22:23], v[34:35] op_sel_hi:[1,0]
	v_pk_mul_f32 v[20:21], v[20:21], v[34:35] op_sel_hi:[1,0]
	v_pk_mul_f32 v[24:25], v[18:19], v[34:35] op_sel_hi:[1,0]
	v_pk_mul_f32 v[18:19], v[16:17], v[34:35] op_sel_hi:[1,0]
	v_cvt_pk_bf16_f32 v16, v20, v21
	v_cvt_pk_bf16_f32 v17, v22, v23
	v_cmp_gt_f32_e32 vcc, s49, v170
	v_cvt_pk_bf16_f32 v18, v18, v19
	v_mul_f32_e32 v19, 0x4b800000, v170
	v_lshl_add_u64 v[32:33], v[144:145], 0, s[12:13]
	v_cndmask_b32_e32 v19, v170, v19, vcc
	v_rsq_f32_e32 v20, v19
	v_cvt_pk_bf16_f32 v19, v24, v25
	global_store_dwordx4 v[32:33], v[16:19], off offset:256
	s_nop 1
	v_mul_f32_e32 v18, 0x45800000, v20
	v_cndmask_b32_e32 v18, v20, v18, vcc
	v_mul_f32_e32 v18, 0x3e0293ee, v18
	v_pk_mul_f32 v[12:13], v[12:13], v[18:19] op_sel_hi:[1,0]
	v_pk_mul_f32 v[20:21], v[10:11], v[18:19] op_sel_hi:[1,0]
	v_pk_mul_f32 v[10:11], v[8:9], v[18:19] op_sel_hi:[1,0]
	v_cvt_pk_bf16_f32 v8, v12, v13
	v_add_co_u32_e32 v12, vcc, s51, v144
	v_pk_mul_f32 v[14:15], v[14:15], v[18:19] op_sel_hi:[1,0]
	s_nop 0
	v_addc_co_u32_e32 v13, vcc, 0, v145, vcc
	v_cvt_pk_bf16_f32 v9, v14, v15
	v_lshl_add_u64 v[16:17], v[144:145], 0, s[16:17]
	v_cvt_pk_bf16_f32 v10, v10, v11
	v_cvt_pk_bf16_f32 v11, v20, v21
	global_store_dwordx4 v[12:13], v[8:11], off
	s_and_b64 vcc, exec, s[6:7]
	v_pk_mul_f32 v[6:7], v[6:7], v[18:19] op_sel_hi:[1,0]
	v_pk_mul_f32 v[8:9], v[2:3], v[18:19] op_sel_hi:[1,0]
	v_pk_mul_f32 v[2:3], v[0:1], v[18:19] op_sel_hi:[1,0]
	v_pk_mul_f32 v[4:5], v[4:5], v[18:19] op_sel_hi:[1,0]
	s_nop 0
	v_cvt_pk_bf16_f32 v0, v4, v5
	v_cvt_pk_bf16_f32 v1, v6, v7
	v_cvt_pk_bf16_f32 v2, v2, v3
	v_cvt_pk_bf16_f32 v3, v8, v9
	global_store_dwordx4 v[16:17], v[0:3], off offset:256
	s_cbranch_vccz .LBB0_705
	s_waitcnt vmcnt(0)
	s_cmpk_gt_u32 s30, 0xff
	s_cbranch_scc1 .LBB0_716
	s_barrier

.LBB0_792:
	ds_read_b128 v[144:147], v178
	ds_read_b128 v[148:151], v178 offset:1024
	ds_read_b128 v[152:155], v178 offset:2048
	ds_read_b128 v[156:159], v178 offset:3072
	s_add_u32 s40, s38, 0xfffe0080
	s_addc_u32 s41, s39, -1
	s_cmp_eq_u32 s63, 4
	s_cselect_b32 s43, s27, s41
	s_cselect_b32 s42, s35, s40
	s_cselect_b32 s41, s25, s62
	s_cselect_b32 s40, s60, s61
	v_lshl_add_u64 v[172:173], s[38:39], 0, v[136:137]
	s_add_i32 m0, s37, 0xc000
	ds_read_b128 v[160:163], v179
	ds_read_b128 v[164:167], v179 offset:1024
	ds_read_b128 v[168:171], v179 offset:2048
	ds_read_b128 v[182:185], v179 offset:3072
	ds_read_b128 v[186:189], v179 offset:4096
	ds_read_b128 v[190:193], v179 offset:5120
	ds_read_b128 v[194:197], v179 offset:6144
	ds_read_b128 v[198:201], v179 offset:7168
	global_load_lds_dwordx4 v[172:173], off
	v_lshl_add_u64 v[172:173], s[38:39], 0, v[138:139]
	s_add_i32 m0, s37, 0xe000
	s_nop 0
	global_load_lds_dwordx4 v[172:173], off
	s_waitcnt lgkmcnt(8)
	s_setprio 1
	s_barrier
	s_waitcnt lgkmcnt(0)
	v_mfma_f32_16x16x32_bf16 v[124:127], v[144:147], v[160:163], v[124:127]
	v_mfma_f32_16x16x32_bf16 v[120:123], v[152:155], v[160:163], v[120:123]
	v_mfma_f32_16x16x32_bf16 v[108:111], v[144:147], v[168:171], v[108:111]
	v_mfma_f32_16x16x32_bf16 v[104:107], v[152:155], v[168:171], v[104:107]
	v_mfma_f32_16x16x32_bf16 v[96:99], v[144:147], v[186:189], v[96:99]
	v_mfma_f32_16x16x32_bf16 v[88:91], v[152:155], v[186:189], v[88:91]
	v_mfma_f32_16x16x32_bf16 v[80:83], v[144:147], v[194:197], v[80:83]
	v_mfma_f32_16x16x32_bf16 v[72:75], v[152:155], v[194:197], v[72:75]
	v_mfma_f32_16x16x32_bf16 v[124:127], v[148:151], v[164:167], v[124:127]
	v_mfma_f32_16x16x32_bf16 v[120:123], v[156:159], v[164:167], v[120:123]
	v_mfma_f32_16x16x32_bf16 v[108:111], v[148:151], v[182:185], v[108:111]
	v_mfma_f32_16x16x32_bf16 v[104:107], v[156:159], v[182:185], v[104:107]
	v_mfma_f32_16x16x32_bf16 v[96:99], v[148:151], v[190:193], v[96:99]
	v_mfma_f32_16x16x32_bf16 v[88:91], v[156:159], v[190:193], v[88:91]
	v_mfma_f32_16x16x32_bf16 v[80:83], v[148:151], v[198:201], v[80:83]
	v_mfma_f32_16x16x32_bf16 v[72:75], v[156:159], v[198:201], v[72:75]
	s_barrier
	s_setprio 0
	s_add_i32 s64, s58, s48
	v_lshl_add_u64 v[172:173], s[40:41], 0, v[130:131]
	s_mov_b32 m0, s64
	ds_read_b128 v[202:205], v180
	ds_read_b128 v[206:209], v180 offset:1024
	ds_read_b128 v[212:215], v180 offset:2048
	ds_read_b128 v[216:219], v180 offset:3072
	global_load_lds_dwordx4 v[172:173], off
	v_lshl_add_u64 v[220:221], s[40:41], 0, v[134:135]
	s_add_i32 m0, s64, 0x2000
	s_nop 0
	global_load_lds_dwordx4 v[220:221], off
	s_setprio 1
	s_barrier
	s_waitcnt lgkmcnt(0)
	v_mfma_f32_16x16x32_bf16 v[116:119], v[202:205], v[160:163], v[116:119]
	v_mfma_f32_16x16x32_bf16 v[112:115], v[212:215], v[160:163], v[112:115]
	v_mfma_f32_16x16x32_bf16 v[100:103], v[202:205], v[168:171], v[100:103]
	v_mfma_f32_16x16x32_bf16 v[92:95], v[212:215], v[168:171], v[92:95]
	v_mfma_f32_16x16x32_bf16 v[84:87], v[202:205], v[186:189], v[84:87]
	v_mfma_f32_16x16x32_bf16 v[76:79], v[212:215], v[186:189], v[76:79]
	v_mfma_f32_16x16x32_bf16 v[68:71], v[202:205], v[194:197], v[68:71]
	v_mfma_f32_16x16x32_bf16 v[64:67], v[212:215], v[194:197], v[64:67]
	v_mfma_f32_16x16x32_bf16 v[116:119], v[206:209], v[164:167], v[116:119]
	v_mfma_f32_16x16x32_bf16 v[112:115], v[216:219], v[164:167], v[112:115]
	v_mfma_f32_16x16x32_bf16 v[100:103], v[206:209], v[182:185], v[100:103]
	v_mfma_f32_16x16x32_bf16 v[92:95], v[216:219], v[182:185], v[92:95]
	v_mfma_f32_16x16x32_bf16 v[84:87], v[206:209], v[190:193], v[84:87]
	v_mfma_f32_16x16x32_bf16 v[76:79], v[216:219], v[190:193], v[76:79]
	v_mfma_f32_16x16x32_bf16 v[68:71], v[206:209], v[198:201], v[68:71]
	v_mfma_f32_16x16x32_bf16 v[64:67], v[216:219], v[198:201], v[64:67]
	s_barrier
	s_setprio 0
	s_mov_b32 m0, s37
	v_lshl_add_u64 v[222:223], s[42:43], 0, v[128:129]
	ds_read_b128 v[160:163], v179 offset:16384
	ds_read_b128 v[164:167], v179 offset:17408
	ds_read_b128 v[168:171], v179 offset:18432
	ds_read_b128 v[182:185], v179 offset:19456
	ds_read_b128 v[186:189], v179 offset:20480
	ds_read_b128 v[190:193], v179 offset:21504
	ds_read_b128 v[194:197], v179 offset:22528
	ds_read_b128 v[198:201], v179 offset:23552
	global_load_lds_dwordx4 v[222:223], off
	v_lshl_add_u64 v[224:225], s[42:43], 0, v[132:133]
	s_mov_b32 m0, s49
	s_nop 0
	global_load_lds_dwordx4 v[224:225], off
	s_setprio 1
	s_barrier
	s_waitcnt lgkmcnt(0)
	v_mfma_f32_16x16x32_bf16 v[60:63], v[144:147], v[160:163], v[60:63]
	v_mfma_f32_16x16x32_bf16 v[56:59], v[152:155], v[160:163], v[56:59]
	v_mfma_f32_16x16x32_bf16 v[44:47], v[144:147], v[168:171], v[44:47]
	v_mfma_f32_16x16x32_bf16 v[40:43], v[152:155], v[168:171], v[40:43]
	v_mfma_f32_16x16x32_bf16 v[32:35], v[144:147], v[186:189], v[32:35]
	v_mfma_f32_16x16x32_bf16 v[24:27], v[152:155], v[186:189], v[24:27]
	v_mfma_f32_16x16x32_bf16 v[16:19], v[144:147], v[194:197], v[16:19]
	v_mfma_f32_16x16x32_bf16 v[8:11], v[152:155], v[194:197], v[8:11]
	v_mfma_f32_16x16x32_bf16 v[60:63], v[148:151], v[164:167], v[60:63]
	v_mfma_f32_16x16x32_bf16 v[56:59], v[156:159], v[164:167], v[56:59]
	v_mfma_f32_16x16x32_bf16 v[44:47], v[148:151], v[182:185], v[44:47]
	v_mfma_f32_16x16x32_bf16 v[40:43], v[156:159], v[182:185], v[40:43]
	v_mfma_f32_16x16x32_bf16 v[32:35], v[148:151], v[190:193], v[32:35]
	v_mfma_f32_16x16x32_bf16 v[24:27], v[156:159], v[190:193], v[24:27]
	v_mfma_f32_16x16x32_bf16 v[16:19], v[148:151], v[198:201], v[16:19]
	v_mfma_f32_16x16x32_bf16 v[8:11], v[156:159], v[198:201], v[8:11]
	s_barrier
	s_setprio 0
	s_add_u32 s64, s40, 0x20000
	s_addc_u32 s65, s41, 0
	s_add_i32 s66, s59, s48
	v_lshl_add_u64 v[144:145], s[64:65], 0, v[130:131]
	s_mov_b32 m0, s66
	s_nop 0
	global_load_lds_dwordx4 v[144:145], off
	v_lshl_add_u64 v[144:145], s[64:65], 0, v[134:135]
	s_add_i32 m0, s66, 0x2000
	s_nop 0
	global_load_lds_dwordx4 v[144:145], off
	s_waitcnt vmcnt(6)
	s_setprio 1
	s_barrier
	v_mfma_f32_16x16x32_bf16 v[52:55], v[202:205], v[160:163], v[52:55]
	v_mfma_f32_16x16x32_bf16 v[48:51], v[212:215], v[160:163], v[48:51]
	v_mfma_f32_16x16x32_bf16 v[36:39], v[202:205], v[168:171], v[36:39]
	v_mfma_f32_16x16x32_bf16 v[28:31], v[212:215], v[168:171], v[28:31]
	v_mfma_f32_16x16x32_bf16 v[20:23], v[202:205], v[186:189], v[20:23]
	v_mfma_f32_16x16x32_bf16 v[12:15], v[212:215], v[186:189], v[12:15]
	v_mfma_f32_16x16x32_bf16 v[4:7], v[202:205], v[194:197], v[4:7]
	v_mfma_f32_16x16x32_bf16 v[0:3], v[212:215], v[194:197], v[0:3]
	v_mfma_f32_16x16x32_bf16 v[52:55], v[206:209], v[164:167], v[52:55]
	v_mfma_f32_16x16x32_bf16 v[48:51], v[216:219], v[164:167], v[48:51]
	v_mfma_f32_16x16x32_bf16 v[36:39], v[206:209], v[182:185], v[36:39]
	v_mfma_f32_16x16x32_bf16 v[28:31], v[216:219], v[182:185], v[28:31]
	v_mfma_f32_16x16x32_bf16 v[20:23], v[206:209], v[190:193], v[20:23]
	v_mfma_f32_16x16x32_bf16 v[12:15], v[216:219], v[190:193], v[12:15]
	v_mfma_f32_16x16x32_bf16 v[4:7], v[206:209], v[198:201], v[4:7]
	v_mfma_f32_16x16x32_bf16 v[0:3], v[216:219], v[198:201], v[0:3]
	s_barrier
	s_setprio 0
	s_add_i32 s64, 0, 0x18000
	v_add_u32_e32 v156, s64, v176
	ds_read_b128 v[144:147], v156
	ds_read_b128 v[148:151], v156 offset:1024
	ds_read_b128 v[152:155], v156 offset:2048
	ds_read_b128 v[156:159], v156 offset:3072
	s_add_u32 s42, s42, 0x20000
	s_addc_u32 s43, s43, 0
	s_mov_b32 m0, s50
	v_lshl_add_u64 v[202:203], s[42:43], 0, v[128:129]
	ds_read_b128 v[160:163], v179 offset:32768
	ds_read_b128 v[164:167], v179 offset:33792
	ds_read_b128 v[168:171], v179 offset:34816
	ds_read_b128 v[182:185], v179 offset:35840
	ds_read_b128 v[186:189], v179 offset:36864
	ds_read_b128 v[190:193], v179 offset:37888
	ds_read_b128 v[194:197], v179 offset:38912
	ds_read_b128 v[198:201], v179 offset:39936
	global_load_lds_dwordx4 v[202:203], off
	v_lshl_add_u64 v[202:203], s[42:43], 0, v[132:133]
	s_mov_b32 m0, s51
	s_nop 0
	global_load_lds_dwordx4 v[202:203], off
	s_waitcnt lgkmcnt(8)
	s_setprio 1
	s_barrier
	s_waitcnt lgkmcnt(0)
	v_mfma_f32_16x16x32_bf16 v[124:127], v[144:147], v[160:163], v[124:127]
	v_mfma_f32_16x16x32_bf16 v[120:123], v[152:155], v[160:163], v[120:123]
	v_mfma_f32_16x16x32_bf16 v[108:111], v[144:147], v[168:171], v[108:111]
	v_mfma_f32_16x16x32_bf16 v[104:107], v[152:155], v[168:171], v[104:107]
	v_mfma_f32_16x16x32_bf16 v[96:99], v[144:147], v[186:189], v[96:99]
	v_mfma_f32_16x16x32_bf16 v[88:91], v[152:155], v[186:189], v[88:91]
	v_mfma_f32_16x16x32_bf16 v[80:83], v[144:147], v[194:197], v[80:83]
	v_mfma_f32_16x16x32_bf16 v[72:75], v[152:155], v[194:197], v[72:75]
	v_mfma_f32_16x16x32_bf16 v[124:127], v[148:151], v[164:167], v[124:127]
	v_mfma_f32_16x16x32_bf16 v[120:123], v[156:159], v[164:167], v[120:123]
	v_mfma_f32_16x16x32_bf16 v[108:111], v[148:151], v[182:185], v[108:111]
	v_mfma_f32_16x16x32_bf16 v[104:107], v[156:159], v[182:185], v[104:107]
	v_mfma_f32_16x16x32_bf16 v[96:99], v[148:151], v[190:193], v[96:99]
	v_mfma_f32_16x16x32_bf16 v[88:91], v[156:159], v[190:193], v[88:91]
	v_mfma_f32_16x16x32_bf16 v[80:83], v[148:151], v[198:201], v[80:83]
	v_mfma_f32_16x16x32_bf16 v[72:75], v[156:159], v[198:201], v[72:75]
	s_barrier
	s_setprio 0
	s_add_i32 s42, 0, 0x1c000
	s_add_i32 s43, s64, s48
	v_add_u32_e32 v181, s42, v176
	v_lshl_add_u64 v[172:173], v[172:173], 0, s[0:1]
	s_mov_b32 m0, s43
	ds_read_b128 v[202:205], v181
	ds_read_b128 v[206:209], v181 offset:1024
	ds_read_b128 v[212:215], v181 offset:2048
	ds_read_b128 v[216:219], v181 offset:3072
	global_load_lds_dwordx4 v[172:173], off
	v_lshl_add_u64 v[172:173], v[220:221], 0, s[0:1]
	s_add_i32 m0, s43, 0x2000
	s_nop 0
	global_load_lds_dwordx4 v[172:173], off
	s_setprio 1
	s_barrier
	s_waitcnt lgkmcnt(0)
	v_mfma_f32_16x16x32_bf16 v[116:119], v[202:205], v[160:163], v[116:119]
	v_mfma_f32_16x16x32_bf16 v[112:115], v[212:215], v[160:163], v[112:115]
	v_mfma_f32_16x16x32_bf16 v[100:103], v[202:205], v[168:171], v[100:103]
	v_mfma_f32_16x16x32_bf16 v[92:95], v[212:215], v[168:171], v[92:95]
	v_mfma_f32_16x16x32_bf16 v[84:87], v[202:205], v[186:189], v[84:87]
	v_mfma_f32_16x16x32_bf16 v[76:79], v[212:215], v[186:189], v[76:79]
	v_mfma_f32_16x16x32_bf16 v[68:71], v[202:205], v[194:197], v[68:71]
	v_mfma_f32_16x16x32_bf16 v[64:67], v[212:215], v[194:197], v[64:67]
	v_mfma_f32_16x16x32_bf16 v[116:119], v[206:209], v[164:167], v[116:119]
	v_mfma_f32_16x16x32_bf16 v[112:115], v[216:219], v[164:167], v[112:115]
	v_mfma_f32_16x16x32_bf16 v[100:103], v[206:209], v[182:185], v[100:103]
	v_mfma_f32_16x16x32_bf16 v[92:95], v[216:219], v[182:185], v[92:95]
	v_mfma_f32_16x16x32_bf16 v[84:87], v[206:209], v[190:193], v[84:87]
	v_mfma_f32_16x16x32_bf16 v[76:79], v[216:219], v[190:193], v[76:79]
	v_mfma_f32_16x16x32_bf16 v[68:71], v[206:209], v[198:201], v[68:71]
	v_mfma_f32_16x16x32_bf16 v[64:67], v[216:219], v[198:201], v[64:67]
	s_barrier
	s_setprio 0
	s_mov_b32 m0, s53
	v_lshl_add_u64 v[172:173], v[222:223], 0, s[0:1]
	ds_read_b128 v[160:163], v179 offset:49152
	ds_read_b128 v[164:167], v179 offset:50176
	ds_read_b128 v[168:171], v179 offset:51200
	ds_read_b128 v[182:185], v179 offset:52224
	ds_read_b128 v[186:189], v179 offset:53248
	ds_read_b128 v[190:193], v179 offset:54272
	ds_read_b128 v[194:197], v179 offset:55296
	ds_read_b128 v[198:201], v179 offset:56320
	global_load_lds_dwordx4 v[172:173], off
	v_lshl_add_u64 v[172:173], v[224:225], 0, s[0:1]
	s_mov_b32 m0, s54
	s_nop 0
	global_load_lds_dwordx4 v[172:173], off
	s_setprio 1
	s_barrier
	s_waitcnt lgkmcnt(0)
	v_mfma_f32_16x16x32_bf16 v[60:63], v[144:147], v[160:163], v[60:63]
	v_mfma_f32_16x16x32_bf16 v[56:59], v[152:155], v[160:163], v[56:59]
	v_mfma_f32_16x16x32_bf16 v[44:47], v[144:147], v[168:171], v[44:47]
	v_mfma_f32_16x16x32_bf16 v[40:43], v[152:155], v[168:171], v[40:43]
	v_mfma_f32_16x16x32_bf16 v[32:35], v[144:147], v[186:189], v[32:35]
	v_mfma_f32_16x16x32_bf16 v[24:27], v[152:155], v[186:189], v[24:27]
	v_mfma_f32_16x16x32_bf16 v[16:19], v[144:147], v[194:197], v[16:19]
	v_mfma_f32_16x16x32_bf16 v[8:11], v[152:155], v[194:197], v[8:11]
	v_mfma_f32_16x16x32_bf16 v[60:63], v[148:151], v[164:167], v[60:63]
	v_mfma_f32_16x16x32_bf16 v[56:59], v[156:159], v[164:167], v[56:59]
	v_mfma_f32_16x16x32_bf16 v[44:47], v[148:151], v[182:185], v[44:47]
	v_mfma_f32_16x16x32_bf16 v[40:43], v[156:159], v[182:185], v[40:43]
	v_mfma_f32_16x16x32_bf16 v[32:35], v[148:151], v[190:193], v[32:35]
	v_mfma_f32_16x16x32_bf16 v[24:27], v[156:159], v[190:193], v[24:27]
	v_mfma_f32_16x16x32_bf16 v[16:19], v[148:151], v[198:201], v[16:19]
	v_mfma_f32_16x16x32_bf16 v[8:11], v[156:159], v[198:201], v[8:11]
	s_barrier
	s_setprio 0
	s_add_u32 s40, s40, 0x20080
	s_addc_u32 s41, s41, 0
	s_add_i32 s42, s42, s48
	v_lshl_add_u64 v[144:145], s[40:41], 0, v[130:131]
	s_mov_b32 m0, s42
	s_nop 0
	global_load_lds_dwordx4 v[144:145], off
	v_lshl_add_u64 v[144:145], s[40:41], 0, v[134:135]
	s_add_i32 m0, s42, 0x2000
	s_nop 0
	global_load_lds_dwordx4 v[144:145], off
	s_waitcnt vmcnt(6)
	s_setprio 1
	s_barrier
	v_mfma_f32_16x16x32_bf16 v[52:55], v[202:205], v[160:163], v[52:55]
	v_mfma_f32_16x16x32_bf16 v[48:51], v[212:215], v[160:163], v[48:51]
	v_mfma_f32_16x16x32_bf16 v[36:39], v[202:205], v[168:171], v[36:39]
	v_mfma_f32_16x16x32_bf16 v[28:31], v[212:215], v[168:171], v[28:31]
	v_mfma_f32_16x16x32_bf16 v[20:23], v[202:205], v[186:189], v[20:23]
	v_mfma_f32_16x16x32_bf16 v[12:15], v[212:215], v[186:189], v[12:15]
	v_mfma_f32_16x16x32_bf16 v[4:7], v[202:205], v[194:197], v[4:7]
	v_mfma_f32_16x16x32_bf16 v[0:3], v[212:215], v[194:197], v[0:3]
	v_mfma_f32_16x16x32_bf16 v[52:55], v[206:209], v[164:167], v[52:55]
	v_mfma_f32_16x16x32_bf16 v[48:51], v[216:219], v[164:167], v[48:51]
	v_mfma_f32_16x16x32_bf16 v[36:39], v[206:209], v[182:185], v[36:39]
	v_mfma_f32_16x16x32_bf16 v[28:31], v[216:219], v[182:185], v[28:31]
	v_mfma_f32_16x16x32_bf16 v[20:23], v[206:209], v[190:193], v[20:23]
	v_mfma_f32_16x16x32_bf16 v[12:15], v[216:219], v[190:193], v[12:15]
	v_mfma_f32_16x16x32_bf16 v[4:7], v[206:209], v[198:201], v[4:7]
	v_mfma_f32_16x16x32_bf16 v[0:3], v[216:219], v[198:201], v[0:3]
	s_barrier
	s_setprio 0
	s_add_i32 s63, s63, 2
	s_add_u32 s38, s38, 0x100
	s_addc_u32 s39, s39, 0
	s_add_u32 s61, s61, 0x100
	s_addc_u32 s62, s62, 0
	s_cmp_gt_u32 s63, 5
	s_cbranch_scc0 .LBB0_792
	v_lshl_or_b32 v144, s36, 8, v177
	v_lshl_add_u32 v150, s34, 8, v175
	v_ashrrev_i32_e32 v145, 31, v144
	v_ashrrev_i32_e32 v151, 31, v150
	v_lshlrev_b64 v[144:145], 1, v[144:145]
	v_lshl_add_u64 v[146:147], s[10:11], 0, v[144:145]
	v_lshlrev_b64 v[148:149], 11, v[150:151]
	v_lshl_add_u64 v[152:153], v[146:147], 0, v[148:149]
	global_load_dwordx4 v[156:159], v[152:153], off
	global_load_dwordx4 v[160:163], v[152:153], off offset:256
	v_or_b32_e32 v152, 16, v150
	v_ashrrev_i32_e32 v153, 31, v152
	v_lshlrev_b64 v[170:171], 11, v[152:153]
	v_lshl_add_u64 v[152:153], v[146:147], 0, v[170:171]
	global_load_dwordx4 v[164:167], v[152:153], off
	global_load_dwordx4 v[182:185], v[152:153], off offset:256
	v_or_b32_e32 v152, 32, v150
	v_ashrrev_i32_e32 v153, 31, v152
	v_lshlrev_b64 v[154:155], 11, v[152:153]
	v_lshl_add_u64 v[152:153], v[146:147], 0, v[154:155]
	global_load_dwordx4 v[186:189], v[152:153], off
	global_load_dwordx4 v[190:193], v[152:153], off offset:256
	v_or_b32_e32 v152, 48, v150
	v_ashrrev_i32_e32 v153, 31, v152
	v_lshlrev_b64 v[152:153], 11, v[152:153]
	v_lshl_add_u64 v[168:169], v[146:147], 0, v[152:153]
	global_load_dwordx4 v[194:197], v[168:169], off
	global_load_dwordx4 v[198:201], v[168:169], off offset:256
	s_waitcnt vmcnt(0)
	v_lshlrev_b32_e32 v202, 16, v156
	v_and_b32_e32 v203, 0xffff0000, v156
	v_lshlrev_b32_e32 v204, 16, v157
	v_and_b32_e32 v205, 0xffff0000, v157
	v_lshlrev_b32_e32 v206, 16, v158
	v_and_b32_e32 v207, 0xffff0000, v158
	v_lshlrev_b32_e32 v208, 16, v159
	v_and_b32_e32 v209, 0xffff0000, v159
	v_pk_add_f32 v[126:127], v[126:127], v[204:205]
	v_pk_add_f32 v[124:125], v[124:125], v[202:203]
	v_lshlrev_b32_e32 v224, 16, v166
	v_and_b32_e32 v225, 0xffff0000, v166
	v_lshlrev_b32_e32 v226, 16, v167
	v_and_b32_e32 v227, 0xffff0000, v167
	v_lshlrev_b32_e32 v212, 16, v160
	v_lshlrev_b32_e32 v166, 16, v194
	v_and_b32_e32 v167, 0xffff0000, v194
	v_lshlrev_b32_e32 v172, 16, v195
	v_and_b32_e32 v173, 0xffff0000, v195
	v_pk_add_f32 v[194:195], v[122:123], v[208:209]
	v_pk_add_f32 v[122:123], v[120:121], v[206:207]
	v_mul_f32_e32 v120, v125, v125
	v_mul_f32_e32 v121, v127, v127
	v_fmac_f32_e32 v120, v124, v124
	v_fmac_f32_e32 v121, v126, v126
	v_add_f32_e32 v120, v120, v121
	v_mul_f32_e32 v121, v123, v123
	v_fmac_f32_e32 v121, v122, v122
	v_add_f32_e32 v120, v121, v120
	v_mul_f32_e32 v121, v195, v195
	v_fmac_f32_e32 v121, v194, v194
	v_and_b32_e32 v213, 0xffff0000, v160
	v_lshlrev_b32_e32 v214, 16, v161
	v_and_b32_e32 v215, 0xffff0000, v161
	v_add_f32_e32 v181, v121, v120
	v_cvt_pk_bf16_f32 v120, v124, v125
	v_lshl_add_u64 v[124:125], s[90:91], 0, v[148:149]
	v_lshlrev_b32_e32 v216, 16, v162
	v_and_b32_e32 v217, 0xffff0000, v162
	v_lshlrev_b32_e32 v218, 16, v163
	v_and_b32_e32 v219, 0xffff0000, v163
	v_cvt_pk_bf16_f32 v121, v126, v127
	v_lshl_add_u64 v[124:125], v[124:125], 0, v[144:145]
	v_pk_add_f32 v[118:119], v[118:119], v[214:215]
	v_pk_add_f32 v[116:117], v[116:117], v[212:213]
	v_cvt_pk_bf16_f32 v122, v122, v123
	v_cvt_pk_bf16_f32 v123, v194, v195
	global_store_dwordx4 v[124:125], v[120:123], off
	v_lshlrev_b32_e32 v220, 16, v164
	v_and_b32_e32 v221, 0xffff0000, v164
	v_pk_add_f32 v[120:121], v[114:115], v[218:219]
	v_pk_add_f32 v[114:115], v[112:113], v[216:217]
	v_mul_f32_e32 v112, v117, v117
	v_mul_f32_e32 v113, v119, v119
	v_fmac_f32_e32 v112, v116, v116
	v_fmac_f32_e32 v113, v118, v118
	v_add_f32_e32 v112, v112, v113
	v_mul_f32_e32 v113, v115, v115
	v_fmac_f32_e32 v113, v114, v114
	v_add_f32_e32 v112, v113, v112
	v_mul_f32_e32 v113, v121, v121
	v_fmac_f32_e32 v113, v120, v120
	v_add_f32_e32 v112, v113, v112
	v_lshlrev_b32_e32 v222, 16, v165
	v_and_b32_e32 v223, 0xffff0000, v165
	v_add_f32_e32 v126, v181, v112
	v_cvt_pk_bf16_f32 v112, v116, v117
	v_cvt_pk_bf16_f32 v113, v118, v119
	v_lshl_add_u64 v[116:117], s[90:91], 0, v[170:171]
	v_lshlrev_b32_e32 v230, 16, v184
	v_and_b32_e32 v231, 0xffff0000, v184
	v_lshlrev_b32_e32 v232, 16, v186
	v_and_b32_e32 v233, 0xffff0000, v186
	v_lshlrev_b32_e32 v186, 16, v187
	v_and_b32_e32 v187, 0xffff0000, v187
	v_cvt_pk_bf16_f32 v114, v114, v115
	v_cvt_pk_bf16_f32 v115, v120, v121
	global_store_dwordx4 v[124:125], v[112:115], off offset:256
	v_pk_add_f32 v[110:111], v[110:111], v[222:223]
	v_pk_add_f32 v[108:109], v[108:109], v[220:221]
	v_lshl_add_u64 v[118:119], v[116:117], 0, v[144:145]
	v_cvt_pk_bf16_f32 v112, v108, v109
	v_cvt_pk_bf16_f32 v113, v110, v111
	v_lshlrev_b32_e32 v228, 16, v182
	v_and_b32_e32 v229, 0xffff0000, v182
	v_lshlrev_b32_e32 v182, 16, v183
	v_and_b32_e32 v183, 0xffff0000, v183
	v_lshlrev_b32_e32 v184, 16, v185
	v_and_b32_e32 v185, 0xffff0000, v185
	v_lshlrev_b32_e32 v238, 16, v192
	v_and_b32_e32 v239, 0xffff0000, v192
	v_pk_add_f32 v[106:107], v[106:107], v[226:227]
	v_pk_add_f32 v[104:105], v[104:105], v[224:225]
	v_lshlrev_b32_e32 v156, 16, v200
	v_cvt_pk_bf16_f32 v114, v104, v105
	v_cvt_pk_bf16_f32 v115, v106, v107
	global_store_dwordx4 v[118:119], v[112:115], off
	v_and_b32_e32 v157, 0xffff0000, v200
	v_pk_add_f32 v[102:103], v[102:103], v[182:183]
	v_pk_add_f32 v[112:113], v[92:93], v[230:231]
	v_pk_add_f32 v[92:93], v[98:99], v[186:187]
	v_lshl_add_u64 v[98:99], s[90:91], 0, v[154:155]
	v_pk_add_f32 v[100:101], v[100:101], v[228:229]
	v_pk_add_f32 v[94:95], v[94:95], v[184:185]
	v_cvt_pk_bf16_f32 v114, v100, v101
	v_cvt_pk_bf16_f32 v115, v102, v103
	v_cvt_pk_bf16_f32 v116, v112, v113
	v_lshlrev_b32_e32 v234, 16, v188
	v_cvt_pk_bf16_f32 v117, v94, v95
	global_store_dwordx4 v[118:119], v[114:117], off offset:256
	v_lshl_add_u64 v[118:119], v[98:99], 0, v[144:145]
	v_pk_add_f32 v[98:99], v[76:77], v[238:239]
	v_pk_add_f32 v[76:77], v[82:83], v[172:173]
	v_lshl_add_u64 v[82:83], s[90:91], 0, v[152:153]
	v_lshl_add_u64 v[122:123], v[82:83], 0, v[144:145]
	v_pk_add_f32 v[82:83], v[64:65], v[156:157]
	v_and_b32_e32 v65, 64, v174
	v_and_b32_e32 v235, 0xffff0000, v188
	v_lshlrev_b32_e32 v188, 16, v189
	v_and_b32_e32 v189, 0xffff0000, v189
	v_lshlrev_b32_e32 v236, 16, v190
	v_and_b32_e32 v237, 0xffff0000, v190
	v_pk_add_f32 v[96:97], v[96:97], v[232:233]
	v_xor_b32_e32 v64, 16, v174
	v_cvt_pk_bf16_f32 v114, v96, v97
	v_add_u32_e32 v65, 64, v65
	v_lshlrev_b32_e32 v190, 16, v191
	v_and_b32_e32 v191, 0xffff0000, v191
	v_lshlrev_b32_e32 v192, 16, v193
	v_and_b32_e32 v193, 0xffff0000, v193
	v_pk_add_f32 v[90:91], v[90:91], v[188:189]
	v_pk_add_f32 v[88:89], v[88:89], v[234:235]
	v_cvt_pk_bf16_f32 v115, v92, v93
	v_pk_add_f32 v[84:85], v[84:85], v[236:237]
	v_cvt_pk_bf16_f32 v116, v88, v89
	v_cvt_pk_bf16_f32 v117, v90, v91
	global_store_dwordx4 v[118:119], v[114:117], off
	v_cmp_lt_i32_e32 vcc, v64, v65
	v_lshlrev_b32_e32 v164, 16, v196
	v_cvt_pk_bf16_f32 v114, v84, v85
	v_and_b32_e32 v165, 0xffff0000, v196
	v_lshlrev_b32_e32 v168, 16, v197
	v_and_b32_e32 v169, 0xffff0000, v197
	v_pk_add_f32 v[86:87], v[86:87], v[190:191]
	v_pk_add_f32 v[78:79], v[78:79], v[192:193]
	v_cvt_pk_bf16_f32 v115, v86, v87
	v_cvt_pk_bf16_f32 v116, v98, v99
	v_pk_add_f32 v[80:81], v[80:81], v[166:167]
	v_cvt_pk_bf16_f32 v117, v78, v79
	global_store_dwordx4 v[118:119], v[114:117], off offset:256
	v_cndmask_b32_e32 v64, v174, v64, vcc
	v_pk_add_f32 v[74:75], v[74:75], v[168:169]
	v_cvt_pk_bf16_f32 v114, v80, v81
	v_pk_add_f32 v[72:73], v[72:73], v[164:165]
	v_cvt_pk_bf16_f32 v115, v76, v77
	v_lshlrev_b32_e32 v158, 16, v198
	v_cvt_pk_bf16_f32 v116, v72, v73
	v_cvt_pk_bf16_f32 v117, v74, v75
	global_store_dwordx4 v[122:123], v[114:117], off
	v_and_b32_e32 v159, 0xffff0000, v198
	v_lshlrev_b32_e32 v162, 16, v199
	v_lshlrev_b32_e32 v114, 2, v64
	ds_bpermute_b32 v64, v114, v126
	v_xor_b32_e32 v115, 32, v174
	v_cmp_lt_i32_e32 vcc, v115, v65
	v_and_b32_e32 v163, 0xffff0000, v199
	v_lshlrev_b32_e32 v160, 16, v201
	v_cndmask_b32_e32 v65, v174, v115, vcc
	v_lshlrev_b32_e32 v115, 2, v65
	s_waitcnt lgkmcnt(0)
	v_add_f32_e32 v116, v126, v64
	ds_bpermute_b32 v117, v115, v116
	v_and_b32_e32 v161, 0xffff0000, v201
	v_pk_add_f32 v[70:71], v[70:71], v[162:163]
	v_pk_add_f32 v[68:69], v[68:69], v[158:159]
	v_pk_add_f32 v[66:67], v[66:67], v[160:161]
	v_lshl_add_u64 v[64:65], v[150:151], 2, s[2:3]
	v_cvt_pk_bf16_f32 v118, v68, v69
	v_cvt_pk_bf16_f32 v119, v70, v71
	v_cvt_pk_bf16_f32 v120, v82, v83
	v_cvt_pk_bf16_f32 v121, v66, v67
	global_store_dwordx4 v[122:123], v[118:121], off offset:256
	s_and_saveexec_b64 s[34:35], s[6:7]
	s_cbranch_execz .LBB0_795
	s_waitcnt lgkmcnt(0)
	v_add_f32_e32 v116, v116, v117
	global_atomic_add_f32 v[64:65], v116, off

.LBB0_850:
	ds_read_b128 v[144:147], v151
	ds_read_b128 v[156:159], v151 offset:1024
	ds_read_b128 v[160:163], v151 offset:2048
	ds_read_b128 v[164:167], v151 offset:3072
	s_add_u32 s36, s34, 0xfffc0080
	s_addc_u32 s37, s35, -1
	s_cmp_eq_u32 s66, 12
	s_cselect_b32 s39, s27, s37
	s_cselect_b32 s38, s62, s36
	s_cselect_b32 s37, s25, s65
	s_cselect_b32 s36, s63, s64
	v_lshl_add_u64 v[172:173], s[34:35], 0, v[136:137]
	s_add_i32 m0, s42, 0xc000
	ds_read_b128 v[168:171], v152
	ds_read_b128 v[176:179], v152 offset:1024
	ds_read_b128 v[180:183], v152 offset:2048
	ds_read_b128 v[184:187], v152 offset:3072
	ds_read_b128 v[188:191], v152 offset:4096
	ds_read_b128 v[192:195], v152 offset:5120
	ds_read_b128 v[196:199], v152 offset:6144
	ds_read_b128 v[200:203], v152 offset:7168
	global_load_lds_dwordx4 v[172:173], off
	v_lshl_add_u64 v[172:173], s[34:35], 0, v[138:139]
	s_add_i32 m0, s42, 0xe000
	s_nop 0
	global_load_lds_dwordx4 v[172:173], off
	s_waitcnt lgkmcnt(8)
	s_setprio 1
	s_barrier
	s_waitcnt lgkmcnt(0)
	v_mfma_f32_16x16x32_bf16 v[124:127], v[144:147], v[168:171], v[124:127]
	v_mfma_f32_16x16x32_bf16 v[120:123], v[160:163], v[168:171], v[120:123]
	v_mfma_f32_16x16x32_bf16 v[116:119], v[144:147], v[180:183], v[116:119]
	v_mfma_f32_16x16x32_bf16 v[112:115], v[160:163], v[180:183], v[112:115]
	v_mfma_f32_16x16x32_bf16 v[92:95], v[144:147], v[188:191], v[92:95]
	v_mfma_f32_16x16x32_bf16 v[88:91], v[160:163], v[188:191], v[88:91]
	v_mfma_f32_16x16x32_bf16 v[76:79], v[144:147], v[196:199], v[76:79]
	v_mfma_f32_16x16x32_bf16 v[72:75], v[160:163], v[196:199], v[72:75]
	v_mfma_f32_16x16x32_bf16 v[124:127], v[156:159], v[176:179], v[124:127]
	v_mfma_f32_16x16x32_bf16 v[120:123], v[164:167], v[176:179], v[120:123]
	v_mfma_f32_16x16x32_bf16 v[116:119], v[156:159], v[184:187], v[116:119]
	v_mfma_f32_16x16x32_bf16 v[112:115], v[164:167], v[184:187], v[112:115]
	v_mfma_f32_16x16x32_bf16 v[92:95], v[156:159], v[192:195], v[92:95]
	v_mfma_f32_16x16x32_bf16 v[88:91], v[164:167], v[192:195], v[88:91]
	v_mfma_f32_16x16x32_bf16 v[76:79], v[156:159], v[200:203], v[76:79]
	v_mfma_f32_16x16x32_bf16 v[72:75], v[164:167], v[200:203], v[72:75]
	s_barrier
	s_setprio 0
	s_add_i32 s67, s55, s41
	v_lshl_add_u64 v[172:173], s[36:37], 0, v[130:131]
	s_mov_b32 m0, s67
	ds_read_b128 v[204:207], v153
	ds_read_b128 v[212:215], v153 offset:1024
	ds_read_b128 v[216:219], v153 offset:2048
	ds_read_b128 v[220:223], v153 offset:3072
	global_load_lds_dwordx4 v[172:173], off
	v_lshl_add_u64 v[208:209], s[36:37], 0, v[134:135]
	s_add_i32 m0, s67, 0x2000
	s_nop 0
	global_load_lds_dwordx4 v[208:209], off
	s_setprio 1
	s_barrier
	s_waitcnt lgkmcnt(0)
	v_mfma_f32_16x16x32_bf16 v[108:111], v[204:207], v[168:171], v[108:111]
	v_mfma_f32_16x16x32_bf16 v[104:107], v[216:219], v[168:171], v[104:107]
	v_mfma_f32_16x16x32_bf16 v[100:103], v[204:207], v[180:183], v[100:103]
	v_mfma_f32_16x16x32_bf16 v[96:99], v[216:219], v[180:183], v[96:99]
	v_mfma_f32_16x16x32_bf16 v[84:87], v[204:207], v[188:191], v[84:87]
	v_mfma_f32_16x16x32_bf16 v[80:83], v[216:219], v[188:191], v[80:83]
	v_mfma_f32_16x16x32_bf16 v[68:71], v[204:207], v[196:199], v[68:71]
	v_mfma_f32_16x16x32_bf16 v[64:67], v[216:219], v[196:199], v[64:67]
	v_mfma_f32_16x16x32_bf16 v[108:111], v[212:215], v[176:179], v[108:111]
	v_mfma_f32_16x16x32_bf16 v[104:107], v[220:223], v[176:179], v[104:107]
	v_mfma_f32_16x16x32_bf16 v[100:103], v[212:215], v[184:187], v[100:103]
	v_mfma_f32_16x16x32_bf16 v[96:99], v[220:223], v[184:187], v[96:99]
	v_mfma_f32_16x16x32_bf16 v[84:87], v[212:215], v[192:195], v[84:87]
	v_mfma_f32_16x16x32_bf16 v[80:83], v[220:223], v[192:195], v[80:83]
	v_mfma_f32_16x16x32_bf16 v[68:71], v[212:215], v[200:203], v[68:71]
	v_mfma_f32_16x16x32_bf16 v[64:67], v[220:223], v[200:203], v[64:67]
	s_barrier
	s_setprio 0
	s_mov_b32 m0, s42
	v_lshl_add_u64 v[224:225], s[38:39], 0, v[128:129]
	ds_read_b128 v[168:171], v152 offset:16384
	ds_read_b128 v[176:179], v152 offset:17408
	ds_read_b128 v[180:183], v152 offset:18432
	ds_read_b128 v[184:187], v152 offset:19456
	ds_read_b128 v[188:191], v152 offset:20480
	ds_read_b128 v[192:195], v152 offset:21504
	ds_read_b128 v[196:199], v152 offset:22528
	ds_read_b128 v[200:203], v152 offset:23552
	global_load_lds_dwordx4 v[224:225], off
	v_lshl_add_u64 v[226:227], s[38:39], 0, v[132:133]
	s_mov_b32 m0, s43
	s_nop 0
	global_load_lds_dwordx4 v[226:227], off
	s_setprio 1
	s_barrier
	s_waitcnt lgkmcnt(0)
	v_mfma_f32_16x16x32_bf16 v[60:63], v[144:147], v[168:171], v[60:63]
	v_mfma_f32_16x16x32_bf16 v[56:59], v[160:163], v[168:171], v[56:59]
	v_mfma_f32_16x16x32_bf16 v[44:47], v[144:147], v[180:183], v[44:47]
	v_mfma_f32_16x16x32_bf16 v[40:43], v[160:163], v[180:183], v[40:43]
	v_mfma_f32_16x16x32_bf16 v[28:31], v[144:147], v[188:191], v[28:31]
	v_mfma_f32_16x16x32_bf16 v[24:27], v[160:163], v[188:191], v[24:27]
	v_mfma_f32_16x16x32_bf16 v[12:15], v[144:147], v[196:199], v[12:15]
	v_mfma_f32_16x16x32_bf16 v[8:11], v[160:163], v[196:199], v[8:11]
	v_mfma_f32_16x16x32_bf16 v[60:63], v[156:159], v[176:179], v[60:63]
	v_mfma_f32_16x16x32_bf16 v[56:59], v[164:167], v[176:179], v[56:59]
	v_mfma_f32_16x16x32_bf16 v[44:47], v[156:159], v[184:187], v[44:47]
	v_mfma_f32_16x16x32_bf16 v[40:43], v[164:167], v[184:187], v[40:43]
	v_mfma_f32_16x16x32_bf16 v[28:31], v[156:159], v[192:195], v[28:31]
	v_mfma_f32_16x16x32_bf16 v[24:27], v[164:167], v[192:195], v[24:27]
	v_mfma_f32_16x16x32_bf16 v[12:15], v[156:159], v[200:203], v[12:15]
	v_mfma_f32_16x16x32_bf16 v[8:11], v[164:167], v[200:203], v[8:11]
	s_barrier
	s_setprio 0
	s_add_u32 s68, s36, 0x40000
	s_addc_u32 s69, s37, 0
	s_add_i32 s67, s56, s41
	v_lshl_add_u64 v[144:145], s[68:69], 0, v[130:131]
	s_mov_b32 m0, s67
	s_nop 0
	global_load_lds_dwordx4 v[144:145], off
	v_lshl_add_u64 v[144:145], s[68:69], 0, v[134:135]
	s_add_i32 m0, s67, 0x2000
	s_nop 0
	global_load_lds_dwordx4 v[144:145], off
	s_waitcnt vmcnt(6)
	s_setprio 1
	s_barrier
	v_mfma_f32_16x16x32_bf16 v[52:55], v[204:207], v[168:171], v[52:55]
	v_mfma_f32_16x16x32_bf16 v[48:51], v[216:219], v[168:171], v[48:51]
	v_mfma_f32_16x16x32_bf16 v[36:39], v[204:207], v[180:183], v[36:39]
	v_mfma_f32_16x16x32_bf16 v[32:35], v[216:219], v[180:183], v[32:35]
	v_mfma_f32_16x16x32_bf16 v[20:23], v[204:207], v[188:191], v[20:23]
	v_mfma_f32_16x16x32_bf16 v[16:19], v[216:219], v[188:191], v[16:19]
	v_mfma_f32_16x16x32_bf16 v[4:7], v[204:207], v[196:199], v[4:7]
	v_mfma_f32_16x16x32_bf16 v[0:3], v[216:219], v[196:199], v[0:3]
	v_mfma_f32_16x16x32_bf16 v[52:55], v[212:215], v[176:179], v[52:55]
	v_mfma_f32_16x16x32_bf16 v[48:51], v[220:223], v[176:179], v[48:51]
	v_mfma_f32_16x16x32_bf16 v[36:39], v[212:215], v[184:187], v[36:39]
	v_mfma_f32_16x16x32_bf16 v[32:35], v[220:223], v[184:187], v[32:35]
	v_mfma_f32_16x16x32_bf16 v[20:23], v[212:215], v[192:195], v[20:23]
	v_mfma_f32_16x16x32_bf16 v[16:19], v[220:223], v[192:195], v[16:19]
	v_mfma_f32_16x16x32_bf16 v[4:7], v[212:215], v[200:203], v[4:7]
	v_mfma_f32_16x16x32_bf16 v[0:3], v[220:223], v[200:203], v[0:3]
	s_barrier
	s_setprio 0
	s_add_i32 s67, 0, 0x18000
	v_add_u32_e32 v155, s67, v149
	ds_read_b128 v[144:147], v155
	ds_read_b128 v[156:159], v155 offset:1024
	ds_read_b128 v[160:163], v155 offset:2048
	ds_read_b128 v[164:167], v155 offset:3072
	s_add_u32 s38, s38, 0x40000
	s_addc_u32 s39, s39, 0
	s_mov_b32 m0, s48
	v_lshl_add_u64 v[204:205], s[38:39], 0, v[128:129]
	ds_read_b128 v[168:171], v152 offset:32768
	ds_read_b128 v[176:179], v152 offset:33792
	ds_read_b128 v[180:183], v152 offset:34816
	ds_read_b128 v[184:187], v152 offset:35840
	ds_read_b128 v[188:191], v152 offset:36864
	ds_read_b128 v[192:195], v152 offset:37888
	ds_read_b128 v[196:199], v152 offset:38912
	ds_read_b128 v[200:203], v152 offset:39936
	global_load_lds_dwordx4 v[204:205], off
	v_lshl_add_u64 v[204:205], s[38:39], 0, v[132:133]
	s_mov_b32 m0, s49
	s_nop 0
	global_load_lds_dwordx4 v[204:205], off
	s_waitcnt lgkmcnt(8)
	s_setprio 1
	s_barrier
	s_waitcnt lgkmcnt(0)
	v_mfma_f32_16x16x32_bf16 v[124:127], v[144:147], v[168:171], v[124:127]
	v_mfma_f32_16x16x32_bf16 v[120:123], v[160:163], v[168:171], v[120:123]
	v_mfma_f32_16x16x32_bf16 v[116:119], v[144:147], v[180:183], v[116:119]
	v_mfma_f32_16x16x32_bf16 v[112:115], v[160:163], v[180:183], v[112:115]
	v_mfma_f32_16x16x32_bf16 v[92:95], v[144:147], v[188:191], v[92:95]
	v_mfma_f32_16x16x32_bf16 v[88:91], v[160:163], v[188:191], v[88:91]
	v_mfma_f32_16x16x32_bf16 v[76:79], v[144:147], v[196:199], v[76:79]
	v_mfma_f32_16x16x32_bf16 v[72:75], v[160:163], v[196:199], v[72:75]
	v_mfma_f32_16x16x32_bf16 v[124:127], v[156:159], v[176:179], v[124:127]
	v_mfma_f32_16x16x32_bf16 v[120:123], v[164:167], v[176:179], v[120:123]
	v_mfma_f32_16x16x32_bf16 v[116:119], v[156:159], v[184:187], v[116:119]
	v_mfma_f32_16x16x32_bf16 v[112:115], v[164:167], v[184:187], v[112:115]
	v_mfma_f32_16x16x32_bf16 v[92:95], v[156:159], v[192:195], v[92:95]
	v_mfma_f32_16x16x32_bf16 v[88:91], v[164:167], v[192:195], v[88:91]
	v_mfma_f32_16x16x32_bf16 v[76:79], v[156:159], v[200:203], v[76:79]
	v_mfma_f32_16x16x32_bf16 v[72:75], v[164:167], v[200:203], v[72:75]
	s_barrier
	s_setprio 0
	s_add_i32 s38, 0, 0x1c000
	s_add_i32 s39, s67, s41
	v_add_u32_e32 v155, s38, v149
	v_lshl_add_u64 v[172:173], v[172:173], 0, s[8:9]
	s_mov_b32 m0, s39
	ds_read_b128 v[204:207], v155
	ds_read_b128 v[212:215], v155 offset:1024
	ds_read_b128 v[216:219], v155 offset:2048
	ds_read_b128 v[220:223], v155 offset:3072
	global_load_lds_dwordx4 v[172:173], off
	v_lshl_add_u64 v[172:173], v[208:209], 0, s[8:9]
	s_add_i32 m0, s39, 0x2000
	s_nop 0
	global_load_lds_dwordx4 v[172:173], off
	s_setprio 1
	s_barrier
	s_waitcnt lgkmcnt(0)
	v_mfma_f32_16x16x32_bf16 v[108:111], v[204:207], v[168:171], v[108:111]
	v_mfma_f32_16x16x32_bf16 v[104:107], v[216:219], v[168:171], v[104:107]
	v_mfma_f32_16x16x32_bf16 v[100:103], v[204:207], v[180:183], v[100:103]
	v_mfma_f32_16x16x32_bf16 v[96:99], v[216:219], v[180:183], v[96:99]
	v_mfma_f32_16x16x32_bf16 v[84:87], v[204:207], v[188:191], v[84:87]
	v_mfma_f32_16x16x32_bf16 v[80:83], v[216:219], v[188:191], v[80:83]
	v_mfma_f32_16x16x32_bf16 v[68:71], v[204:207], v[196:199], v[68:71]
	v_mfma_f32_16x16x32_bf16 v[64:67], v[216:219], v[196:199], v[64:67]
	v_mfma_f32_16x16x32_bf16 v[108:111], v[212:215], v[176:179], v[108:111]
	v_mfma_f32_16x16x32_bf16 v[104:107], v[220:223], v[176:179], v[104:107]
	v_mfma_f32_16x16x32_bf16 v[100:103], v[212:215], v[184:187], v[100:103]
	v_mfma_f32_16x16x32_bf16 v[96:99], v[220:223], v[184:187], v[96:99]
	v_mfma_f32_16x16x32_bf16 v[84:87], v[212:215], v[192:195], v[84:87]
	v_mfma_f32_16x16x32_bf16 v[80:83], v[220:223], v[192:195], v[80:83]
	v_mfma_f32_16x16x32_bf16 v[68:71], v[212:215], v[200:203], v[68:71]
	v_mfma_f32_16x16x32_bf16 v[64:67], v[220:223], v[200:203], v[64:67]
	s_barrier
	s_setprio 0
	s_mov_b32 m0, s51
	v_lshl_add_u64 v[172:173], v[224:225], 0, s[8:9]
	ds_read_b128 v[168:171], v152 offset:49152
	ds_read_b128 v[176:179], v152 offset:50176
	ds_read_b128 v[180:183], v152 offset:51200
	ds_read_b128 v[184:187], v152 offset:52224
	ds_read_b128 v[188:191], v152 offset:53248
	ds_read_b128 v[192:195], v152 offset:54272
	ds_read_b128 v[196:199], v152 offset:55296
	ds_read_b128 v[200:203], v152 offset:56320
	global_load_lds_dwordx4 v[172:173], off
	v_lshl_add_u64 v[172:173], v[226:227], 0, s[8:9]
	s_mov_b32 m0, s52
	s_nop 0
	global_load_lds_dwordx4 v[172:173], off
	s_setprio 1
	s_barrier
	s_waitcnt lgkmcnt(0)
	v_mfma_f32_16x16x32_bf16 v[60:63], v[144:147], v[168:171], v[60:63]
	v_mfma_f32_16x16x32_bf16 v[56:59], v[160:163], v[168:171], v[56:59]
	v_mfma_f32_16x16x32_bf16 v[44:47], v[144:147], v[180:183], v[44:47]
	v_mfma_f32_16x16x32_bf16 v[40:43], v[160:163], v[180:183], v[40:43]
	v_mfma_f32_16x16x32_bf16 v[28:31], v[144:147], v[188:191], v[28:31]
	v_mfma_f32_16x16x32_bf16 v[24:27], v[160:163], v[188:191], v[24:27]
	v_mfma_f32_16x16x32_bf16 v[12:15], v[144:147], v[196:199], v[12:15]
	v_mfma_f32_16x16x32_bf16 v[8:11], v[160:163], v[196:199], v[8:11]
	v_mfma_f32_16x16x32_bf16 v[60:63], v[156:159], v[176:179], v[60:63]
	v_mfma_f32_16x16x32_bf16 v[56:59], v[164:167], v[176:179], v[56:59]
	v_mfma_f32_16x16x32_bf16 v[44:47], v[156:159], v[184:187], v[44:47]
	v_mfma_f32_16x16x32_bf16 v[40:43], v[164:167], v[184:187], v[40:43]
	v_mfma_f32_16x16x32_bf16 v[28:31], v[156:159], v[192:195], v[28:31]
	v_mfma_f32_16x16x32_bf16 v[24:27], v[164:167], v[192:195], v[24:27]
	v_mfma_f32_16x16x32_bf16 v[12:15], v[156:159], v[200:203], v[12:15]
	v_mfma_f32_16x16x32_bf16 v[8:11], v[164:167], v[200:203], v[8:11]
	s_barrier
	s_setprio 0
	s_add_u32 s36, s36, 0x40080
	s_addc_u32 s37, s37, 0
	s_add_i32 s38, s38, s41
	v_lshl_add_u64 v[144:145], s[36:37], 0, v[130:131]
	s_mov_b32 m0, s38
	s_nop 0
	global_load_lds_dwordx4 v[144:145], off
	v_lshl_add_u64 v[144:145], s[36:37], 0, v[134:135]
	s_add_i32 m0, s38, 0x2000
	s_nop 0
	global_load_lds_dwordx4 v[144:145], off
	s_waitcnt vmcnt(6)
	s_setprio 1
	s_barrier
	v_mfma_f32_16x16x32_bf16 v[52:55], v[204:207], v[168:171], v[52:55]
	v_mfma_f32_16x16x32_bf16 v[48:51], v[216:219], v[168:171], v[48:51]
	v_mfma_f32_16x16x32_bf16 v[36:39], v[204:207], v[180:183], v[36:39]
	v_mfma_f32_16x16x32_bf16 v[32:35], v[216:219], v[180:183], v[32:35]
	v_mfma_f32_16x16x32_bf16 v[20:23], v[204:207], v[188:191], v[20:23]
	v_mfma_f32_16x16x32_bf16 v[16:19], v[216:219], v[188:191], v[16:19]
	v_mfma_f32_16x16x32_bf16 v[4:7], v[204:207], v[196:199], v[4:7]
	v_mfma_f32_16x16x32_bf16 v[0:3], v[216:219], v[196:199], v[0:3]
	v_mfma_f32_16x16x32_bf16 v[52:55], v[212:215], v[176:179], v[52:55]
	v_mfma_f32_16x16x32_bf16 v[48:51], v[220:223], v[176:179], v[48:51]
	v_mfma_f32_16x16x32_bf16 v[36:39], v[212:215], v[184:187], v[36:39]
	v_mfma_f32_16x16x32_bf16 v[32:35], v[220:223], v[184:187], v[32:35]
	v_mfma_f32_16x16x32_bf16 v[20:23], v[212:215], v[192:195], v[20:23]
	v_mfma_f32_16x16x32_bf16 v[16:19], v[220:223], v[192:195], v[16:19]
	v_mfma_f32_16x16x32_bf16 v[4:7], v[212:215], v[200:203], v[4:7]
	v_mfma_f32_16x16x32_bf16 v[0:3], v[220:223], v[200:203], v[0:3]
	s_barrier
	s_setprio 0
	s_add_i32 s66, s66, 2
	s_add_u32 s34, s34, 0x100
	s_addc_u32 s35, s35, 0
	s_add_u32 s64, s64, 0x100
	s_addc_u32 s65, s65, 0
	s_cmp_gt_u32 s66, 13
	s_cbranch_scc0 .LBB0_850
	v_lshl_add_u32 v146, s0, 8, v148
	v_ashrrev_i32_e32 v147, 31, v146
	v_lshl_add_u64 v[144:145], v[146:147], 2, s[2:3]
	global_load_dword v155, v[144:145], off
	global_load_dword v162, v[144:145], off offset:64
	global_load_dword v163, v[144:145], off offset:128
	global_load_dword v164, v[144:145], off offset:192
	global_load_dword v165, v[144:145], off offset:512
	global_load_dword v166, v[144:145], off offset:576
	global_load_dword v167, v[144:145], off offset:640
	global_load_dword v168, v[144:145], off offset:704
	v_lshl_or_b32 v144, s1, 8, v150
	v_ashrrev_i32_e32 v145, 31, v144
	v_lshlrev_b64 v[158:159], 13, v[146:147]
	v_lshlrev_b64 v[160:161], 1, v[144:145]
	v_lshl_add_u64 v[144:145], s[92:93], 0, v[158:159]
	v_lshl_add_u64 v[144:145], v[144:145], 0, v[160:161]
	v_or_b32_e32 v156, 16, v146
	v_ashrrev_i32_e32 v157, 31, v156
	v_lshlrev_b64 v[156:157], 13, v[156:157]
	v_lshl_add_u64 v[156:157], s[92:93], 0, v[156:157]
	v_lshl_add_u64 v[156:157], v[156:157], 0, v[160:161]
	s_mov_b64 s[36:37], s[30:31]
	s_mov_b64 s[34:35], s[28:29]
	s_waitcnt vmcnt(0)
	v_fmamk_f32 v147, v155, 0x3a800000, v154
	v_mul_f32_e32 v158, 0x4b800000, v147
	v_cmp_gt_f32_e32 vcc, s57, v147
	v_fmamk_f32 v155, v162, 0x3a800000, v154
	v_mul_f32_e32 v162, 0x4b800000, v155
	v_cndmask_b32_e32 v147, v147, v158, vcc
	v_rsq_f32_e32 v158, v147
	v_cmp_gt_f32_e64 s[0:1], s57, v155
	v_fmamk_f32 v159, v163, 0x3a800000, v154
	v_fmamk_f32 v163, v164, 0x3a800000, v154
	v_cndmask_b32_e64 v155, v155, v162, s[0:1]
	v_rsq_f32_e32 v155, v155
	v_mul_f32_e32 v162, 0x45800000, v158
	v_cndmask_b32_e32 v158, v158, v162, vcc
	v_pk_mul_f32 v[124:125], v[124:125], v[158:159] op_sel_hi:[1,0]
	v_pk_mul_f32 v[104:105], v[104:105], v[158:159] op_sel_hi:[1,0]
	v_fmamk_f32 v164, v165, 0x3a800000, v154
	v_fmamk_f32 v165, v166, 0x3a800000, v154
	v_fmamk_f32 v166, v167, 0x3a800000, v154
	v_mul_f32_e32 v167, 0x45800000, v155
	v_pk_mul_f32 v[126:127], v[126:127], v[158:159] op_sel_hi:[1,0]
	v_pk_mul_f32 v[122:123], v[122:123], v[158:159] op_sel_hi:[1,0]
	v_pk_mul_f32 v[120:121], v[120:121], v[158:159] op_sel_hi:[1,0]
	v_pk_mul_f32 v[108:109], v[108:109], v[158:159] op_sel_hi:[1,0]
	v_pk_mul_f32 v[106:107], v[106:107], v[158:159] op_sel_hi:[1,0]
	v_max_f32_e32 v124, 0, v124
	v_max_f32_e32 v125, 0, v125
	v_max_f32_e32 v104, 0, v104
	v_cndmask_b32_e64 v162, v155, v167, s[0:1]
	v_pk_mul_f32 v[110:111], v[110:111], v[158:159] op_sel_hi:[1,0]
	v_max_f32_e32 v120, 0, v120
	v_max_f32_e32 v121, 0, v121
	v_max_f32_e32 v126, 0, v126
	v_max_f32_e32 v122, 0, v122
	v_max_f32_e32 v127, 0, v127
	v_max_f32_e32 v123, 0, v123
	v_max_f32_e32 v108, 0, v108
	v_max_f32_e32 v109, 0, v109
	v_max_f32_e32 v105, 0, v105
	v_max_f32_e32 v106, 0, v106
	v_max_f32_e32 v107, 0, v107
	v_mul_f32_e32 v124, v124, v124
	v_mul_f32_e32 v125, v125, v125
	v_mul_f32_e32 v155, v104, v104
	v_cvt_pk_bf16_f32 v104, v124, v125
	v_fmamk_f32 v147, v168, 0x3a800000, v154
	v_pk_mul_f32 v[112:113], v[112:113], v[162:163] op_sel_hi:[1,0]
	v_max_f32_e32 v110, 0, v110
	v_max_f32_e32 v111, 0, v111
	v_mul_f32_e32 v120, v120, v120
	v_mul_f32_e32 v121, v121, v121
	v_mul_f32_e32 v126, v126, v126
	v_mul_f32_e32 v122, v122, v122
	v_mul_f32_e32 v127, v127, v127
	v_mul_f32_e32 v123, v123, v123
	v_mul_f32_e32 v108, v108, v108
	v_mul_f32_e32 v109, v109, v109
	v_mul_f32_e32 v158, v105, v105
	v_mul_f32_e32 v167, v106, v106
	v_mul_f32_e32 v168, v107, v107
	v_cvt_pk_bf16_f32 v105, v126, v127
	v_cvt_pk_bf16_f32 v106, v120, v121
	v_cvt_pk_bf16_f32 v107, v122, v123
	global_store_dwordx4 v[144:145], v[104:107], off nt
	v_pk_mul_f32 v[116:117], v[116:117], v[162:163] op_sel_hi:[1,0]
	v_mul_f32_e32 v110, v110, v110
	v_cvt_pk_bf16_f32 v104, v108, v109
	v_mul_f32_e32 v111, v111, v111
	v_cvt_pk_bf16_f32 v105, v110, v111
	v_cvt_pk_bf16_f32 v106, v155, v158
	v_cvt_pk_bf16_f32 v107, v167, v168
	global_store_dwordx4 v[144:145], v[104:107], off offset:256 nt
	v_pk_mul_f32 v[118:119], v[118:119], v[162:163] op_sel_hi:[1,0]
	v_pk_mul_f32 v[114:115], v[114:115], v[162:163] op_sel_hi:[1,0]
	v_max_f32_e32 v104, 0, v112
	v_mul_f32_e32 v106, v104, v104
	v_max_f32_e32 v104, 0, v117
	v_max_f32_e32 v116, 0, v116
	v_max_f32_e32 v107, 0, v113
	v_mul_f32_e32 v104, v104, v104
	v_pk_mul_f32 v[98:99], v[98:99], v[162:163] op_sel_hi:[1,0]
	v_pk_mul_f32 v[96:97], v[96:97], v[162:163] op_sel_hi:[1,0]
	v_mul_f32_e32 v105, v116, v116
	v_mul_f32_e32 v107, v107, v107
	v_max_f32_e32 v108, 0, v118
	v_max_f32_e32 v109, 0, v114
	v_max_f32_e32 v110, 0, v119
	v_max_f32_e32 v111, 0, v115
	v_cvt_pk_bf16_f32 v104, v105, v104
	v_pk_mul_f32 v[102:103], v[102:103], v[162:163] op_sel_hi:[1,0]
	v_pk_mul_f32 v[100:101], v[100:101], v[162:163] op_sel_hi:[1,0]
	v_max_f32_e32 v96, 0, v96
	v_max_f32_e32 v97, 0, v97
	v_max_f32_e32 v98, 0, v98
	v_mul_f32_e32 v108, v108, v108
	v_mul_f32_e32 v109, v109, v109
	v_mul_f32_e32 v110, v110, v110
	v_mul_f32_e32 v111, v111, v111
	v_cvt_pk_bf16_f32 v105, v108, v110
	v_cvt_pk_bf16_f32 v106, v106, v107
	v_cvt_pk_bf16_f32 v107, v109, v111
	global_store_dwordx4 v[156:157], v[104:107], off nt
	v_max_f32_e32 v100, 0, v100
	v_max_f32_e32 v99, 0, v99
	v_mul_f32_e32 v104, v96, v96
	v_max_f32_e32 v96, 0, v101
	v_mul_f32_e32 v101, v97, v97
	v_max_f32_e32 v97, 0, v102
	v_mul_f32_e32 v102, v98, v98
	v_max_f32_e32 v98, 0, v103
	v_mul_f32_e32 v96, v96, v96
	v_mul_f32_e32 v97, v97, v97
	v_mul_f32_e32 v98, v98, v98
	v_mul_f32_e32 v100, v100, v100
	v_mul_f32_e32 v99, v99, v99
	v_cvt_pk_bf16_f32 v96, v100, v96
	v_cvt_pk_bf16_f32 v97, v97, v98
	v_cvt_pk_bf16_f32 v98, v104, v101
	v_cvt_pk_bf16_f32 v99, v102, v99
	global_store_dwordx4 v[156:157], v[96:99], off offset:256 nt
	v_cmp_gt_f32_e32 vcc, s57, v159
	s_mov_b64 s[0:1], 0x100000
	v_mul_f32_e32 v98, 0x4b800000, v159
	v_cndmask_b32_e32 v98, v159, v98, vcc
	v_rsq_f32_e32 v98, v98
	v_or_b32_e32 v96, 32, v146
	v_ashrrev_i32_e32 v97, 31, v96
	v_lshlrev_b64 v[96:97], 13, v[96:97]
	v_mul_f32_e32 v99, 0x45800000, v98
	v_cndmask_b32_e32 v98, v98, v99, vcc
	v_pk_mul_f32 v[88:89], v[88:89], v[98:99] op_sel_hi:[1,0]
	v_pk_mul_f32 v[92:93], v[92:93], v[98:99] op_sel_hi:[1,0]
	v_pk_mul_f32 v[90:91], v[90:91], v[98:99] op_sel_hi:[1,0]
	v_max_f32_e32 v88, 0, v88
	v_pk_mul_f32 v[94:95], v[94:95], v[98:99] op_sel_hi:[1,0]
	v_mul_f32_e32 v99, v88, v88
	v_max_f32_e32 v88, 0, v93
	v_max_f32_e32 v89, 0, v89
	v_max_f32_e32 v90, 0, v90
	v_lshl_add_u64 v[96:97], s[92:93], 0, v[96:97]
	v_max_f32_e32 v92, 0, v92
	v_mul_f32_e32 v88, v88, v88
	v_mul_f32_e32 v93, v89, v89
	v_max_f32_e32 v89, 0, v94
	v_mul_f32_e32 v94, v90, v90
	v_max_f32_e32 v90, 0, v95
	v_max_f32_e32 v91, 0, v91
	v_pk_mul_f32 v[82:83], v[82:83], v[98:99] op_sel_hi:[1,0]
	v_pk_mul_f32 v[80:81], v[80:81], v[98:99] op_sel_hi:[1,0]
	v_lshl_add_u64 v[96:97], v[96:97], 0, v[160:161]
	v_mul_f32_e32 v92, v92, v92
	v_mul_f32_e32 v89, v89, v89
	v_mul_f32_e32 v90, v90, v90
	v_mul_f32_e32 v91, v91, v91
	v_cvt_pk_bf16_f32 v88, v92, v88
	v_pk_mul_f32 v[86:87], v[86:87], v[98:99] op_sel_hi:[1,0]
	v_pk_mul_f32 v[84:85], v[84:85], v[98:99] op_sel_hi:[1,0]
	v_max_f32_e32 v80, 0, v80
	v_max_f32_e32 v81, 0, v81
	v_max_f32_e32 v82, 0, v82
	v_cvt_pk_bf16_f32 v89, v89, v90
	v_cvt_pk_bf16_f32 v90, v99, v93
	v_cvt_pk_bf16_f32 v91, v94, v91
	global_store_dwordx4 v[96:97], v[88:91], off nt
	v_max_f32_e32 v84, 0, v84
	v_max_f32_e32 v83, 0, v83
	v_mul_f32_e32 v88, v80, v80
	v_max_f32_e32 v80, 0, v85
	v_mul_f32_e32 v85, v81, v81
	v_max_f32_e32 v81, 0, v86
	v_mul_f32_e32 v86, v82, v82
	v_max_f32_e32 v82, 0, v87
	v_mul_f32_e32 v80, v80, v80
	v_mul_f32_e32 v81, v81, v81
	v_mul_f32_e32 v82, v82, v82
	v_mul_f32_e32 v84, v84, v84
	v_mul_f32_e32 v83, v83, v83
	v_cvt_pk_bf16_f32 v80, v84, v80
	v_cvt_pk_bf16_f32 v81, v81, v82
	v_cvt_pk_bf16_f32 v82, v88, v85
	v_cvt_pk_bf16_f32 v83, v86, v83
	global_store_dwordx4 v[96:97], v[80:83], off offset:256 nt
	v_cmp_gt_f32_e32 vcc, s57, v163
	s_nop 0
	v_mul_f32_e32 v82, 0x4b800000, v163
	v_cndmask_b32_e32 v82, v163, v82, vcc
	v_rsq_f32_e32 v82, v82
	v_or_b32_e32 v80, 48, v146
	v_ashrrev_i32_e32 v81, 31, v80
	v_lshlrev_b64 v[80:81], 13, v[80:81]
	v_mul_f32_e32 v83, 0x45800000, v82
	v_cndmask_b32_e32 v82, v82, v83, vcc
	v_pk_mul_f32 v[72:73], v[72:73], v[82:83] op_sel_hi:[1,0]
	v_pk_mul_f32 v[76:77], v[76:77], v[82:83] op_sel_hi:[1,0]
	v_pk_mul_f32 v[74:75], v[74:75], v[82:83] op_sel_hi:[1,0]
	v_max_f32_e32 v72, 0, v72
	v_pk_mul_f32 v[78:79], v[78:79], v[82:83] op_sel_hi:[1,0]
	v_mul_f32_e32 v83, v72, v72
	v_max_f32_e32 v72, 0, v77
	v_max_f32_e32 v73, 0, v73
	v_max_f32_e32 v74, 0, v74
	v_lshl_add_u64 v[80:81], s[92:93], 0, v[80:81]
	v_max_f32_e32 v76, 0, v76
	v_mul_f32_e32 v72, v72, v72
	v_mul_f32_e32 v77, v73, v73
	v_max_f32_e32 v73, 0, v78
	v_mul_f32_e32 v78, v74, v74
	v_max_f32_e32 v74, 0, v79
	v_max_f32_e32 v75, 0, v75
	v_pk_mul_f32 v[64:65], v[64:65], v[82:83] op_sel_hi:[1,0]
	v_lshl_add_u64 v[80:81], v[80:81], 0, v[160:161]
	v_mul_f32_e32 v76, v76, v76
	v_mul_f32_e32 v73, v73, v73
	v_mul_f32_e32 v74, v74, v74
	v_mul_f32_e32 v75, v75, v75
	v_cvt_pk_bf16_f32 v72, v76, v72
	v_pk_mul_f32 v[68:69], v[68:69], v[82:83] op_sel_hi:[1,0]
	v_max_f32_e32 v64, 0, v64
	v_cvt_pk_bf16_f32 v73, v73, v74
	v_cvt_pk_bf16_f32 v74, v83, v77
	v_cvt_pk_bf16_f32 v75, v78, v75
	global_store_dwordx4 v[80:81], v[72:75], off nt
	v_max_f32_e32 v68, 0, v68
	v_mul_f32_e32 v68, v68, v68
	v_mul_f32_e32 v72, v64, v64
	v_max_f32_e32 v64, 0, v69
	v_mul_f32_e32 v64, v64, v64
	v_cvt_pk_bf16_f32 v64, v68, v64
	v_mul_f32_e32 v68, 0x4b800000, v164
	v_cmp_gt_f32_e32 vcc, s57, v164
	v_pk_mul_f32 v[66:67], v[66:67], v[82:83] op_sel_hi:[1,0]
	v_pk_mul_f32 v[70:71], v[70:71], v[82:83] op_sel_hi:[1,0]
	v_cndmask_b32_e32 v68, v164, v68, vcc
	v_max_f32_e32 v65, 0, v65
	v_max_f32_e32 v66, 0, v66
	v_rsq_f32_e32 v68, v68
	v_mul_f32_e32 v69, v65, v65
	v_max_f32_e32 v65, 0, v70
	v_mul_f32_e32 v70, v66, v66
	v_max_f32_e32 v66, 0, v71
	v_mul_f32_e32 v65, v65, v65
	v_max_f32_e32 v67, 0, v67
	v_mul_f32_e32 v66, v66, v66
	v_mul_f32_e32 v67, v67, v67
	v_cvt_pk_bf16_f32 v65, v65, v66
	v_cvt_pk_bf16_f32 v66, v72, v69
	v_cvt_pk_bf16_f32 v67, v70, v67
	global_store_dwordx4 v[80:81], v[64:67], off offset:256 nt
	s_nop 1
	v_mul_f32_e32 v66, 0x45800000, v68
	v_cndmask_b32_e32 v66, v68, v66, vcc
	v_pk_mul_f32 v[56:57], v[56:57], v[66:67] op_sel_hi:[1,0]
	v_pk_mul_f32 v[60:61], v[60:61], v[66:67] op_sel_hi:[1,0]
	v_pk_mul_f32 v[58:59], v[58:59], v[66:67] op_sel_hi:[1,0]
	v_max_f32_e32 v56, 0, v56
	v_pk_mul_f32 v[62:63], v[62:63], v[66:67] op_sel_hi:[1,0]
	v_max_f32_e32 v60, 0, v60
	v_mul_f32_e32 v67, v56, v56
	v_max_f32_e32 v56, 0, v61
	v_max_f32_e32 v57, 0, v57
	v_max_f32_e32 v58, 0, v58
	v_mul_f32_e32 v60, v60, v60
	v_mul_f32_e32 v56, v56, v56
	v_mul_f32_e32 v61, v57, v57
	v_max_f32_e32 v57, 0, v62
	v_mul_f32_e32 v62, v58, v58
	v_max_f32_e32 v58, 0, v63
	v_mul_f32_e32 v57, v57, v57
	v_max_f32_e32 v59, 0, v59
	v_mul_f32_e32 v58, v58, v58
	v_cvt_pk_bf16_f32 v56, v60, v56
	v_add_co_u32_e32 v60, vcc, s58, v144
	v_pk_mul_f32 v[48:49], v[48:49], v[66:67] op_sel_hi:[1,0]
	v_mul_f32_e32 v59, v59, v59
	v_cvt_pk_bf16_f32 v57, v57, v58
	v_cvt_pk_bf16_f32 v58, v67, v61
	v_addc_co_u32_e32 v61, vcc, 0, v145, vcc
	v_pk_mul_f32 v[52:53], v[52:53], v[66:67] op_sel_hi:[1,0]
	v_max_f32_e32 v48, 0, v48
	v_cvt_pk_bf16_f32 v59, v62, v59
	global_store_dwordx4 v[60:61], v[56:59], off nt
	v_max_f32_e32 v52, 0, v52
	v_mul_f32_e32 v52, v52, v52
	v_mul_f32_e32 v56, v48, v48
	v_max_f32_e32 v48, 0, v53
	v_mul_f32_e32 v48, v48, v48
	v_cvt_pk_bf16_f32 v48, v52, v48
	v_mul_f32_e32 v52, 0x4b800000, v165
	v_cmp_gt_f32_e32 vcc, s57, v165
	v_pk_mul_f32 v[50:51], v[50:51], v[66:67] op_sel_hi:[1,0]
	v_pk_mul_f32 v[54:55], v[54:55], v[66:67] op_sel_hi:[1,0]
	v_cndmask_b32_e32 v52, v165, v52, vcc
	v_max_f32_e32 v49, 0, v49
	v_max_f32_e32 v50, 0, v50
	v_rsq_f32_e32 v52, v52
	v_mul_f32_e32 v53, v49, v49
	v_max_f32_e32 v49, 0, v54
	v_mul_f32_e32 v54, v50, v50
	v_max_f32_e32 v50, 0, v55
	v_mul_f32_e32 v49, v49, v49
	v_max_f32_e32 v51, 0, v51
	v_mul_f32_e32 v50, v50, v50
	v_lshl_add_u64 v[64:65], v[144:145], 0, s[0:1]
	v_mul_f32_e32 v51, v51, v51
	v_cvt_pk_bf16_f32 v49, v49, v50
	v_cvt_pk_bf16_f32 v50, v56, v53
	v_cvt_pk_bf16_f32 v51, v54, v51
	global_store_dwordx4 v[64:65], v[48:51], off offset:256 nt
	s_mov_b32 s1, s24
	s_mov_b32 s0, s26
	v_mul_f32_e32 v50, 0x45800000, v52
	v_cndmask_b32_e32 v50, v52, v50, vcc
	v_pk_mul_f32 v[40:41], v[40:41], v[50:51] op_sel_hi:[1,0]
	v_pk_mul_f32 v[44:45], v[44:45], v[50:51] op_sel_hi:[1,0]
	v_pk_mul_f32 v[42:43], v[42:43], v[50:51] op_sel_hi:[1,0]
	v_max_f32_e32 v40, 0, v40
	v_pk_mul_f32 v[46:47], v[46:47], v[50:51] op_sel_hi:[1,0]
	v_max_f32_e32 v44, 0, v44
	v_mul_f32_e32 v51, v40, v40
	v_max_f32_e32 v40, 0, v45
	v_max_f32_e32 v41, 0, v41
	v_max_f32_e32 v42, 0, v42
	v_mul_f32_e32 v44, v44, v44
	v_mul_f32_e32 v40, v40, v40
	v_mul_f32_e32 v45, v41, v41
	v_max_f32_e32 v41, 0, v46
	v_mul_f32_e32 v46, v42, v42
	v_max_f32_e32 v42, 0, v47
	v_mul_f32_e32 v41, v41, v41
	v_max_f32_e32 v43, 0, v43
	v_mul_f32_e32 v42, v42, v42
	v_cvt_pk_bf16_f32 v40, v44, v40
	v_add_co_u32_e32 v44, vcc, s59, v144
	v_pk_mul_f32 v[32:33], v[32:33], v[50:51] op_sel_hi:[1,0]
	v_mul_f32_e32 v43, v43, v43
	v_cvt_pk_bf16_f32 v41, v41, v42
	v_cvt_pk_bf16_f32 v42, v51, v45
	v_addc_co_u32_e32 v45, vcc, 0, v145, vcc
	v_pk_mul_f32 v[36:37], v[36:37], v[50:51] op_sel_hi:[1,0]
	v_max_f32_e32 v32, 0, v32
	v_cvt_pk_bf16_f32 v43, v46, v43
	global_store_dwordx4 v[44:45], v[40:43], off nt
	v_max_f32_e32 v36, 0, v36
	v_mul_f32_e32 v36, v36, v36
	v_mul_f32_e32 v40, v32, v32
	v_max_f32_e32 v32, 0, v37
	v_mul_f32_e32 v32, v32, v32
	v_cvt_pk_bf16_f32 v32, v36, v32
	v_mul_f32_e32 v36, 0x4b800000, v166
	v_cmp_gt_f32_e32 vcc, s57, v166
	v_pk_mul_f32 v[34:35], v[34:35], v[50:51] op_sel_hi:[1,0]
	v_pk_mul_f32 v[38:39], v[38:39], v[50:51] op_sel_hi:[1,0]
	v_cndmask_b32_e32 v36, v166, v36, vcc
	v_max_f32_e32 v33, 0, v33
	v_max_f32_e32 v34, 0, v34
	v_rsq_f32_e32 v36, v36
	v_mul_f32_e32 v37, v33, v33
	v_max_f32_e32 v33, 0, v38
	v_mul_f32_e32 v38, v34, v34
	v_max_f32_e32 v34, 0, v39
	v_mul_f32_e32 v33, v33, v33
	v_max_f32_e32 v35, 0, v35
	v_mul_f32_e32 v34, v34, v34
	v_lshl_add_u64 v[48:49], v[144:145], 0, s[18:19]
	v_mul_f32_e32 v35, v35, v35
	v_cvt_pk_bf16_f32 v33, v33, v34
	v_cvt_pk_bf16_f32 v34, v40, v37
	v_cvt_pk_bf16_f32 v35, v38, v35
	global_store_dwordx4 v[48:49], v[32:35], off offset:256 nt
	s_nop 1
	v_mul_f32_e32 v34, 0x45800000, v36
	v_cndmask_b32_e32 v34, v36, v34, vcc
	v_pk_mul_f32 v[24:25], v[24:25], v[34:35] op_sel_hi:[1,0]
	v_pk_mul_f32 v[28:29], v[28:29], v[34:35] op_sel_hi:[1,0]
	v_pk_mul_f32 v[26:27], v[26:27], v[34:35] op_sel_hi:[1,0]
	v_max_f32_e32 v24, 0, v24
	v_pk_mul_f32 v[30:31], v[30:31], v[34:35] op_sel_hi:[1,0]
	v_max_f32_e32 v28, 0, v28
	v_mul_f32_e32 v35, v24, v24
	v_max_f32_e32 v24, 0, v29
	v_max_f32_e32 v25, 0, v25
	v_max_f32_e32 v26, 0, v26
	v_mul_f32_e32 v28, v28, v28
	v_mul_f32_e32 v24, v24, v24
	v_mul_f32_e32 v29, v25, v25
	v_max_f32_e32 v25, 0, v30
	v_mul_f32_e32 v30, v26, v26
	v_max_f32_e32 v26, 0, v31
	v_mul_f32_e32 v25, v25, v25
	v_max_f32_e32 v27, 0, v27
	v_mul_f32_e32 v26, v26, v26
	v_cvt_pk_bf16_f32 v24, v28, v24
	v_add_co_u32_e32 v28, vcc, s60, v144
	v_pk_mul_f32 v[16:17], v[16:17], v[34:35] op_sel_hi:[1,0]
	v_mul_f32_e32 v27, v27, v27
	v_cvt_pk_bf16_f32 v25, v25, v26
	v_cvt_pk_bf16_f32 v26, v35, v29
	v_addc_co_u32_e32 v29, vcc, 0, v145, vcc
	v_pk_mul_f32 v[20:21], v[20:21], v[34:35] op_sel_hi:[1,0]
	v_max_f32_e32 v16, 0, v16
	v_cvt_pk_bf16_f32 v27, v30, v27
	global_store_dwordx4 v[28:29], v[24:27], off nt
	v_max_f32_e32 v20, 0, v20
	v_mul_f32_e32 v20, v20, v20
	v_mul_f32_e32 v24, v16, v16
	v_max_f32_e32 v16, 0, v21
	v_mul_f32_e32 v16, v16, v16
	v_cvt_pk_bf16_f32 v16, v20, v16
	v_mul_f32_e32 v20, 0x4b800000, v147
	v_cmp_gt_f32_e32 vcc, s57, v147
	v_pk_mul_f32 v[18:19], v[18:19], v[34:35] op_sel_hi:[1,0]
	v_pk_mul_f32 v[22:23], v[22:23], v[34:35] op_sel_hi:[1,0]
	v_cndmask_b32_e32 v20, v147, v20, vcc
	v_max_f32_e32 v17, 0, v17
	v_max_f32_e32 v18, 0, v18
	v_rsq_f32_e32 v20, v20
	v_mul_f32_e32 v21, v17, v17
	v_max_f32_e32 v17, 0, v22
	v_mul_f32_e32 v22, v18, v18
	v_max_f32_e32 v18, 0, v23
	v_mul_f32_e32 v17, v17, v17
	v_max_f32_e32 v19, 0, v19
	v_mul_f32_e32 v18, v18, v18
	v_lshl_add_u64 v[32:33], v[144:145], 0, s[20:21]
	v_mul_f32_e32 v19, v19, v19
	v_cvt_pk_bf16_f32 v17, v17, v18
	v_cvt_pk_bf16_f32 v18, v24, v21
	v_cvt_pk_bf16_f32 v19, v22, v19
	global_store_dwordx4 v[32:33], v[16:19], off offset:256 nt
	s_nop 1
	v_mul_f32_e32 v18, 0x45800000, v20
	v_cndmask_b32_e32 v18, v20, v18, vcc
	v_pk_mul_f32 v[8:9], v[8:9], v[18:19] op_sel_hi:[1,0]
	v_pk_mul_f32 v[12:13], v[12:13], v[18:19] op_sel_hi:[1,0]
	v_pk_mul_f32 v[10:11], v[10:11], v[18:19] op_sel_hi:[1,0]
	v_max_f32_e32 v8, 0, v8
	v_pk_mul_f32 v[14:15], v[14:15], v[18:19] op_sel_hi:[1,0]
	v_max_f32_e32 v12, 0, v12
	v_mul_f32_e32 v19, v8, v8
	v_max_f32_e32 v8, 0, v13
	v_max_f32_e32 v9, 0, v9
	v_max_f32_e32 v10, 0, v10
	v_mul_f32_e32 v12, v12, v12
	v_mul_f32_e32 v8, v8, v8
	v_mul_f32_e32 v13, v9, v9
	v_max_f32_e32 v9, 0, v14
	v_mul_f32_e32 v14, v10, v10
	v_max_f32_e32 v10, 0, v15
	v_mul_f32_e32 v9, v9, v9
	v_max_f32_e32 v11, 0, v11
	v_mul_f32_e32 v10, v10, v10
	v_cvt_pk_bf16_f32 v8, v12, v8
	v_add_co_u32_e32 v12, vcc, s61, v144
	v_pk_mul_f32 v[2:3], v[2:3], v[18:19] op_sel_hi:[1,0]
	v_pk_mul_f32 v[0:1], v[0:1], v[18:19] op_sel_hi:[1,0]
	v_mul_f32_e32 v11, v11, v11
	v_cvt_pk_bf16_f32 v9, v9, v10
	v_cvt_pk_bf16_f32 v10, v19, v13
	v_addc_co_u32_e32 v13, vcc, 0, v145, vcc
	v_pk_mul_f32 v[6:7], v[6:7], v[18:19] op_sel_hi:[1,0]
	v_pk_mul_f32 v[4:5], v[4:5], v[18:19] op_sel_hi:[1,0]
	v_max_f32_e32 v0, 0, v0
	v_max_f32_e32 v1, 0, v1
	v_max_f32_e32 v2, 0, v2
	v_cvt_pk_bf16_f32 v11, v14, v11
	global_store_dwordx4 v[12:13], v[8:11], off nt
	v_max_f32_e32 v3, 0, v3
	v_lshl_add_u64 v[16:17], v[144:145], 0, s[22:23]
	v_mul_f32_e32 v8, v0, v0
	v_max_f32_e32 v0, 0, v5
	v_mul_f32_e32 v5, v1, v1
	v_max_f32_e32 v1, 0, v6
	v_mul_f32_e32 v6, v2, v2
	v_max_f32_e32 v2, 0, v7
	v_max_f32_e32 v4, 0, v4
	v_mul_f32_e32 v0, v0, v0
	v_mul_f32_e32 v1, v1, v1
	v_mul_f32_e32 v2, v2, v2
	v_mul_f32_e32 v3, v3, v3
	s_and_b64 vcc, exec, s[6:7]
	v_mul_f32_e32 v4, v4, v4
	v_cvt_pk_bf16_f32 v0, v4, v0
	v_cvt_pk_bf16_f32 v1, v1, v2
	v_cvt_pk_bf16_f32 v2, v8, v5
	v_cvt_pk_bf16_f32 v3, v6, v3
	global_store_dwordx4 v[16:17], v[0:3], off offset:256 nt
	s_cbranch_vccz .LBB0_843
	s_waitcnt vmcnt(0)
	s_cmpk_gt_u32 s33, 0xff
	s_cbranch_scc1 .LBB0_854
	s_barrier

.LBB0_896:
	ds_read_b128 v[144:147], v178
	ds_read_b128 v[148:151], v178 offset:1024
	ds_read_b128 v[152:155], v178 offset:2048
	ds_read_b128 v[156:159], v178 offset:3072
	s_add_u32 s42, s40, 0xfff00080
	s_addc_u32 s43, s41, -1
	s_cmp_eq_u32 s65, 60
	s_cselect_b32 s49, s29, s43
	s_cselect_b32 s48, s37, s42
	s_cselect_b32 s43, s27, s64
	s_cselect_b32 s42, s62, s63
	v_lshl_add_u64 v[172:173], s[40:41], 0, v[136:137]
	s_add_i32 m0, s39, 0xc000
	ds_read_b128 v[160:163], v179
	ds_read_b128 v[164:167], v179 offset:1024
	ds_read_b128 v[168:171], v179 offset:2048
	ds_read_b128 v[182:185], v179 offset:3072
	ds_read_b128 v[186:189], v179 offset:4096
	ds_read_b128 v[190:193], v179 offset:5120
	ds_read_b128 v[194:197], v179 offset:6144
	ds_read_b128 v[198:201], v179 offset:7168
	global_load_lds_dwordx4 v[172:173], off
	v_lshl_add_u64 v[172:173], s[40:41], 0, v[138:139]
	s_add_i32 m0, s39, 0xe000
	s_nop 0
	global_load_lds_dwordx4 v[172:173], off
	s_waitcnt lgkmcnt(8)
	s_setprio 1
	s_barrier
	s_waitcnt lgkmcnt(0)
	v_mfma_f32_16x16x32_bf16 v[124:127], v[144:147], v[160:163], v[124:127]
	v_mfma_f32_16x16x32_bf16 v[120:123], v[152:155], v[160:163], v[120:123]
	v_mfma_f32_16x16x32_bf16 v[108:111], v[144:147], v[168:171], v[108:111]
	v_mfma_f32_16x16x32_bf16 v[104:107], v[152:155], v[168:171], v[104:107]
	v_mfma_f32_16x16x32_bf16 v[96:99], v[144:147], v[186:189], v[96:99]
	v_mfma_f32_16x16x32_bf16 v[88:91], v[152:155], v[186:189], v[88:91]
	v_mfma_f32_16x16x32_bf16 v[80:83], v[144:147], v[194:197], v[80:83]
	v_mfma_f32_16x16x32_bf16 v[72:75], v[152:155], v[194:197], v[72:75]
	v_mfma_f32_16x16x32_bf16 v[124:127], v[148:151], v[164:167], v[124:127]
	v_mfma_f32_16x16x32_bf16 v[120:123], v[156:159], v[164:167], v[120:123]
	v_mfma_f32_16x16x32_bf16 v[108:111], v[148:151], v[182:185], v[108:111]
	v_mfma_f32_16x16x32_bf16 v[104:107], v[156:159], v[182:185], v[104:107]
	v_mfma_f32_16x16x32_bf16 v[96:99], v[148:151], v[190:193], v[96:99]
	v_mfma_f32_16x16x32_bf16 v[88:91], v[156:159], v[190:193], v[88:91]
	v_mfma_f32_16x16x32_bf16 v[80:83], v[148:151], v[198:201], v[80:83]
	v_mfma_f32_16x16x32_bf16 v[72:75], v[156:159], v[198:201], v[72:75]
	s_barrier
	s_setprio 0
	s_add_i32 s66, s60, s50
	v_lshl_add_u64 v[172:173], s[42:43], 0, v[130:131]
	s_mov_b32 m0, s66
	ds_read_b128 v[202:205], v180
	ds_read_b128 v[206:209], v180 offset:1024
	ds_read_b128 v[212:215], v180 offset:2048
	ds_read_b128 v[216:219], v180 offset:3072
	global_load_lds_dwordx4 v[172:173], off
	v_lshl_add_u64 v[220:221], s[42:43], 0, v[134:135]
	s_add_i32 m0, s66, 0x2000
	s_nop 0
	global_load_lds_dwordx4 v[220:221], off
	s_setprio 1
	s_barrier
	s_waitcnt lgkmcnt(0)
	v_mfma_f32_16x16x32_bf16 v[116:119], v[202:205], v[160:163], v[116:119]
	v_mfma_f32_16x16x32_bf16 v[112:115], v[212:215], v[160:163], v[112:115]
	v_mfma_f32_16x16x32_bf16 v[100:103], v[202:205], v[168:171], v[100:103]
	v_mfma_f32_16x16x32_bf16 v[92:95], v[212:215], v[168:171], v[92:95]
	v_mfma_f32_16x16x32_bf16 v[84:87], v[202:205], v[186:189], v[84:87]
	v_mfma_f32_16x16x32_bf16 v[76:79], v[212:215], v[186:189], v[76:79]
	v_mfma_f32_16x16x32_bf16 v[68:71], v[202:205], v[194:197], v[68:71]
	v_mfma_f32_16x16x32_bf16 v[64:67], v[212:215], v[194:197], v[64:67]
	v_mfma_f32_16x16x32_bf16 v[116:119], v[206:209], v[164:167], v[116:119]
	v_mfma_f32_16x16x32_bf16 v[112:115], v[216:219], v[164:167], v[112:115]
	v_mfma_f32_16x16x32_bf16 v[100:103], v[206:209], v[182:185], v[100:103]
	v_mfma_f32_16x16x32_bf16 v[92:95], v[216:219], v[182:185], v[92:95]
	v_mfma_f32_16x16x32_bf16 v[84:87], v[206:209], v[190:193], v[84:87]
	v_mfma_f32_16x16x32_bf16 v[76:79], v[216:219], v[190:193], v[76:79]
	v_mfma_f32_16x16x32_bf16 v[68:71], v[206:209], v[198:201], v[68:71]
	v_mfma_f32_16x16x32_bf16 v[64:67], v[216:219], v[198:201], v[64:67]
	s_barrier
	s_setprio 0
	s_mov_b32 m0, s39
	v_lshl_add_u64 v[222:223], s[48:49], 0, v[128:129]
	ds_read_b128 v[160:163], v179 offset:16384
	ds_read_b128 v[164:167], v179 offset:17408
	ds_read_b128 v[168:171], v179 offset:18432
	ds_read_b128 v[182:185], v179 offset:19456
	ds_read_b128 v[186:189], v179 offset:20480
	ds_read_b128 v[190:193], v179 offset:21504
	ds_read_b128 v[194:197], v179 offset:22528
	ds_read_b128 v[198:201], v179 offset:23552
	global_load_lds_dwordx4 v[222:223], off
	v_lshl_add_u64 v[224:225], s[48:49], 0, v[132:133]
	s_mov_b32 m0, s51
	s_nop 0
	global_load_lds_dwordx4 v[224:225], off
	s_setprio 1
	s_barrier
	s_waitcnt lgkmcnt(0)
	v_mfma_f32_16x16x32_bf16 v[60:63], v[144:147], v[160:163], v[60:63]
	v_mfma_f32_16x16x32_bf16 v[56:59], v[152:155], v[160:163], v[56:59]
	v_mfma_f32_16x16x32_bf16 v[44:47], v[144:147], v[168:171], v[44:47]
	v_mfma_f32_16x16x32_bf16 v[40:43], v[152:155], v[168:171], v[40:43]
	v_mfma_f32_16x16x32_bf16 v[32:35], v[144:147], v[186:189], v[32:35]
	v_mfma_f32_16x16x32_bf16 v[24:27], v[152:155], v[186:189], v[24:27]
	v_mfma_f32_16x16x32_bf16 v[16:19], v[144:147], v[194:197], v[16:19]
	v_mfma_f32_16x16x32_bf16 v[8:11], v[152:155], v[194:197], v[8:11]
	v_mfma_f32_16x16x32_bf16 v[60:63], v[148:151], v[164:167], v[60:63]
	v_mfma_f32_16x16x32_bf16 v[56:59], v[156:159], v[164:167], v[56:59]
	v_mfma_f32_16x16x32_bf16 v[44:47], v[148:151], v[182:185], v[44:47]
	v_mfma_f32_16x16x32_bf16 v[40:43], v[156:159], v[182:185], v[40:43]
	v_mfma_f32_16x16x32_bf16 v[32:35], v[148:151], v[190:193], v[32:35]
	v_mfma_f32_16x16x32_bf16 v[24:27], v[156:159], v[190:193], v[24:27]
	v_mfma_f32_16x16x32_bf16 v[16:19], v[148:151], v[198:201], v[16:19]
	v_mfma_f32_16x16x32_bf16 v[8:11], v[156:159], v[198:201], v[8:11]
	s_barrier
	s_setprio 0
	s_add_u32 s66, s42, 0x100000
	s_addc_u32 s67, s43, 0
	s_add_i32 s68, s61, s50
	v_lshl_add_u64 v[144:145], s[66:67], 0, v[130:131]
	s_mov_b32 m0, s68
	s_nop 0
	global_load_lds_dwordx4 v[144:145], off
	v_lshl_add_u64 v[144:145], s[66:67], 0, v[134:135]
	s_add_i32 m0, s68, 0x2000
	s_nop 0
	global_load_lds_dwordx4 v[144:145], off
	s_waitcnt vmcnt(6)
	s_setprio 1
	s_barrier
	v_mfma_f32_16x16x32_bf16 v[52:55], v[202:205], v[160:163], v[52:55]
	v_mfma_f32_16x16x32_bf16 v[48:51], v[212:215], v[160:163], v[48:51]
	v_mfma_f32_16x16x32_bf16 v[36:39], v[202:205], v[168:171], v[36:39]
	v_mfma_f32_16x16x32_bf16 v[28:31], v[212:215], v[168:171], v[28:31]
	v_mfma_f32_16x16x32_bf16 v[20:23], v[202:205], v[186:189], v[20:23]
	v_mfma_f32_16x16x32_bf16 v[12:15], v[212:215], v[186:189], v[12:15]
	v_mfma_f32_16x16x32_bf16 v[4:7], v[202:205], v[194:197], v[4:7]
	v_mfma_f32_16x16x32_bf16 v[0:3], v[212:215], v[194:197], v[0:3]
	v_mfma_f32_16x16x32_bf16 v[52:55], v[206:209], v[164:167], v[52:55]
	v_mfma_f32_16x16x32_bf16 v[48:51], v[216:219], v[164:167], v[48:51]
	v_mfma_f32_16x16x32_bf16 v[36:39], v[206:209], v[182:185], v[36:39]
	v_mfma_f32_16x16x32_bf16 v[28:31], v[216:219], v[182:185], v[28:31]
	v_mfma_f32_16x16x32_bf16 v[20:23], v[206:209], v[190:193], v[20:23]
	v_mfma_f32_16x16x32_bf16 v[12:15], v[216:219], v[190:193], v[12:15]
	v_mfma_f32_16x16x32_bf16 v[4:7], v[206:209], v[198:201], v[4:7]
	v_mfma_f32_16x16x32_bf16 v[0:3], v[216:219], v[198:201], v[0:3]
	s_barrier
	s_setprio 0
	s_add_i32 s66, 0, 0x18000
	v_add_u32_e32 v156, s66, v176
	ds_read_b128 v[144:147], v156
	ds_read_b128 v[148:151], v156 offset:1024
	ds_read_b128 v[152:155], v156 offset:2048
	ds_read_b128 v[156:159], v156 offset:3072
	s_add_u32 s48, s48, 0x100000
	s_addc_u32 s49, s49, 0
	s_mov_b32 m0, s52
	v_lshl_add_u64 v[202:203], s[48:49], 0, v[128:129]
	ds_read_b128 v[160:163], v179 offset:32768
	ds_read_b128 v[164:167], v179 offset:33792
	ds_read_b128 v[168:171], v179 offset:34816
	ds_read_b128 v[182:185], v179 offset:35840
	ds_read_b128 v[186:189], v179 offset:36864
	ds_read_b128 v[190:193], v179 offset:37888
	ds_read_b128 v[194:197], v179 offset:38912
	ds_read_b128 v[198:201], v179 offset:39936
	global_load_lds_dwordx4 v[202:203], off
	v_lshl_add_u64 v[202:203], s[48:49], 0, v[132:133]
	s_mov_b32 m0, s53
	s_nop 0
	global_load_lds_dwordx4 v[202:203], off
	s_waitcnt lgkmcnt(8)
	s_setprio 1
	s_barrier
	s_waitcnt lgkmcnt(0)
	v_mfma_f32_16x16x32_bf16 v[124:127], v[144:147], v[160:163], v[124:127]
	v_mfma_f32_16x16x32_bf16 v[120:123], v[152:155], v[160:163], v[120:123]
	v_mfma_f32_16x16x32_bf16 v[108:111], v[144:147], v[168:171], v[108:111]
	v_mfma_f32_16x16x32_bf16 v[104:107], v[152:155], v[168:171], v[104:107]
	v_mfma_f32_16x16x32_bf16 v[96:99], v[144:147], v[186:189], v[96:99]
	v_mfma_f32_16x16x32_bf16 v[88:91], v[152:155], v[186:189], v[88:91]
	v_mfma_f32_16x16x32_bf16 v[80:83], v[144:147], v[194:197], v[80:83]
	v_mfma_f32_16x16x32_bf16 v[72:75], v[152:155], v[194:197], v[72:75]
	v_mfma_f32_16x16x32_bf16 v[124:127], v[148:151], v[164:167], v[124:127]
	v_mfma_f32_16x16x32_bf16 v[120:123], v[156:159], v[164:167], v[120:123]
	v_mfma_f32_16x16x32_bf16 v[108:111], v[148:151], v[182:185], v[108:111]
	v_mfma_f32_16x16x32_bf16 v[104:107], v[156:159], v[182:185], v[104:107]
	v_mfma_f32_16x16x32_bf16 v[96:99], v[148:151], v[190:193], v[96:99]
	v_mfma_f32_16x16x32_bf16 v[88:91], v[156:159], v[190:193], v[88:91]
	v_mfma_f32_16x16x32_bf16 v[80:83], v[148:151], v[198:201], v[80:83]
	v_mfma_f32_16x16x32_bf16 v[72:75], v[156:159], v[198:201], v[72:75]
	s_barrier
	s_setprio 0
	s_add_i32 s48, 0, 0x1c000
	s_add_i32 s49, s66, s50
	v_add_u32_e32 v181, s48, v176
	v_lshl_add_u64 v[172:173], v[172:173], 0, s[0:1]
	s_mov_b32 m0, s49
	ds_read_b128 v[202:205], v181
	ds_read_b128 v[206:209], v181 offset:1024
	ds_read_b128 v[212:215], v181 offset:2048
	ds_read_b128 v[216:219], v181 offset:3072
	global_load_lds_dwordx4 v[172:173], off
	v_lshl_add_u64 v[172:173], v[220:221], 0, s[0:1]
	s_add_i32 m0, s49, 0x2000
	s_nop 0
	global_load_lds_dwordx4 v[172:173], off
	s_setprio 1
	s_barrier
	s_waitcnt lgkmcnt(0)
	v_mfma_f32_16x16x32_bf16 v[116:119], v[202:205], v[160:163], v[116:119]
	v_mfma_f32_16x16x32_bf16 v[112:115], v[212:215], v[160:163], v[112:115]
	v_mfma_f32_16x16x32_bf16 v[100:103], v[202:205], v[168:171], v[100:103]
	v_mfma_f32_16x16x32_bf16 v[92:95], v[212:215], v[168:171], v[92:95]
	v_mfma_f32_16x16x32_bf16 v[84:87], v[202:205], v[186:189], v[84:87]
	v_mfma_f32_16x16x32_bf16 v[76:79], v[212:215], v[186:189], v[76:79]
	v_mfma_f32_16x16x32_bf16 v[68:71], v[202:205], v[194:197], v[68:71]
	v_mfma_f32_16x16x32_bf16 v[64:67], v[212:215], v[194:197], v[64:67]
	v_mfma_f32_16x16x32_bf16 v[116:119], v[206:209], v[164:167], v[116:119]
	v_mfma_f32_16x16x32_bf16 v[112:115], v[216:219], v[164:167], v[112:115]
	v_mfma_f32_16x16x32_bf16 v[100:103], v[206:209], v[182:185], v[100:103]
	v_mfma_f32_16x16x32_bf16 v[92:95], v[216:219], v[182:185], v[92:95]
	v_mfma_f32_16x16x32_bf16 v[84:87], v[206:209], v[190:193], v[84:87]
	v_mfma_f32_16x16x32_bf16 v[76:79], v[216:219], v[190:193], v[76:79]
	v_mfma_f32_16x16x32_bf16 v[68:71], v[206:209], v[198:201], v[68:71]
	v_mfma_f32_16x16x32_bf16 v[64:67], v[216:219], v[198:201], v[64:67]
	s_barrier
	s_setprio 0
	s_mov_b32 m0, s55
	v_lshl_add_u64 v[172:173], v[222:223], 0, s[0:1]
	ds_read_b128 v[160:163], v179 offset:49152
	ds_read_b128 v[164:167], v179 offset:50176
	ds_read_b128 v[168:171], v179 offset:51200
	ds_read_b128 v[182:185], v179 offset:52224
	ds_read_b128 v[186:189], v179 offset:53248
	ds_read_b128 v[190:193], v179 offset:54272
	ds_read_b128 v[194:197], v179 offset:55296
	ds_read_b128 v[198:201], v179 offset:56320
	global_load_lds_dwordx4 v[172:173], off
	v_lshl_add_u64 v[172:173], v[224:225], 0, s[0:1]
	s_mov_b32 m0, s56
	s_nop 0
	global_load_lds_dwordx4 v[172:173], off
	s_setprio 1
	s_barrier
	s_waitcnt lgkmcnt(0)
	v_mfma_f32_16x16x32_bf16 v[60:63], v[144:147], v[160:163], v[60:63]
	v_mfma_f32_16x16x32_bf16 v[56:59], v[152:155], v[160:163], v[56:59]
	v_mfma_f32_16x16x32_bf16 v[44:47], v[144:147], v[168:171], v[44:47]
	v_mfma_f32_16x16x32_bf16 v[40:43], v[152:155], v[168:171], v[40:43]
	v_mfma_f32_16x16x32_bf16 v[32:35], v[144:147], v[186:189], v[32:35]
	v_mfma_f32_16x16x32_bf16 v[24:27], v[152:155], v[186:189], v[24:27]
	v_mfma_f32_16x16x32_bf16 v[16:19], v[144:147], v[194:197], v[16:19]
	v_mfma_f32_16x16x32_bf16 v[8:11], v[152:155], v[194:197], v[8:11]
	v_mfma_f32_16x16x32_bf16 v[60:63], v[148:151], v[164:167], v[60:63]
	v_mfma_f32_16x16x32_bf16 v[56:59], v[156:159], v[164:167], v[56:59]
	v_mfma_f32_16x16x32_bf16 v[44:47], v[148:151], v[182:185], v[44:47]
	v_mfma_f32_16x16x32_bf16 v[40:43], v[156:159], v[182:185], v[40:43]
	v_mfma_f32_16x16x32_bf16 v[32:35], v[148:151], v[190:193], v[32:35]
	v_mfma_f32_16x16x32_bf16 v[24:27], v[156:159], v[190:193], v[24:27]
	v_mfma_f32_16x16x32_bf16 v[16:19], v[148:151], v[198:201], v[16:19]
	v_mfma_f32_16x16x32_bf16 v[8:11], v[156:159], v[198:201], v[8:11]
	s_barrier
	s_setprio 0
	s_add_u32 s42, s42, 0x100080
	s_addc_u32 s43, s43, 0
	s_add_i32 s48, s48, s50
	v_lshl_add_u64 v[144:145], s[42:43], 0, v[130:131]
	s_mov_b32 m0, s48
	s_nop 0
	global_load_lds_dwordx4 v[144:145], off
	v_lshl_add_u64 v[144:145], s[42:43], 0, v[134:135]
	s_add_i32 m0, s48, 0x2000
	s_nop 0
	global_load_lds_dwordx4 v[144:145], off
	s_waitcnt vmcnt(6)
	s_setprio 1
	s_barrier
	v_mfma_f32_16x16x32_bf16 v[52:55], v[202:205], v[160:163], v[52:55]
	v_mfma_f32_16x16x32_bf16 v[48:51], v[212:215], v[160:163], v[48:51]
	v_mfma_f32_16x16x32_bf16 v[36:39], v[202:205], v[168:171], v[36:39]
	v_mfma_f32_16x16x32_bf16 v[28:31], v[212:215], v[168:171], v[28:31]
	v_mfma_f32_16x16x32_bf16 v[20:23], v[202:205], v[186:189], v[20:23]
	v_mfma_f32_16x16x32_bf16 v[12:15], v[212:215], v[186:189], v[12:15]
	v_mfma_f32_16x16x32_bf16 v[4:7], v[202:205], v[194:197], v[4:7]
	v_mfma_f32_16x16x32_bf16 v[0:3], v[212:215], v[194:197], v[0:3]
	v_mfma_f32_16x16x32_bf16 v[52:55], v[206:209], v[164:167], v[52:55]
	v_mfma_f32_16x16x32_bf16 v[48:51], v[216:219], v[164:167], v[48:51]
	v_mfma_f32_16x16x32_bf16 v[36:39], v[206:209], v[182:185], v[36:39]
	v_mfma_f32_16x16x32_bf16 v[28:31], v[216:219], v[182:185], v[28:31]
	v_mfma_f32_16x16x32_bf16 v[20:23], v[206:209], v[190:193], v[20:23]
	v_mfma_f32_16x16x32_bf16 v[12:15], v[216:219], v[190:193], v[12:15]
	v_mfma_f32_16x16x32_bf16 v[4:7], v[206:209], v[198:201], v[4:7]
	v_mfma_f32_16x16x32_bf16 v[0:3], v[216:219], v[198:201], v[0:3]
	s_barrier
	s_setprio 0
	s_add_i32 s65, s65, 2
	s_add_u32 s40, s40, 0x100
	s_addc_u32 s41, s41, 0
	s_add_u32 s63, s63, 0x100
	s_addc_u32 s64, s64, 0
	s_cmp_gt_u32 s65, 61
	s_cbranch_scc0 .LBB0_896
	v_lshl_or_b32 v144, s38, 8, v177
	v_lshl_add_u32 v150, s36, 8, v175
	v_ashrrev_i32_e32 v145, 31, v144
	v_ashrrev_i32_e32 v151, 31, v150
	v_lshlrev_b64 v[144:145], 1, v[144:145]
	v_lshl_add_u64 v[146:147], s[90:91], 0, v[144:145]
	v_lshlrev_b64 v[148:149], 11, v[150:151]
	v_lshl_add_u64 v[152:153], v[146:147], 0, v[148:149]
	global_load_dwordx4 v[156:159], v[152:153], off
	global_load_dwordx4 v[160:163], v[152:153], off offset:256
	v_or_b32_e32 v152, 16, v150
	v_ashrrev_i32_e32 v153, 31, v152
	v_lshlrev_b64 v[170:171], 11, v[152:153]
	v_lshl_add_u64 v[152:153], v[146:147], 0, v[170:171]
	global_load_dwordx4 v[164:167], v[152:153], off
	global_load_dwordx4 v[182:185], v[152:153], off offset:256
	v_or_b32_e32 v152, 32, v150
	v_ashrrev_i32_e32 v153, 31, v152
	v_lshlrev_b64 v[154:155], 11, v[152:153]
	v_lshl_add_u64 v[152:153], v[146:147], 0, v[154:155]
	global_load_dwordx4 v[186:189], v[152:153], off
	global_load_dwordx4 v[190:193], v[152:153], off offset:256
	v_or_b32_e32 v152, 48, v150
	v_ashrrev_i32_e32 v153, 31, v152
	v_lshlrev_b64 v[152:153], 11, v[152:153]
	v_lshl_add_u64 v[168:169], v[146:147], 0, v[152:153]
	global_load_dwordx4 v[194:197], v[168:169], off
	global_load_dwordx4 v[198:201], v[168:169], off offset:256
	s_waitcnt vmcnt(0)
	v_lshlrev_b32_e32 v202, 16, v156
	v_and_b32_e32 v203, 0xffff0000, v156
	v_lshlrev_b32_e32 v204, 16, v157
	v_and_b32_e32 v205, 0xffff0000, v157
	v_lshlrev_b32_e32 v206, 16, v158
	v_and_b32_e32 v207, 0xffff0000, v158
	v_lshlrev_b32_e32 v208, 16, v159
	v_and_b32_e32 v209, 0xffff0000, v159
	v_pk_add_f32 v[126:127], v[126:127], v[204:205]
	v_pk_add_f32 v[124:125], v[124:125], v[202:203]
	v_lshlrev_b32_e32 v224, 16, v166
	v_and_b32_e32 v225, 0xffff0000, v166
	v_lshlrev_b32_e32 v226, 16, v167
	v_and_b32_e32 v227, 0xffff0000, v167
	v_lshlrev_b32_e32 v212, 16, v160
	v_lshlrev_b32_e32 v166, 16, v194
	v_and_b32_e32 v167, 0xffff0000, v194
	v_lshlrev_b32_e32 v172, 16, v195
	v_and_b32_e32 v173, 0xffff0000, v195
	v_pk_add_f32 v[194:195], v[122:123], v[208:209]
	v_pk_add_f32 v[122:123], v[120:121], v[206:207]
	v_mul_f32_e32 v120, v125, v125
	v_mul_f32_e32 v121, v127, v127
	v_fmac_f32_e32 v120, v124, v124
	v_fmac_f32_e32 v121, v126, v126
	v_add_f32_e32 v120, v120, v121
	v_mul_f32_e32 v121, v123, v123
	v_fmac_f32_e32 v121, v122, v122
	v_add_f32_e32 v120, v121, v120
	v_mul_f32_e32 v121, v195, v195
	v_fmac_f32_e32 v121, v194, v194
	v_and_b32_e32 v213, 0xffff0000, v160
	v_lshlrev_b32_e32 v214, 16, v161
	v_and_b32_e32 v215, 0xffff0000, v161
	v_add_f32_e32 v181, v121, v120
	v_cvt_pk_bf16_f32 v120, v124, v125
	v_lshl_add_u64 v[124:125], s[10:11], 0, v[148:149]
	v_lshlrev_b32_e32 v216, 16, v162
	v_and_b32_e32 v217, 0xffff0000, v162
	v_lshlrev_b32_e32 v218, 16, v163
	v_and_b32_e32 v219, 0xffff0000, v163
	v_cvt_pk_bf16_f32 v121, v126, v127
	v_lshl_add_u64 v[124:125], v[124:125], 0, v[144:145]
	v_pk_add_f32 v[118:119], v[118:119], v[214:215]
	v_pk_add_f32 v[116:117], v[116:117], v[212:213]
	v_cvt_pk_bf16_f32 v122, v122, v123
	v_cvt_pk_bf16_f32 v123, v194, v195
	global_store_dwordx4 v[124:125], v[120:123], off
	v_lshlrev_b32_e32 v220, 16, v164
	v_and_b32_e32 v221, 0xffff0000, v164
	v_pk_add_f32 v[120:121], v[114:115], v[218:219]
	v_pk_add_f32 v[114:115], v[112:113], v[216:217]
	v_mul_f32_e32 v112, v117, v117
	v_mul_f32_e32 v113, v119, v119
	v_fmac_f32_e32 v112, v116, v116
	v_fmac_f32_e32 v113, v118, v118
	v_add_f32_e32 v112, v112, v113
	v_mul_f32_e32 v113, v115, v115
	v_fmac_f32_e32 v113, v114, v114
	v_add_f32_e32 v112, v113, v112
	v_mul_f32_e32 v113, v121, v121
	v_fmac_f32_e32 v113, v120, v120
	v_add_f32_e32 v112, v113, v112
	v_lshlrev_b32_e32 v222, 16, v165
	v_and_b32_e32 v223, 0xffff0000, v165
	v_add_f32_e32 v126, v181, v112
	v_cvt_pk_bf16_f32 v112, v116, v117
	v_cvt_pk_bf16_f32 v113, v118, v119
	v_lshl_add_u64 v[116:117], s[10:11], 0, v[170:171]
	v_lshlrev_b32_e32 v230, 16, v184
	v_and_b32_e32 v231, 0xffff0000, v184
	v_lshlrev_b32_e32 v232, 16, v186
	v_and_b32_e32 v233, 0xffff0000, v186
	v_lshlrev_b32_e32 v186, 16, v187
	v_and_b32_e32 v187, 0xffff0000, v187
	v_cvt_pk_bf16_f32 v114, v114, v115
	v_cvt_pk_bf16_f32 v115, v120, v121
	global_store_dwordx4 v[124:125], v[112:115], off offset:256
	v_pk_add_f32 v[110:111], v[110:111], v[222:223]
	v_pk_add_f32 v[108:109], v[108:109], v[220:221]
	v_lshl_add_u64 v[118:119], v[116:117], 0, v[144:145]
	v_cvt_pk_bf16_f32 v112, v108, v109
	v_cvt_pk_bf16_f32 v113, v110, v111
	v_lshlrev_b32_e32 v228, 16, v182
	v_and_b32_e32 v229, 0xffff0000, v182
	v_lshlrev_b32_e32 v182, 16, v183
	v_and_b32_e32 v183, 0xffff0000, v183
	v_lshlrev_b32_e32 v184, 16, v185
	v_and_b32_e32 v185, 0xffff0000, v185
	v_lshlrev_b32_e32 v238, 16, v192
	v_and_b32_e32 v239, 0xffff0000, v192
	v_pk_add_f32 v[106:107], v[106:107], v[226:227]
	v_pk_add_f32 v[104:105], v[104:105], v[224:225]
	v_lshlrev_b32_e32 v156, 16, v200
	v_cvt_pk_bf16_f32 v114, v104, v105
	v_cvt_pk_bf16_f32 v115, v106, v107
	global_store_dwordx4 v[118:119], v[112:115], off
	v_and_b32_e32 v157, 0xffff0000, v200
	v_pk_add_f32 v[102:103], v[102:103], v[182:183]
	v_pk_add_f32 v[112:113], v[92:93], v[230:231]
	v_pk_add_f32 v[92:93], v[98:99], v[186:187]
	v_lshl_add_u64 v[98:99], s[10:11], 0, v[154:155]
	v_pk_add_f32 v[100:101], v[100:101], v[228:229]
	v_pk_add_f32 v[94:95], v[94:95], v[184:185]
	v_cvt_pk_bf16_f32 v114, v100, v101
	v_cvt_pk_bf16_f32 v115, v102, v103
	v_cvt_pk_bf16_f32 v116, v112, v113
	v_lshlrev_b32_e32 v234, 16, v188
	v_cvt_pk_bf16_f32 v117, v94, v95
	global_store_dwordx4 v[118:119], v[114:117], off offset:256
	v_lshl_add_u64 v[118:119], v[98:99], 0, v[144:145]
	v_pk_add_f32 v[98:99], v[76:77], v[238:239]
	v_pk_add_f32 v[76:77], v[82:83], v[172:173]
	v_lshl_add_u64 v[82:83], s[10:11], 0, v[152:153]
	v_lshl_add_u64 v[122:123], v[82:83], 0, v[144:145]
	v_pk_add_f32 v[82:83], v[64:65], v[156:157]
	v_and_b32_e32 v65, 64, v174
	v_and_b32_e32 v235, 0xffff0000, v188
	v_lshlrev_b32_e32 v188, 16, v189
	v_and_b32_e32 v189, 0xffff0000, v189
	v_lshlrev_b32_e32 v236, 16, v190
	v_and_b32_e32 v237, 0xffff0000, v190
	v_pk_add_f32 v[96:97], v[96:97], v[232:233]
	v_xor_b32_e32 v64, 16, v174
	v_cvt_pk_bf16_f32 v114, v96, v97
	v_add_u32_e32 v65, 64, v65
	v_lshlrev_b32_e32 v190, 16, v191
	v_and_b32_e32 v191, 0xffff0000, v191
	v_lshlrev_b32_e32 v192, 16, v193
	v_and_b32_e32 v193, 0xffff0000, v193
	v_pk_add_f32 v[90:91], v[90:91], v[188:189]
	v_pk_add_f32 v[88:89], v[88:89], v[234:235]
	v_cvt_pk_bf16_f32 v115, v92, v93
	v_pk_add_f32 v[84:85], v[84:85], v[236:237]
	v_cvt_pk_bf16_f32 v116, v88, v89
	v_cvt_pk_bf16_f32 v117, v90, v91
	global_store_dwordx4 v[118:119], v[114:117], off
	v_cmp_lt_i32_e32 vcc, v64, v65
	v_lshlrev_b32_e32 v164, 16, v196
	v_cvt_pk_bf16_f32 v114, v84, v85
	v_and_b32_e32 v165, 0xffff0000, v196
	v_lshlrev_b32_e32 v168, 16, v197
	v_and_b32_e32 v169, 0xffff0000, v197
	v_pk_add_f32 v[86:87], v[86:87], v[190:191]
	v_pk_add_f32 v[78:79], v[78:79], v[192:193]
	v_cvt_pk_bf16_f32 v115, v86, v87
	v_cvt_pk_bf16_f32 v116, v98, v99
	v_pk_add_f32 v[80:81], v[80:81], v[166:167]
	v_cvt_pk_bf16_f32 v117, v78, v79
	global_store_dwordx4 v[118:119], v[114:117], off offset:256
	v_cndmask_b32_e32 v64, v174, v64, vcc
	v_pk_add_f32 v[74:75], v[74:75], v[168:169]
	v_cvt_pk_bf16_f32 v114, v80, v81
	v_pk_add_f32 v[72:73], v[72:73], v[164:165]
	v_cvt_pk_bf16_f32 v115, v76, v77
	v_lshlrev_b32_e32 v158, 16, v198
	v_cvt_pk_bf16_f32 v116, v72, v73
	v_cvt_pk_bf16_f32 v117, v74, v75
	global_store_dwordx4 v[122:123], v[114:117], off
	v_and_b32_e32 v159, 0xffff0000, v198
	v_lshlrev_b32_e32 v162, 16, v199
	v_lshlrev_b32_e32 v114, 2, v64
	ds_bpermute_b32 v64, v114, v126
	v_xor_b32_e32 v115, 32, v174
	v_cmp_lt_i32_e32 vcc, v115, v65
	v_and_b32_e32 v163, 0xffff0000, v199
	v_lshlrev_b32_e32 v160, 16, v201
	v_cndmask_b32_e32 v65, v174, v115, vcc
	v_lshlrev_b32_e32 v115, 2, v65
	s_waitcnt lgkmcnt(0)
	v_add_f32_e32 v116, v126, v64
	ds_bpermute_b32 v117, v115, v116
	v_and_b32_e32 v161, 0xffff0000, v201
	v_pk_add_f32 v[70:71], v[70:71], v[162:163]
	v_pk_add_f32 v[68:69], v[68:69], v[158:159]
	v_pk_add_f32 v[66:67], v[66:67], v[160:161]
	v_lshl_add_u64 v[64:65], v[150:151], 2, s[18:19]
	v_cvt_pk_bf16_f32 v118, v68, v69
	v_cvt_pk_bf16_f32 v119, v70, v71
	v_cvt_pk_bf16_f32 v120, v82, v83
	v_cvt_pk_bf16_f32 v121, v66, v67
	global_store_dwordx4 v[122:123], v[118:121], off offset:256
	s_and_saveexec_b64 s[36:37], s[6:7]
	s_cbranch_execz .LBB0_899
	s_waitcnt lgkmcnt(0)
	v_add_f32_e32 v116, v116, v117
	global_atomic_add_f32 v[64:65], v116, off

.LBB0_946:
	ds_read_b128 v[144:147], v153
	ds_read_b128 v[158:161], v153 offset:1024
	ds_read_b128 v[162:165], v153 offset:2048
	ds_read_b128 v[166:169], v153 offset:3072
	s_add_u32 s28, s2, 0xfffc0080
	s_addc_u32 s29, s3, -1
	s_cmp_eq_u32 s58, 12
	s_cselect_b32 s31, s23, s29
	s_cselect_b32 s30, s54, s28
	s_cselect_b32 s29, s21, s57
	s_cselect_b32 s28, s55, s56
	v_lshl_add_u64 v[148:149], s[2:3], 0, v[136:137]
	s_add_i32 m0, s37, 0xc000
	ds_read_b128 v[170:173], v154
	ds_read_b128 v[176:179], v154 offset:1024
	ds_read_b128 v[180:183], v154 offset:2048
	ds_read_b128 v[184:187], v154 offset:3072
	ds_read_b128 v[188:191], v154 offset:4096
	ds_read_b128 v[192:195], v154 offset:5120
	ds_read_b128 v[196:199], v154 offset:6144
	ds_read_b128 v[200:203], v154 offset:7168
	global_load_lds_dwordx4 v[148:149], off
	v_lshl_add_u64 v[148:149], s[2:3], 0, v[138:139]
	s_add_i32 m0, s37, 0xe000
	s_nop 0
	global_load_lds_dwordx4 v[148:149], off
	s_waitcnt lgkmcnt(8)
	s_setprio 1
	s_barrier
	s_waitcnt lgkmcnt(0)
	v_mfma_f32_16x16x32_bf16 v[124:127], v[144:147], v[170:173], v[124:127]
	v_mfma_f32_16x16x32_bf16 v[120:123], v[162:165], v[170:173], v[120:123]
	v_mfma_f32_16x16x32_bf16 v[116:119], v[144:147], v[180:183], v[116:119]
	v_mfma_f32_16x16x32_bf16 v[112:115], v[162:165], v[180:183], v[112:115]
	v_mfma_f32_16x16x32_bf16 v[104:107], v[144:147], v[188:191], v[104:107]
	v_mfma_f32_16x16x32_bf16 v[96:99], v[162:165], v[188:191], v[96:99]
	v_mfma_f32_16x16x32_bf16 v[76:79], v[144:147], v[196:199], v[76:79]
	v_mfma_f32_16x16x32_bf16 v[72:75], v[162:165], v[196:199], v[72:75]
	v_mfma_f32_16x16x32_bf16 v[124:127], v[158:161], v[176:179], v[124:127]
	v_mfma_f32_16x16x32_bf16 v[120:123], v[166:169], v[176:179], v[120:123]
	v_mfma_f32_16x16x32_bf16 v[116:119], v[158:161], v[184:187], v[116:119]
	v_mfma_f32_16x16x32_bf16 v[112:115], v[166:169], v[184:187], v[112:115]
	v_mfma_f32_16x16x32_bf16 v[104:107], v[158:161], v[192:195], v[104:107]
	v_mfma_f32_16x16x32_bf16 v[96:99], v[166:169], v[192:195], v[96:99]
	v_mfma_f32_16x16x32_bf16 v[76:79], v[158:161], v[200:203], v[76:79]
	v_mfma_f32_16x16x32_bf16 v[72:75], v[166:169], v[200:203], v[72:75]
	s_barrier
	s_setprio 0
	s_add_i32 s59, s50, s34
	v_lshl_add_u64 v[148:149], s[28:29], 0, v[132:133]
	s_mov_b32 m0, s59
	ds_read_b128 v[204:207], v155
	ds_read_b128 v[212:215], v155 offset:1024
	ds_read_b128 v[216:219], v155 offset:2048
	ds_read_b128 v[220:223], v155 offset:3072
	global_load_lds_dwordx4 v[148:149], off
	v_lshl_add_u64 v[208:209], s[28:29], 0, v[128:129]
	s_add_i32 m0, s59, 0x2000
	s_nop 0
	global_load_lds_dwordx4 v[208:209], off
	s_setprio 1
	s_barrier
	s_waitcnt lgkmcnt(0)
	v_mfma_f32_16x16x32_bf16 v[108:111], v[204:207], v[170:173], v[108:111]
	v_mfma_f32_16x16x32_bf16 v[100:103], v[216:219], v[170:173], v[100:103]
	v_mfma_f32_16x16x32_bf16 v[92:95], v[204:207], v[180:183], v[92:95]
	v_mfma_f32_16x16x32_bf16 v[88:91], v[216:219], v[180:183], v[88:91]
	v_mfma_f32_16x16x32_bf16 v[84:87], v[204:207], v[188:191], v[84:87]
	v_mfma_f32_16x16x32_bf16 v[80:83], v[216:219], v[188:191], v[80:83]
	v_mfma_f32_16x16x32_bf16 v[68:71], v[204:207], v[196:199], v[68:71]
	v_mfma_f32_16x16x32_bf16 v[64:67], v[216:219], v[196:199], v[64:67]
	v_mfma_f32_16x16x32_bf16 v[108:111], v[212:215], v[176:179], v[108:111]
	v_mfma_f32_16x16x32_bf16 v[100:103], v[220:223], v[176:179], v[100:103]
	v_mfma_f32_16x16x32_bf16 v[92:95], v[212:215], v[184:187], v[92:95]
	v_mfma_f32_16x16x32_bf16 v[88:91], v[220:223], v[184:187], v[88:91]
	v_mfma_f32_16x16x32_bf16 v[84:87], v[212:215], v[192:195], v[84:87]
	v_mfma_f32_16x16x32_bf16 v[80:83], v[220:223], v[192:195], v[80:83]
	v_mfma_f32_16x16x32_bf16 v[68:71], v[212:215], v[200:203], v[68:71]
	v_mfma_f32_16x16x32_bf16 v[64:67], v[220:223], v[200:203], v[64:67]
	s_barrier
	s_setprio 0
	s_mov_b32 m0, s37
	v_lshl_add_u64 v[224:225], s[30:31], 0, v[134:135]
	ds_read_b128 v[170:173], v154 offset:16384
	ds_read_b128 v[176:179], v154 offset:17408
	ds_read_b128 v[180:183], v154 offset:18432
	ds_read_b128 v[184:187], v154 offset:19456
	ds_read_b128 v[188:191], v154 offset:20480
	ds_read_b128 v[192:195], v154 offset:21504
	ds_read_b128 v[196:199], v154 offset:22528
	ds_read_b128 v[200:203], v154 offset:23552
	global_load_lds_dwordx4 v[224:225], off
	v_lshl_add_u64 v[226:227], s[30:31], 0, v[130:131]
	s_mov_b32 m0, s38
	s_nop 0
	global_load_lds_dwordx4 v[226:227], off
	s_setprio 1
	s_barrier
	s_waitcnt lgkmcnt(0)
	v_mfma_f32_16x16x32_bf16 v[60:63], v[144:147], v[170:173], v[60:63]
	v_mfma_f32_16x16x32_bf16 v[56:59], v[162:165], v[170:173], v[56:59]
	v_mfma_f32_16x16x32_bf16 v[44:47], v[144:147], v[180:183], v[44:47]
	v_mfma_f32_16x16x32_bf16 v[40:43], v[162:165], v[180:183], v[40:43]
	v_mfma_f32_16x16x32_bf16 v[28:31], v[144:147], v[188:191], v[28:31]
	v_mfma_f32_16x16x32_bf16 v[24:27], v[162:165], v[188:191], v[24:27]
	v_mfma_f32_16x16x32_bf16 v[12:15], v[144:147], v[196:199], v[12:15]
	v_mfma_f32_16x16x32_bf16 v[8:11], v[162:165], v[196:199], v[8:11]
	v_mfma_f32_16x16x32_bf16 v[60:63], v[158:161], v[176:179], v[60:63]
	v_mfma_f32_16x16x32_bf16 v[56:59], v[166:169], v[176:179], v[56:59]
	v_mfma_f32_16x16x32_bf16 v[44:47], v[158:161], v[184:187], v[44:47]
	v_mfma_f32_16x16x32_bf16 v[40:43], v[166:169], v[184:187], v[40:43]
	v_mfma_f32_16x16x32_bf16 v[28:31], v[158:161], v[192:195], v[28:31]
	v_mfma_f32_16x16x32_bf16 v[24:27], v[166:169], v[192:195], v[24:27]
	v_mfma_f32_16x16x32_bf16 v[12:15], v[158:161], v[200:203], v[12:15]
	v_mfma_f32_16x16x32_bf16 v[8:11], v[166:169], v[200:203], v[8:11]
	s_barrier
	s_setprio 0
	s_add_u32 s60, s28, 0x40000
	s_addc_u32 s61, s29, 0
	s_add_i32 s59, s51, s34
	v_lshl_add_u64 v[144:145], s[60:61], 0, v[132:133]
	s_mov_b32 m0, s59
	s_nop 0
	global_load_lds_dwordx4 v[144:145], off
	v_lshl_add_u64 v[144:145], s[60:61], 0, v[128:129]
	s_add_i32 m0, s59, 0x2000
	s_nop 0
	global_load_lds_dwordx4 v[144:145], off
	s_waitcnt vmcnt(6)
	s_setprio 1
	s_barrier
	v_mfma_f32_16x16x32_bf16 v[52:55], v[204:207], v[170:173], v[52:55]
	v_mfma_f32_16x16x32_bf16 v[48:51], v[216:219], v[170:173], v[48:51]
	v_mfma_f32_16x16x32_bf16 v[36:39], v[204:207], v[180:183], v[36:39]
	v_mfma_f32_16x16x32_bf16 v[32:35], v[216:219], v[180:183], v[32:35]
	v_mfma_f32_16x16x32_bf16 v[20:23], v[204:207], v[188:191], v[20:23]
	v_mfma_f32_16x16x32_bf16 v[16:19], v[216:219], v[188:191], v[16:19]
	v_mfma_f32_16x16x32_bf16 v[4:7], v[204:207], v[196:199], v[4:7]
	v_mfma_f32_16x16x32_bf16 v[0:3], v[216:219], v[196:199], v[0:3]
	v_mfma_f32_16x16x32_bf16 v[52:55], v[212:215], v[176:179], v[52:55]
	v_mfma_f32_16x16x32_bf16 v[48:51], v[220:223], v[176:179], v[48:51]
	v_mfma_f32_16x16x32_bf16 v[36:39], v[212:215], v[184:187], v[36:39]
	v_mfma_f32_16x16x32_bf16 v[32:35], v[220:223], v[184:187], v[32:35]
	v_mfma_f32_16x16x32_bf16 v[20:23], v[212:215], v[192:195], v[20:23]
	v_mfma_f32_16x16x32_bf16 v[16:19], v[220:223], v[192:195], v[16:19]
	v_mfma_f32_16x16x32_bf16 v[4:7], v[212:215], v[200:203], v[4:7]
	v_mfma_f32_16x16x32_bf16 v[0:3], v[220:223], v[200:203], v[0:3]
	s_barrier
	s_setprio 0
	s_add_i32 s59, 0, 0x18000
	v_add_u32_e32 v157, s59, v151
	ds_read_b128 v[144:147], v157
	ds_read_b128 v[158:161], v157 offset:1024
	ds_read_b128 v[162:165], v157 offset:2048
	ds_read_b128 v[166:169], v157 offset:3072
	s_add_u32 s30, s30, 0x40000
	s_addc_u32 s31, s31, 0
	s_mov_b32 m0, s39
	v_lshl_add_u64 v[204:205], s[30:31], 0, v[134:135]
	ds_read_b128 v[170:173], v154 offset:32768
	ds_read_b128 v[176:179], v154 offset:33792
	ds_read_b128 v[180:183], v154 offset:34816
	ds_read_b128 v[184:187], v154 offset:35840
	ds_read_b128 v[188:191], v154 offset:36864
	ds_read_b128 v[192:195], v154 offset:37888
	ds_read_b128 v[196:199], v154 offset:38912
	ds_read_b128 v[200:203], v154 offset:39936
	global_load_lds_dwordx4 v[204:205], off
	v_lshl_add_u64 v[204:205], s[30:31], 0, v[130:131]
	s_mov_b32 m0, s40
	s_nop 0
	global_load_lds_dwordx4 v[204:205], off
	s_waitcnt lgkmcnt(8)
	s_setprio 1
	s_barrier
	s_waitcnt lgkmcnt(0)
	v_mfma_f32_16x16x32_bf16 v[124:127], v[144:147], v[170:173], v[124:127]
	v_mfma_f32_16x16x32_bf16 v[120:123], v[162:165], v[170:173], v[120:123]
	v_mfma_f32_16x16x32_bf16 v[116:119], v[144:147], v[180:183], v[116:119]
	v_mfma_f32_16x16x32_bf16 v[112:115], v[162:165], v[180:183], v[112:115]
	v_mfma_f32_16x16x32_bf16 v[104:107], v[144:147], v[188:191], v[104:107]
	v_mfma_f32_16x16x32_bf16 v[96:99], v[162:165], v[188:191], v[96:99]
	v_mfma_f32_16x16x32_bf16 v[76:79], v[144:147], v[196:199], v[76:79]
	v_mfma_f32_16x16x32_bf16 v[72:75], v[162:165], v[196:199], v[72:75]
	v_mfma_f32_16x16x32_bf16 v[124:127], v[158:161], v[176:179], v[124:127]
	v_mfma_f32_16x16x32_bf16 v[120:123], v[166:169], v[176:179], v[120:123]
	v_mfma_f32_16x16x32_bf16 v[116:119], v[158:161], v[184:187], v[116:119]
	v_mfma_f32_16x16x32_bf16 v[112:115], v[166:169], v[184:187], v[112:115]
	v_mfma_f32_16x16x32_bf16 v[104:107], v[158:161], v[192:195], v[104:107]
	v_mfma_f32_16x16x32_bf16 v[96:99], v[166:169], v[192:195], v[96:99]
	v_mfma_f32_16x16x32_bf16 v[76:79], v[158:161], v[200:203], v[76:79]
	v_mfma_f32_16x16x32_bf16 v[72:75], v[166:169], v[200:203], v[72:75]
	s_barrier
	s_setprio 0
	s_add_i32 s30, 0, 0x1c000
	s_add_i32 s31, s59, s34
	v_add_u32_e32 v157, s30, v151
	v_lshl_add_u64 v[148:149], v[148:149], 0, s[8:9]
	s_mov_b32 m0, s31
	ds_read_b128 v[204:207], v157
	ds_read_b128 v[212:215], v157 offset:1024
	ds_read_b128 v[216:219], v157 offset:2048
	ds_read_b128 v[220:223], v157 offset:3072
	global_load_lds_dwordx4 v[148:149], off
	v_lshl_add_u64 v[148:149], v[208:209], 0, s[8:9]
	s_add_i32 m0, s31, 0x2000
	s_nop 0
	global_load_lds_dwordx4 v[148:149], off
	s_setprio 1
	s_barrier
	s_waitcnt lgkmcnt(0)
	v_mfma_f32_16x16x32_bf16 v[108:111], v[204:207], v[170:173], v[108:111]
	v_mfma_f32_16x16x32_bf16 v[100:103], v[216:219], v[170:173], v[100:103]
	v_mfma_f32_16x16x32_bf16 v[92:95], v[204:207], v[180:183], v[92:95]
	v_mfma_f32_16x16x32_bf16 v[88:91], v[216:219], v[180:183], v[88:91]
	v_mfma_f32_16x16x32_bf16 v[84:87], v[204:207], v[188:191], v[84:87]
	v_mfma_f32_16x16x32_bf16 v[80:83], v[216:219], v[188:191], v[80:83]
	v_mfma_f32_16x16x32_bf16 v[68:71], v[204:207], v[196:199], v[68:71]
	v_mfma_f32_16x16x32_bf16 v[64:67], v[216:219], v[196:199], v[64:67]
	v_mfma_f32_16x16x32_bf16 v[108:111], v[212:215], v[176:179], v[108:111]
	v_mfma_f32_16x16x32_bf16 v[100:103], v[220:223], v[176:179], v[100:103]
	v_mfma_f32_16x16x32_bf16 v[92:95], v[212:215], v[184:187], v[92:95]
	v_mfma_f32_16x16x32_bf16 v[88:91], v[220:223], v[184:187], v[88:91]
	v_mfma_f32_16x16x32_bf16 v[84:87], v[212:215], v[192:195], v[84:87]
	v_mfma_f32_16x16x32_bf16 v[80:83], v[220:223], v[192:195], v[80:83]
	v_mfma_f32_16x16x32_bf16 v[68:71], v[212:215], v[200:203], v[68:71]
	v_mfma_f32_16x16x32_bf16 v[64:67], v[220:223], v[200:203], v[64:67]
	s_barrier
	s_setprio 0
	s_mov_b32 m0, s42
	v_lshl_add_u64 v[148:149], v[224:225], 0, s[8:9]
	ds_read_b128 v[170:173], v154 offset:49152
	ds_read_b128 v[176:179], v154 offset:50176
	ds_read_b128 v[180:183], v154 offset:51200
	ds_read_b128 v[184:187], v154 offset:52224
	ds_read_b128 v[188:191], v154 offset:53248
	ds_read_b128 v[192:195], v154 offset:54272
	ds_read_b128 v[196:199], v154 offset:55296
	ds_read_b128 v[200:203], v154 offset:56320
	global_load_lds_dwordx4 v[148:149], off
	v_lshl_add_u64 v[148:149], v[226:227], 0, s[8:9]
	s_mov_b32 m0, s43
	s_nop 0
	global_load_lds_dwordx4 v[148:149], off
	s_setprio 1
	s_barrier
	s_waitcnt lgkmcnt(0)
	v_mfma_f32_16x16x32_bf16 v[60:63], v[144:147], v[170:173], v[60:63]
	v_mfma_f32_16x16x32_bf16 v[56:59], v[162:165], v[170:173], v[56:59]
	v_mfma_f32_16x16x32_bf16 v[44:47], v[144:147], v[180:183], v[44:47]
	v_mfma_f32_16x16x32_bf16 v[40:43], v[162:165], v[180:183], v[40:43]
	v_mfma_f32_16x16x32_bf16 v[28:31], v[144:147], v[188:191], v[28:31]
	v_mfma_f32_16x16x32_bf16 v[24:27], v[162:165], v[188:191], v[24:27]
	v_mfma_f32_16x16x32_bf16 v[12:15], v[144:147], v[196:199], v[12:15]
	v_mfma_f32_16x16x32_bf16 v[8:11], v[162:165], v[196:199], v[8:11]
	v_mfma_f32_16x16x32_bf16 v[60:63], v[158:161], v[176:179], v[60:63]
	v_mfma_f32_16x16x32_bf16 v[56:59], v[166:169], v[176:179], v[56:59]
	v_mfma_f32_16x16x32_bf16 v[44:47], v[158:161], v[184:187], v[44:47]
	v_mfma_f32_16x16x32_bf16 v[40:43], v[166:169], v[184:187], v[40:43]
	v_mfma_f32_16x16x32_bf16 v[28:31], v[158:161], v[192:195], v[28:31]
	v_mfma_f32_16x16x32_bf16 v[24:27], v[166:169], v[192:195], v[24:27]
	v_mfma_f32_16x16x32_bf16 v[12:15], v[158:161], v[200:203], v[12:15]
	v_mfma_f32_16x16x32_bf16 v[8:11], v[166:169], v[200:203], v[8:11]
	s_barrier
	s_setprio 0
	s_add_u32 s28, s28, 0x40080
	s_addc_u32 s29, s29, 0
	s_add_i32 s30, s30, s34
	v_lshl_add_u64 v[144:145], s[28:29], 0, v[132:133]
	s_mov_b32 m0, s30
	s_nop 0
	global_load_lds_dwordx4 v[144:145], off
	v_lshl_add_u64 v[144:145], s[28:29], 0, v[128:129]
	s_add_i32 m0, s30, 0x2000
	s_nop 0
	global_load_lds_dwordx4 v[144:145], off
	s_waitcnt vmcnt(6)
	s_setprio 1
	s_barrier
	v_mfma_f32_16x16x32_bf16 v[52:55], v[204:207], v[170:173], v[52:55]
	v_mfma_f32_16x16x32_bf16 v[48:51], v[216:219], v[170:173], v[48:51]
	v_mfma_f32_16x16x32_bf16 v[36:39], v[204:207], v[180:183], v[36:39]
	v_mfma_f32_16x16x32_bf16 v[32:35], v[216:219], v[180:183], v[32:35]
	v_mfma_f32_16x16x32_bf16 v[20:23], v[204:207], v[188:191], v[20:23]
	v_mfma_f32_16x16x32_bf16 v[16:19], v[216:219], v[188:191], v[16:19]
	v_mfma_f32_16x16x32_bf16 v[4:7], v[204:207], v[196:199], v[4:7]
	v_mfma_f32_16x16x32_bf16 v[0:3], v[216:219], v[196:199], v[0:3]
	v_mfma_f32_16x16x32_bf16 v[52:55], v[212:215], v[176:179], v[52:55]
	v_mfma_f32_16x16x32_bf16 v[48:51], v[220:223], v[176:179], v[48:51]
	v_mfma_f32_16x16x32_bf16 v[36:39], v[212:215], v[184:187], v[36:39]
	v_mfma_f32_16x16x32_bf16 v[32:35], v[220:223], v[184:187], v[32:35]
	v_mfma_f32_16x16x32_bf16 v[20:23], v[212:215], v[192:195], v[20:23]
	v_mfma_f32_16x16x32_bf16 v[16:19], v[220:223], v[192:195], v[16:19]
	v_mfma_f32_16x16x32_bf16 v[4:7], v[212:215], v[200:203], v[4:7]
	v_mfma_f32_16x16x32_bf16 v[0:3], v[220:223], v[200:203], v[0:3]
	s_barrier
	s_setprio 0
	s_add_i32 s58, s58, 2
	s_add_u32 s2, s2, 0x100
	s_addc_u32 s3, s3, 0
	s_add_u32 s56, s56, 0x100
	s_addc_u32 s57, s57, 0
	s_cmp_gt_u32 s58, 13
	s_cbranch_scc0 .LBB0_946
	v_lshl_add_u32 v144, s0, 8, v150
	v_ashrrev_i32_e32 v145, 31, v144
	v_lshl_add_u64 v[146:147], v[144:145], 2, s[18:19]
	global_load_dword v145, v[146:147], off
	global_load_dword v157, v[146:147], off offset:64
	global_load_dword v164, v[146:147], off offset:128
	global_load_dword v165, v[146:147], off offset:192
	global_load_dword v166, v[146:147], off offset:512
	global_load_dword v167, v[146:147], off offset:576
	global_load_dword v168, v[146:147], off offset:640
	global_load_dword v169, v[146:147], off offset:704
	v_mov_b64_e32 v[146:147], s[92:93]
	v_or_b32_e32 v160, 16, v144
	v_or_b32_e32 v162, 32, v144
	v_lshl_or_b32 v148, s1, 8, v152
	v_mad_i64_i32 v[158:159], s[0:1], v144, s52, v[146:147]
	v_mad_i64_i32 v[160:161], s[0:1], v160, s52, v[146:147]
	v_mad_i64_i32 v[162:163], s[0:1], v162, s52, v[146:147]
	v_ashrrev_i32_e32 v149, 31, v148
	v_lshlrev_b64 v[148:149], 1, v[148:149]
	v_lshl_add_u64 v[158:159], v[158:159], 0, v[148:149]
	v_lshl_add_u64 v[160:161], v[160:161], 0, v[148:149]
	v_lshl_add_u64 v[162:163], v[162:163], 0, v[148:149]
	v_add_u32_e32 v170, 0x80, v144
	s_mov_b64 s[28:29], s[26:27]
	s_waitcnt vmcnt(0)
	v_fmamk_f32 v145, v145, 0x3a800000, v156
	v_fmamk_f32 v157, v157, 0x3a800000, v156
	v_fmamk_f32 v164, v164, 0x3a800000, v156
	v_fmamk_f32 v171, v165, 0x3a800000, v156
	v_fmamk_f32 v172, v166, 0x3a800000, v156
	v_mul_f32_e32 v165, 0x4b800000, v145
	v_mul_f32_e32 v166, 0x4b800000, v157
	v_cmp_gt_f32_e32 vcc, s53, v145
	v_cmp_gt_f32_e64 s[0:1], s53, v157
	v_fmamk_f32 v173, v167, 0x3a800000, v156
	v_mul_f32_e32 v167, 0x4b800000, v164
	v_cndmask_b32_e32 v145, v145, v165, vcc
	v_cndmask_b32_e64 v157, v157, v166, s[0:1]
	v_cmp_gt_f32_e64 s[2:3], s53, v164
	v_rsq_f32_e32 v145, v145
	v_rsq_f32_e32 v157, v157
	v_cndmask_b32_e64 v164, v164, v167, s[2:3]
	v_rsq_f32_e32 v165, v164
	v_mul_f32_e32 v164, 0x45800000, v145
	v_mul_f32_e32 v166, 0x45800000, v157
	v_cndmask_b32_e32 v164, v145, v164, vcc
	v_mul_f32_e32 v167, 0x45800000, v165
	v_cndmask_b32_e64 v166, v157, v166, s[0:1]
	v_fmamk_f32 v175, v168, 0x3a800000, v156
	v_cndmask_b32_e64 v168, v165, v167, s[2:3]
	v_pk_mul_f32 v[126:127], v[126:127], v[164:165] op_sel_hi:[1,0]
	v_pk_mul_f32 v[124:125], v[124:125], v[164:165] op_sel_hi:[1,0]
	v_pk_mul_f32 v[122:123], v[122:123], v[164:165] op_sel_hi:[1,0]
	v_pk_mul_f32 v[120:121], v[120:121], v[164:165] op_sel_hi:[1,0]
	v_pk_mul_f32 v[110:111], v[110:111], v[164:165] op_sel_hi:[1,0]
	v_pk_mul_f32 v[108:109], v[108:109], v[164:165] op_sel_hi:[1,0]
	v_pk_mul_f32 v[102:103], v[102:103], v[164:165] op_sel_hi:[1,0]
	v_pk_mul_f32 v[100:101], v[100:101], v[164:165] op_sel_hi:[1,0]
	v_pk_mul_f32 v[118:119], v[118:119], v[166:167] op_sel_hi:[1,0]
	v_pk_mul_f32 v[116:117], v[116:117], v[166:167] op_sel_hi:[1,0]
	v_pk_mul_f32 v[114:115], v[114:115], v[166:167] op_sel_hi:[1,0]
	v_pk_mul_f32 v[112:113], v[112:113], v[166:167] op_sel_hi:[1,0]
	v_pk_mul_f32 v[94:95], v[94:95], v[166:167] op_sel_hi:[1,0]
	v_pk_mul_f32 v[92:93], v[92:93], v[166:167] op_sel_hi:[1,0]
	v_pk_mul_f32 v[164:165], v[90:91], v[166:167] op_sel_hi:[1,0]
	v_pk_mul_f32 v[166:167], v[88:89], v[166:167] op_sel_hi:[1,0]
	v_cvt_pk_bf16_f32 v88, v124, v125
	v_cvt_pk_bf16_f32 v89, v126, v127
	v_cvt_pk_bf16_f32 v90, v120, v121
	v_cvt_pk_bf16_f32 v91, v122, v123
	global_store_dwordx4 v[158:159], v[88:91], off nt
	v_fmamk_f32 v169, v169, 0x3a800000, v156
	v_pk_mul_f32 v[106:107], v[106:107], v[168:169] op_sel_hi:[1,0]
	v_cvt_pk_bf16_f32 v88, v108, v109
	v_cvt_pk_bf16_f32 v89, v110, v111
	v_cvt_pk_bf16_f32 v90, v100, v101
	v_cvt_pk_bf16_f32 v91, v102, v103
	global_store_dwordx4 v[158:159], v[88:91], off offset:256 nt
	v_pk_mul_f32 v[104:105], v[104:105], v[168:169] op_sel_hi:[1,0]
	v_pk_mul_f32 v[98:99], v[98:99], v[168:169] op_sel_hi:[1,0]
	v_cvt_pk_bf16_f32 v88, v116, v117
	v_cvt_pk_bf16_f32 v89, v118, v119
	v_cvt_pk_bf16_f32 v90, v112, v113
	v_cvt_pk_bf16_f32 v91, v114, v115
	global_store_dwordx4 v[160:161], v[88:91], off nt
	v_pk_mul_f32 v[96:97], v[96:97], v[168:169] op_sel_hi:[1,0]
	v_pk_mul_f32 v[86:87], v[86:87], v[168:169] op_sel_hi:[1,0]
	v_cvt_pk_bf16_f32 v88, v92, v93
	v_cvt_pk_bf16_f32 v89, v94, v95
	v_cvt_pk_bf16_f32 v90, v166, v167
	v_cvt_pk_bf16_f32 v91, v164, v165
	global_store_dwordx4 v[160:161], v[88:91], off offset:256 nt
	v_pk_mul_f32 v[84:85], v[84:85], v[168:169] op_sel_hi:[1,0]
	v_cmp_gt_f32_e32 vcc, s53, v171
	v_cvt_pk_bf16_f32 v88, v104, v105
	v_cvt_pk_bf16_f32 v89, v106, v107
	v_cvt_pk_bf16_f32 v90, v96, v97
	v_cvt_pk_bf16_f32 v91, v98, v99
	global_store_dwordx4 v[162:163], v[88:91], off nt
	s_mov_b64 s[2:3], s[24:25]
	s_nop 0
	v_pk_mul_f32 v[88:89], v[82:83], v[168:169] op_sel_hi:[1,0]
	v_pk_mul_f32 v[82:83], v[80:81], v[168:169] op_sel_hi:[1,0]
	v_cvt_pk_bf16_f32 v80, v84, v85
	v_cvt_pk_bf16_f32 v81, v86, v87
	s_nop 0
	v_cvt_pk_bf16_f32 v82, v82, v83
	v_cvt_pk_bf16_f32 v83, v88, v89
	global_store_dwordx4 v[162:163], v[80:83], off offset:256 nt
	s_nop 1
	v_mul_f32_e32 v81, 0x4b800000, v171
	v_cndmask_b32_e32 v81, v171, v81, vcc
	v_rsq_f32_e32 v82, v81
	v_or_b32_e32 v80, 48, v144
	v_mad_i64_i32 v[80:81], s[0:1], v80, s52, v[146:147]
	v_mul_f32_e32 v83, 0x45800000, v82
	v_cndmask_b32_e32 v82, v82, v83, vcc
	v_lshl_add_u64 v[80:81], v[80:81], 0, v[148:149]
	v_pk_mul_f32 v[78:79], v[78:79], v[82:83] op_sel_hi:[1,0]
	v_pk_mul_f32 v[76:77], v[76:77], v[82:83] op_sel_hi:[1,0]
	v_pk_mul_f32 v[84:85], v[74:75], v[82:83] op_sel_hi:[1,0]
	v_pk_mul_f32 v[74:75], v[72:73], v[82:83] op_sel_hi:[1,0]
	v_cvt_pk_bf16_f32 v72, v76, v77
	v_cvt_pk_bf16_f32 v73, v78, v79
	v_pk_mul_f32 v[68:69], v[68:69], v[82:83] op_sel_hi:[1,0]
	v_cvt_pk_bf16_f32 v74, v74, v75
	v_cvt_pk_bf16_f32 v75, v84, v85
	global_store_dwordx4 v[80:81], v[72:75], off nt
	v_pk_mul_f32 v[70:71], v[70:71], v[82:83] op_sel_hi:[1,0]
	v_cmp_gt_f32_e32 vcc, s53, v172
	v_pk_mul_f32 v[72:73], v[66:67], v[82:83] op_sel_hi:[1,0]
	v_pk_mul_f32 v[66:67], v[64:65], v[82:83] op_sel_hi:[1,0]
	v_cvt_pk_bf16_f32 v64, v68, v69
	v_cvt_pk_bf16_f32 v65, v70, v71
	s_nop 0
	v_cvt_pk_bf16_f32 v66, v66, v67
	v_cvt_pk_bf16_f32 v67, v72, v73
	global_store_dwordx4 v[80:81], v[64:67], off offset:256 nt
	s_nop 1
	v_mul_f32_e32 v64, 0x4b800000, v172
	v_cndmask_b32_e32 v64, v172, v64, vcc
	v_rsq_f32_e32 v66, v64
	v_mad_i64_i32 v[64:65], s[0:1], v170, s52, v[146:147]
	v_lshl_add_u64 v[64:65], v[64:65], 0, v[148:149]
	v_mul_f32_e32 v67, 0x45800000, v66
	v_cndmask_b32_e32 v66, v66, v67, vcc
	v_pk_mul_f32 v[62:63], v[62:63], v[66:67] op_sel_hi:[1,0]
	v_pk_mul_f32 v[60:61], v[60:61], v[66:67] op_sel_hi:[1,0]
	v_pk_mul_f32 v[68:69], v[58:59], v[66:67] op_sel_hi:[1,0]
	v_pk_mul_f32 v[58:59], v[56:57], v[66:67] op_sel_hi:[1,0]
	v_cvt_pk_bf16_f32 v56, v60, v61
	v_cvt_pk_bf16_f32 v57, v62, v63
	v_pk_mul_f32 v[54:55], v[54:55], v[66:67] op_sel_hi:[1,0]
	v_cvt_pk_bf16_f32 v58, v58, v59
	v_cvt_pk_bf16_f32 v59, v68, v69
	global_store_dwordx4 v[64:65], v[56:59], off nt
	v_pk_mul_f32 v[52:53], v[52:53], v[66:67] op_sel_hi:[1,0]
	v_cmp_gt_f32_e32 vcc, s53, v173
	v_pk_mul_f32 v[56:57], v[50:51], v[66:67] op_sel_hi:[1,0]
	v_pk_mul_f32 v[50:51], v[48:49], v[66:67] op_sel_hi:[1,0]
	v_cvt_pk_bf16_f32 v48, v52, v53
	v_cvt_pk_bf16_f32 v49, v54, v55
	s_nop 0
	v_cvt_pk_bf16_f32 v50, v50, v51
	v_cvt_pk_bf16_f32 v51, v56, v57
	global_store_dwordx4 v[64:65], v[48:51], off offset:256 nt
	s_nop 1
	v_mul_f32_e32 v49, 0x4b800000, v173
	v_cndmask_b32_e32 v49, v173, v49, vcc
	v_rsq_f32_e32 v50, v49
	v_add_u32_e32 v48, 0x90, v144
	v_mad_i64_i32 v[48:49], s[0:1], v48, s52, v[146:147]
	v_mul_f32_e32 v51, 0x45800000, v50
	v_cndmask_b32_e32 v50, v50, v51, vcc
	v_lshl_add_u64 v[48:49], v[48:49], 0, v[148:149]
	v_pk_mul_f32 v[46:47], v[46:47], v[50:51] op_sel_hi:[1,0]
	v_pk_mul_f32 v[44:45], v[44:45], v[50:51] op_sel_hi:[1,0]
	v_pk_mul_f32 v[52:53], v[42:43], v[50:51] op_sel_hi:[1,0]
	v_pk_mul_f32 v[42:43], v[40:41], v[50:51] op_sel_hi:[1,0]
	v_cvt_pk_bf16_f32 v40, v44, v45
	v_cvt_pk_bf16_f32 v41, v46, v47
	v_pk_mul_f32 v[38:39], v[38:39], v[50:51] op_sel_hi:[1,0]
	v_cvt_pk_bf16_f32 v42, v42, v43
	v_cvt_pk_bf16_f32 v43, v52, v53
	global_store_dwordx4 v[48:49], v[40:43], off nt
	v_pk_mul_f32 v[36:37], v[36:37], v[50:51] op_sel_hi:[1,0]
	v_cmp_gt_f32_e32 vcc, s53, v175
	v_pk_mul_f32 v[40:41], v[34:35], v[50:51] op_sel_hi:[1,0]
	v_pk_mul_f32 v[34:35], v[32:33], v[50:51] op_sel_hi:[1,0]
	v_cvt_pk_bf16_f32 v32, v36, v37
	v_cvt_pk_bf16_f32 v33, v38, v39
	s_nop 0
	v_cvt_pk_bf16_f32 v34, v34, v35
	v_cvt_pk_bf16_f32 v35, v40, v41
	global_store_dwordx4 v[48:49], v[32:35], off offset:256 nt
	s_nop 1
	v_mul_f32_e32 v33, 0x4b800000, v175
	v_cndmask_b32_e32 v33, v175, v33, vcc
	v_rsq_f32_e32 v34, v33
	v_add_u32_e32 v32, 0xa0, v144
	v_mad_i64_i32 v[32:33], s[0:1], v32, s52, v[146:147]
	v_mul_f32_e32 v35, 0x45800000, v34
	v_cndmask_b32_e32 v34, v34, v35, vcc
	v_lshl_add_u64 v[32:33], v[32:33], 0, v[148:149]
	v_pk_mul_f32 v[30:31], v[30:31], v[34:35] op_sel_hi:[1,0]
	v_pk_mul_f32 v[28:29], v[28:29], v[34:35] op_sel_hi:[1,0]
	v_pk_mul_f32 v[36:37], v[26:27], v[34:35] op_sel_hi:[1,0]
	v_pk_mul_f32 v[26:27], v[24:25], v[34:35] op_sel_hi:[1,0]
	v_cvt_pk_bf16_f32 v24, v28, v29
	v_cvt_pk_bf16_f32 v25, v30, v31
	v_pk_mul_f32 v[22:23], v[22:23], v[34:35] op_sel_hi:[1,0]
	v_cvt_pk_bf16_f32 v26, v26, v27
	v_cvt_pk_bf16_f32 v27, v36, v37
	global_store_dwordx4 v[32:33], v[24:27], off nt
	v_pk_mul_f32 v[20:21], v[20:21], v[34:35] op_sel_hi:[1,0]
	v_cmp_gt_f32_e32 vcc, s53, v169
	v_pk_mul_f32 v[24:25], v[18:19], v[34:35] op_sel_hi:[1,0]
	v_pk_mul_f32 v[18:19], v[16:17], v[34:35] op_sel_hi:[1,0]
	v_cvt_pk_bf16_f32 v16, v20, v21
	v_cvt_pk_bf16_f32 v17, v22, v23
	s_nop 0
	v_cvt_pk_bf16_f32 v18, v18, v19
	v_cvt_pk_bf16_f32 v19, v24, v25
	global_store_dwordx4 v[32:33], v[16:19], off offset:256 nt
	s_nop 1
	v_mul_f32_e32 v17, 0x4b800000, v169
	v_cndmask_b32_e32 v17, v169, v17, vcc
	v_rsq_f32_e32 v18, v17
	v_add_u32_e32 v16, 0xb0, v144
	v_mad_i64_i32 v[16:17], s[0:1], v16, s52, v[146:147]
	v_mul_f32_e32 v19, 0x45800000, v18
	v_cndmask_b32_e32 v18, v18, v19, vcc
	v_lshl_add_u64 v[16:17], v[16:17], 0, v[148:149]
	v_pk_mul_f32 v[14:15], v[14:15], v[18:19] op_sel_hi:[1,0]
	v_pk_mul_f32 v[12:13], v[12:13], v[18:19] op_sel_hi:[1,0]
	v_pk_mul_f32 v[20:21], v[10:11], v[18:19] op_sel_hi:[1,0]
	v_pk_mul_f32 v[10:11], v[8:9], v[18:19] op_sel_hi:[1,0]
	v_cvt_pk_bf16_f32 v8, v12, v13
	v_cvt_pk_bf16_f32 v9, v14, v15
	s_and_b64 vcc, exec, s[6:7]
	v_cvt_pk_bf16_f32 v10, v10, v11
	v_cvt_pk_bf16_f32 v11, v20, v21
	global_store_dwordx4 v[16:17], v[8:11], off nt
	s_mov_b32 s1, s20
	s_mov_b32 s0, s22
	v_pk_mul_f32 v[8:9], v[2:3], v[18:19] op_sel_hi:[1,0]
	v_pk_mul_f32 v[2:3], v[0:1], v[18:19] op_sel_hi:[1,0]
	v_pk_mul_f32 v[6:7], v[6:7], v[18:19] op_sel_hi:[1,0]
	v_pk_mul_f32 v[4:5], v[4:5], v[18:19] op_sel_hi:[1,0]
	s_nop 0
	v_cvt_pk_bf16_f32 v0, v4, v5
	v_cvt_pk_bf16_f32 v1, v6, v7
	v_cvt_pk_bf16_f32 v2, v2, v3
	v_cvt_pk_bf16_f32 v3, v8, v9
	global_store_dwordx4 v[16:17], v[0:3], off offset:256 nt
	s_cbranch_vccz .LBB0_943
	s_waitcnt vmcnt(0)
	s_cmpk_gt_u32 s33, 0xff
	s_cbranch_scc1 .LBB0_950
	s_barrier

.LBB0_1022:
	ds_read_b128 v[144:147], v178
	ds_read_b128 v[148:151], v178 offset:1024
	ds_read_b128 v[152:155], v178 offset:2048
	ds_read_b128 v[156:159], v178 offset:3072
	s_add_u32 s42, s40, 0xfffc0080
	s_addc_u32 s43, s41, -1
	s_cmp_eq_u32 s64, 12
	s_cselect_b32 s49, s29, s43
	s_cselect_b32 s48, s37, s42
	s_cselect_b32 s43, s27, s63
	s_cselect_b32 s42, s61, s62
	v_lshl_add_u64 v[172:173], s[40:41], 0, v[136:137]
	s_add_i32 m0, s39, 0xc000
	ds_read_b128 v[160:163], v179
	ds_read_b128 v[164:167], v179 offset:1024
	ds_read_b128 v[168:171], v179 offset:2048
	ds_read_b128 v[182:185], v179 offset:3072
	ds_read_b128 v[186:189], v179 offset:4096
	ds_read_b128 v[190:193], v179 offset:5120
	ds_read_b128 v[194:197], v179 offset:6144
	ds_read_b128 v[198:201], v179 offset:7168
	global_load_lds_dwordx4 v[172:173], off
	v_lshl_add_u64 v[172:173], s[40:41], 0, v[138:139]
	s_add_i32 m0, s39, 0xe000
	s_nop 0
	global_load_lds_dwordx4 v[172:173], off
	s_waitcnt lgkmcnt(8)
	s_setprio 1
	s_barrier
	s_waitcnt lgkmcnt(0)
	v_mfma_f32_16x16x32_bf16 v[124:127], v[144:147], v[160:163], v[124:127]
	v_mfma_f32_16x16x32_bf16 v[120:123], v[152:155], v[160:163], v[120:123]
	v_mfma_f32_16x16x32_bf16 v[108:111], v[144:147], v[168:171], v[108:111]
	v_mfma_f32_16x16x32_bf16 v[104:107], v[152:155], v[168:171], v[104:107]
	v_mfma_f32_16x16x32_bf16 v[96:99], v[144:147], v[186:189], v[96:99]
	v_mfma_f32_16x16x32_bf16 v[88:91], v[152:155], v[186:189], v[88:91]
	v_mfma_f32_16x16x32_bf16 v[80:83], v[144:147], v[194:197], v[80:83]
	v_mfma_f32_16x16x32_bf16 v[72:75], v[152:155], v[194:197], v[72:75]
	v_mfma_f32_16x16x32_bf16 v[124:127], v[148:151], v[164:167], v[124:127]
	v_mfma_f32_16x16x32_bf16 v[120:123], v[156:159], v[164:167], v[120:123]
	v_mfma_f32_16x16x32_bf16 v[108:111], v[148:151], v[182:185], v[108:111]
	v_mfma_f32_16x16x32_bf16 v[104:107], v[156:159], v[182:185], v[104:107]
	v_mfma_f32_16x16x32_bf16 v[96:99], v[148:151], v[190:193], v[96:99]
	v_mfma_f32_16x16x32_bf16 v[88:91], v[156:159], v[190:193], v[88:91]
	v_mfma_f32_16x16x32_bf16 v[80:83], v[148:151], v[198:201], v[80:83]
	v_mfma_f32_16x16x32_bf16 v[72:75], v[156:159], v[198:201], v[72:75]
	s_barrier
	s_setprio 0
	s_add_i32 s65, s59, s50
	v_lshl_add_u64 v[172:173], s[42:43], 0, v[130:131]
	s_mov_b32 m0, s65
	ds_read_b128 v[202:205], v180
	ds_read_b128 v[206:209], v180 offset:1024
	ds_read_b128 v[212:215], v180 offset:2048
	ds_read_b128 v[216:219], v180 offset:3072
	global_load_lds_dwordx4 v[172:173], off
	v_lshl_add_u64 v[220:221], s[42:43], 0, v[134:135]
	s_add_i32 m0, s65, 0x2000
	s_nop 0
	global_load_lds_dwordx4 v[220:221], off
	s_setprio 1
	s_barrier
	s_waitcnt lgkmcnt(0)
	v_mfma_f32_16x16x32_bf16 v[116:119], v[202:205], v[160:163], v[116:119]
	v_mfma_f32_16x16x32_bf16 v[112:115], v[212:215], v[160:163], v[112:115]
	v_mfma_f32_16x16x32_bf16 v[100:103], v[202:205], v[168:171], v[100:103]
	v_mfma_f32_16x16x32_bf16 v[92:95], v[212:215], v[168:171], v[92:95]
	v_mfma_f32_16x16x32_bf16 v[84:87], v[202:205], v[186:189], v[84:87]
	v_mfma_f32_16x16x32_bf16 v[76:79], v[212:215], v[186:189], v[76:79]
	v_mfma_f32_16x16x32_bf16 v[68:71], v[202:205], v[194:197], v[68:71]
	v_mfma_f32_16x16x32_bf16 v[64:67], v[212:215], v[194:197], v[64:67]
	v_mfma_f32_16x16x32_bf16 v[116:119], v[206:209], v[164:167], v[116:119]
	v_mfma_f32_16x16x32_bf16 v[112:115], v[216:219], v[164:167], v[112:115]
	v_mfma_f32_16x16x32_bf16 v[100:103], v[206:209], v[182:185], v[100:103]
	v_mfma_f32_16x16x32_bf16 v[92:95], v[216:219], v[182:185], v[92:95]
	v_mfma_f32_16x16x32_bf16 v[84:87], v[206:209], v[190:193], v[84:87]
	v_mfma_f32_16x16x32_bf16 v[76:79], v[216:219], v[190:193], v[76:79]
	v_mfma_f32_16x16x32_bf16 v[68:71], v[206:209], v[198:201], v[68:71]
	v_mfma_f32_16x16x32_bf16 v[64:67], v[216:219], v[198:201], v[64:67]
	s_barrier
	s_setprio 0
	s_mov_b32 m0, s39
	v_lshl_add_u64 v[222:223], s[48:49], 0, v[128:129]
	ds_read_b128 v[160:163], v179 offset:16384
	ds_read_b128 v[164:167], v179 offset:17408
	ds_read_b128 v[168:171], v179 offset:18432
	ds_read_b128 v[182:185], v179 offset:19456
	ds_read_b128 v[186:189], v179 offset:20480
	ds_read_b128 v[190:193], v179 offset:21504
	ds_read_b128 v[194:197], v179 offset:22528
	ds_read_b128 v[198:201], v179 offset:23552
	global_load_lds_dwordx4 v[222:223], off
	v_lshl_add_u64 v[224:225], s[48:49], 0, v[132:133]
	s_mov_b32 m0, s51
	s_nop 0
	global_load_lds_dwordx4 v[224:225], off
	s_setprio 1
	s_barrier
	s_waitcnt lgkmcnt(0)
	v_mfma_f32_16x16x32_bf16 v[60:63], v[144:147], v[160:163], v[60:63]
	v_mfma_f32_16x16x32_bf16 v[56:59], v[152:155], v[160:163], v[56:59]
	v_mfma_f32_16x16x32_bf16 v[44:47], v[144:147], v[168:171], v[44:47]
	v_mfma_f32_16x16x32_bf16 v[40:43], v[152:155], v[168:171], v[40:43]
	v_mfma_f32_16x16x32_bf16 v[32:35], v[144:147], v[186:189], v[32:35]
	v_mfma_f32_16x16x32_bf16 v[24:27], v[152:155], v[186:189], v[24:27]
	v_mfma_f32_16x16x32_bf16 v[16:19], v[144:147], v[194:197], v[16:19]
	v_mfma_f32_16x16x32_bf16 v[8:11], v[152:155], v[194:197], v[8:11]
	v_mfma_f32_16x16x32_bf16 v[60:63], v[148:151], v[164:167], v[60:63]
	v_mfma_f32_16x16x32_bf16 v[56:59], v[156:159], v[164:167], v[56:59]
	v_mfma_f32_16x16x32_bf16 v[44:47], v[148:151], v[182:185], v[44:47]
	v_mfma_f32_16x16x32_bf16 v[40:43], v[156:159], v[182:185], v[40:43]
	v_mfma_f32_16x16x32_bf16 v[32:35], v[148:151], v[190:193], v[32:35]
	v_mfma_f32_16x16x32_bf16 v[24:27], v[156:159], v[190:193], v[24:27]
	v_mfma_f32_16x16x32_bf16 v[16:19], v[148:151], v[198:201], v[16:19]
	v_mfma_f32_16x16x32_bf16 v[8:11], v[156:159], v[198:201], v[8:11]
	s_barrier
	s_setprio 0
	s_add_u32 s66, s42, 0x40000
	s_addc_u32 s67, s43, 0
	s_add_i32 s65, s60, s50
	v_lshl_add_u64 v[144:145], s[66:67], 0, v[130:131]
	s_mov_b32 m0, s65
	s_nop 0
	global_load_lds_dwordx4 v[144:145], off
	v_lshl_add_u64 v[144:145], s[66:67], 0, v[134:135]
	s_add_i32 m0, s65, 0x2000
	s_nop 0
	global_load_lds_dwordx4 v[144:145], off
	s_waitcnt vmcnt(6)
	s_setprio 1
	s_barrier
	v_mfma_f32_16x16x32_bf16 v[52:55], v[202:205], v[160:163], v[52:55]
	v_mfma_f32_16x16x32_bf16 v[48:51], v[212:215], v[160:163], v[48:51]
	v_mfma_f32_16x16x32_bf16 v[36:39], v[202:205], v[168:171], v[36:39]
	v_mfma_f32_16x16x32_bf16 v[28:31], v[212:215], v[168:171], v[28:31]
	v_mfma_f32_16x16x32_bf16 v[20:23], v[202:205], v[186:189], v[20:23]
	v_mfma_f32_16x16x32_bf16 v[12:15], v[212:215], v[186:189], v[12:15]
	v_mfma_f32_16x16x32_bf16 v[4:7], v[202:205], v[194:197], v[4:7]
	v_mfma_f32_16x16x32_bf16 v[0:3], v[212:215], v[194:197], v[0:3]
	v_mfma_f32_16x16x32_bf16 v[52:55], v[206:209], v[164:167], v[52:55]
	v_mfma_f32_16x16x32_bf16 v[48:51], v[216:219], v[164:167], v[48:51]
	v_mfma_f32_16x16x32_bf16 v[36:39], v[206:209], v[182:185], v[36:39]
	v_mfma_f32_16x16x32_bf16 v[28:31], v[216:219], v[182:185], v[28:31]
	v_mfma_f32_16x16x32_bf16 v[20:23], v[206:209], v[190:193], v[20:23]
	v_mfma_f32_16x16x32_bf16 v[12:15], v[216:219], v[190:193], v[12:15]
	v_mfma_f32_16x16x32_bf16 v[4:7], v[206:209], v[198:201], v[4:7]
	v_mfma_f32_16x16x32_bf16 v[0:3], v[216:219], v[198:201], v[0:3]
	s_barrier
	s_setprio 0
	s_add_i32 s65, 0, 0x18000
	v_add_u32_e32 v156, s65, v176
	ds_read_b128 v[144:147], v156
	ds_read_b128 v[148:151], v156 offset:1024
	ds_read_b128 v[152:155], v156 offset:2048
	ds_read_b128 v[156:159], v156 offset:3072
	s_add_u32 s48, s48, 0x40000
	s_addc_u32 s49, s49, 0
	s_mov_b32 m0, s52
	v_lshl_add_u64 v[202:203], s[48:49], 0, v[128:129]
	ds_read_b128 v[160:163], v179 offset:32768
	ds_read_b128 v[164:167], v179 offset:33792
	ds_read_b128 v[168:171], v179 offset:34816
	ds_read_b128 v[182:185], v179 offset:35840
	ds_read_b128 v[186:189], v179 offset:36864
	ds_read_b128 v[190:193], v179 offset:37888
	ds_read_b128 v[194:197], v179 offset:38912
	ds_read_b128 v[198:201], v179 offset:39936
	global_load_lds_dwordx4 v[202:203], off
	v_lshl_add_u64 v[202:203], s[48:49], 0, v[132:133]
	s_mov_b32 m0, s53
	s_nop 0
	global_load_lds_dwordx4 v[202:203], off
	s_waitcnt lgkmcnt(8)
	s_setprio 1
	s_barrier
	s_waitcnt lgkmcnt(0)
	v_mfma_f32_16x16x32_bf16 v[124:127], v[144:147], v[160:163], v[124:127]
	v_mfma_f32_16x16x32_bf16 v[120:123], v[152:155], v[160:163], v[120:123]
	v_mfma_f32_16x16x32_bf16 v[108:111], v[144:147], v[168:171], v[108:111]
	v_mfma_f32_16x16x32_bf16 v[104:107], v[152:155], v[168:171], v[104:107]
	v_mfma_f32_16x16x32_bf16 v[96:99], v[144:147], v[186:189], v[96:99]
	v_mfma_f32_16x16x32_bf16 v[88:91], v[152:155], v[186:189], v[88:91]
	v_mfma_f32_16x16x32_bf16 v[80:83], v[144:147], v[194:197], v[80:83]
	v_mfma_f32_16x16x32_bf16 v[72:75], v[152:155], v[194:197], v[72:75]
	v_mfma_f32_16x16x32_bf16 v[124:127], v[148:151], v[164:167], v[124:127]
	v_mfma_f32_16x16x32_bf16 v[120:123], v[156:159], v[164:167], v[120:123]
	v_mfma_f32_16x16x32_bf16 v[108:111], v[148:151], v[182:185], v[108:111]
	v_mfma_f32_16x16x32_bf16 v[104:107], v[156:159], v[182:185], v[104:107]
	v_mfma_f32_16x16x32_bf16 v[96:99], v[148:151], v[190:193], v[96:99]
	v_mfma_f32_16x16x32_bf16 v[88:91], v[156:159], v[190:193], v[88:91]
	v_mfma_f32_16x16x32_bf16 v[80:83], v[148:151], v[198:201], v[80:83]
	v_mfma_f32_16x16x32_bf16 v[72:75], v[156:159], v[198:201], v[72:75]
	s_barrier
	s_setprio 0
	s_add_i32 s48, 0, 0x1c000
	s_add_i32 s49, s65, s50
	v_add_u32_e32 v181, s48, v176
	v_lshl_add_u64 v[172:173], v[172:173], 0, s[2:3]
	s_mov_b32 m0, s49
	ds_read_b128 v[202:205], v181
	ds_read_b128 v[206:209], v181 offset:1024
	ds_read_b128 v[212:215], v181 offset:2048
	ds_read_b128 v[216:219], v181 offset:3072
	global_load_lds_dwordx4 v[172:173], off
	v_lshl_add_u64 v[172:173], v[220:221], 0, s[2:3]
	s_add_i32 m0, s49, 0x2000
	s_nop 0
	global_load_lds_dwordx4 v[172:173], off
	s_setprio 1
	s_barrier
	s_waitcnt lgkmcnt(0)
	v_mfma_f32_16x16x32_bf16 v[116:119], v[202:205], v[160:163], v[116:119]
	v_mfma_f32_16x16x32_bf16 v[112:115], v[212:215], v[160:163], v[112:115]
	v_mfma_f32_16x16x32_bf16 v[100:103], v[202:205], v[168:171], v[100:103]
	v_mfma_f32_16x16x32_bf16 v[92:95], v[212:215], v[168:171], v[92:95]
	v_mfma_f32_16x16x32_bf16 v[84:87], v[202:205], v[186:189], v[84:87]
	v_mfma_f32_16x16x32_bf16 v[76:79], v[212:215], v[186:189], v[76:79]
	v_mfma_f32_16x16x32_bf16 v[68:71], v[202:205], v[194:197], v[68:71]
	v_mfma_f32_16x16x32_bf16 v[64:67], v[212:215], v[194:197], v[64:67]
	v_mfma_f32_16x16x32_bf16 v[116:119], v[206:209], v[164:167], v[116:119]
	v_mfma_f32_16x16x32_bf16 v[112:115], v[216:219], v[164:167], v[112:115]
	v_mfma_f32_16x16x32_bf16 v[100:103], v[206:209], v[182:185], v[100:103]
	v_mfma_f32_16x16x32_bf16 v[92:95], v[216:219], v[182:185], v[92:95]
	v_mfma_f32_16x16x32_bf16 v[84:87], v[206:209], v[190:193], v[84:87]
	v_mfma_f32_16x16x32_bf16 v[76:79], v[216:219], v[190:193], v[76:79]
	v_mfma_f32_16x16x32_bf16 v[68:71], v[206:209], v[198:201], v[68:71]
	v_mfma_f32_16x16x32_bf16 v[64:67], v[216:219], v[198:201], v[64:67]
	s_barrier
	s_setprio 0
	s_mov_b32 m0, s55
	v_lshl_add_u64 v[172:173], v[222:223], 0, s[2:3]
	ds_read_b128 v[160:163], v179 offset:49152
	ds_read_b128 v[164:167], v179 offset:50176
	ds_read_b128 v[168:171], v179 offset:51200
	ds_read_b128 v[182:185], v179 offset:52224
	ds_read_b128 v[186:189], v179 offset:53248
	ds_read_b128 v[190:193], v179 offset:54272
	ds_read_b128 v[194:197], v179 offset:55296
	ds_read_b128 v[198:201], v179 offset:56320
	global_load_lds_dwordx4 v[172:173], off
	v_lshl_add_u64 v[172:173], v[224:225], 0, s[2:3]
	s_mov_b32 m0, s56
	s_nop 0
	global_load_lds_dwordx4 v[172:173], off
	s_setprio 1
	s_barrier
	s_waitcnt lgkmcnt(0)
	v_mfma_f32_16x16x32_bf16 v[60:63], v[144:147], v[160:163], v[60:63]
	v_mfma_f32_16x16x32_bf16 v[56:59], v[152:155], v[160:163], v[56:59]
	v_mfma_f32_16x16x32_bf16 v[44:47], v[144:147], v[168:171], v[44:47]
	v_mfma_f32_16x16x32_bf16 v[40:43], v[152:155], v[168:171], v[40:43]
	v_mfma_f32_16x16x32_bf16 v[32:35], v[144:147], v[186:189], v[32:35]
	v_mfma_f32_16x16x32_bf16 v[24:27], v[152:155], v[186:189], v[24:27]
	v_mfma_f32_16x16x32_bf16 v[16:19], v[144:147], v[194:197], v[16:19]
	v_mfma_f32_16x16x32_bf16 v[8:11], v[152:155], v[194:197], v[8:11]
	v_mfma_f32_16x16x32_bf16 v[60:63], v[148:151], v[164:167], v[60:63]
	v_mfma_f32_16x16x32_bf16 v[56:59], v[156:159], v[164:167], v[56:59]
	v_mfma_f32_16x16x32_bf16 v[44:47], v[148:151], v[182:185], v[44:47]
	v_mfma_f32_16x16x32_bf16 v[40:43], v[156:159], v[182:185], v[40:43]
	v_mfma_f32_16x16x32_bf16 v[32:35], v[148:151], v[190:193], v[32:35]
	v_mfma_f32_16x16x32_bf16 v[24:27], v[156:159], v[190:193], v[24:27]
	v_mfma_f32_16x16x32_bf16 v[16:19], v[148:151], v[198:201], v[16:19]
	v_mfma_f32_16x16x32_bf16 v[8:11], v[156:159], v[198:201], v[8:11]
	s_barrier
	s_setprio 0
	s_add_u32 s42, s42, 0x40080
	s_addc_u32 s43, s43, 0
	s_add_i32 s48, s48, s50
	v_lshl_add_u64 v[144:145], s[42:43], 0, v[130:131]
	s_mov_b32 m0, s48
	s_nop 0
	global_load_lds_dwordx4 v[144:145], off
	v_lshl_add_u64 v[144:145], s[42:43], 0, v[134:135]
	s_add_i32 m0, s48, 0x2000
	s_nop 0
	global_load_lds_dwordx4 v[144:145], off
	s_waitcnt vmcnt(6)
	s_setprio 1
	s_barrier
	v_mfma_f32_16x16x32_bf16 v[52:55], v[202:205], v[160:163], v[52:55]
	v_mfma_f32_16x16x32_bf16 v[48:51], v[212:215], v[160:163], v[48:51]
	v_mfma_f32_16x16x32_bf16 v[36:39], v[202:205], v[168:171], v[36:39]
	v_mfma_f32_16x16x32_bf16 v[28:31], v[212:215], v[168:171], v[28:31]
	v_mfma_f32_16x16x32_bf16 v[20:23], v[202:205], v[186:189], v[20:23]
	v_mfma_f32_16x16x32_bf16 v[12:15], v[212:215], v[186:189], v[12:15]
	v_mfma_f32_16x16x32_bf16 v[4:7], v[202:205], v[194:197], v[4:7]
	v_mfma_f32_16x16x32_bf16 v[0:3], v[212:215], v[194:197], v[0:3]
	v_mfma_f32_16x16x32_bf16 v[52:55], v[206:209], v[164:167], v[52:55]
	v_mfma_f32_16x16x32_bf16 v[48:51], v[216:219], v[164:167], v[48:51]
	v_mfma_f32_16x16x32_bf16 v[36:39], v[206:209], v[182:185], v[36:39]
	v_mfma_f32_16x16x32_bf16 v[28:31], v[216:219], v[182:185], v[28:31]
	v_mfma_f32_16x16x32_bf16 v[20:23], v[206:209], v[190:193], v[20:23]
	v_mfma_f32_16x16x32_bf16 v[12:15], v[216:219], v[190:193], v[12:15]
	v_mfma_f32_16x16x32_bf16 v[4:7], v[206:209], v[198:201], v[4:7]
	v_mfma_f32_16x16x32_bf16 v[0:3], v[216:219], v[198:201], v[0:3]
	s_barrier
	s_setprio 0
	s_add_i32 s64, s64, 2
	s_add_u32 s40, s40, 0x100
	s_addc_u32 s41, s41, 0
	s_add_u32 s62, s62, 0x100
	s_addc_u32 s63, s63, 0
	s_cmp_gt_u32 s64, 13
	s_cbranch_scc0 .LBB0_1022
	v_lshl_or_b32 v144, s38, 8, v177
	v_lshl_add_u32 v150, s36, 8, v175
	v_ashrrev_i32_e32 v145, 31, v144
	v_ashrrev_i32_e32 v151, 31, v150
	v_lshlrev_b64 v[144:145], 1, v[144:145]
	v_lshl_add_u64 v[146:147], s[10:11], 0, v[144:145]
	v_lshlrev_b64 v[148:149], 11, v[150:151]
	v_lshl_add_u64 v[152:153], v[146:147], 0, v[148:149]
	global_load_dwordx4 v[156:159], v[152:153], off
	global_load_dwordx4 v[160:163], v[152:153], off offset:256
	v_or_b32_e32 v152, 16, v150
	v_ashrrev_i32_e32 v153, 31, v152
	v_lshlrev_b64 v[170:171], 11, v[152:153]
	v_lshl_add_u64 v[152:153], v[146:147], 0, v[170:171]
	global_load_dwordx4 v[164:167], v[152:153], off
	global_load_dwordx4 v[182:185], v[152:153], off offset:256
	v_or_b32_e32 v152, 32, v150
	v_ashrrev_i32_e32 v153, 31, v152
	v_lshlrev_b64 v[154:155], 11, v[152:153]
	v_lshl_add_u64 v[152:153], v[146:147], 0, v[154:155]
	global_load_dwordx4 v[186:189], v[152:153], off
	global_load_dwordx4 v[190:193], v[152:153], off offset:256
	v_or_b32_e32 v152, 48, v150
	v_ashrrev_i32_e32 v153, 31, v152
	v_lshlrev_b64 v[152:153], 11, v[152:153]
	v_lshl_add_u64 v[168:169], v[146:147], 0, v[152:153]
	global_load_dwordx4 v[194:197], v[168:169], off
	global_load_dwordx4 v[198:201], v[168:169], off offset:256
	s_waitcnt vmcnt(0)
	v_lshlrev_b32_e32 v202, 16, v156
	v_and_b32_e32 v203, 0xffff0000, v156
	v_lshlrev_b32_e32 v204, 16, v157
	v_and_b32_e32 v205, 0xffff0000, v157
	v_lshlrev_b32_e32 v206, 16, v158
	v_and_b32_e32 v207, 0xffff0000, v158
	v_lshlrev_b32_e32 v208, 16, v159
	v_and_b32_e32 v209, 0xffff0000, v159
	v_pk_add_f32 v[126:127], v[126:127], v[204:205]
	v_pk_add_f32 v[124:125], v[124:125], v[202:203]
	v_lshlrev_b32_e32 v224, 16, v166
	v_and_b32_e32 v225, 0xffff0000, v166
	v_lshlrev_b32_e32 v226, 16, v167
	v_and_b32_e32 v227, 0xffff0000, v167
	v_lshlrev_b32_e32 v212, 16, v160
	v_lshlrev_b32_e32 v166, 16, v194
	v_and_b32_e32 v167, 0xffff0000, v194
	v_lshlrev_b32_e32 v172, 16, v195
	v_and_b32_e32 v173, 0xffff0000, v195
	v_pk_add_f32 v[194:195], v[122:123], v[208:209]
	v_pk_add_f32 v[122:123], v[120:121], v[206:207]
	v_mul_f32_e32 v120, v125, v125
	v_mul_f32_e32 v121, v127, v127
	v_fmac_f32_e32 v120, v124, v124
	v_fmac_f32_e32 v121, v126, v126
	v_add_f32_e32 v120, v120, v121
	v_mul_f32_e32 v121, v123, v123
	v_fmac_f32_e32 v121, v122, v122
	v_add_f32_e32 v120, v121, v120
	v_mul_f32_e32 v121, v195, v195
	v_fmac_f32_e32 v121, v194, v194
	v_and_b32_e32 v213, 0xffff0000, v160
	v_lshlrev_b32_e32 v214, 16, v161
	v_and_b32_e32 v215, 0xffff0000, v161
	v_add_f32_e32 v181, v121, v120
	v_cvt_pk_bf16_f32 v120, v124, v125
	v_lshl_add_u64 v[124:125], s[10:11], 0, v[148:149]
	v_lshlrev_b32_e32 v216, 16, v162
	v_and_b32_e32 v217, 0xffff0000, v162
	v_lshlrev_b32_e32 v218, 16, v163
	v_and_b32_e32 v219, 0xffff0000, v163
	v_cvt_pk_bf16_f32 v121, v126, v127
	v_lshl_add_u64 v[124:125], v[124:125], 0, v[144:145]
	v_pk_add_f32 v[118:119], v[118:119], v[214:215]
	v_pk_add_f32 v[116:117], v[116:117], v[212:213]
	v_cvt_pk_bf16_f32 v122, v122, v123
	v_cvt_pk_bf16_f32 v123, v194, v195
	global_store_dwordx4 v[124:125], v[120:123], off
	v_lshlrev_b32_e32 v220, 16, v164
	v_and_b32_e32 v221, 0xffff0000, v164
	v_pk_add_f32 v[120:121], v[114:115], v[218:219]
	v_pk_add_f32 v[114:115], v[112:113], v[216:217]
	v_mul_f32_e32 v112, v117, v117
	v_mul_f32_e32 v113, v119, v119
	v_fmac_f32_e32 v112, v116, v116
	v_fmac_f32_e32 v113, v118, v118
	v_add_f32_e32 v112, v112, v113
	v_mul_f32_e32 v113, v115, v115
	v_fmac_f32_e32 v113, v114, v114
	v_add_f32_e32 v112, v113, v112
	v_mul_f32_e32 v113, v121, v121
	v_fmac_f32_e32 v113, v120, v120
	v_add_f32_e32 v112, v113, v112
	v_lshlrev_b32_e32 v222, 16, v165
	v_and_b32_e32 v223, 0xffff0000, v165
	v_add_f32_e32 v126, v181, v112
	v_cvt_pk_bf16_f32 v112, v116, v117
	v_cvt_pk_bf16_f32 v113, v118, v119
	v_lshl_add_u64 v[116:117], s[10:11], 0, v[170:171]
	v_lshlrev_b32_e32 v230, 16, v184
	v_and_b32_e32 v231, 0xffff0000, v184
	v_lshlrev_b32_e32 v232, 16, v186
	v_and_b32_e32 v233, 0xffff0000, v186
	v_lshlrev_b32_e32 v186, 16, v187
	v_and_b32_e32 v187, 0xffff0000, v187
	v_cvt_pk_bf16_f32 v114, v114, v115
	v_cvt_pk_bf16_f32 v115, v120, v121
	global_store_dwordx4 v[124:125], v[112:115], off offset:256
	v_pk_add_f32 v[110:111], v[110:111], v[222:223]
	v_pk_add_f32 v[108:109], v[108:109], v[220:221]
	v_lshl_add_u64 v[118:119], v[116:117], 0, v[144:145]
	v_cvt_pk_bf16_f32 v112, v108, v109
	v_cvt_pk_bf16_f32 v113, v110, v111
	v_lshlrev_b32_e32 v228, 16, v182
	v_and_b32_e32 v229, 0xffff0000, v182
	v_lshlrev_b32_e32 v182, 16, v183
	v_and_b32_e32 v183, 0xffff0000, v183
	v_lshlrev_b32_e32 v184, 16, v185
	v_and_b32_e32 v185, 0xffff0000, v185
	v_lshlrev_b32_e32 v238, 16, v192
	v_and_b32_e32 v239, 0xffff0000, v192
	v_pk_add_f32 v[106:107], v[106:107], v[226:227]
	v_pk_add_f32 v[104:105], v[104:105], v[224:225]
	v_lshlrev_b32_e32 v156, 16, v200
	v_cvt_pk_bf16_f32 v114, v104, v105
	v_cvt_pk_bf16_f32 v115, v106, v107
	global_store_dwordx4 v[118:119], v[112:115], off
	v_and_b32_e32 v157, 0xffff0000, v200
	v_pk_add_f32 v[102:103], v[102:103], v[182:183]
	v_pk_add_f32 v[112:113], v[92:93], v[230:231]
	v_pk_add_f32 v[92:93], v[98:99], v[186:187]
	v_lshl_add_u64 v[98:99], s[10:11], 0, v[154:155]
	v_pk_add_f32 v[100:101], v[100:101], v[228:229]
	v_pk_add_f32 v[94:95], v[94:95], v[184:185]
	v_cvt_pk_bf16_f32 v114, v100, v101
	v_cvt_pk_bf16_f32 v115, v102, v103
	v_cvt_pk_bf16_f32 v116, v112, v113
	v_lshlrev_b32_e32 v234, 16, v188
	v_cvt_pk_bf16_f32 v117, v94, v95
	global_store_dwordx4 v[118:119], v[114:117], off offset:256
	v_lshl_add_u64 v[118:119], v[98:99], 0, v[144:145]
	v_pk_add_f32 v[98:99], v[76:77], v[238:239]
	v_pk_add_f32 v[76:77], v[82:83], v[172:173]
	v_lshl_add_u64 v[82:83], s[10:11], 0, v[152:153]
	v_lshl_add_u64 v[122:123], v[82:83], 0, v[144:145]
	v_pk_add_f32 v[82:83], v[64:65], v[156:157]
	v_and_b32_e32 v65, 64, v174
	v_and_b32_e32 v235, 0xffff0000, v188
	v_lshlrev_b32_e32 v188, 16, v189
	v_and_b32_e32 v189, 0xffff0000, v189
	v_lshlrev_b32_e32 v236, 16, v190
	v_and_b32_e32 v237, 0xffff0000, v190
	v_pk_add_f32 v[96:97], v[96:97], v[232:233]
	v_xor_b32_e32 v64, 16, v174
	v_cvt_pk_bf16_f32 v114, v96, v97
	v_add_u32_e32 v65, 64, v65
	v_lshlrev_b32_e32 v190, 16, v191
	v_and_b32_e32 v191, 0xffff0000, v191
	v_lshlrev_b32_e32 v192, 16, v193
	v_and_b32_e32 v193, 0xffff0000, v193
	v_pk_add_f32 v[90:91], v[90:91], v[188:189]
	v_pk_add_f32 v[88:89], v[88:89], v[234:235]
	v_cvt_pk_bf16_f32 v115, v92, v93
	v_pk_add_f32 v[84:85], v[84:85], v[236:237]
	v_cvt_pk_bf16_f32 v116, v88, v89
	v_cvt_pk_bf16_f32 v117, v90, v91
	global_store_dwordx4 v[118:119], v[114:117], off
	v_cmp_lt_i32_e32 vcc, v64, v65
	v_lshlrev_b32_e32 v164, 16, v196
	v_cvt_pk_bf16_f32 v114, v84, v85
	v_and_b32_e32 v165, 0xffff0000, v196
	v_lshlrev_b32_e32 v168, 16, v197
	v_and_b32_e32 v169, 0xffff0000, v197
	v_pk_add_f32 v[86:87], v[86:87], v[190:191]
	v_pk_add_f32 v[78:79], v[78:79], v[192:193]
	v_cvt_pk_bf16_f32 v115, v86, v87
	v_cvt_pk_bf16_f32 v116, v98, v99
	v_pk_add_f32 v[80:81], v[80:81], v[166:167]
	v_cvt_pk_bf16_f32 v117, v78, v79
	global_store_dwordx4 v[118:119], v[114:117], off offset:256
	v_cndmask_b32_e32 v64, v174, v64, vcc
	v_pk_add_f32 v[74:75], v[74:75], v[168:169]
	v_cvt_pk_bf16_f32 v114, v80, v81
	v_pk_add_f32 v[72:73], v[72:73], v[164:165]
	v_cvt_pk_bf16_f32 v115, v76, v77
	v_lshlrev_b32_e32 v158, 16, v198
	v_cvt_pk_bf16_f32 v116, v72, v73
	v_cvt_pk_bf16_f32 v117, v74, v75
	global_store_dwordx4 v[122:123], v[114:117], off
	v_and_b32_e32 v159, 0xffff0000, v198
	v_lshlrev_b32_e32 v162, 16, v199
	v_lshlrev_b32_e32 v114, 2, v64
	ds_bpermute_b32 v64, v114, v126
	v_xor_b32_e32 v115, 32, v174
	v_cmp_lt_i32_e32 vcc, v115, v65
	v_and_b32_e32 v163, 0xffff0000, v199
	v_lshlrev_b32_e32 v160, 16, v201
	v_cndmask_b32_e32 v65, v174, v115, vcc
	v_lshlrev_b32_e32 v115, 2, v65
	s_waitcnt lgkmcnt(0)
	v_add_f32_e32 v116, v126, v64
	ds_bpermute_b32 v117, v115, v116
	v_and_b32_e32 v161, 0xffff0000, v201
	v_pk_add_f32 v[70:71], v[70:71], v[162:163]
	v_pk_add_f32 v[68:69], v[68:69], v[158:159]
	v_pk_add_f32 v[66:67], v[66:67], v[160:161]
	v_lshl_add_u64 v[64:65], v[150:151], 2, s[18:19]
	v_cvt_pk_bf16_f32 v118, v68, v69
	v_cvt_pk_bf16_f32 v119, v70, v71
	v_cvt_pk_bf16_f32 v120, v82, v83
	v_cvt_pk_bf16_f32 v121, v66, v67
	global_store_dwordx4 v[122:123], v[118:121], off offset:256
	s_and_saveexec_b64 s[36:37], s[6:7]
	s_cbranch_execz .LBB0_1025
	s_waitcnt lgkmcnt(0)
	v_add_f32_e32 v116, v116, v117
	global_atomic_add_f32 v[64:65], v116, off

.LBB0_1080:
	ds_read_b128 v[144:147], v151
	ds_read_b128 v[156:159], v151 offset:1024
	ds_read_b128 v[160:163], v151 offset:2048
	ds_read_b128 v[164:167], v151 offset:3072
	s_add_u32 s36, s2, 0xfffc0080
	s_addc_u32 s37, s3, -1
	s_cmp_eq_u32 s67, 12
	s_cselect_b32 s39, s29, s37
	s_cselect_b32 s38, s63, s36
	s_cselect_b32 s37, s27, s66
	s_cselect_b32 s36, s64, s65
	v_lshl_add_u64 v[172:173], s[2:3], 0, v[136:137]
	s_add_i32 m0, s48, 0xc000
	ds_read_b128 v[168:171], v152
	ds_read_b128 v[176:179], v152 offset:1024
	ds_read_b128 v[180:183], v152 offset:2048
	ds_read_b128 v[184:187], v152 offset:3072
	ds_read_b128 v[188:191], v152 offset:4096
	ds_read_b128 v[192:195], v152 offset:5120
	ds_read_b128 v[196:199], v152 offset:6144
	ds_read_b128 v[200:203], v152 offset:7168
	global_load_lds_dwordx4 v[172:173], off
	v_lshl_add_u64 v[172:173], s[2:3], 0, v[138:139]
	s_add_i32 m0, s48, 0xe000
	s_nop 0
	global_load_lds_dwordx4 v[172:173], off
	s_waitcnt lgkmcnt(8)
	s_setprio 1
	s_barrier
	s_waitcnt lgkmcnt(0)
	v_mfma_f32_16x16x32_bf16 v[124:127], v[144:147], v[168:171], v[124:127]
	v_mfma_f32_16x16x32_bf16 v[120:123], v[160:163], v[168:171], v[120:123]
	v_mfma_f32_16x16x32_bf16 v[116:119], v[144:147], v[180:183], v[116:119]
	v_mfma_f32_16x16x32_bf16 v[112:115], v[160:163], v[180:183], v[112:115]
	v_mfma_f32_16x16x32_bf16 v[104:107], v[144:147], v[188:191], v[104:107]
	v_mfma_f32_16x16x32_bf16 v[96:99], v[160:163], v[188:191], v[96:99]
	v_mfma_f32_16x16x32_bf16 v[76:79], v[144:147], v[196:199], v[76:79]
	v_mfma_f32_16x16x32_bf16 v[72:75], v[160:163], v[196:199], v[72:75]
	v_mfma_f32_16x16x32_bf16 v[124:127], v[156:159], v[176:179], v[124:127]
	v_mfma_f32_16x16x32_bf16 v[120:123], v[164:167], v[176:179], v[120:123]
	v_mfma_f32_16x16x32_bf16 v[116:119], v[156:159], v[184:187], v[116:119]
	v_mfma_f32_16x16x32_bf16 v[112:115], v[164:167], v[184:187], v[112:115]
	v_mfma_f32_16x16x32_bf16 v[104:107], v[156:159], v[192:195], v[104:107]
	v_mfma_f32_16x16x32_bf16 v[96:99], v[164:167], v[192:195], v[96:99]
	v_mfma_f32_16x16x32_bf16 v[76:79], v[156:159], v[200:203], v[76:79]
	v_mfma_f32_16x16x32_bf16 v[72:75], v[164:167], v[200:203], v[72:75]
	s_barrier
	s_setprio 0
	s_add_i32 s68, s56, s43
	v_lshl_add_u64 v[172:173], s[36:37], 0, v[130:131]
	s_mov_b32 m0, s68
	ds_read_b128 v[204:207], v153
	ds_read_b128 v[212:215], v153 offset:1024
	ds_read_b128 v[216:219], v153 offset:2048
	ds_read_b128 v[220:223], v153 offset:3072
	global_load_lds_dwordx4 v[172:173], off
	v_lshl_add_u64 v[208:209], s[36:37], 0, v[134:135]
	s_add_i32 m0, s68, 0x2000
	s_nop 0
	global_load_lds_dwordx4 v[208:209], off
	s_setprio 1
	s_barrier
	s_waitcnt lgkmcnt(0)
	v_mfma_f32_16x16x32_bf16 v[108:111], v[204:207], v[168:171], v[108:111]
	v_mfma_f32_16x16x32_bf16 v[100:103], v[216:219], v[168:171], v[100:103]
	v_mfma_f32_16x16x32_bf16 v[92:95], v[204:207], v[180:183], v[92:95]
	v_mfma_f32_16x16x32_bf16 v[88:91], v[216:219], v[180:183], v[88:91]
	v_mfma_f32_16x16x32_bf16 v[84:87], v[204:207], v[188:191], v[84:87]
	v_mfma_f32_16x16x32_bf16 v[80:83], v[216:219], v[188:191], v[80:83]
	v_mfma_f32_16x16x32_bf16 v[68:71], v[204:207], v[196:199], v[68:71]
	v_mfma_f32_16x16x32_bf16 v[64:67], v[216:219], v[196:199], v[64:67]
	v_mfma_f32_16x16x32_bf16 v[108:111], v[212:215], v[176:179], v[108:111]
	v_mfma_f32_16x16x32_bf16 v[100:103], v[220:223], v[176:179], v[100:103]
	v_mfma_f32_16x16x32_bf16 v[92:95], v[212:215], v[184:187], v[92:95]
	v_mfma_f32_16x16x32_bf16 v[88:91], v[220:223], v[184:187], v[88:91]
	v_mfma_f32_16x16x32_bf16 v[84:87], v[212:215], v[192:195], v[84:87]
	v_mfma_f32_16x16x32_bf16 v[80:83], v[220:223], v[192:195], v[80:83]
	v_mfma_f32_16x16x32_bf16 v[68:71], v[212:215], v[200:203], v[68:71]
	v_mfma_f32_16x16x32_bf16 v[64:67], v[220:223], v[200:203], v[64:67]
	s_barrier
	s_setprio 0
	s_mov_b32 m0, s48
	v_lshl_add_u64 v[224:225], s[38:39], 0, v[128:129]
	ds_read_b128 v[168:171], v152 offset:16384
	ds_read_b128 v[176:179], v152 offset:17408
	ds_read_b128 v[180:183], v152 offset:18432
	ds_read_b128 v[184:187], v152 offset:19456
	ds_read_b128 v[188:191], v152 offset:20480
	ds_read_b128 v[192:195], v152 offset:21504
	ds_read_b128 v[196:199], v152 offset:22528
	ds_read_b128 v[200:203], v152 offset:23552
	global_load_lds_dwordx4 v[224:225], off
	v_lshl_add_u64 v[226:227], s[38:39], 0, v[132:133]
	s_mov_b32 m0, s49
	s_nop 0
	global_load_lds_dwordx4 v[226:227], off
	s_setprio 1
	s_barrier
	s_waitcnt lgkmcnt(0)
	v_mfma_f32_16x16x32_bf16 v[60:63], v[144:147], v[168:171], v[60:63]
	v_mfma_f32_16x16x32_bf16 v[56:59], v[160:163], v[168:171], v[56:59]
	v_mfma_f32_16x16x32_bf16 v[44:47], v[144:147], v[180:183], v[44:47]
	v_mfma_f32_16x16x32_bf16 v[40:43], v[160:163], v[180:183], v[40:43]
	v_mfma_f32_16x16x32_bf16 v[28:31], v[144:147], v[188:191], v[28:31]
	v_mfma_f32_16x16x32_bf16 v[24:27], v[160:163], v[188:191], v[24:27]
	v_mfma_f32_16x16x32_bf16 v[12:15], v[144:147], v[196:199], v[12:15]
	v_mfma_f32_16x16x32_bf16 v[8:11], v[160:163], v[196:199], v[8:11]
	v_mfma_f32_16x16x32_bf16 v[60:63], v[156:159], v[176:179], v[60:63]
	v_mfma_f32_16x16x32_bf16 v[56:59], v[164:167], v[176:179], v[56:59]
	v_mfma_f32_16x16x32_bf16 v[44:47], v[156:159], v[184:187], v[44:47]
	v_mfma_f32_16x16x32_bf16 v[40:43], v[164:167], v[184:187], v[40:43]
	v_mfma_f32_16x16x32_bf16 v[28:31], v[156:159], v[192:195], v[28:31]
	v_mfma_f32_16x16x32_bf16 v[24:27], v[164:167], v[192:195], v[24:27]
	v_mfma_f32_16x16x32_bf16 v[12:15], v[156:159], v[200:203], v[12:15]
	v_mfma_f32_16x16x32_bf16 v[8:11], v[164:167], v[200:203], v[8:11]
	s_barrier
	s_setprio 0
	s_add_u32 s68, s36, 0x40000
	s_addc_u32 s69, s37, 0
	s_add_i32 s70, s57, s43
	v_lshl_add_u64 v[144:145], s[68:69], 0, v[130:131]
	s_mov_b32 m0, s70
	s_nop 0
	global_load_lds_dwordx4 v[144:145], off
	v_lshl_add_u64 v[144:145], s[68:69], 0, v[134:135]
	s_add_i32 m0, s70, 0x2000
	s_nop 0
	global_load_lds_dwordx4 v[144:145], off
	s_waitcnt vmcnt(6)
	s_setprio 1
	s_barrier
	v_mfma_f32_16x16x32_bf16 v[52:55], v[204:207], v[168:171], v[52:55]
	v_mfma_f32_16x16x32_bf16 v[48:51], v[216:219], v[168:171], v[48:51]
	v_mfma_f32_16x16x32_bf16 v[36:39], v[204:207], v[180:183], v[36:39]
	v_mfma_f32_16x16x32_bf16 v[32:35], v[216:219], v[180:183], v[32:35]
	v_mfma_f32_16x16x32_bf16 v[20:23], v[204:207], v[188:191], v[20:23]
	v_mfma_f32_16x16x32_bf16 v[16:19], v[216:219], v[188:191], v[16:19]
	v_mfma_f32_16x16x32_bf16 v[4:7], v[204:207], v[196:199], v[4:7]
	v_mfma_f32_16x16x32_bf16 v[0:3], v[216:219], v[196:199], v[0:3]
	v_mfma_f32_16x16x32_bf16 v[52:55], v[212:215], v[176:179], v[52:55]
	v_mfma_f32_16x16x32_bf16 v[48:51], v[220:223], v[176:179], v[48:51]
	v_mfma_f32_16x16x32_bf16 v[36:39], v[212:215], v[184:187], v[36:39]
	v_mfma_f32_16x16x32_bf16 v[32:35], v[220:223], v[184:187], v[32:35]
	v_mfma_f32_16x16x32_bf16 v[20:23], v[212:215], v[192:195], v[20:23]
	v_mfma_f32_16x16x32_bf16 v[16:19], v[220:223], v[192:195], v[16:19]
	v_mfma_f32_16x16x32_bf16 v[4:7], v[212:215], v[200:203], v[4:7]
	v_mfma_f32_16x16x32_bf16 v[0:3], v[220:223], v[200:203], v[0:3]
	s_barrier
	s_setprio 0
	s_add_i32 s68, 0, 0x18000
	v_add_u32_e32 v155, s68, v149
	ds_read_b128 v[144:147], v155
	ds_read_b128 v[156:159], v155 offset:1024
	ds_read_b128 v[160:163], v155 offset:2048
	ds_read_b128 v[164:167], v155 offset:3072
	s_add_u32 s38, s38, 0x40000
	s_addc_u32 s39, s39, 0
	s_mov_b32 m0, s50
	v_lshl_add_u64 v[204:205], s[38:39], 0, v[128:129]
	ds_read_b128 v[168:171], v152 offset:32768
	ds_read_b128 v[176:179], v152 offset:33792
	ds_read_b128 v[180:183], v152 offset:34816
	ds_read_b128 v[184:187], v152 offset:35840
	ds_read_b128 v[188:191], v152 offset:36864
	ds_read_b128 v[192:195], v152 offset:37888
	ds_read_b128 v[196:199], v152 offset:38912
	ds_read_b128 v[200:203], v152 offset:39936
	global_load_lds_dwordx4 v[204:205], off
	v_lshl_add_u64 v[204:205], s[38:39], 0, v[132:133]
	s_mov_b32 m0, s51
	s_nop 0
	global_load_lds_dwordx4 v[204:205], off
	s_waitcnt lgkmcnt(8)
	s_setprio 1
	s_barrier
	s_waitcnt lgkmcnt(0)
	v_mfma_f32_16x16x32_bf16 v[124:127], v[144:147], v[168:171], v[124:127]
	v_mfma_f32_16x16x32_bf16 v[120:123], v[160:163], v[168:171], v[120:123]
	v_mfma_f32_16x16x32_bf16 v[116:119], v[144:147], v[180:183], v[116:119]
	v_mfma_f32_16x16x32_bf16 v[112:115], v[160:163], v[180:183], v[112:115]
	v_mfma_f32_16x16x32_bf16 v[104:107], v[144:147], v[188:191], v[104:107]
	v_mfma_f32_16x16x32_bf16 v[96:99], v[160:163], v[188:191], v[96:99]
	v_mfma_f32_16x16x32_bf16 v[76:79], v[144:147], v[196:199], v[76:79]
	v_mfma_f32_16x16x32_bf16 v[72:75], v[160:163], v[196:199], v[72:75]
	v_mfma_f32_16x16x32_bf16 v[124:127], v[156:159], v[176:179], v[124:127]
	v_mfma_f32_16x16x32_bf16 v[120:123], v[164:167], v[176:179], v[120:123]
	v_mfma_f32_16x16x32_bf16 v[116:119], v[156:159], v[184:187], v[116:119]
	v_mfma_f32_16x16x32_bf16 v[112:115], v[164:167], v[184:187], v[112:115]
	v_mfma_f32_16x16x32_bf16 v[104:107], v[156:159], v[192:195], v[104:107]
	v_mfma_f32_16x16x32_bf16 v[96:99], v[164:167], v[192:195], v[96:99]
	v_mfma_f32_16x16x32_bf16 v[76:79], v[156:159], v[200:203], v[76:79]
	v_mfma_f32_16x16x32_bf16 v[72:75], v[164:167], v[200:203], v[72:75]
	s_barrier
	s_setprio 0
	s_add_i32 s38, 0, 0x1c000
	s_add_i32 s39, s68, s43
	v_add_u32_e32 v155, s38, v149
	v_lshl_add_u64 v[172:173], v[172:173], 0, s[8:9]
	s_mov_b32 m0, s39
	ds_read_b128 v[204:207], v155
	ds_read_b128 v[212:215], v155 offset:1024
	ds_read_b128 v[216:219], v155 offset:2048
	ds_read_b128 v[220:223], v155 offset:3072
	global_load_lds_dwordx4 v[172:173], off
	v_lshl_add_u64 v[172:173], v[208:209], 0, s[8:9]
	s_add_i32 m0, s39, 0x2000
	s_nop 0
	global_load_lds_dwordx4 v[172:173], off
	s_setprio 1
	s_barrier
	s_waitcnt lgkmcnt(0)
	v_mfma_f32_16x16x32_bf16 v[108:111], v[204:207], v[168:171], v[108:111]
	v_mfma_f32_16x16x32_bf16 v[100:103], v[216:219], v[168:171], v[100:103]
	v_mfma_f32_16x16x32_bf16 v[92:95], v[204:207], v[180:183], v[92:95]
	v_mfma_f32_16x16x32_bf16 v[88:91], v[216:219], v[180:183], v[88:91]
	v_mfma_f32_16x16x32_bf16 v[84:87], v[204:207], v[188:191], v[84:87]
	v_mfma_f32_16x16x32_bf16 v[80:83], v[216:219], v[188:191], v[80:83]
	v_mfma_f32_16x16x32_bf16 v[68:71], v[204:207], v[196:199], v[68:71]
	v_mfma_f32_16x16x32_bf16 v[64:67], v[216:219], v[196:199], v[64:67]
	v_mfma_f32_16x16x32_bf16 v[108:111], v[212:215], v[176:179], v[108:111]
	v_mfma_f32_16x16x32_bf16 v[100:103], v[220:223], v[176:179], v[100:103]
	v_mfma_f32_16x16x32_bf16 v[92:95], v[212:215], v[184:187], v[92:95]
	v_mfma_f32_16x16x32_bf16 v[88:91], v[220:223], v[184:187], v[88:91]
	v_mfma_f32_16x16x32_bf16 v[84:87], v[212:215], v[192:195], v[84:87]
	v_mfma_f32_16x16x32_bf16 v[80:83], v[220:223], v[192:195], v[80:83]
	v_mfma_f32_16x16x32_bf16 v[68:71], v[212:215], v[200:203], v[68:71]
	v_mfma_f32_16x16x32_bf16 v[64:67], v[220:223], v[200:203], v[64:67]
	s_barrier
	s_setprio 0
	s_mov_b32 m0, s53
	v_lshl_add_u64 v[172:173], v[224:225], 0, s[8:9]
	ds_read_b128 v[168:171], v152 offset:49152
	ds_read_b128 v[176:179], v152 offset:50176
	ds_read_b128 v[180:183], v152 offset:51200
	ds_read_b128 v[184:187], v152 offset:52224
	ds_read_b128 v[188:191], v152 offset:53248
	ds_read_b128 v[192:195], v152 offset:54272
	ds_read_b128 v[196:199], v152 offset:55296
	ds_read_b128 v[200:203], v152 offset:56320
	global_load_lds_dwordx4 v[172:173], off
	v_lshl_add_u64 v[172:173], v[226:227], 0, s[8:9]
	s_mov_b32 m0, s54
	s_nop 0
	global_load_lds_dwordx4 v[172:173], off
	s_setprio 1
	s_barrier
	s_waitcnt lgkmcnt(0)
	v_mfma_f32_16x16x32_bf16 v[60:63], v[144:147], v[168:171], v[60:63]
	v_mfma_f32_16x16x32_bf16 v[56:59], v[160:163], v[168:171], v[56:59]
	v_mfma_f32_16x16x32_bf16 v[44:47], v[144:147], v[180:183], v[44:47]
	v_mfma_f32_16x16x32_bf16 v[40:43], v[160:163], v[180:183], v[40:43]
	v_mfma_f32_16x16x32_bf16 v[28:31], v[144:147], v[188:191], v[28:31]
	v_mfma_f32_16x16x32_bf16 v[24:27], v[160:163], v[188:191], v[24:27]
	v_mfma_f32_16x16x32_bf16 v[12:15], v[144:147], v[196:199], v[12:15]
	v_mfma_f32_16x16x32_bf16 v[8:11], v[160:163], v[196:199], v[8:11]
	v_mfma_f32_16x16x32_bf16 v[60:63], v[156:159], v[176:179], v[60:63]
	v_mfma_f32_16x16x32_bf16 v[56:59], v[164:167], v[176:179], v[56:59]
	v_mfma_f32_16x16x32_bf16 v[44:47], v[156:159], v[184:187], v[44:47]
	v_mfma_f32_16x16x32_bf16 v[40:43], v[164:167], v[184:187], v[40:43]
	v_mfma_f32_16x16x32_bf16 v[28:31], v[156:159], v[192:195], v[28:31]
	v_mfma_f32_16x16x32_bf16 v[24:27], v[164:167], v[192:195], v[24:27]
	v_mfma_f32_16x16x32_bf16 v[12:15], v[156:159], v[200:203], v[12:15]
	v_mfma_f32_16x16x32_bf16 v[8:11], v[164:167], v[200:203], v[8:11]
	s_barrier
	s_setprio 0
	s_add_u32 s36, s36, 0x40080
	s_addc_u32 s37, s37, 0
	s_add_i32 s38, s38, s43
	v_lshl_add_u64 v[144:145], s[36:37], 0, v[130:131]
	s_mov_b32 m0, s38
	s_nop 0
	global_load_lds_dwordx4 v[144:145], off
	v_lshl_add_u64 v[144:145], s[36:37], 0, v[134:135]
	s_add_i32 m0, s38, 0x2000
	s_nop 0
	global_load_lds_dwordx4 v[144:145], off
	s_waitcnt vmcnt(6)
	s_setprio 1
	s_barrier
	v_mfma_f32_16x16x32_bf16 v[52:55], v[204:207], v[168:171], v[52:55]
	v_mfma_f32_16x16x32_bf16 v[48:51], v[216:219], v[168:171], v[48:51]
	v_mfma_f32_16x16x32_bf16 v[36:39], v[204:207], v[180:183], v[36:39]
	v_mfma_f32_16x16x32_bf16 v[32:35], v[216:219], v[180:183], v[32:35]
	v_mfma_f32_16x16x32_bf16 v[20:23], v[204:207], v[188:191], v[20:23]
	v_mfma_f32_16x16x32_bf16 v[16:19], v[216:219], v[188:191], v[16:19]
	v_mfma_f32_16x16x32_bf16 v[4:7], v[204:207], v[196:199], v[4:7]
	v_mfma_f32_16x16x32_bf16 v[0:3], v[216:219], v[196:199], v[0:3]
	v_mfma_f32_16x16x32_bf16 v[52:55], v[212:215], v[176:179], v[52:55]
	v_mfma_f32_16x16x32_bf16 v[48:51], v[220:223], v[176:179], v[48:51]
	v_mfma_f32_16x16x32_bf16 v[36:39], v[212:215], v[184:187], v[36:39]
	v_mfma_f32_16x16x32_bf16 v[32:35], v[220:223], v[184:187], v[32:35]
	v_mfma_f32_16x16x32_bf16 v[20:23], v[212:215], v[192:195], v[20:23]
	v_mfma_f32_16x16x32_bf16 v[16:19], v[220:223], v[192:195], v[16:19]
	v_mfma_f32_16x16x32_bf16 v[4:7], v[212:215], v[200:203], v[4:7]
	v_mfma_f32_16x16x32_bf16 v[0:3], v[220:223], v[200:203], v[0:3]
	s_barrier
	s_setprio 0
	s_add_i32 s67, s67, 2
	s_add_u32 s2, s2, 0x100
	s_addc_u32 s3, s3, 0
	s_add_u32 s65, s65, 0x100
	s_addc_u32 s66, s66, 0
	s_cmp_gt_u32 s67, 13
	s_cbranch_scc0 .LBB0_1080
	v_lshl_add_u32 v146, s0, 8, v148
	v_ashrrev_i32_e32 v147, 31, v146
	v_lshl_add_u64 v[144:145], v[146:147], 2, s[18:19]
	global_load_dword v155, v[144:145], off
	global_load_dword v164, v[144:145], off offset:64
	global_load_dword v165, v[144:145], off offset:128
	global_load_dword v166, v[144:145], off offset:192
	global_load_dword v167, v[144:145], off offset:512
	global_load_dword v168, v[144:145], off offset:576
	global_load_dword v169, v[144:145], off offset:640
	global_load_dword v170, v[144:145], off offset:704
	v_lshl_or_b32 v144, s1, 8, v150
	v_ashrrev_i32_e32 v145, 31, v144
	v_lshlrev_b64 v[160:161], 10, v[146:147]
	v_lshlrev_b64 v[162:163], 1, v[144:145]
	v_lshl_add_u64 v[144:145], s[92:93], 0, v[160:161]
	v_or_b32_e32 v156, 16, v146
	v_ashrrev_i32_e32 v157, 31, v156
	v_or_b32_e32 v158, 32, v146
	v_lshlrev_b64 v[156:157], 10, v[156:157]
	v_lshl_add_u64 v[144:145], v[144:145], 0, v[162:163]
	v_ashrrev_i32_e32 v159, 31, v158
	v_lshl_add_u64 v[156:157], s[92:93], 0, v[156:157]
	v_lshlrev_b64 v[158:159], 10, v[158:159]
	v_lshl_add_u64 v[156:157], v[156:157], 0, v[162:163]
	v_lshl_add_u64 v[158:159], s[92:93], 0, v[158:159]
	v_lshl_add_u64 v[158:159], v[158:159], 0, v[162:163]
	s_mov_b64 s[36:37], s[34:35]
	s_waitcnt vmcnt(0)
	v_fmamk_f32 v147, v155, 0x3a800000, v154
	v_fmamk_f32 v155, v164, 0x3a800000, v154
	v_fmamk_f32 v160, v165, 0x3a800000, v154
	v_mul_f32_e32 v161, 0x4b800000, v147
	v_mul_f32_e32 v164, 0x4b800000, v155
	v_cmp_gt_f32_e32 vcc, s58, v147
	v_cmp_gt_f32_e64 s[0:1], s58, v155
	v_mul_f32_e32 v165, 0x4b800000, v160
	v_cndmask_b32_e32 v147, v147, v161, vcc
	v_cndmask_b32_e64 v155, v155, v164, s[0:1]
	v_cmp_gt_f32_e64 s[2:3], s58, v160
	v_rsq_f32_e32 v147, v147
	v_rsq_f32_e32 v155, v155
	v_cndmask_b32_e64 v160, v160, v165, s[2:3]
	v_rsq_f32_e32 v160, v160
	v_mul_f32_e32 v161, 0x45800000, v147
	v_mul_f32_e32 v164, 0x45800000, v155
	v_cndmask_b32_e32 v147, v147, v161, vcc
	v_mul_f32_e32 v165, 0x45800000, v160
	v_cndmask_b32_e64 v155, v155, v164, s[0:1]
	v_cndmask_b32_e64 v161, v160, v165, s[2:3]
	v_mul_f32_e32 v160, 0x3e0293ee, v147
	v_mul_f32_e32 v164, 0x3e0293ee, v155
	v_fmamk_f32 v171, v166, 0x3a800000, v154
	v_mul_f32_e32 v166, 0x3e0293ee, v161
	v_pk_mul_f32 v[126:127], v[126:127], v[160:161] op_sel_hi:[1,0]
	v_pk_mul_f32 v[124:125], v[124:125], v[160:161] op_sel_hi:[1,0]
	v_pk_mul_f32 v[122:123], v[122:123], v[160:161] op_sel_hi:[1,0]
	v_pk_mul_f32 v[120:121], v[120:121], v[160:161] op_sel_hi:[1,0]
	v_pk_mul_f32 v[110:111], v[110:111], v[160:161] op_sel_hi:[1,0]
	v_pk_mul_f32 v[108:109], v[108:109], v[160:161] op_sel_hi:[1,0]
	v_pk_mul_f32 v[102:103], v[102:103], v[160:161] op_sel_hi:[1,0]
	v_pk_mul_f32 v[100:101], v[100:101], v[160:161] op_sel_hi:[1,0]
	v_pk_mul_f32 v[118:119], v[118:119], v[164:165] op_sel_hi:[1,0]
	v_pk_mul_f32 v[116:117], v[116:117], v[164:165] op_sel_hi:[1,0]
	v_pk_mul_f32 v[114:115], v[114:115], v[164:165] op_sel_hi:[1,0]
	v_pk_mul_f32 v[112:113], v[112:113], v[164:165] op_sel_hi:[1,0]
	v_pk_mul_f32 v[94:95], v[94:95], v[164:165] op_sel_hi:[1,0]
	v_pk_mul_f32 v[92:93], v[92:93], v[164:165] op_sel_hi:[1,0]
	v_pk_mul_f32 v[160:161], v[90:91], v[164:165] op_sel_hi:[1,0]
	v_pk_mul_f32 v[164:165], v[88:89], v[164:165] op_sel_hi:[1,0]
	v_cvt_pk_bf16_f32 v88, v124, v125
	v_cvt_pk_bf16_f32 v89, v126, v127
	v_cvt_pk_bf16_f32 v90, v120, v121
	v_cvt_pk_bf16_f32 v91, v122, v123
	global_store_dwordx4 v[144:145], v[88:91], off
	v_fmamk_f32 v167, v167, 0x3a800000, v154
	v_pk_mul_f32 v[106:107], v[106:107], v[166:167] op_sel_hi:[1,0]
	v_cvt_pk_bf16_f32 v88, v108, v109
	v_cvt_pk_bf16_f32 v89, v110, v111
	v_cvt_pk_bf16_f32 v90, v100, v101
	v_cvt_pk_bf16_f32 v91, v102, v103
	global_store_dwordx4 v[144:145], v[88:91], off offset:256
	v_pk_mul_f32 v[104:105], v[104:105], v[166:167] op_sel_hi:[1,0]
	v_pk_mul_f32 v[98:99], v[98:99], v[166:167] op_sel_hi:[1,0]
	v_cvt_pk_bf16_f32 v88, v116, v117
	v_cvt_pk_bf16_f32 v89, v118, v119
	v_cvt_pk_bf16_f32 v90, v112, v113
	v_cvt_pk_bf16_f32 v91, v114, v115
	global_store_dwordx4 v[156:157], v[88:91], off
	v_pk_mul_f32 v[96:97], v[96:97], v[166:167] op_sel_hi:[1,0]
	v_pk_mul_f32 v[86:87], v[86:87], v[166:167] op_sel_hi:[1,0]
	v_cvt_pk_bf16_f32 v88, v92, v93
	v_cvt_pk_bf16_f32 v89, v94, v95
	v_cvt_pk_bf16_f32 v90, v164, v165
	v_cvt_pk_bf16_f32 v91, v160, v161
	global_store_dwordx4 v[156:157], v[88:91], off offset:256
	v_pk_mul_f32 v[84:85], v[84:85], v[166:167] op_sel_hi:[1,0]
	v_cmp_gt_f32_e32 vcc, s58, v171
	v_cvt_pk_bf16_f32 v88, v104, v105
	v_cvt_pk_bf16_f32 v89, v106, v107
	v_cvt_pk_bf16_f32 v90, v96, v97
	v_cvt_pk_bf16_f32 v91, v98, v99
	global_store_dwordx4 v[158:159], v[88:91], off
	v_fmamk_f32 v168, v168, 0x3a800000, v154
	v_fmamk_f32 v169, v169, 0x3a800000, v154
	v_pk_mul_f32 v[88:89], v[82:83], v[166:167] op_sel_hi:[1,0]
	v_pk_mul_f32 v[82:83], v[80:81], v[166:167] op_sel_hi:[1,0]
	v_cvt_pk_bf16_f32 v80, v84, v85
	v_cvt_pk_bf16_f32 v81, v86, v87
	v_fmamk_f32 v170, v170, 0x3a800000, v154
	v_cvt_pk_bf16_f32 v82, v82, v83
	v_cvt_pk_bf16_f32 v83, v88, v89
	global_store_dwordx4 v[158:159], v[80:83], off offset:256
	s_mov_b32 s1, s26
	s_mov_b32 s0, s28
	v_mul_f32_e32 v82, 0x4b800000, v171
	v_cndmask_b32_e32 v82, v171, v82, vcc
	v_rsq_f32_e32 v82, v82
	v_or_b32_e32 v80, 48, v146
	v_ashrrev_i32_e32 v81, 31, v80
	v_lshlrev_b64 v[80:81], 10, v[80:81]
	v_mul_f32_e32 v83, 0x45800000, v82
	v_cndmask_b32_e32 v82, v82, v83, vcc
	v_lshl_add_u64 v[80:81], s[92:93], 0, v[80:81]
	v_mul_f32_e32 v82, 0x3e0293ee, v82
	v_lshl_add_u64 v[80:81], v[80:81], 0, v[162:163]
	v_pk_mul_f32 v[78:79], v[78:79], v[82:83] op_sel_hi:[1,0]
	v_pk_mul_f32 v[76:77], v[76:77], v[82:83] op_sel_hi:[1,0]
	v_pk_mul_f32 v[84:85], v[74:75], v[82:83] op_sel_hi:[1,0]
	v_pk_mul_f32 v[74:75], v[72:73], v[82:83] op_sel_hi:[1,0]
	v_cvt_pk_bf16_f32 v72, v76, v77
	v_cvt_pk_bf16_f32 v73, v78, v79
	v_pk_mul_f32 v[70:71], v[70:71], v[82:83] op_sel_hi:[1,0]
	v_cvt_pk_bf16_f32 v74, v74, v75
	v_cvt_pk_bf16_f32 v75, v84, v85
	global_store_dwordx4 v[80:81], v[72:75], off
	v_pk_mul_f32 v[68:69], v[68:69], v[82:83] op_sel_hi:[1,0]
	v_cmp_gt_f32_e32 vcc, s58, v167
	v_pk_mul_f32 v[72:73], v[66:67], v[82:83] op_sel_hi:[1,0]
	v_pk_mul_f32 v[66:67], v[64:65], v[82:83] op_sel_hi:[1,0]
	v_cvt_pk_bf16_f32 v64, v68, v69
	v_cvt_pk_bf16_f32 v65, v70, v71
	s_mov_b64 s[2:3], s[30:31]
	v_cvt_pk_bf16_f32 v66, v66, v67
	v_mul_f32_e32 v67, 0x4b800000, v167
	v_cndmask_b32_e32 v67, v167, v67, vcc
	v_rsq_f32_e32 v68, v67
	v_cvt_pk_bf16_f32 v67, v72, v73
	global_store_dwordx4 v[80:81], v[64:67], off offset:256
	s_nop 1
	v_mul_f32_e32 v66, 0x45800000, v68
	v_cndmask_b32_e32 v66, v68, v66, vcc
	v_mul_f32_e32 v66, 0x3e0293ee, v66
	v_pk_mul_f32 v[60:61], v[60:61], v[66:67] op_sel_hi:[1,0]
	v_pk_mul_f32 v[68:69], v[58:59], v[66:67] op_sel_hi:[1,0]
	v_pk_mul_f32 v[58:59], v[56:57], v[66:67] op_sel_hi:[1,0]
	v_cvt_pk_bf16_f32 v56, v60, v61
	v_add_co_u32_e32 v60, vcc, s59, v144
	v_pk_mul_f32 v[62:63], v[62:63], v[66:67] op_sel_hi:[1,0]
	s_nop 0
	v_addc_co_u32_e32 v61, vcc, 0, v145, vcc
	v_cvt_pk_bf16_f32 v57, v62, v63
	v_cvt_pk_bf16_f32 v58, v58, v59
	v_cvt_pk_bf16_f32 v59, v68, v69
	global_store_dwordx4 v[60:61], v[56:59], off
	v_pk_mul_f32 v[54:55], v[54:55], v[66:67] op_sel_hi:[1,0]
	v_pk_mul_f32 v[52:53], v[52:53], v[66:67] op_sel_hi:[1,0]
	v_pk_mul_f32 v[56:57], v[50:51], v[66:67] op_sel_hi:[1,0]
	v_pk_mul_f32 v[50:51], v[48:49], v[66:67] op_sel_hi:[1,0]
	v_cvt_pk_bf16_f32 v48, v52, v53
	v_cvt_pk_bf16_f32 v49, v54, v55
	v_cmp_gt_f32_e32 vcc, s58, v168
	v_cvt_pk_bf16_f32 v50, v50, v51
	v_mul_f32_e32 v51, 0x4b800000, v168
	v_lshl_add_u64 v[64:65], v[144:145], 0, s[14:15]
	v_cndmask_b32_e32 v51, v168, v51, vcc
	v_rsq_f32_e32 v52, v51
	v_cvt_pk_bf16_f32 v51, v56, v57
	global_store_dwordx4 v[64:65], v[48:51], off offset:256
	s_nop 1
	v_mul_f32_e32 v50, 0x45800000, v52
	v_cndmask_b32_e32 v50, v52, v50, vcc
	v_mul_f32_e32 v50, 0x3e0293ee, v50
	v_pk_mul_f32 v[44:45], v[44:45], v[50:51] op_sel_hi:[1,0]
	v_pk_mul_f32 v[52:53], v[42:43], v[50:51] op_sel_hi:[1,0]
	v_pk_mul_f32 v[42:43], v[40:41], v[50:51] op_sel_hi:[1,0]
	v_cvt_pk_bf16_f32 v40, v44, v45
	v_add_co_u32_e32 v44, vcc, s60, v144
	v_pk_mul_f32 v[46:47], v[46:47], v[50:51] op_sel_hi:[1,0]
	s_nop 0
	v_addc_co_u32_e32 v45, vcc, 0, v145, vcc
	v_cvt_pk_bf16_f32 v41, v46, v47
	v_cvt_pk_bf16_f32 v42, v42, v43
	v_cvt_pk_bf16_f32 v43, v52, v53
	global_store_dwordx4 v[44:45], v[40:43], off
	v_pk_mul_f32 v[38:39], v[38:39], v[50:51] op_sel_hi:[1,0]
	v_pk_mul_f32 v[36:37], v[36:37], v[50:51] op_sel_hi:[1,0]
	v_pk_mul_f32 v[40:41], v[34:35], v[50:51] op_sel_hi:[1,0]
	v_pk_mul_f32 v[34:35], v[32:33], v[50:51] op_sel_hi:[1,0]
	v_cvt_pk_bf16_f32 v32, v36, v37
	v_cvt_pk_bf16_f32 v33, v38, v39
	v_cmp_gt_f32_e32 vcc, s58, v169
	v_cvt_pk_bf16_f32 v34, v34, v35
	v_mul_f32_e32 v35, 0x4b800000, v169
	v_lshl_add_u64 v[48:49], v[144:145], 0, s[20:21]
	v_cndmask_b32_e32 v35, v169, v35, vcc
	v_rsq_f32_e32 v36, v35
	v_cvt_pk_bf16_f32 v35, v40, v41
	global_store_dwordx4 v[48:49], v[32:35], off offset:256
	s_nop 1
	v_mul_f32_e32 v34, 0x45800000, v36
	v_cndmask_b32_e32 v34, v36, v34, vcc
	v_mul_f32_e32 v34, 0x3e0293ee, v34
	v_pk_mul_f32 v[28:29], v[28:29], v[34:35] op_sel_hi:[1,0]
	v_pk_mul_f32 v[36:37], v[26:27], v[34:35] op_sel_hi:[1,0]
	v_pk_mul_f32 v[26:27], v[24:25], v[34:35] op_sel_hi:[1,0]
	v_cvt_pk_bf16_f32 v24, v28, v29
	v_add_co_u32_e32 v28, vcc, s61, v144
	v_pk_mul_f32 v[30:31], v[30:31], v[34:35] op_sel_hi:[1,0]
	s_nop 0
	v_addc_co_u32_e32 v29, vcc, 0, v145, vcc
	v_cvt_pk_bf16_f32 v25, v30, v31
	v_cvt_pk_bf16_f32 v26, v26, v27
	v_cvt_pk_bf16_f32 v27, v36, v37
	global_store_dwordx4 v[28:29], v[24:27], off
	v_pk_mul_f32 v[22:23], v[22:23], v[34:35] op_sel_hi:[1,0]
	v_pk_mul_f32 v[20:21], v[20:21], v[34:35] op_sel_hi:[1,0]
	v_pk_mul_f32 v[24:25], v[18:19], v[34:35] op_sel_hi:[1,0]
	v_pk_mul_f32 v[18:19], v[16:17], v[34:35] op_sel_hi:[1,0]
	v_cvt_pk_bf16_f32 v16, v20, v21
	v_cvt_pk_bf16_f32 v17, v22, v23
	v_cmp_gt_f32_e32 vcc, s58, v170
	v_cvt_pk_bf16_f32 v18, v18, v19
	v_mul_f32_e32 v19, 0x4b800000, v170
	v_lshl_add_u64 v[32:33], v[144:145], 0, s[22:23]
	v_cndmask_b32_e32 v19, v170, v19, vcc
	v_rsq_f32_e32 v20, v19
	v_cvt_pk_bf16_f32 v19, v24, v25
	global_store_dwordx4 v[32:33], v[16:19], off offset:256
	s_nop 1
	v_mul_f32_e32 v18, 0x45800000, v20
	v_cndmask_b32_e32 v18, v20, v18, vcc
	v_mul_f32_e32 v18, 0x3e0293ee, v18
	v_pk_mul_f32 v[12:13], v[12:13], v[18:19] op_sel_hi:[1,0]
	v_pk_mul_f32 v[20:21], v[10:11], v[18:19] op_sel_hi:[1,0]
	v_pk_mul_f32 v[10:11], v[8:9], v[18:19] op_sel_hi:[1,0]
	v_cvt_pk_bf16_f32 v8, v12, v13
	v_add_co_u32_e32 v12, vcc, s62, v144
	v_pk_mul_f32 v[14:15], v[14:15], v[18:19] op_sel_hi:[1,0]
	s_nop 0
	v_addc_co_u32_e32 v13, vcc, 0, v145, vcc
	v_cvt_pk_bf16_f32 v9, v14, v15
	v_lshl_add_u64 v[16:17], v[144:145], 0, s[24:25]
	v_cvt_pk_bf16_f32 v10, v10, v11
	v_cvt_pk_bf16_f32 v11, v20, v21
	global_store_dwordx4 v[12:13], v[8:11], off
	s_and_b64 vcc, exec, s[6:7]
	v_pk_mul_f32 v[6:7], v[6:7], v[18:19] op_sel_hi:[1,0]
	v_pk_mul_f32 v[8:9], v[2:3], v[18:19] op_sel_hi:[1,0]
	v_pk_mul_f32 v[2:3], v[0:1], v[18:19] op_sel_hi:[1,0]
	v_pk_mul_f32 v[4:5], v[4:5], v[18:19] op_sel_hi:[1,0]
	s_nop 0
	v_cvt_pk_bf16_f32 v0, v4, v5
	v_cvt_pk_bf16_f32 v1, v6, v7
	v_cvt_pk_bf16_f32 v2, v2, v3
	v_cvt_pk_bf16_f32 v3, v8, v9
	global_store_dwordx4 v[16:17], v[0:3], off offset:256
	s_cbranch_vccz .LBB0_1073
	s_waitcnt vmcnt(0)
	s_cmpk_gt_u32 s33, 0xff
	s_cbranch_scc1 .LBB0_1084
	s_barrier

.LBB0_1160:
	ds_read_b128 v[144:147], v178
	ds_read_b128 v[148:151], v178 offset:1024
	ds_read_b128 v[152:155], v178 offset:2048
	ds_read_b128 v[156:159], v178 offset:3072
	s_add_u32 s38, s36, 0xfffe0080
	s_addc_u32 s39, s37, -1
	s_cmp_eq_u32 s62, 4
	s_cselect_b32 s41, s25, s39
	s_cselect_b32 s40, s31, s38
	s_cselect_b32 s39, s23, s61
	s_cselect_b32 s38, s59, s60
	v_lshl_add_u64 v[172:173], s[36:37], 0, v[136:137]
	s_add_i32 m0, s35, 0xc000
	ds_read_b128 v[160:163], v179
	ds_read_b128 v[164:167], v179 offset:1024
	ds_read_b128 v[168:171], v179 offset:2048
	ds_read_b128 v[182:185], v179 offset:3072
	ds_read_b128 v[186:189], v179 offset:4096
	ds_read_b128 v[190:193], v179 offset:5120
	ds_read_b128 v[194:197], v179 offset:6144
	ds_read_b128 v[198:201], v179 offset:7168
	global_load_lds_dwordx4 v[172:173], off
	v_lshl_add_u64 v[172:173], s[36:37], 0, v[138:139]
	s_add_i32 m0, s35, 0xe000
	s_nop 0
	global_load_lds_dwordx4 v[172:173], off
	s_waitcnt lgkmcnt(8)
	s_setprio 1
	s_barrier
	s_waitcnt lgkmcnt(0)
	v_mfma_f32_16x16x32_bf16 v[124:127], v[144:147], v[160:163], v[124:127]
	v_mfma_f32_16x16x32_bf16 v[120:123], v[152:155], v[160:163], v[120:123]
	v_mfma_f32_16x16x32_bf16 v[108:111], v[144:147], v[168:171], v[108:111]
	v_mfma_f32_16x16x32_bf16 v[104:107], v[152:155], v[168:171], v[104:107]
	v_mfma_f32_16x16x32_bf16 v[96:99], v[144:147], v[186:189], v[96:99]
	v_mfma_f32_16x16x32_bf16 v[88:91], v[152:155], v[186:189], v[88:91]
	v_mfma_f32_16x16x32_bf16 v[80:83], v[144:147], v[194:197], v[80:83]
	v_mfma_f32_16x16x32_bf16 v[72:75], v[152:155], v[194:197], v[72:75]
	v_mfma_f32_16x16x32_bf16 v[124:127], v[148:151], v[164:167], v[124:127]
	v_mfma_f32_16x16x32_bf16 v[120:123], v[156:159], v[164:167], v[120:123]
	v_mfma_f32_16x16x32_bf16 v[108:111], v[148:151], v[182:185], v[108:111]
	v_mfma_f32_16x16x32_bf16 v[104:107], v[156:159], v[182:185], v[104:107]
	v_mfma_f32_16x16x32_bf16 v[96:99], v[148:151], v[190:193], v[96:99]
	v_mfma_f32_16x16x32_bf16 v[88:91], v[156:159], v[190:193], v[88:91]
	v_mfma_f32_16x16x32_bf16 v[80:83], v[148:151], v[198:201], v[80:83]
	v_mfma_f32_16x16x32_bf16 v[72:75], v[156:159], v[198:201], v[72:75]
	s_barrier
	s_setprio 0
	s_add_i32 s63, s57, s48
	v_lshl_add_u64 v[172:173], s[38:39], 0, v[130:131]
	s_mov_b32 m0, s63
	ds_read_b128 v[202:205], v180
	ds_read_b128 v[206:209], v180 offset:1024
	ds_read_b128 v[212:215], v180 offset:2048
	ds_read_b128 v[216:219], v180 offset:3072
	global_load_lds_dwordx4 v[172:173], off
	v_lshl_add_u64 v[220:221], s[38:39], 0, v[134:135]
	s_add_i32 m0, s63, 0x2000
	s_nop 0
	global_load_lds_dwordx4 v[220:221], off
	s_setprio 1
	s_barrier
	s_waitcnt lgkmcnt(0)
	v_mfma_f32_16x16x32_bf16 v[116:119], v[202:205], v[160:163], v[116:119]
	v_mfma_f32_16x16x32_bf16 v[112:115], v[212:215], v[160:163], v[112:115]
	v_mfma_f32_16x16x32_bf16 v[100:103], v[202:205], v[168:171], v[100:103]
	v_mfma_f32_16x16x32_bf16 v[92:95], v[212:215], v[168:171], v[92:95]
	v_mfma_f32_16x16x32_bf16 v[84:87], v[202:205], v[186:189], v[84:87]
	v_mfma_f32_16x16x32_bf16 v[76:79], v[212:215], v[186:189], v[76:79]
	v_mfma_f32_16x16x32_bf16 v[68:71], v[202:205], v[194:197], v[68:71]
	v_mfma_f32_16x16x32_bf16 v[64:67], v[212:215], v[194:197], v[64:67]
	v_mfma_f32_16x16x32_bf16 v[116:119], v[206:209], v[164:167], v[116:119]
	v_mfma_f32_16x16x32_bf16 v[112:115], v[216:219], v[164:167], v[112:115]
	v_mfma_f32_16x16x32_bf16 v[100:103], v[206:209], v[182:185], v[100:103]
	v_mfma_f32_16x16x32_bf16 v[92:95], v[216:219], v[182:185], v[92:95]
	v_mfma_f32_16x16x32_bf16 v[84:87], v[206:209], v[190:193], v[84:87]
	v_mfma_f32_16x16x32_bf16 v[76:79], v[216:219], v[190:193], v[76:79]
	v_mfma_f32_16x16x32_bf16 v[68:71], v[206:209], v[198:201], v[68:71]
	v_mfma_f32_16x16x32_bf16 v[64:67], v[216:219], v[198:201], v[64:67]
	s_barrier
	s_setprio 0
	s_mov_b32 m0, s35
	v_lshl_add_u64 v[222:223], s[40:41], 0, v[128:129]
	ds_read_b128 v[160:163], v179 offset:16384
	ds_read_b128 v[164:167], v179 offset:17408
	ds_read_b128 v[168:171], v179 offset:18432
	ds_read_b128 v[182:185], v179 offset:19456
	ds_read_b128 v[186:189], v179 offset:20480
	ds_read_b128 v[190:193], v179 offset:21504
	ds_read_b128 v[194:197], v179 offset:22528
	ds_read_b128 v[198:201], v179 offset:23552
	global_load_lds_dwordx4 v[222:223], off
	v_lshl_add_u64 v[224:225], s[40:41], 0, v[132:133]
	s_mov_b32 m0, s49
	s_nop 0
	global_load_lds_dwordx4 v[224:225], off
	s_setprio 1
	s_barrier
	s_waitcnt lgkmcnt(0)
	v_mfma_f32_16x16x32_bf16 v[60:63], v[144:147], v[160:163], v[60:63]
	v_mfma_f32_16x16x32_bf16 v[56:59], v[152:155], v[160:163], v[56:59]
	v_mfma_f32_16x16x32_bf16 v[44:47], v[144:147], v[168:171], v[44:47]
	v_mfma_f32_16x16x32_bf16 v[40:43], v[152:155], v[168:171], v[40:43]
	v_mfma_f32_16x16x32_bf16 v[32:35], v[144:147], v[186:189], v[32:35]
	v_mfma_f32_16x16x32_bf16 v[24:27], v[152:155], v[186:189], v[24:27]
	v_mfma_f32_16x16x32_bf16 v[16:19], v[144:147], v[194:197], v[16:19]
	v_mfma_f32_16x16x32_bf16 v[8:11], v[152:155], v[194:197], v[8:11]
	v_mfma_f32_16x16x32_bf16 v[60:63], v[148:151], v[164:167], v[60:63]
	v_mfma_f32_16x16x32_bf16 v[56:59], v[156:159], v[164:167], v[56:59]
	v_mfma_f32_16x16x32_bf16 v[44:47], v[148:151], v[182:185], v[44:47]
	v_mfma_f32_16x16x32_bf16 v[40:43], v[156:159], v[182:185], v[40:43]
	v_mfma_f32_16x16x32_bf16 v[32:35], v[148:151], v[190:193], v[32:35]
	v_mfma_f32_16x16x32_bf16 v[24:27], v[156:159], v[190:193], v[24:27]
	v_mfma_f32_16x16x32_bf16 v[16:19], v[148:151], v[198:201], v[16:19]
	v_mfma_f32_16x16x32_bf16 v[8:11], v[156:159], v[198:201], v[8:11]
	s_barrier
	s_setprio 0
	s_add_u32 s64, s38, 0x20000
	s_addc_u32 s65, s39, 0
	s_add_i32 s63, s58, s48
	v_lshl_add_u64 v[144:145], s[64:65], 0, v[130:131]
	s_mov_b32 m0, s63
	s_nop 0
	global_load_lds_dwordx4 v[144:145], off
	v_lshl_add_u64 v[144:145], s[64:65], 0, v[134:135]
	s_add_i32 m0, s63, 0x2000
	s_nop 0
	global_load_lds_dwordx4 v[144:145], off
	s_waitcnt vmcnt(6)
	s_setprio 1
	s_barrier
	v_mfma_f32_16x16x32_bf16 v[52:55], v[202:205], v[160:163], v[52:55]
	v_mfma_f32_16x16x32_bf16 v[48:51], v[212:215], v[160:163], v[48:51]
	v_mfma_f32_16x16x32_bf16 v[36:39], v[202:205], v[168:171], v[36:39]
	v_mfma_f32_16x16x32_bf16 v[28:31], v[212:215], v[168:171], v[28:31]
	v_mfma_f32_16x16x32_bf16 v[20:23], v[202:205], v[186:189], v[20:23]
	v_mfma_f32_16x16x32_bf16 v[12:15], v[212:215], v[186:189], v[12:15]
	v_mfma_f32_16x16x32_bf16 v[4:7], v[202:205], v[194:197], v[4:7]
	v_mfma_f32_16x16x32_bf16 v[0:3], v[212:215], v[194:197], v[0:3]
	v_mfma_f32_16x16x32_bf16 v[52:55], v[206:209], v[164:167], v[52:55]
	v_mfma_f32_16x16x32_bf16 v[48:51], v[216:219], v[164:167], v[48:51]
	v_mfma_f32_16x16x32_bf16 v[36:39], v[206:209], v[182:185], v[36:39]
	v_mfma_f32_16x16x32_bf16 v[28:31], v[216:219], v[182:185], v[28:31]
	v_mfma_f32_16x16x32_bf16 v[20:23], v[206:209], v[190:193], v[20:23]
	v_mfma_f32_16x16x32_bf16 v[12:15], v[216:219], v[190:193], v[12:15]
	v_mfma_f32_16x16x32_bf16 v[4:7], v[206:209], v[198:201], v[4:7]
	v_mfma_f32_16x16x32_bf16 v[0:3], v[216:219], v[198:201], v[0:3]
	s_barrier
	s_setprio 0
	s_add_i32 s63, 0, 0x18000
	v_add_u32_e32 v156, s63, v176
	ds_read_b128 v[144:147], v156
	ds_read_b128 v[148:151], v156 offset:1024
	ds_read_b128 v[152:155], v156 offset:2048
	ds_read_b128 v[156:159], v156 offset:3072
	s_add_u32 s40, s40, 0x20000
	s_addc_u32 s41, s41, 0
	s_mov_b32 m0, s50
	v_lshl_add_u64 v[202:203], s[40:41], 0, v[128:129]
	ds_read_b128 v[160:163], v179 offset:32768
	ds_read_b128 v[164:167], v179 offset:33792
	ds_read_b128 v[168:171], v179 offset:34816
	ds_read_b128 v[182:185], v179 offset:35840
	ds_read_b128 v[186:189], v179 offset:36864
	ds_read_b128 v[190:193], v179 offset:37888
	ds_read_b128 v[194:197], v179 offset:38912
	ds_read_b128 v[198:201], v179 offset:39936
	global_load_lds_dwordx4 v[202:203], off
	v_lshl_add_u64 v[202:203], s[40:41], 0, v[132:133]
	s_mov_b32 m0, s51
	s_nop 0
	global_load_lds_dwordx4 v[202:203], off
	s_waitcnt lgkmcnt(8)
	s_setprio 1
	s_barrier
	s_waitcnt lgkmcnt(0)
	v_mfma_f32_16x16x32_bf16 v[124:127], v[144:147], v[160:163], v[124:127]
	v_mfma_f32_16x16x32_bf16 v[120:123], v[152:155], v[160:163], v[120:123]
	v_mfma_f32_16x16x32_bf16 v[108:111], v[144:147], v[168:171], v[108:111]
	v_mfma_f32_16x16x32_bf16 v[104:107], v[152:155], v[168:171], v[104:107]
	v_mfma_f32_16x16x32_bf16 v[96:99], v[144:147], v[186:189], v[96:99]
	v_mfma_f32_16x16x32_bf16 v[88:91], v[152:155], v[186:189], v[88:91]
	v_mfma_f32_16x16x32_bf16 v[80:83], v[144:147], v[194:197], v[80:83]
	v_mfma_f32_16x16x32_bf16 v[72:75], v[152:155], v[194:197], v[72:75]
	v_mfma_f32_16x16x32_bf16 v[124:127], v[148:151], v[164:167], v[124:127]
	v_mfma_f32_16x16x32_bf16 v[120:123], v[156:159], v[164:167], v[120:123]
	v_mfma_f32_16x16x32_bf16 v[108:111], v[148:151], v[182:185], v[108:111]
	v_mfma_f32_16x16x32_bf16 v[104:107], v[156:159], v[182:185], v[104:107]
	v_mfma_f32_16x16x32_bf16 v[96:99], v[148:151], v[190:193], v[96:99]
	v_mfma_f32_16x16x32_bf16 v[88:91], v[156:159], v[190:193], v[88:91]
	v_mfma_f32_16x16x32_bf16 v[80:83], v[148:151], v[198:201], v[80:83]
	v_mfma_f32_16x16x32_bf16 v[72:75], v[156:159], v[198:201], v[72:75]
	s_barrier
	s_setprio 0
	s_add_i32 s40, 0, 0x1c000
	s_add_i32 s41, s63, s48
	v_add_u32_e32 v181, s40, v176
	v_lshl_add_u64 v[172:173], v[172:173], 0, s[0:1]
	s_mov_b32 m0, s41
	ds_read_b128 v[202:205], v181
	ds_read_b128 v[206:209], v181 offset:1024
	ds_read_b128 v[212:215], v181 offset:2048
	ds_read_b128 v[216:219], v181 offset:3072
	global_load_lds_dwordx4 v[172:173], off
	v_lshl_add_u64 v[172:173], v[220:221], 0, s[0:1]
	s_add_i32 m0, s41, 0x2000
	s_nop 0
	global_load_lds_dwordx4 v[172:173], off
	s_setprio 1
	s_barrier
	s_waitcnt lgkmcnt(0)
	v_mfma_f32_16x16x32_bf16 v[116:119], v[202:205], v[160:163], v[116:119]
	v_mfma_f32_16x16x32_bf16 v[112:115], v[212:215], v[160:163], v[112:115]
	v_mfma_f32_16x16x32_bf16 v[100:103], v[202:205], v[168:171], v[100:103]
	v_mfma_f32_16x16x32_bf16 v[92:95], v[212:215], v[168:171], v[92:95]
	v_mfma_f32_16x16x32_bf16 v[84:87], v[202:205], v[186:189], v[84:87]
	v_mfma_f32_16x16x32_bf16 v[76:79], v[212:215], v[186:189], v[76:79]
	v_mfma_f32_16x16x32_bf16 v[68:71], v[202:205], v[194:197], v[68:71]
	v_mfma_f32_16x16x32_bf16 v[64:67], v[212:215], v[194:197], v[64:67]
	v_mfma_f32_16x16x32_bf16 v[116:119], v[206:209], v[164:167], v[116:119]
	v_mfma_f32_16x16x32_bf16 v[112:115], v[216:219], v[164:167], v[112:115]
	v_mfma_f32_16x16x32_bf16 v[100:103], v[206:209], v[182:185], v[100:103]
	v_mfma_f32_16x16x32_bf16 v[92:95], v[216:219], v[182:185], v[92:95]
	v_mfma_f32_16x16x32_bf16 v[84:87], v[206:209], v[190:193], v[84:87]
	v_mfma_f32_16x16x32_bf16 v[76:79], v[216:219], v[190:193], v[76:79]
	v_mfma_f32_16x16x32_bf16 v[68:71], v[206:209], v[198:201], v[68:71]
	v_mfma_f32_16x16x32_bf16 v[64:67], v[216:219], v[198:201], v[64:67]
	s_barrier
	s_setprio 0
	s_mov_b32 m0, s53
	v_lshl_add_u64 v[172:173], v[222:223], 0, s[0:1]
	ds_read_b128 v[160:163], v179 offset:49152
	ds_read_b128 v[164:167], v179 offset:50176
	ds_read_b128 v[168:171], v179 offset:51200
	ds_read_b128 v[182:185], v179 offset:52224
	ds_read_b128 v[186:189], v179 offset:53248
	ds_read_b128 v[190:193], v179 offset:54272
	ds_read_b128 v[194:197], v179 offset:55296
	ds_read_b128 v[198:201], v179 offset:56320
	global_load_lds_dwordx4 v[172:173], off
	v_lshl_add_u64 v[172:173], v[224:225], 0, s[0:1]
	s_mov_b32 m0, s54
	s_nop 0
	global_load_lds_dwordx4 v[172:173], off
	s_setprio 1
	s_barrier
	s_waitcnt lgkmcnt(0)
	v_mfma_f32_16x16x32_bf16 v[60:63], v[144:147], v[160:163], v[60:63]
	v_mfma_f32_16x16x32_bf16 v[56:59], v[152:155], v[160:163], v[56:59]
	v_mfma_f32_16x16x32_bf16 v[44:47], v[144:147], v[168:171], v[44:47]
	v_mfma_f32_16x16x32_bf16 v[40:43], v[152:155], v[168:171], v[40:43]
	v_mfma_f32_16x16x32_bf16 v[32:35], v[144:147], v[186:189], v[32:35]
	v_mfma_f32_16x16x32_bf16 v[24:27], v[152:155], v[186:189], v[24:27]
	v_mfma_f32_16x16x32_bf16 v[16:19], v[144:147], v[194:197], v[16:19]
	v_mfma_f32_16x16x32_bf16 v[8:11], v[152:155], v[194:197], v[8:11]
	v_mfma_f32_16x16x32_bf16 v[60:63], v[148:151], v[164:167], v[60:63]
	v_mfma_f32_16x16x32_bf16 v[56:59], v[156:159], v[164:167], v[56:59]
	v_mfma_f32_16x16x32_bf16 v[44:47], v[148:151], v[182:185], v[44:47]
	v_mfma_f32_16x16x32_bf16 v[40:43], v[156:159], v[182:185], v[40:43]
	v_mfma_f32_16x16x32_bf16 v[32:35], v[148:151], v[190:193], v[32:35]
	v_mfma_f32_16x16x32_bf16 v[24:27], v[156:159], v[190:193], v[24:27]
	v_mfma_f32_16x16x32_bf16 v[16:19], v[148:151], v[198:201], v[16:19]
	v_mfma_f32_16x16x32_bf16 v[8:11], v[156:159], v[198:201], v[8:11]
	s_barrier
	s_setprio 0
	s_add_u32 s38, s38, 0x20080
	s_addc_u32 s39, s39, 0
	s_add_i32 s40, s40, s48
	v_lshl_add_u64 v[144:145], s[38:39], 0, v[130:131]
	s_mov_b32 m0, s40
	s_nop 0
	global_load_lds_dwordx4 v[144:145], off
	v_lshl_add_u64 v[144:145], s[38:39], 0, v[134:135]
	s_add_i32 m0, s40, 0x2000
	s_nop 0
	global_load_lds_dwordx4 v[144:145], off
	s_waitcnt vmcnt(6)
	s_setprio 1
	s_barrier
	v_mfma_f32_16x16x32_bf16 v[52:55], v[202:205], v[160:163], v[52:55]
	v_mfma_f32_16x16x32_bf16 v[48:51], v[212:215], v[160:163], v[48:51]
	v_mfma_f32_16x16x32_bf16 v[36:39], v[202:205], v[168:171], v[36:39]
	v_mfma_f32_16x16x32_bf16 v[28:31], v[212:215], v[168:171], v[28:31]
	v_mfma_f32_16x16x32_bf16 v[20:23], v[202:205], v[186:189], v[20:23]
	v_mfma_f32_16x16x32_bf16 v[12:15], v[212:215], v[186:189], v[12:15]
	v_mfma_f32_16x16x32_bf16 v[4:7], v[202:205], v[194:197], v[4:7]
	v_mfma_f32_16x16x32_bf16 v[0:3], v[212:215], v[194:197], v[0:3]
	v_mfma_f32_16x16x32_bf16 v[52:55], v[206:209], v[164:167], v[52:55]
	v_mfma_f32_16x16x32_bf16 v[48:51], v[216:219], v[164:167], v[48:51]
	v_mfma_f32_16x16x32_bf16 v[36:39], v[206:209], v[182:185], v[36:39]
	v_mfma_f32_16x16x32_bf16 v[28:31], v[216:219], v[182:185], v[28:31]
	v_mfma_f32_16x16x32_bf16 v[20:23], v[206:209], v[190:193], v[20:23]
	v_mfma_f32_16x16x32_bf16 v[12:15], v[216:219], v[190:193], v[12:15]
	v_mfma_f32_16x16x32_bf16 v[4:7], v[206:209], v[198:201], v[4:7]
	v_mfma_f32_16x16x32_bf16 v[0:3], v[216:219], v[198:201], v[0:3]
	s_barrier
	s_setprio 0
	s_add_i32 s62, s62, 2
	s_add_u32 s36, s36, 0x100
	s_addc_u32 s37, s37, 0
	s_add_u32 s60, s60, 0x100
	s_addc_u32 s61, s61, 0
	s_cmp_gt_u32 s62, 5
	s_cbranch_scc0 .LBB0_1160
	v_lshl_or_b32 v144, s34, 8, v177
	v_lshl_add_u32 v150, s30, 8, v175
	v_ashrrev_i32_e32 v145, 31, v144
	v_ashrrev_i32_e32 v151, 31, v150
	v_lshlrev_b64 v[144:145], 1, v[144:145]
	v_lshl_add_u64 v[146:147], s[10:11], 0, v[144:145]
	v_lshlrev_b64 v[148:149], 11, v[150:151]
	v_lshl_add_u64 v[152:153], v[146:147], 0, v[148:149]
	global_load_dwordx4 v[156:159], v[152:153], off
	global_load_dwordx4 v[160:163], v[152:153], off offset:256
	v_or_b32_e32 v152, 16, v150
	v_ashrrev_i32_e32 v153, 31, v152
	v_lshlrev_b64 v[170:171], 11, v[152:153]
	v_lshl_add_u64 v[152:153], v[146:147], 0, v[170:171]
	global_load_dwordx4 v[164:167], v[152:153], off
	global_load_dwordx4 v[182:185], v[152:153], off offset:256
	v_or_b32_e32 v152, 32, v150
	v_ashrrev_i32_e32 v153, 31, v152
	v_lshlrev_b64 v[154:155], 11, v[152:153]
	v_lshl_add_u64 v[152:153], v[146:147], 0, v[154:155]
	global_load_dwordx4 v[186:189], v[152:153], off
	global_load_dwordx4 v[190:193], v[152:153], off offset:256
	v_or_b32_e32 v152, 48, v150
	v_ashrrev_i32_e32 v153, 31, v152
	v_lshlrev_b64 v[152:153], 11, v[152:153]
	v_lshl_add_u64 v[168:169], v[146:147], 0, v[152:153]
	global_load_dwordx4 v[194:197], v[168:169], off
	global_load_dwordx4 v[198:201], v[168:169], off offset:256
	s_waitcnt vmcnt(0)
	v_lshlrev_b32_e32 v202, 16, v156
	v_and_b32_e32 v203, 0xffff0000, v156
	v_lshlrev_b32_e32 v204, 16, v157
	v_and_b32_e32 v205, 0xffff0000, v157
	v_lshlrev_b32_e32 v206, 16, v158
	v_and_b32_e32 v207, 0xffff0000, v158
	v_lshlrev_b32_e32 v208, 16, v159
	v_and_b32_e32 v209, 0xffff0000, v159
	v_pk_add_f32 v[126:127], v[126:127], v[204:205]
	v_pk_add_f32 v[124:125], v[124:125], v[202:203]
	v_lshlrev_b32_e32 v224, 16, v166
	v_and_b32_e32 v225, 0xffff0000, v166
	v_lshlrev_b32_e32 v226, 16, v167
	v_and_b32_e32 v227, 0xffff0000, v167
	v_lshlrev_b32_e32 v212, 16, v160
	v_lshlrev_b32_e32 v166, 16, v194
	v_and_b32_e32 v167, 0xffff0000, v194
	v_lshlrev_b32_e32 v172, 16, v195
	v_and_b32_e32 v173, 0xffff0000, v195
	v_pk_add_f32 v[194:195], v[122:123], v[208:209]
	v_pk_add_f32 v[122:123], v[120:121], v[206:207]
	v_mul_f32_e32 v120, v125, v125
	v_mul_f32_e32 v121, v127, v127
	v_fmac_f32_e32 v120, v124, v124
	v_fmac_f32_e32 v121, v126, v126
	v_add_f32_e32 v120, v120, v121
	v_mul_f32_e32 v121, v123, v123
	v_fmac_f32_e32 v121, v122, v122
	v_add_f32_e32 v120, v121, v120
	v_mul_f32_e32 v121, v195, v195
	v_fmac_f32_e32 v121, v194, v194
	v_and_b32_e32 v213, 0xffff0000, v160
	v_lshlrev_b32_e32 v214, 16, v161
	v_and_b32_e32 v215, 0xffff0000, v161
	v_add_f32_e32 v181, v121, v120
	v_cvt_pk_bf16_f32 v120, v124, v125
	v_lshl_add_u64 v[124:125], s[90:91], 0, v[148:149]
	v_lshlrev_b32_e32 v216, 16, v162
	v_and_b32_e32 v217, 0xffff0000, v162
	v_lshlrev_b32_e32 v218, 16, v163
	v_and_b32_e32 v219, 0xffff0000, v163
	v_cvt_pk_bf16_f32 v121, v126, v127
	v_lshl_add_u64 v[124:125], v[124:125], 0, v[144:145]
	v_pk_add_f32 v[118:119], v[118:119], v[214:215]
	v_pk_add_f32 v[116:117], v[116:117], v[212:213]
	v_cvt_pk_bf16_f32 v122, v122, v123
	v_cvt_pk_bf16_f32 v123, v194, v195
	global_store_dwordx4 v[124:125], v[120:123], off
	v_lshlrev_b32_e32 v220, 16, v164
	v_and_b32_e32 v221, 0xffff0000, v164
	v_pk_add_f32 v[120:121], v[114:115], v[218:219]
	v_pk_add_f32 v[114:115], v[112:113], v[216:217]
	v_mul_f32_e32 v112, v117, v117
	v_mul_f32_e32 v113, v119, v119
	v_fmac_f32_e32 v112, v116, v116
	v_fmac_f32_e32 v113, v118, v118
	v_add_f32_e32 v112, v112, v113
	v_mul_f32_e32 v113, v115, v115
	v_fmac_f32_e32 v113, v114, v114
	v_add_f32_e32 v112, v113, v112
	v_mul_f32_e32 v113, v121, v121
	v_fmac_f32_e32 v113, v120, v120
	v_add_f32_e32 v112, v113, v112
	v_lshlrev_b32_e32 v222, 16, v165
	v_and_b32_e32 v223, 0xffff0000, v165
	v_add_f32_e32 v126, v181, v112
	v_cvt_pk_bf16_f32 v112, v116, v117
	v_cvt_pk_bf16_f32 v113, v118, v119
	v_lshl_add_u64 v[116:117], s[90:91], 0, v[170:171]
	v_lshlrev_b32_e32 v230, 16, v184
	v_and_b32_e32 v231, 0xffff0000, v184
	v_lshlrev_b32_e32 v232, 16, v186
	v_and_b32_e32 v233, 0xffff0000, v186
	v_lshlrev_b32_e32 v186, 16, v187
	v_and_b32_e32 v187, 0xffff0000, v187
	v_cvt_pk_bf16_f32 v114, v114, v115
	v_cvt_pk_bf16_f32 v115, v120, v121
	global_store_dwordx4 v[124:125], v[112:115], off offset:256
	v_pk_add_f32 v[110:111], v[110:111], v[222:223]
	v_pk_add_f32 v[108:109], v[108:109], v[220:221]
	v_lshl_add_u64 v[118:119], v[116:117], 0, v[144:145]
	v_cvt_pk_bf16_f32 v112, v108, v109
	v_cvt_pk_bf16_f32 v113, v110, v111
	v_lshlrev_b32_e32 v228, 16, v182
	v_and_b32_e32 v229, 0xffff0000, v182
	v_lshlrev_b32_e32 v182, 16, v183
	v_and_b32_e32 v183, 0xffff0000, v183
	v_lshlrev_b32_e32 v184, 16, v185
	v_and_b32_e32 v185, 0xffff0000, v185
	v_lshlrev_b32_e32 v238, 16, v192
	v_and_b32_e32 v239, 0xffff0000, v192
	v_pk_add_f32 v[106:107], v[106:107], v[226:227]
	v_pk_add_f32 v[104:105], v[104:105], v[224:225]
	v_lshlrev_b32_e32 v156, 16, v200
	v_cvt_pk_bf16_f32 v114, v104, v105
	v_cvt_pk_bf16_f32 v115, v106, v107
	global_store_dwordx4 v[118:119], v[112:115], off
	v_and_b32_e32 v157, 0xffff0000, v200
	v_pk_add_f32 v[102:103], v[102:103], v[182:183]
	v_pk_add_f32 v[112:113], v[92:93], v[230:231]
	v_pk_add_f32 v[92:93], v[98:99], v[186:187]
	v_lshl_add_u64 v[98:99], s[90:91], 0, v[154:155]
	v_pk_add_f32 v[100:101], v[100:101], v[228:229]
	v_pk_add_f32 v[94:95], v[94:95], v[184:185]
	v_cvt_pk_bf16_f32 v114, v100, v101
	v_cvt_pk_bf16_f32 v115, v102, v103
	v_cvt_pk_bf16_f32 v116, v112, v113
	v_lshlrev_b32_e32 v234, 16, v188
	v_cvt_pk_bf16_f32 v117, v94, v95
	global_store_dwordx4 v[118:119], v[114:117], off offset:256
	v_lshl_add_u64 v[118:119], v[98:99], 0, v[144:145]
	v_pk_add_f32 v[98:99], v[76:77], v[238:239]
	v_pk_add_f32 v[76:77], v[82:83], v[172:173]
	v_lshl_add_u64 v[82:83], s[90:91], 0, v[152:153]
	v_lshl_add_u64 v[122:123], v[82:83], 0, v[144:145]
	v_pk_add_f32 v[82:83], v[64:65], v[156:157]
	v_and_b32_e32 v65, 64, v174
	v_and_b32_e32 v235, 0xffff0000, v188
	v_lshlrev_b32_e32 v188, 16, v189
	v_and_b32_e32 v189, 0xffff0000, v189
	v_lshlrev_b32_e32 v236, 16, v190
	v_and_b32_e32 v237, 0xffff0000, v190
	v_pk_add_f32 v[96:97], v[96:97], v[232:233]
	v_xor_b32_e32 v64, 16, v174
	v_cvt_pk_bf16_f32 v114, v96, v97
	v_add_u32_e32 v65, 64, v65
	v_lshlrev_b32_e32 v190, 16, v191
	v_and_b32_e32 v191, 0xffff0000, v191
	v_lshlrev_b32_e32 v192, 16, v193
	v_and_b32_e32 v193, 0xffff0000, v193
	v_pk_add_f32 v[90:91], v[90:91], v[188:189]
	v_pk_add_f32 v[88:89], v[88:89], v[234:235]
	v_cvt_pk_bf16_f32 v115, v92, v93
	v_pk_add_f32 v[84:85], v[84:85], v[236:237]
	v_cvt_pk_bf16_f32 v116, v88, v89
	v_cvt_pk_bf16_f32 v117, v90, v91
	global_store_dwordx4 v[118:119], v[114:117], off
	v_cmp_lt_i32_e32 vcc, v64, v65
	v_lshlrev_b32_e32 v164, 16, v196
	v_cvt_pk_bf16_f32 v114, v84, v85
	v_and_b32_e32 v165, 0xffff0000, v196
	v_lshlrev_b32_e32 v168, 16, v197
	v_and_b32_e32 v169, 0xffff0000, v197
	v_pk_add_f32 v[86:87], v[86:87], v[190:191]
	v_pk_add_f32 v[78:79], v[78:79], v[192:193]
	v_cvt_pk_bf16_f32 v115, v86, v87
	v_cvt_pk_bf16_f32 v116, v98, v99
	v_pk_add_f32 v[80:81], v[80:81], v[166:167]
	v_cvt_pk_bf16_f32 v117, v78, v79
	global_store_dwordx4 v[118:119], v[114:117], off offset:256
	v_cndmask_b32_e32 v64, v174, v64, vcc
	v_pk_add_f32 v[74:75], v[74:75], v[168:169]
	v_cvt_pk_bf16_f32 v114, v80, v81
	v_pk_add_f32 v[72:73], v[72:73], v[164:165]
	v_cvt_pk_bf16_f32 v115, v76, v77
	v_lshlrev_b32_e32 v158, 16, v198
	v_cvt_pk_bf16_f32 v116, v72, v73
	v_cvt_pk_bf16_f32 v117, v74, v75
	global_store_dwordx4 v[122:123], v[114:117], off
	v_and_b32_e32 v159, 0xffff0000, v198
	v_lshlrev_b32_e32 v162, 16, v199
	v_lshlrev_b32_e32 v114, 2, v64
	ds_bpermute_b32 v64, v114, v126
	v_xor_b32_e32 v115, 32, v174
	v_cmp_lt_i32_e32 vcc, v115, v65
	v_and_b32_e32 v163, 0xffff0000, v199
	v_lshlrev_b32_e32 v160, 16, v201
	v_cndmask_b32_e32 v65, v174, v115, vcc
	v_lshlrev_b32_e32 v115, 2, v65
	s_waitcnt lgkmcnt(0)
	v_add_f32_e32 v116, v126, v64
	ds_bpermute_b32 v117, v115, v116
	v_and_b32_e32 v161, 0xffff0000, v201
	v_pk_add_f32 v[70:71], v[70:71], v[162:163]
	v_pk_add_f32 v[68:69], v[68:69], v[158:159]
	v_pk_add_f32 v[66:67], v[66:67], v[160:161]
	v_lshl_add_u64 v[64:65], v[150:151], 2, s[8:9]
	v_cvt_pk_bf16_f32 v118, v68, v69
	v_cvt_pk_bf16_f32 v119, v70, v71
	v_cvt_pk_bf16_f32 v120, v82, v83
	v_cvt_pk_bf16_f32 v121, v66, v67
	global_store_dwordx4 v[122:123], v[118:121], off offset:256
	s_and_saveexec_b64 s[30:31], s[2:3]
	s_cbranch_execz .LBB0_1163
	s_waitcnt lgkmcnt(0)
	v_add_f32_e32 v116, v116, v117
	global_atomic_add_f32 v[64:65], v116, off

.LBB0_1218:
	ds_read_b128 v[144:147], v151
	ds_read_b128 v[156:159], v151 offset:1024
	ds_read_b128 v[160:163], v151 offset:2048
	ds_read_b128 v[164:167], v151 offset:3072
	s_add_u32 s30, s28, 0xfffc0080
	s_addc_u32 s31, s29, -1
	s_cmp_eq_u32 s63, 12
	s_cselect_b32 s35, s23, s31
	s_cselect_b32 s34, s59, s30
	s_cselect_b32 s31, s21, s62
	s_cselect_b32 s30, s60, s61
	v_lshl_add_u64 v[172:173], s[28:29], 0, v[136:137]
	s_add_i32 m0, s40, 0xc000
	ds_read_b128 v[168:171], v152
	ds_read_b128 v[176:179], v152 offset:1024
	ds_read_b128 v[180:183], v152 offset:2048
	ds_read_b128 v[184:187], v152 offset:3072
	ds_read_b128 v[188:191], v152 offset:4096
	ds_read_b128 v[192:195], v152 offset:5120
	ds_read_b128 v[196:199], v152 offset:6144
	ds_read_b128 v[200:203], v152 offset:7168
	global_load_lds_dwordx4 v[172:173], off
	v_lshl_add_u64 v[172:173], s[28:29], 0, v[138:139]
	s_add_i32 m0, s40, 0xe000
	s_nop 0
	global_load_lds_dwordx4 v[172:173], off
	s_waitcnt lgkmcnt(8)
	s_setprio 1
	s_barrier
	s_waitcnt lgkmcnt(0)
	v_mfma_f32_16x16x32_bf16 v[124:127], v[144:147], v[168:171], v[124:127]
	v_mfma_f32_16x16x32_bf16 v[120:123], v[160:163], v[168:171], v[120:123]
	v_mfma_f32_16x16x32_bf16 v[116:119], v[144:147], v[180:183], v[116:119]
	v_mfma_f32_16x16x32_bf16 v[112:115], v[160:163], v[180:183], v[112:115]
	v_mfma_f32_16x16x32_bf16 v[92:95], v[144:147], v[188:191], v[92:95]
	v_mfma_f32_16x16x32_bf16 v[88:91], v[160:163], v[188:191], v[88:91]
	v_mfma_f32_16x16x32_bf16 v[76:79], v[144:147], v[196:199], v[76:79]
	v_mfma_f32_16x16x32_bf16 v[72:75], v[160:163], v[196:199], v[72:75]
	v_mfma_f32_16x16x32_bf16 v[124:127], v[156:159], v[176:179], v[124:127]
	v_mfma_f32_16x16x32_bf16 v[120:123], v[164:167], v[176:179], v[120:123]
	v_mfma_f32_16x16x32_bf16 v[116:119], v[156:159], v[184:187], v[116:119]
	v_mfma_f32_16x16x32_bf16 v[112:115], v[164:167], v[184:187], v[112:115]
	v_mfma_f32_16x16x32_bf16 v[92:95], v[156:159], v[192:195], v[92:95]
	v_mfma_f32_16x16x32_bf16 v[88:91], v[164:167], v[192:195], v[88:91]
	v_mfma_f32_16x16x32_bf16 v[76:79], v[156:159], v[200:203], v[76:79]
	v_mfma_f32_16x16x32_bf16 v[72:75], v[164:167], v[200:203], v[72:75]
	s_barrier
	s_setprio 0
	s_add_i32 s64, s52, s39
	v_lshl_add_u64 v[172:173], s[30:31], 0, v[130:131]
	s_mov_b32 m0, s64
	ds_read_b128 v[204:207], v153
	ds_read_b128 v[212:215], v153 offset:1024
	ds_read_b128 v[216:219], v153 offset:2048
	ds_read_b128 v[220:223], v153 offset:3072
	global_load_lds_dwordx4 v[172:173], off
	v_lshl_add_u64 v[208:209], s[30:31], 0, v[134:135]
	s_add_i32 m0, s64, 0x2000
	s_nop 0
	global_load_lds_dwordx4 v[208:209], off
	s_setprio 1
	s_barrier
	s_waitcnt lgkmcnt(0)
	v_mfma_f32_16x16x32_bf16 v[108:111], v[204:207], v[168:171], v[108:111]
	v_mfma_f32_16x16x32_bf16 v[104:107], v[216:219], v[168:171], v[104:107]
	v_mfma_f32_16x16x32_bf16 v[100:103], v[204:207], v[180:183], v[100:103]
	v_mfma_f32_16x16x32_bf16 v[96:99], v[216:219], v[180:183], v[96:99]
	v_mfma_f32_16x16x32_bf16 v[84:87], v[204:207], v[188:191], v[84:87]
	v_mfma_f32_16x16x32_bf16 v[80:83], v[216:219], v[188:191], v[80:83]
	v_mfma_f32_16x16x32_bf16 v[68:71], v[204:207], v[196:199], v[68:71]
	v_mfma_f32_16x16x32_bf16 v[64:67], v[216:219], v[196:199], v[64:67]
	v_mfma_f32_16x16x32_bf16 v[108:111], v[212:215], v[176:179], v[108:111]
	v_mfma_f32_16x16x32_bf16 v[104:107], v[220:223], v[176:179], v[104:107]
	v_mfma_f32_16x16x32_bf16 v[100:103], v[212:215], v[184:187], v[100:103]
	v_mfma_f32_16x16x32_bf16 v[96:99], v[220:223], v[184:187], v[96:99]
	v_mfma_f32_16x16x32_bf16 v[84:87], v[212:215], v[192:195], v[84:87]
	v_mfma_f32_16x16x32_bf16 v[80:83], v[220:223], v[192:195], v[80:83]
	v_mfma_f32_16x16x32_bf16 v[68:71], v[212:215], v[200:203], v[68:71]
	v_mfma_f32_16x16x32_bf16 v[64:67], v[220:223], v[200:203], v[64:67]
	s_barrier
	s_setprio 0
	s_mov_b32 m0, s40
	v_lshl_add_u64 v[224:225], s[34:35], 0, v[128:129]
	ds_read_b128 v[168:171], v152 offset:16384
	ds_read_b128 v[176:179], v152 offset:17408
	ds_read_b128 v[180:183], v152 offset:18432
	ds_read_b128 v[184:187], v152 offset:19456
	ds_read_b128 v[188:191], v152 offset:20480
	ds_read_b128 v[192:195], v152 offset:21504
	ds_read_b128 v[196:199], v152 offset:22528
	ds_read_b128 v[200:203], v152 offset:23552
	global_load_lds_dwordx4 v[224:225], off
	v_lshl_add_u64 v[226:227], s[34:35], 0, v[132:133]
	s_mov_b32 m0, s41
	s_nop 0
	global_load_lds_dwordx4 v[226:227], off
	s_setprio 1
	s_barrier
	s_waitcnt lgkmcnt(0)
	v_mfma_f32_16x16x32_bf16 v[60:63], v[144:147], v[168:171], v[60:63]
	v_mfma_f32_16x16x32_bf16 v[56:59], v[160:163], v[168:171], v[56:59]
	v_mfma_f32_16x16x32_bf16 v[44:47], v[144:147], v[180:183], v[44:47]
	v_mfma_f32_16x16x32_bf16 v[40:43], v[160:163], v[180:183], v[40:43]
	v_mfma_f32_16x16x32_bf16 v[28:31], v[144:147], v[188:191], v[28:31]
	v_mfma_f32_16x16x32_bf16 v[24:27], v[160:163], v[188:191], v[24:27]
	v_mfma_f32_16x16x32_bf16 v[12:15], v[144:147], v[196:199], v[12:15]
	v_mfma_f32_16x16x32_bf16 v[8:11], v[160:163], v[196:199], v[8:11]
	v_mfma_f32_16x16x32_bf16 v[60:63], v[156:159], v[176:179], v[60:63]
	v_mfma_f32_16x16x32_bf16 v[56:59], v[164:167], v[176:179], v[56:59]
	v_mfma_f32_16x16x32_bf16 v[44:47], v[156:159], v[184:187], v[44:47]
	v_mfma_f32_16x16x32_bf16 v[40:43], v[164:167], v[184:187], v[40:43]
	v_mfma_f32_16x16x32_bf16 v[28:31], v[156:159], v[192:195], v[28:31]
	v_mfma_f32_16x16x32_bf16 v[24:27], v[164:167], v[192:195], v[24:27]
	v_mfma_f32_16x16x32_bf16 v[12:15], v[156:159], v[200:203], v[12:15]
	v_mfma_f32_16x16x32_bf16 v[8:11], v[164:167], v[200:203], v[8:11]
	s_barrier
	s_setprio 0
	s_add_u32 s64, s30, 0x40000
	s_addc_u32 s65, s31, 0
	s_add_i32 s66, s53, s39
	v_lshl_add_u64 v[144:145], s[64:65], 0, v[130:131]
	s_mov_b32 m0, s66
	s_nop 0
	global_load_lds_dwordx4 v[144:145], off
	v_lshl_add_u64 v[144:145], s[64:65], 0, v[134:135]
	s_add_i32 m0, s66, 0x2000
	s_nop 0
	global_load_lds_dwordx4 v[144:145], off
	s_waitcnt vmcnt(6)
	s_setprio 1
	s_barrier
	v_mfma_f32_16x16x32_bf16 v[52:55], v[204:207], v[168:171], v[52:55]
	v_mfma_f32_16x16x32_bf16 v[48:51], v[216:219], v[168:171], v[48:51]
	v_mfma_f32_16x16x32_bf16 v[36:39], v[204:207], v[180:183], v[36:39]
	v_mfma_f32_16x16x32_bf16 v[32:35], v[216:219], v[180:183], v[32:35]
	v_mfma_f32_16x16x32_bf16 v[20:23], v[204:207], v[188:191], v[20:23]
	v_mfma_f32_16x16x32_bf16 v[16:19], v[216:219], v[188:191], v[16:19]
	v_mfma_f32_16x16x32_bf16 v[4:7], v[204:207], v[196:199], v[4:7]
	v_mfma_f32_16x16x32_bf16 v[0:3], v[216:219], v[196:199], v[0:3]
	v_mfma_f32_16x16x32_bf16 v[52:55], v[212:215], v[176:179], v[52:55]
	v_mfma_f32_16x16x32_bf16 v[48:51], v[220:223], v[176:179], v[48:51]
	v_mfma_f32_16x16x32_bf16 v[36:39], v[212:215], v[184:187], v[36:39]
	v_mfma_f32_16x16x32_bf16 v[32:35], v[220:223], v[184:187], v[32:35]
	v_mfma_f32_16x16x32_bf16 v[20:23], v[212:215], v[192:195], v[20:23]
	v_mfma_f32_16x16x32_bf16 v[16:19], v[220:223], v[192:195], v[16:19]
	v_mfma_f32_16x16x32_bf16 v[4:7], v[212:215], v[200:203], v[4:7]
	v_mfma_f32_16x16x32_bf16 v[0:3], v[220:223], v[200:203], v[0:3]
	s_barrier
	s_setprio 0
	s_add_i32 s64, 0, 0x18000
	v_add_u32_e32 v155, s64, v149
	ds_read_b128 v[144:147], v155
	ds_read_b128 v[156:159], v155 offset:1024
	ds_read_b128 v[160:163], v155 offset:2048
	ds_read_b128 v[164:167], v155 offset:3072
	s_add_u32 s34, s34, 0x40000
	s_addc_u32 s35, s35, 0
	s_mov_b32 m0, s42
	v_lshl_add_u64 v[204:205], s[34:35], 0, v[128:129]
	ds_read_b128 v[168:171], v152 offset:32768
	ds_read_b128 v[176:179], v152 offset:33792
	ds_read_b128 v[180:183], v152 offset:34816
	ds_read_b128 v[184:187], v152 offset:35840
	ds_read_b128 v[188:191], v152 offset:36864
	ds_read_b128 v[192:195], v152 offset:37888
	ds_read_b128 v[196:199], v152 offset:38912
	ds_read_b128 v[200:203], v152 offset:39936
	global_load_lds_dwordx4 v[204:205], off
	v_lshl_add_u64 v[204:205], s[34:35], 0, v[132:133]
	s_mov_b32 m0, s43
	s_nop 0
	global_load_lds_dwordx4 v[204:205], off
	s_waitcnt lgkmcnt(8)
	s_setprio 1
	s_barrier
	s_waitcnt lgkmcnt(0)
	v_mfma_f32_16x16x32_bf16 v[124:127], v[144:147], v[168:171], v[124:127]
	v_mfma_f32_16x16x32_bf16 v[120:123], v[160:163], v[168:171], v[120:123]
	v_mfma_f32_16x16x32_bf16 v[116:119], v[144:147], v[180:183], v[116:119]
	v_mfma_f32_16x16x32_bf16 v[112:115], v[160:163], v[180:183], v[112:115]
	v_mfma_f32_16x16x32_bf16 v[92:95], v[144:147], v[188:191], v[92:95]
	v_mfma_f32_16x16x32_bf16 v[88:91], v[160:163], v[188:191], v[88:91]
	v_mfma_f32_16x16x32_bf16 v[76:79], v[144:147], v[196:199], v[76:79]
	v_mfma_f32_16x16x32_bf16 v[72:75], v[160:163], v[196:199], v[72:75]
	v_mfma_f32_16x16x32_bf16 v[124:127], v[156:159], v[176:179], v[124:127]
	v_mfma_f32_16x16x32_bf16 v[120:123], v[164:167], v[176:179], v[120:123]
	v_mfma_f32_16x16x32_bf16 v[116:119], v[156:159], v[184:187], v[116:119]
	v_mfma_f32_16x16x32_bf16 v[112:115], v[164:167], v[184:187], v[112:115]
	v_mfma_f32_16x16x32_bf16 v[92:95], v[156:159], v[192:195], v[92:95]
	v_mfma_f32_16x16x32_bf16 v[88:91], v[164:167], v[192:195], v[88:91]
	v_mfma_f32_16x16x32_bf16 v[76:79], v[156:159], v[200:203], v[76:79]
	v_mfma_f32_16x16x32_bf16 v[72:75], v[164:167], v[200:203], v[72:75]
	s_barrier
	s_setprio 0
	s_add_i32 s34, 0, 0x1c000
	s_add_i32 s35, s64, s39
	v_add_u32_e32 v155, s34, v149
	v_lshl_add_u64 v[172:173], v[172:173], 0, s[6:7]
	s_mov_b32 m0, s35
	ds_read_b128 v[204:207], v155
	ds_read_b128 v[212:215], v155 offset:1024
	ds_read_b128 v[216:219], v155 offset:2048
	ds_read_b128 v[220:223], v155 offset:3072
	global_load_lds_dwordx4 v[172:173], off
	v_lshl_add_u64 v[172:173], v[208:209], 0, s[6:7]
	s_add_i32 m0, s35, 0x2000
	s_nop 0
	global_load_lds_dwordx4 v[172:173], off
	s_setprio 1
	s_barrier
	s_waitcnt lgkmcnt(0)
	v_mfma_f32_16x16x32_bf16 v[108:111], v[204:207], v[168:171], v[108:111]
	v_mfma_f32_16x16x32_bf16 v[104:107], v[216:219], v[168:171], v[104:107]
	v_mfma_f32_16x16x32_bf16 v[100:103], v[204:207], v[180:183], v[100:103]
	v_mfma_f32_16x16x32_bf16 v[96:99], v[216:219], v[180:183], v[96:99]
	v_mfma_f32_16x16x32_bf16 v[84:87], v[204:207], v[188:191], v[84:87]
	v_mfma_f32_16x16x32_bf16 v[80:83], v[216:219], v[188:191], v[80:83]
	v_mfma_f32_16x16x32_bf16 v[68:71], v[204:207], v[196:199], v[68:71]
	v_mfma_f32_16x16x32_bf16 v[64:67], v[216:219], v[196:199], v[64:67]
	v_mfma_f32_16x16x32_bf16 v[108:111], v[212:215], v[176:179], v[108:111]
	v_mfma_f32_16x16x32_bf16 v[104:107], v[220:223], v[176:179], v[104:107]
	v_mfma_f32_16x16x32_bf16 v[100:103], v[212:215], v[184:187], v[100:103]
	v_mfma_f32_16x16x32_bf16 v[96:99], v[220:223], v[184:187], v[96:99]
	v_mfma_f32_16x16x32_bf16 v[84:87], v[212:215], v[192:195], v[84:87]
	v_mfma_f32_16x16x32_bf16 v[80:83], v[220:223], v[192:195], v[80:83]
	v_mfma_f32_16x16x32_bf16 v[68:71], v[212:215], v[200:203], v[68:71]
	v_mfma_f32_16x16x32_bf16 v[64:67], v[220:223], v[200:203], v[64:67]
	s_barrier
	s_setprio 0
	s_mov_b32 m0, s49
	v_lshl_add_u64 v[172:173], v[224:225], 0, s[6:7]
	ds_read_b128 v[168:171], v152 offset:49152
	ds_read_b128 v[176:179], v152 offset:50176
	ds_read_b128 v[180:183], v152 offset:51200
	ds_read_b128 v[184:187], v152 offset:52224
	ds_read_b128 v[188:191], v152 offset:53248
	ds_read_b128 v[192:195], v152 offset:54272
	ds_read_b128 v[196:199], v152 offset:55296
	ds_read_b128 v[200:203], v152 offset:56320
	global_load_lds_dwordx4 v[172:173], off
	v_lshl_add_u64 v[172:173], v[226:227], 0, s[6:7]
	s_mov_b32 m0, s50
	s_nop 0
	global_load_lds_dwordx4 v[172:173], off
	s_setprio 1
	s_barrier
	s_waitcnt lgkmcnt(0)
	v_mfma_f32_16x16x32_bf16 v[60:63], v[144:147], v[168:171], v[60:63]
	v_mfma_f32_16x16x32_bf16 v[56:59], v[160:163], v[168:171], v[56:59]
	v_mfma_f32_16x16x32_bf16 v[44:47], v[144:147], v[180:183], v[44:47]
	v_mfma_f32_16x16x32_bf16 v[40:43], v[160:163], v[180:183], v[40:43]
	v_mfma_f32_16x16x32_bf16 v[28:31], v[144:147], v[188:191], v[28:31]
	v_mfma_f32_16x16x32_bf16 v[24:27], v[160:163], v[188:191], v[24:27]
	v_mfma_f32_16x16x32_bf16 v[12:15], v[144:147], v[196:199], v[12:15]
	v_mfma_f32_16x16x32_bf16 v[8:11], v[160:163], v[196:199], v[8:11]
	v_mfma_f32_16x16x32_bf16 v[60:63], v[156:159], v[176:179], v[60:63]
	v_mfma_f32_16x16x32_bf16 v[56:59], v[164:167], v[176:179], v[56:59]
	v_mfma_f32_16x16x32_bf16 v[44:47], v[156:159], v[184:187], v[44:47]
	v_mfma_f32_16x16x32_bf16 v[40:43], v[164:167], v[184:187], v[40:43]
	v_mfma_f32_16x16x32_bf16 v[28:31], v[156:159], v[192:195], v[28:31]
	v_mfma_f32_16x16x32_bf16 v[24:27], v[164:167], v[192:195], v[24:27]
	v_mfma_f32_16x16x32_bf16 v[12:15], v[156:159], v[200:203], v[12:15]
	v_mfma_f32_16x16x32_bf16 v[8:11], v[164:167], v[200:203], v[8:11]
	s_barrier
	s_setprio 0
	s_add_u32 s30, s30, 0x40080
	s_addc_u32 s31, s31, 0
	s_add_i32 s34, s34, s39
	v_lshl_add_u64 v[144:145], s[30:31], 0, v[130:131]
	s_mov_b32 m0, s34
	s_nop 0
	global_load_lds_dwordx4 v[144:145], off
	v_lshl_add_u64 v[144:145], s[30:31], 0, v[134:135]
	s_add_i32 m0, s34, 0x2000
	s_nop 0
	global_load_lds_dwordx4 v[144:145], off
	s_waitcnt vmcnt(6)
	s_setprio 1
	s_barrier
	v_mfma_f32_16x16x32_bf16 v[52:55], v[204:207], v[168:171], v[52:55]
	v_mfma_f32_16x16x32_bf16 v[48:51], v[216:219], v[168:171], v[48:51]
	v_mfma_f32_16x16x32_bf16 v[36:39], v[204:207], v[180:183], v[36:39]
	v_mfma_f32_16x16x32_bf16 v[32:35], v[216:219], v[180:183], v[32:35]
	v_mfma_f32_16x16x32_bf16 v[20:23], v[204:207], v[188:191], v[20:23]
	v_mfma_f32_16x16x32_bf16 v[16:19], v[216:219], v[188:191], v[16:19]
	v_mfma_f32_16x16x32_bf16 v[4:7], v[204:207], v[196:199], v[4:7]
	v_mfma_f32_16x16x32_bf16 v[0:3], v[216:219], v[196:199], v[0:3]
	v_mfma_f32_16x16x32_bf16 v[52:55], v[212:215], v[176:179], v[52:55]
	v_mfma_f32_16x16x32_bf16 v[48:51], v[220:223], v[176:179], v[48:51]
	v_mfma_f32_16x16x32_bf16 v[36:39], v[212:215], v[184:187], v[36:39]
	v_mfma_f32_16x16x32_bf16 v[32:35], v[220:223], v[184:187], v[32:35]
	v_mfma_f32_16x16x32_bf16 v[20:23], v[212:215], v[192:195], v[20:23]
	v_mfma_f32_16x16x32_bf16 v[16:19], v[220:223], v[192:195], v[16:19]
	v_mfma_f32_16x16x32_bf16 v[4:7], v[212:215], v[200:203], v[4:7]
	v_mfma_f32_16x16x32_bf16 v[0:3], v[220:223], v[200:203], v[0:3]
	s_barrier
	s_setprio 0
	s_add_i32 s63, s63, 2
	s_add_u32 s28, s28, 0x100
	s_addc_u32 s29, s29, 0
	s_add_u32 s61, s61, 0x100
	s_addc_u32 s62, s62, 0
	s_cmp_gt_u32 s63, 13
	s_cbranch_scc0 .LBB0_1218
	v_lshl_add_u32 v146, s0, 8, v148
	v_ashrrev_i32_e32 v147, 31, v146
	v_lshl_add_u64 v[144:145], v[146:147], 2, s[8:9]
	global_load_dword v155, v[144:145], off
	global_load_dword v162, v[144:145], off offset:64
	global_load_dword v163, v[144:145], off offset:128
	global_load_dword v164, v[144:145], off offset:192
	global_load_dword v165, v[144:145], off offset:512
	global_load_dword v166, v[144:145], off offset:576
	global_load_dword v167, v[144:145], off offset:640
	global_load_dword v168, v[144:145], off offset:704
	v_lshl_or_b32 v144, s1, 8, v150
	v_ashrrev_i32_e32 v145, 31, v144
	v_lshlrev_b64 v[158:159], 13, v[146:147]
	v_lshlrev_b64 v[160:161], 1, v[144:145]
	v_lshl_add_u64 v[144:145], s[92:93], 0, v[158:159]
	v_lshl_add_u64 v[144:145], v[144:145], 0, v[160:161]
	v_or_b32_e32 v156, 16, v146
	v_ashrrev_i32_e32 v157, 31, v156
	v_lshlrev_b64 v[156:157], 13, v[156:157]
	v_lshl_add_u64 v[156:157], s[92:93], 0, v[156:157]
	v_lshl_add_u64 v[156:157], v[156:157], 0, v[160:161]
	s_mov_b64 s[30:31], s[26:27]
	s_mov_b64 s[28:29], s[24:25]
	s_waitcnt vmcnt(0)
	v_fmamk_f32 v147, v155, 0x3a800000, v154
	v_mul_f32_e32 v158, 0x4b800000, v147
	v_cmp_gt_f32_e32 vcc, s54, v147
	v_fmamk_f32 v155, v162, 0x3a800000, v154
	v_mul_f32_e32 v162, 0x4b800000, v155
	v_cndmask_b32_e32 v147, v147, v158, vcc
	v_rsq_f32_e32 v158, v147
	v_cmp_gt_f32_e64 s[0:1], s54, v155
	v_fmamk_f32 v159, v163, 0x3a800000, v154
	v_fmamk_f32 v163, v164, 0x3a800000, v154
	v_cndmask_b32_e64 v155, v155, v162, s[0:1]
	v_rsq_f32_e32 v155, v155
	v_mul_f32_e32 v162, 0x45800000, v158
	v_cndmask_b32_e32 v158, v158, v162, vcc
	v_pk_mul_f32 v[124:125], v[124:125], v[158:159] op_sel_hi:[1,0]
	v_pk_mul_f32 v[104:105], v[104:105], v[158:159] op_sel_hi:[1,0]
	v_fmamk_f32 v164, v165, 0x3a800000, v154
	v_fmamk_f32 v165, v166, 0x3a800000, v154
	v_fmamk_f32 v166, v167, 0x3a800000, v154
	v_mul_f32_e32 v167, 0x45800000, v155
	v_pk_mul_f32 v[126:127], v[126:127], v[158:159] op_sel_hi:[1,0]
	v_pk_mul_f32 v[122:123], v[122:123], v[158:159] op_sel_hi:[1,0]
	v_pk_mul_f32 v[120:121], v[120:121], v[158:159] op_sel_hi:[1,0]
	v_pk_mul_f32 v[108:109], v[108:109], v[158:159] op_sel_hi:[1,0]
	v_pk_mul_f32 v[106:107], v[106:107], v[158:159] op_sel_hi:[1,0]
	v_max_f32_e32 v124, 0, v124
	v_max_f32_e32 v125, 0, v125
	v_max_f32_e32 v104, 0, v104
	v_cndmask_b32_e64 v162, v155, v167, s[0:1]
	v_pk_mul_f32 v[110:111], v[110:111], v[158:159] op_sel_hi:[1,0]
	v_max_f32_e32 v120, 0, v120
	v_max_f32_e32 v121, 0, v121
	v_max_f32_e32 v126, 0, v126
	v_max_f32_e32 v122, 0, v122
	v_max_f32_e32 v127, 0, v127
	v_max_f32_e32 v123, 0, v123
	v_max_f32_e32 v108, 0, v108
	v_max_f32_e32 v109, 0, v109
	v_max_f32_e32 v105, 0, v105
	v_max_f32_e32 v106, 0, v106
	v_max_f32_e32 v107, 0, v107
	v_mul_f32_e32 v124, v124, v124
	v_mul_f32_e32 v125, v125, v125
	v_mul_f32_e32 v155, v104, v104
	v_cvt_pk_bf16_f32 v104, v124, v125
	v_fmamk_f32 v147, v168, 0x3a800000, v154
	v_pk_mul_f32 v[112:113], v[112:113], v[162:163] op_sel_hi:[1,0]
	v_max_f32_e32 v110, 0, v110
	v_max_f32_e32 v111, 0, v111
	v_mul_f32_e32 v120, v120, v120
	v_mul_f32_e32 v121, v121, v121
	v_mul_f32_e32 v126, v126, v126
	v_mul_f32_e32 v122, v122, v122
	v_mul_f32_e32 v127, v127, v127
	v_mul_f32_e32 v123, v123, v123
	v_mul_f32_e32 v108, v108, v108
	v_mul_f32_e32 v109, v109, v109
	v_mul_f32_e32 v158, v105, v105
	v_mul_f32_e32 v167, v106, v106
	v_mul_f32_e32 v168, v107, v107
	v_cvt_pk_bf16_f32 v105, v126, v127
	v_cvt_pk_bf16_f32 v106, v120, v121
	v_cvt_pk_bf16_f32 v107, v122, v123
	global_store_dwordx4 v[144:145], v[104:107], off nt
	v_pk_mul_f32 v[116:117], v[116:117], v[162:163] op_sel_hi:[1,0]
	v_mul_f32_e32 v110, v110, v110
	v_cvt_pk_bf16_f32 v104, v108, v109
	v_mul_f32_e32 v111, v111, v111
	v_cvt_pk_bf16_f32 v105, v110, v111
	v_cvt_pk_bf16_f32 v106, v155, v158
	v_cvt_pk_bf16_f32 v107, v167, v168
	global_store_dwordx4 v[144:145], v[104:107], off offset:256 nt
	v_pk_mul_f32 v[118:119], v[118:119], v[162:163] op_sel_hi:[1,0]
	v_pk_mul_f32 v[114:115], v[114:115], v[162:163] op_sel_hi:[1,0]
	v_max_f32_e32 v104, 0, v112
	v_mul_f32_e32 v106, v104, v104
	v_max_f32_e32 v104, 0, v117
	v_max_f32_e32 v116, 0, v116
	v_max_f32_e32 v107, 0, v113
	v_mul_f32_e32 v104, v104, v104
	v_pk_mul_f32 v[98:99], v[98:99], v[162:163] op_sel_hi:[1,0]
	v_pk_mul_f32 v[96:97], v[96:97], v[162:163] op_sel_hi:[1,0]
	v_mul_f32_e32 v105, v116, v116
	v_mul_f32_e32 v107, v107, v107
	v_max_f32_e32 v108, 0, v118
	v_max_f32_e32 v109, 0, v114
	v_max_f32_e32 v110, 0, v119
	v_max_f32_e32 v111, 0, v115
	v_cvt_pk_bf16_f32 v104, v105, v104
	v_pk_mul_f32 v[102:103], v[102:103], v[162:163] op_sel_hi:[1,0]
	v_pk_mul_f32 v[100:101], v[100:101], v[162:163] op_sel_hi:[1,0]
	v_max_f32_e32 v96, 0, v96
	v_max_f32_e32 v97, 0, v97
	v_max_f32_e32 v98, 0, v98
	v_mul_f32_e32 v108, v108, v108
	v_mul_f32_e32 v109, v109, v109
	v_mul_f32_e32 v110, v110, v110
	v_mul_f32_e32 v111, v111, v111
	v_cvt_pk_bf16_f32 v105, v108, v110
	v_cvt_pk_bf16_f32 v106, v106, v107
	v_cvt_pk_bf16_f32 v107, v109, v111
	global_store_dwordx4 v[156:157], v[104:107], off nt
	v_max_f32_e32 v100, 0, v100
	v_max_f32_e32 v99, 0, v99
	v_mul_f32_e32 v104, v96, v96
	v_max_f32_e32 v96, 0, v101
	v_mul_f32_e32 v101, v97, v97
	v_max_f32_e32 v97, 0, v102
	v_mul_f32_e32 v102, v98, v98
	v_max_f32_e32 v98, 0, v103
	v_mul_f32_e32 v96, v96, v96
	v_mul_f32_e32 v97, v97, v97
	v_mul_f32_e32 v98, v98, v98
	v_mul_f32_e32 v100, v100, v100
	v_mul_f32_e32 v99, v99, v99
	v_cvt_pk_bf16_f32 v96, v100, v96
	v_cvt_pk_bf16_f32 v97, v97, v98
	v_cvt_pk_bf16_f32 v98, v104, v101
	v_cvt_pk_bf16_f32 v99, v102, v99
	global_store_dwordx4 v[156:157], v[96:99], off offset:256 nt
	v_cmp_gt_f32_e32 vcc, s54, v159
	s_mov_b32 s1, s20
	v_mul_f32_e32 v98, 0x4b800000, v159
	v_cndmask_b32_e32 v98, v159, v98, vcc
	v_rsq_f32_e32 v98, v98
	v_or_b32_e32 v96, 32, v146
	v_ashrrev_i32_e32 v97, 31, v96
	v_lshlrev_b64 v[96:97], 13, v[96:97]
	v_mul_f32_e32 v99, 0x45800000, v98
	v_cndmask_b32_e32 v98, v98, v99, vcc
	v_pk_mul_f32 v[88:89], v[88:89], v[98:99] op_sel_hi:[1,0]
	v_pk_mul_f32 v[92:93], v[92:93], v[98:99] op_sel_hi:[1,0]
	v_pk_mul_f32 v[90:91], v[90:91], v[98:99] op_sel_hi:[1,0]
	v_max_f32_e32 v88, 0, v88
	v_pk_mul_f32 v[94:95], v[94:95], v[98:99] op_sel_hi:[1,0]
	v_mul_f32_e32 v99, v88, v88
	v_max_f32_e32 v88, 0, v93
	v_max_f32_e32 v89, 0, v89
	v_max_f32_e32 v90, 0, v90
	v_lshl_add_u64 v[96:97], s[92:93], 0, v[96:97]
	v_max_f32_e32 v92, 0, v92
	v_mul_f32_e32 v88, v88, v88
	v_mul_f32_e32 v93, v89, v89
	v_max_f32_e32 v89, 0, v94
	v_mul_f32_e32 v94, v90, v90
	v_max_f32_e32 v90, 0, v95
	v_max_f32_e32 v91, 0, v91
	v_pk_mul_f32 v[82:83], v[82:83], v[98:99] op_sel_hi:[1,0]
	v_pk_mul_f32 v[80:81], v[80:81], v[98:99] op_sel_hi:[1,0]
	v_lshl_add_u64 v[96:97], v[96:97], 0, v[160:161]
	v_mul_f32_e32 v92, v92, v92
	v_mul_f32_e32 v89, v89, v89
	v_mul_f32_e32 v90, v90, v90
	v_mul_f32_e32 v91, v91, v91
	v_cvt_pk_bf16_f32 v88, v92, v88
	v_pk_mul_f32 v[86:87], v[86:87], v[98:99] op_sel_hi:[1,0]
	v_pk_mul_f32 v[84:85], v[84:85], v[98:99] op_sel_hi:[1,0]
	v_max_f32_e32 v80, 0, v80
	v_max_f32_e32 v81, 0, v81
	v_max_f32_e32 v82, 0, v82
	v_cvt_pk_bf16_f32 v89, v89, v90
	v_cvt_pk_bf16_f32 v90, v99, v93
	v_cvt_pk_bf16_f32 v91, v94, v91
	global_store_dwordx4 v[96:97], v[88:91], off nt
	v_max_f32_e32 v84, 0, v84
	v_max_f32_e32 v83, 0, v83
	v_mul_f32_e32 v88, v80, v80
	v_max_f32_e32 v80, 0, v85
	v_mul_f32_e32 v85, v81, v81
	v_max_f32_e32 v81, 0, v86
	v_mul_f32_e32 v86, v82, v82
	v_max_f32_e32 v82, 0, v87
	v_mul_f32_e32 v80, v80, v80
	v_mul_f32_e32 v81, v81, v81
	v_mul_f32_e32 v82, v82, v82
	v_mul_f32_e32 v84, v84, v84
	v_mul_f32_e32 v83, v83, v83
	v_cvt_pk_bf16_f32 v80, v84, v80
	v_cvt_pk_bf16_f32 v81, v81, v82
	v_cvt_pk_bf16_f32 v82, v88, v85
	v_cvt_pk_bf16_f32 v83, v86, v83
	global_store_dwordx4 v[96:97], v[80:83], off offset:256 nt
	v_cmp_gt_f32_e32 vcc, s54, v163
	s_mov_b32 s0, s22
	v_mul_f32_e32 v82, 0x4b800000, v163
	v_cndmask_b32_e32 v82, v163, v82, vcc
	v_rsq_f32_e32 v82, v82
	v_or_b32_e32 v80, 48, v146
	v_ashrrev_i32_e32 v81, 31, v80
	v_lshlrev_b64 v[80:81], 13, v[80:81]
	v_mul_f32_e32 v83, 0x45800000, v82
	v_cndmask_b32_e32 v82, v82, v83, vcc
	v_pk_mul_f32 v[72:73], v[72:73], v[82:83] op_sel_hi:[1,0]
	v_pk_mul_f32 v[76:77], v[76:77], v[82:83] op_sel_hi:[1,0]
	v_pk_mul_f32 v[74:75], v[74:75], v[82:83] op_sel_hi:[1,0]
	v_max_f32_e32 v72, 0, v72
	v_pk_mul_f32 v[78:79], v[78:79], v[82:83] op_sel_hi:[1,0]
	v_mul_f32_e32 v83, v72, v72
	v_max_f32_e32 v72, 0, v77
	v_max_f32_e32 v73, 0, v73
	v_max_f32_e32 v74, 0, v74
	v_lshl_add_u64 v[80:81], s[92:93], 0, v[80:81]
	v_max_f32_e32 v76, 0, v76
	v_mul_f32_e32 v72, v72, v72
	v_mul_f32_e32 v77, v73, v73
	v_max_f32_e32 v73, 0, v78
	v_mul_f32_e32 v78, v74, v74
	v_max_f32_e32 v74, 0, v79
	v_max_f32_e32 v75, 0, v75
	v_pk_mul_f32 v[64:65], v[64:65], v[82:83] op_sel_hi:[1,0]
	v_lshl_add_u64 v[80:81], v[80:81], 0, v[160:161]
	v_mul_f32_e32 v76, v76, v76
	v_mul_f32_e32 v73, v73, v73
	v_mul_f32_e32 v74, v74, v74
	v_mul_f32_e32 v75, v75, v75
	v_cvt_pk_bf16_f32 v72, v76, v72
	v_pk_mul_f32 v[68:69], v[68:69], v[82:83] op_sel_hi:[1,0]
	v_max_f32_e32 v64, 0, v64
	v_cvt_pk_bf16_f32 v73, v73, v74
	v_cvt_pk_bf16_f32 v74, v83, v77
	v_cvt_pk_bf16_f32 v75, v78, v75
	global_store_dwordx4 v[80:81], v[72:75], off nt
	v_max_f32_e32 v68, 0, v68
	v_mul_f32_e32 v68, v68, v68
	v_mul_f32_e32 v72, v64, v64
	v_max_f32_e32 v64, 0, v69
	v_mul_f32_e32 v64, v64, v64
	v_cvt_pk_bf16_f32 v64, v68, v64
	v_mul_f32_e32 v68, 0x4b800000, v164
	v_cmp_gt_f32_e32 vcc, s54, v164
	v_pk_mul_f32 v[66:67], v[66:67], v[82:83] op_sel_hi:[1,0]
	v_pk_mul_f32 v[70:71], v[70:71], v[82:83] op_sel_hi:[1,0]
	v_cndmask_b32_e32 v68, v164, v68, vcc
	v_max_f32_e32 v65, 0, v65
	v_max_f32_e32 v66, 0, v66
	v_rsq_f32_e32 v68, v68
	v_mul_f32_e32 v69, v65, v65
	v_max_f32_e32 v65, 0, v70
	v_mul_f32_e32 v70, v66, v66
	v_max_f32_e32 v66, 0, v71
	v_mul_f32_e32 v65, v65, v65
	v_max_f32_e32 v67, 0, v67
	v_mul_f32_e32 v66, v66, v66
	v_mul_f32_e32 v67, v67, v67
	v_cvt_pk_bf16_f32 v65, v65, v66
	v_cvt_pk_bf16_f32 v66, v72, v69
	v_cvt_pk_bf16_f32 v67, v70, v67
	global_store_dwordx4 v[80:81], v[64:67], off offset:256 nt
	s_nop 1
	v_mul_f32_e32 v66, 0x45800000, v68
	v_cndmask_b32_e32 v66, v68, v66, vcc
	v_pk_mul_f32 v[56:57], v[56:57], v[66:67] op_sel_hi:[1,0]
	v_pk_mul_f32 v[60:61], v[60:61], v[66:67] op_sel_hi:[1,0]
	v_pk_mul_f32 v[58:59], v[58:59], v[66:67] op_sel_hi:[1,0]
	v_max_f32_e32 v56, 0, v56
	v_pk_mul_f32 v[62:63], v[62:63], v[66:67] op_sel_hi:[1,0]
	v_max_f32_e32 v60, 0, v60
	v_mul_f32_e32 v67, v56, v56
	v_max_f32_e32 v56, 0, v61
	v_max_f32_e32 v57, 0, v57
	v_max_f32_e32 v58, 0, v58
	v_mul_f32_e32 v60, v60, v60
	v_mul_f32_e32 v56, v56, v56
	v_mul_f32_e32 v61, v57, v57
	v_max_f32_e32 v57, 0, v62
	v_mul_f32_e32 v62, v58, v58
	v_max_f32_e32 v58, 0, v63
	v_mul_f32_e32 v57, v57, v57
	v_max_f32_e32 v59, 0, v59
	v_mul_f32_e32 v58, v58, v58
	v_cvt_pk_bf16_f32 v56, v60, v56
	v_add_co_u32_e32 v60, vcc, s55, v144
	v_pk_mul_f32 v[48:49], v[48:49], v[66:67] op_sel_hi:[1,0]
	v_mul_f32_e32 v59, v59, v59
	v_cvt_pk_bf16_f32 v57, v57, v58
	v_cvt_pk_bf16_f32 v58, v67, v61
	v_addc_co_u32_e32 v61, vcc, 0, v145, vcc
	v_pk_mul_f32 v[52:53], v[52:53], v[66:67] op_sel_hi:[1,0]
	v_max_f32_e32 v48, 0, v48
	v_cvt_pk_bf16_f32 v59, v62, v59
	global_store_dwordx4 v[60:61], v[56:59], off nt
	v_max_f32_e32 v52, 0, v52
	v_mul_f32_e32 v52, v52, v52
	v_mul_f32_e32 v56, v48, v48
	v_max_f32_e32 v48, 0, v53
	v_mul_f32_e32 v48, v48, v48
	v_cvt_pk_bf16_f32 v48, v52, v48
	v_mul_f32_e32 v52, 0x4b800000, v165
	v_cmp_gt_f32_e32 vcc, s54, v165
	v_pk_mul_f32 v[50:51], v[50:51], v[66:67] op_sel_hi:[1,0]
	v_pk_mul_f32 v[54:55], v[54:55], v[66:67] op_sel_hi:[1,0]
	v_cndmask_b32_e32 v52, v165, v52, vcc
	v_max_f32_e32 v49, 0, v49
	v_max_f32_e32 v50, 0, v50
	v_rsq_f32_e32 v52, v52
	v_mul_f32_e32 v53, v49, v49
	v_max_f32_e32 v49, 0, v54
	v_mul_f32_e32 v54, v50, v50
	v_max_f32_e32 v50, 0, v55
	v_mul_f32_e32 v49, v49, v49
	v_max_f32_e32 v51, 0, v51
	v_mul_f32_e32 v50, v50, v50
	v_lshl_add_u64 v[64:65], v[144:145], 0, s[12:13]
	v_mul_f32_e32 v51, v51, v51
	v_cvt_pk_bf16_f32 v49, v49, v50
	v_cvt_pk_bf16_f32 v50, v56, v53
	v_cvt_pk_bf16_f32 v51, v54, v51
	global_store_dwordx4 v[64:65], v[48:51], off offset:256 nt
	s_nop 1
	v_mul_f32_e32 v50, 0x45800000, v52
	v_cndmask_b32_e32 v50, v52, v50, vcc
	v_pk_mul_f32 v[40:41], v[40:41], v[50:51] op_sel_hi:[1,0]
	v_pk_mul_f32 v[44:45], v[44:45], v[50:51] op_sel_hi:[1,0]
	v_pk_mul_f32 v[42:43], v[42:43], v[50:51] op_sel_hi:[1,0]
	v_max_f32_e32 v40, 0, v40
	v_pk_mul_f32 v[46:47], v[46:47], v[50:51] op_sel_hi:[1,0]
	v_max_f32_e32 v44, 0, v44
	v_mul_f32_e32 v51, v40, v40
	v_max_f32_e32 v40, 0, v45
	v_max_f32_e32 v41, 0, v41
	v_max_f32_e32 v42, 0, v42
	v_mul_f32_e32 v44, v44, v44
	v_mul_f32_e32 v40, v40, v40
	v_mul_f32_e32 v45, v41, v41
	v_max_f32_e32 v41, 0, v46
	v_mul_f32_e32 v46, v42, v42
	v_max_f32_e32 v42, 0, v47
	v_mul_f32_e32 v41, v41, v41
	v_max_f32_e32 v43, 0, v43
	v_mul_f32_e32 v42, v42, v42
	v_cvt_pk_bf16_f32 v40, v44, v40
	v_add_co_u32_e32 v44, vcc, s56, v144
	v_pk_mul_f32 v[32:33], v[32:33], v[50:51] op_sel_hi:[1,0]
	v_mul_f32_e32 v43, v43, v43
	v_cvt_pk_bf16_f32 v41, v41, v42
	v_cvt_pk_bf16_f32 v42, v51, v45
	v_addc_co_u32_e32 v45, vcc, 0, v145, vcc
	v_pk_mul_f32 v[36:37], v[36:37], v[50:51] op_sel_hi:[1,0]
	v_max_f32_e32 v32, 0, v32
	v_cvt_pk_bf16_f32 v43, v46, v43
	global_store_dwordx4 v[44:45], v[40:43], off nt
	v_max_f32_e32 v36, 0, v36
	v_mul_f32_e32 v36, v36, v36
	v_mul_f32_e32 v40, v32, v32
	v_max_f32_e32 v32, 0, v37
	v_mul_f32_e32 v32, v32, v32
	v_cvt_pk_bf16_f32 v32, v36, v32
	v_mul_f32_e32 v36, 0x4b800000, v166
	v_cmp_gt_f32_e32 vcc, s54, v166
	v_pk_mul_f32 v[34:35], v[34:35], v[50:51] op_sel_hi:[1,0]
	v_pk_mul_f32 v[38:39], v[38:39], v[50:51] op_sel_hi:[1,0]
	v_cndmask_b32_e32 v36, v166, v36, vcc
	v_max_f32_e32 v33, 0, v33
	v_max_f32_e32 v34, 0, v34
	v_rsq_f32_e32 v36, v36
	v_mul_f32_e32 v37, v33, v33
	v_max_f32_e32 v33, 0, v38
	v_mul_f32_e32 v38, v34, v34
	v_max_f32_e32 v34, 0, v39
	v_mul_f32_e32 v33, v33, v33
	v_max_f32_e32 v35, 0, v35
	v_mul_f32_e32 v34, v34, v34
	v_lshl_add_u64 v[48:49], v[144:145], 0, s[14:15]
	v_mul_f32_e32 v35, v35, v35
	v_cvt_pk_bf16_f32 v33, v33, v34
	v_cvt_pk_bf16_f32 v34, v40, v37
	v_cvt_pk_bf16_f32 v35, v38, v35
	global_store_dwordx4 v[48:49], v[32:35], off offset:256 nt
	s_nop 1
	v_mul_f32_e32 v34, 0x45800000, v36
	v_cndmask_b32_e32 v34, v36, v34, vcc
	v_pk_mul_f32 v[24:25], v[24:25], v[34:35] op_sel_hi:[1,0]
	v_pk_mul_f32 v[28:29], v[28:29], v[34:35] op_sel_hi:[1,0]
	v_pk_mul_f32 v[26:27], v[26:27], v[34:35] op_sel_hi:[1,0]
	v_max_f32_e32 v24, 0, v24
	v_pk_mul_f32 v[30:31], v[30:31], v[34:35] op_sel_hi:[1,0]
	v_max_f32_e32 v28, 0, v28
	v_mul_f32_e32 v35, v24, v24
	v_max_f32_e32 v24, 0, v29
	v_max_f32_e32 v25, 0, v25
	v_max_f32_e32 v26, 0, v26
	v_mul_f32_e32 v28, v28, v28
	v_mul_f32_e32 v24, v24, v24
	v_mul_f32_e32 v29, v25, v25
	v_max_f32_e32 v25, 0, v30
	v_mul_f32_e32 v30, v26, v26
	v_max_f32_e32 v26, 0, v31
	v_mul_f32_e32 v25, v25, v25
	v_max_f32_e32 v27, 0, v27
	v_mul_f32_e32 v26, v26, v26
	v_cvt_pk_bf16_f32 v24, v28, v24
	v_add_co_u32_e32 v28, vcc, s57, v144
	v_pk_mul_f32 v[16:17], v[16:17], v[34:35] op_sel_hi:[1,0]
	v_mul_f32_e32 v27, v27, v27
	v_cvt_pk_bf16_f32 v25, v25, v26
	v_cvt_pk_bf16_f32 v26, v35, v29
	v_addc_co_u32_e32 v29, vcc, 0, v145, vcc
	v_pk_mul_f32 v[20:21], v[20:21], v[34:35] op_sel_hi:[1,0]
	v_max_f32_e32 v16, 0, v16
	v_cvt_pk_bf16_f32 v27, v30, v27
	global_store_dwordx4 v[28:29], v[24:27], off nt
	v_max_f32_e32 v20, 0, v20
	v_mul_f32_e32 v20, v20, v20
	v_mul_f32_e32 v24, v16, v16
	v_max_f32_e32 v16, 0, v21
	v_mul_f32_e32 v16, v16, v16
	v_cvt_pk_bf16_f32 v16, v20, v16
	v_mul_f32_e32 v20, 0x4b800000, v147
	v_cmp_gt_f32_e32 vcc, s54, v147
	v_pk_mul_f32 v[18:19], v[18:19], v[34:35] op_sel_hi:[1,0]
	v_pk_mul_f32 v[22:23], v[22:23], v[34:35] op_sel_hi:[1,0]
	v_cndmask_b32_e32 v20, v147, v20, vcc
	v_max_f32_e32 v17, 0, v17
	v_max_f32_e32 v18, 0, v18
	v_rsq_f32_e32 v20, v20
	v_mul_f32_e32 v21, v17, v17
	v_max_f32_e32 v17, 0, v22
	v_mul_f32_e32 v22, v18, v18
	v_max_f32_e32 v18, 0, v23
	v_mul_f32_e32 v17, v17, v17
	v_max_f32_e32 v19, 0, v19
	v_mul_f32_e32 v18, v18, v18
	v_lshl_add_u64 v[32:33], v[144:145], 0, s[16:17]
	v_mul_f32_e32 v19, v19, v19
	v_cvt_pk_bf16_f32 v17, v17, v18
	v_cvt_pk_bf16_f32 v18, v24, v21
	v_cvt_pk_bf16_f32 v19, v22, v19
	global_store_dwordx4 v[32:33], v[16:19], off offset:256 nt
	s_nop 1
	v_mul_f32_e32 v18, 0x45800000, v20
	v_cndmask_b32_e32 v18, v20, v18, vcc
	v_pk_mul_f32 v[8:9], v[8:9], v[18:19] op_sel_hi:[1,0]
	v_pk_mul_f32 v[12:13], v[12:13], v[18:19] op_sel_hi:[1,0]
	v_pk_mul_f32 v[10:11], v[10:11], v[18:19] op_sel_hi:[1,0]
	v_max_f32_e32 v8, 0, v8
	v_pk_mul_f32 v[14:15], v[14:15], v[18:19] op_sel_hi:[1,0]
	v_max_f32_e32 v12, 0, v12
	v_mul_f32_e32 v19, v8, v8
	v_max_f32_e32 v8, 0, v13
	v_max_f32_e32 v9, 0, v9
	v_max_f32_e32 v10, 0, v10
	v_mul_f32_e32 v12, v12, v12
	v_mul_f32_e32 v8, v8, v8
	v_mul_f32_e32 v13, v9, v9
	v_max_f32_e32 v9, 0, v14
	v_mul_f32_e32 v14, v10, v10
	v_max_f32_e32 v10, 0, v15
	v_mul_f32_e32 v9, v9, v9
	v_max_f32_e32 v11, 0, v11
	v_mul_f32_e32 v10, v10, v10
	v_cvt_pk_bf16_f32 v8, v12, v8
	v_add_co_u32_e32 v12, vcc, s58, v144
	v_pk_mul_f32 v[2:3], v[2:3], v[18:19] op_sel_hi:[1,0]
	v_pk_mul_f32 v[0:1], v[0:1], v[18:19] op_sel_hi:[1,0]
	v_mul_f32_e32 v11, v11, v11
	v_cvt_pk_bf16_f32 v9, v9, v10
	v_cvt_pk_bf16_f32 v10, v19, v13
	v_addc_co_u32_e32 v13, vcc, 0, v145, vcc
	v_pk_mul_f32 v[6:7], v[6:7], v[18:19] op_sel_hi:[1,0]
	v_pk_mul_f32 v[4:5], v[4:5], v[18:19] op_sel_hi:[1,0]
	v_max_f32_e32 v0, 0, v0
	v_max_f32_e32 v1, 0, v1
	v_max_f32_e32 v2, 0, v2
	v_cvt_pk_bf16_f32 v11, v14, v11
	global_store_dwordx4 v[12:13], v[8:11], off nt
	v_max_f32_e32 v3, 0, v3
	v_lshl_add_u64 v[16:17], v[144:145], 0, s[18:19]
	v_mul_f32_e32 v8, v0, v0
	v_max_f32_e32 v0, 0, v5
	v_mul_f32_e32 v5, v1, v1
	v_max_f32_e32 v1, 0, v6
	v_mul_f32_e32 v6, v2, v2
	v_max_f32_e32 v2, 0, v7
	v_max_f32_e32 v4, 0, v4
	v_mul_f32_e32 v0, v0, v0
	v_mul_f32_e32 v1, v1, v1
	v_mul_f32_e32 v2, v2, v2
	v_mul_f32_e32 v3, v3, v3
	s_and_b64 vcc, exec, s[2:3]
	v_mul_f32_e32 v4, v4, v4
	v_cvt_pk_bf16_f32 v0, v4, v0
	v_cvt_pk_bf16_f32 v1, v1, v2
	v_cvt_pk_bf16_f32 v2, v8, v5
	v_cvt_pk_bf16_f32 v3, v6, v3
	global_store_dwordx4 v[16:17], v[0:3], off offset:256 nt
	s_cbranch_vccz .LBB0_1211
	s_waitcnt vmcnt(0)
	s_cmpk_gt_u32 s33, 0xff
	s_cbranch_scc1 .LBB0_1222
	s_barrier

.LBB0_1264:
	ds_read_b128 v[144:147], v178
	ds_read_b128 v[148:151], v178 offset:1024
	ds_read_b128 v[152:155], v178 offset:2048
	ds_read_b128 v[156:159], v178 offset:3072
	s_add_u32 s34, s30, 0xfff00080
	s_addc_u32 s35, s31, -1
	s_cmp_eq_u32 s58, 60
	s_cselect_b32 s37, s21, s35
	s_cselect_b32 s36, s27, s34
	s_cselect_b32 s35, s19, s57
	s_cselect_b32 s34, s55, s56
	v_lshl_add_u64 v[172:173], s[30:31], 0, v[136:137]
	s_add_i32 m0, s29, 0xc000
	ds_read_b128 v[160:163], v179
	ds_read_b128 v[164:167], v179 offset:1024
	ds_read_b128 v[168:171], v179 offset:2048
	ds_read_b128 v[182:185], v179 offset:3072
	ds_read_b128 v[186:189], v179 offset:4096
	ds_read_b128 v[190:193], v179 offset:5120
	ds_read_b128 v[194:197], v179 offset:6144
	ds_read_b128 v[198:201], v179 offset:7168
	global_load_lds_dwordx4 v[172:173], off
	v_lshl_add_u64 v[172:173], s[30:31], 0, v[138:139]
	s_add_i32 m0, s29, 0xe000
	s_nop 0
	global_load_lds_dwordx4 v[172:173], off
	s_waitcnt lgkmcnt(8)
	s_setprio 1
	s_barrier
	s_waitcnt lgkmcnt(0)
	v_mfma_f32_16x16x32_bf16 v[124:127], v[144:147], v[160:163], v[124:127]
	v_mfma_f32_16x16x32_bf16 v[120:123], v[152:155], v[160:163], v[120:123]
	v_mfma_f32_16x16x32_bf16 v[108:111], v[144:147], v[168:171], v[108:111]
	v_mfma_f32_16x16x32_bf16 v[104:107], v[152:155], v[168:171], v[104:107]
	v_mfma_f32_16x16x32_bf16 v[96:99], v[144:147], v[186:189], v[96:99]
	v_mfma_f32_16x16x32_bf16 v[88:91], v[152:155], v[186:189], v[88:91]
	v_mfma_f32_16x16x32_bf16 v[80:83], v[144:147], v[194:197], v[80:83]
	v_mfma_f32_16x16x32_bf16 v[72:75], v[152:155], v[194:197], v[72:75]
	v_mfma_f32_16x16x32_bf16 v[124:127], v[148:151], v[164:167], v[124:127]
	v_mfma_f32_16x16x32_bf16 v[120:123], v[156:159], v[164:167], v[120:123]
	v_mfma_f32_16x16x32_bf16 v[108:111], v[148:151], v[182:185], v[108:111]
	v_mfma_f32_16x16x32_bf16 v[104:107], v[156:159], v[182:185], v[104:107]
	v_mfma_f32_16x16x32_bf16 v[96:99], v[148:151], v[190:193], v[96:99]
	v_mfma_f32_16x16x32_bf16 v[88:91], v[156:159], v[190:193], v[88:91]
	v_mfma_f32_16x16x32_bf16 v[80:83], v[148:151], v[198:201], v[80:83]
	v_mfma_f32_16x16x32_bf16 v[72:75], v[156:159], v[198:201], v[72:75]
	s_barrier
	s_setprio 0
	s_add_i32 s59, s53, s40
	v_lshl_add_u64 v[172:173], s[34:35], 0, v[130:131]
	s_mov_b32 m0, s59
	ds_read_b128 v[202:205], v180
	ds_read_b128 v[206:209], v180 offset:1024
	ds_read_b128 v[212:215], v180 offset:2048
	ds_read_b128 v[216:219], v180 offset:3072
	global_load_lds_dwordx4 v[172:173], off
	v_lshl_add_u64 v[220:221], s[34:35], 0, v[134:135]
	s_add_i32 m0, s59, 0x2000
	s_nop 0
	global_load_lds_dwordx4 v[220:221], off
	s_setprio 1
	s_barrier
	s_waitcnt lgkmcnt(0)
	v_mfma_f32_16x16x32_bf16 v[116:119], v[202:205], v[160:163], v[116:119]
	v_mfma_f32_16x16x32_bf16 v[112:115], v[212:215], v[160:163], v[112:115]
	v_mfma_f32_16x16x32_bf16 v[100:103], v[202:205], v[168:171], v[100:103]
	v_mfma_f32_16x16x32_bf16 v[92:95], v[212:215], v[168:171], v[92:95]
	v_mfma_f32_16x16x32_bf16 v[84:87], v[202:205], v[186:189], v[84:87]
	v_mfma_f32_16x16x32_bf16 v[76:79], v[212:215], v[186:189], v[76:79]
	v_mfma_f32_16x16x32_bf16 v[68:71], v[202:205], v[194:197], v[68:71]
	v_mfma_f32_16x16x32_bf16 v[64:67], v[212:215], v[194:197], v[64:67]
	v_mfma_f32_16x16x32_bf16 v[116:119], v[206:209], v[164:167], v[116:119]
	v_mfma_f32_16x16x32_bf16 v[112:115], v[216:219], v[164:167], v[112:115]
	v_mfma_f32_16x16x32_bf16 v[100:103], v[206:209], v[182:185], v[100:103]
	v_mfma_f32_16x16x32_bf16 v[92:95], v[216:219], v[182:185], v[92:95]
	v_mfma_f32_16x16x32_bf16 v[84:87], v[206:209], v[190:193], v[84:87]
	v_mfma_f32_16x16x32_bf16 v[76:79], v[216:219], v[190:193], v[76:79]
	v_mfma_f32_16x16x32_bf16 v[68:71], v[206:209], v[198:201], v[68:71]
	v_mfma_f32_16x16x32_bf16 v[64:67], v[216:219], v[198:201], v[64:67]
	s_barrier
	s_setprio 0
	s_mov_b32 m0, s29
	v_lshl_add_u64 v[222:223], s[36:37], 0, v[128:129]
	ds_read_b128 v[160:163], v179 offset:16384
	ds_read_b128 v[164:167], v179 offset:17408
	ds_read_b128 v[168:171], v179 offset:18432
	ds_read_b128 v[182:185], v179 offset:19456
	ds_read_b128 v[186:189], v179 offset:20480
	ds_read_b128 v[190:193], v179 offset:21504
	ds_read_b128 v[194:197], v179 offset:22528
	ds_read_b128 v[198:201], v179 offset:23552
	global_load_lds_dwordx4 v[222:223], off
	v_lshl_add_u64 v[224:225], s[36:37], 0, v[132:133]
	s_mov_b32 m0, s41
	s_nop 0
	global_load_lds_dwordx4 v[224:225], off
	s_setprio 1
	s_barrier
	s_waitcnt lgkmcnt(0)
	v_mfma_f32_16x16x32_bf16 v[60:63], v[144:147], v[160:163], v[60:63]
	v_mfma_f32_16x16x32_bf16 v[56:59], v[152:155], v[160:163], v[56:59]
	v_mfma_f32_16x16x32_bf16 v[44:47], v[144:147], v[168:171], v[44:47]
	v_mfma_f32_16x16x32_bf16 v[40:43], v[152:155], v[168:171], v[40:43]
	v_mfma_f32_16x16x32_bf16 v[32:35], v[144:147], v[186:189], v[32:35]
	v_mfma_f32_16x16x32_bf16 v[24:27], v[152:155], v[186:189], v[24:27]
	v_mfma_f32_16x16x32_bf16 v[16:19], v[144:147], v[194:197], v[16:19]
	v_mfma_f32_16x16x32_bf16 v[8:11], v[152:155], v[194:197], v[8:11]
	v_mfma_f32_16x16x32_bf16 v[60:63], v[148:151], v[164:167], v[60:63]
	v_mfma_f32_16x16x32_bf16 v[56:59], v[156:159], v[164:167], v[56:59]
	v_mfma_f32_16x16x32_bf16 v[44:47], v[148:151], v[182:185], v[44:47]
	v_mfma_f32_16x16x32_bf16 v[40:43], v[156:159], v[182:185], v[40:43]
	v_mfma_f32_16x16x32_bf16 v[32:35], v[148:151], v[190:193], v[32:35]
	v_mfma_f32_16x16x32_bf16 v[24:27], v[156:159], v[190:193], v[24:27]
	v_mfma_f32_16x16x32_bf16 v[16:19], v[148:151], v[198:201], v[16:19]
	v_mfma_f32_16x16x32_bf16 v[8:11], v[156:159], v[198:201], v[8:11]
	s_barrier
	s_setprio 0
	s_add_u32 s60, s34, 0x100000
	s_addc_u32 s61, s35, 0
	s_add_i32 s59, s54, s40
	v_lshl_add_u64 v[144:145], s[60:61], 0, v[130:131]
	s_mov_b32 m0, s59
	s_nop 0
	global_load_lds_dwordx4 v[144:145], off
	v_lshl_add_u64 v[144:145], s[60:61], 0, v[134:135]
	s_add_i32 m0, s59, 0x2000
	s_nop 0
	global_load_lds_dwordx4 v[144:145], off
	s_waitcnt vmcnt(6)
	s_setprio 1
	s_barrier
	v_mfma_f32_16x16x32_bf16 v[52:55], v[202:205], v[160:163], v[52:55]
	v_mfma_f32_16x16x32_bf16 v[48:51], v[212:215], v[160:163], v[48:51]
	v_mfma_f32_16x16x32_bf16 v[36:39], v[202:205], v[168:171], v[36:39]
	v_mfma_f32_16x16x32_bf16 v[28:31], v[212:215], v[168:171], v[28:31]
	v_mfma_f32_16x16x32_bf16 v[20:23], v[202:205], v[186:189], v[20:23]
	v_mfma_f32_16x16x32_bf16 v[12:15], v[212:215], v[186:189], v[12:15]
	v_mfma_f32_16x16x32_bf16 v[4:7], v[202:205], v[194:197], v[4:7]
	v_mfma_f32_16x16x32_bf16 v[0:3], v[212:215], v[194:197], v[0:3]
	v_mfma_f32_16x16x32_bf16 v[52:55], v[206:209], v[164:167], v[52:55]
	v_mfma_f32_16x16x32_bf16 v[48:51], v[216:219], v[164:167], v[48:51]
	v_mfma_f32_16x16x32_bf16 v[36:39], v[206:209], v[182:185], v[36:39]
	v_mfma_f32_16x16x32_bf16 v[28:31], v[216:219], v[182:185], v[28:31]
	v_mfma_f32_16x16x32_bf16 v[20:23], v[206:209], v[190:193], v[20:23]
	v_mfma_f32_16x16x32_bf16 v[12:15], v[216:219], v[190:193], v[12:15]
	v_mfma_f32_16x16x32_bf16 v[4:7], v[206:209], v[198:201], v[4:7]
	v_mfma_f32_16x16x32_bf16 v[0:3], v[216:219], v[198:201], v[0:3]
	s_barrier
	s_setprio 0
	s_add_i32 s59, 0, 0x18000
	v_add_u32_e32 v156, s59, v176
	ds_read_b128 v[144:147], v156
	ds_read_b128 v[148:151], v156 offset:1024
	ds_read_b128 v[152:155], v156 offset:2048
	ds_read_b128 v[156:159], v156 offset:3072
	s_add_u32 s36, s36, 0x100000
	s_addc_u32 s37, s37, 0
	s_mov_b32 m0, s42
	v_lshl_add_u64 v[202:203], s[36:37], 0, v[128:129]
	ds_read_b128 v[160:163], v179 offset:32768
	ds_read_b128 v[164:167], v179 offset:33792
	ds_read_b128 v[168:171], v179 offset:34816
	ds_read_b128 v[182:185], v179 offset:35840
	ds_read_b128 v[186:189], v179 offset:36864
	ds_read_b128 v[190:193], v179 offset:37888
	ds_read_b128 v[194:197], v179 offset:38912
	ds_read_b128 v[198:201], v179 offset:39936
	global_load_lds_dwordx4 v[202:203], off
	v_lshl_add_u64 v[202:203], s[36:37], 0, v[132:133]
	s_mov_b32 m0, s43
	s_nop 0
	global_load_lds_dwordx4 v[202:203], off
	s_waitcnt lgkmcnt(8)
	s_setprio 1
	s_barrier
	s_waitcnt lgkmcnt(0)
	v_mfma_f32_16x16x32_bf16 v[124:127], v[144:147], v[160:163], v[124:127]
	v_mfma_f32_16x16x32_bf16 v[120:123], v[152:155], v[160:163], v[120:123]
	v_mfma_f32_16x16x32_bf16 v[108:111], v[144:147], v[168:171], v[108:111]
	v_mfma_f32_16x16x32_bf16 v[104:107], v[152:155], v[168:171], v[104:107]
	v_mfma_f32_16x16x32_bf16 v[96:99], v[144:147], v[186:189], v[96:99]
	v_mfma_f32_16x16x32_bf16 v[88:91], v[152:155], v[186:189], v[88:91]
	v_mfma_f32_16x16x32_bf16 v[80:83], v[144:147], v[194:197], v[80:83]
	v_mfma_f32_16x16x32_bf16 v[72:75], v[152:155], v[194:197], v[72:75]
	v_mfma_f32_16x16x32_bf16 v[124:127], v[148:151], v[164:167], v[124:127]
	v_mfma_f32_16x16x32_bf16 v[120:123], v[156:159], v[164:167], v[120:123]
	v_mfma_f32_16x16x32_bf16 v[108:111], v[148:151], v[182:185], v[108:111]
	v_mfma_f32_16x16x32_bf16 v[104:107], v[156:159], v[182:185], v[104:107]
	v_mfma_f32_16x16x32_bf16 v[96:99], v[148:151], v[190:193], v[96:99]
	v_mfma_f32_16x16x32_bf16 v[88:91], v[156:159], v[190:193], v[88:91]
	v_mfma_f32_16x16x32_bf16 v[80:83], v[148:151], v[198:201], v[80:83]
	v_mfma_f32_16x16x32_bf16 v[72:75], v[156:159], v[198:201], v[72:75]
	s_barrier
	s_setprio 0
	s_add_i32 s36, 0, 0x1c000
	s_add_i32 s37, s59, s40
	v_add_u32_e32 v181, s36, v176
	v_lshl_add_u64 v[172:173], v[172:173], 0, s[0:1]
	s_mov_b32 m0, s37
	ds_read_b128 v[202:205], v181
	ds_read_b128 v[206:209], v181 offset:1024
	ds_read_b128 v[212:215], v181 offset:2048
	ds_read_b128 v[216:219], v181 offset:3072
	global_load_lds_dwordx4 v[172:173], off
	v_lshl_add_u64 v[172:173], v[220:221], 0, s[0:1]
	s_add_i32 m0, s37, 0x2000
	s_nop 0
	global_load_lds_dwordx4 v[172:173], off
	s_setprio 1
	s_barrier
	s_waitcnt lgkmcnt(0)
	v_mfma_f32_16x16x32_bf16 v[116:119], v[202:205], v[160:163], v[116:119]
	v_mfma_f32_16x16x32_bf16 v[112:115], v[212:215], v[160:163], v[112:115]
	v_mfma_f32_16x16x32_bf16 v[100:103], v[202:205], v[168:171], v[100:103]
	v_mfma_f32_16x16x32_bf16 v[92:95], v[212:215], v[168:171], v[92:95]
	v_mfma_f32_16x16x32_bf16 v[84:87], v[202:205], v[186:189], v[84:87]
	v_mfma_f32_16x16x32_bf16 v[76:79], v[212:215], v[186:189], v[76:79]
	v_mfma_f32_16x16x32_bf16 v[68:71], v[202:205], v[194:197], v[68:71]
	v_mfma_f32_16x16x32_bf16 v[64:67], v[212:215], v[194:197], v[64:67]
	v_mfma_f32_16x16x32_bf16 v[116:119], v[206:209], v[164:167], v[116:119]
	v_mfma_f32_16x16x32_bf16 v[112:115], v[216:219], v[164:167], v[112:115]
	v_mfma_f32_16x16x32_bf16 v[100:103], v[206:209], v[182:185], v[100:103]
	v_mfma_f32_16x16x32_bf16 v[92:95], v[216:219], v[182:185], v[92:95]
	v_mfma_f32_16x16x32_bf16 v[84:87], v[206:209], v[190:193], v[84:87]
	v_mfma_f32_16x16x32_bf16 v[76:79], v[216:219], v[190:193], v[76:79]
	v_mfma_f32_16x16x32_bf16 v[68:71], v[206:209], v[198:201], v[68:71]
	v_mfma_f32_16x16x32_bf16 v[64:67], v[216:219], v[198:201], v[64:67]
	s_barrier
	s_setprio 0
	s_mov_b32 m0, s49
	v_lshl_add_u64 v[172:173], v[222:223], 0, s[0:1]
	ds_read_b128 v[160:163], v179 offset:49152
	ds_read_b128 v[164:167], v179 offset:50176
	ds_read_b128 v[168:171], v179 offset:51200
	ds_read_b128 v[182:185], v179 offset:52224
	ds_read_b128 v[186:189], v179 offset:53248
	ds_read_b128 v[190:193], v179 offset:54272
	ds_read_b128 v[194:197], v179 offset:55296
	ds_read_b128 v[198:201], v179 offset:56320
	global_load_lds_dwordx4 v[172:173], off
	v_lshl_add_u64 v[172:173], v[224:225], 0, s[0:1]
	s_mov_b32 m0, s50
	s_nop 0
	global_load_lds_dwordx4 v[172:173], off
	s_setprio 1
	s_barrier
	s_waitcnt lgkmcnt(0)
	v_mfma_f32_16x16x32_bf16 v[60:63], v[144:147], v[160:163], v[60:63]
	v_mfma_f32_16x16x32_bf16 v[56:59], v[152:155], v[160:163], v[56:59]
	v_mfma_f32_16x16x32_bf16 v[44:47], v[144:147], v[168:171], v[44:47]
	v_mfma_f32_16x16x32_bf16 v[40:43], v[152:155], v[168:171], v[40:43]
	v_mfma_f32_16x16x32_bf16 v[32:35], v[144:147], v[186:189], v[32:35]
	v_mfma_f32_16x16x32_bf16 v[24:27], v[152:155], v[186:189], v[24:27]
	v_mfma_f32_16x16x32_bf16 v[16:19], v[144:147], v[194:197], v[16:19]
	v_mfma_f32_16x16x32_bf16 v[8:11], v[152:155], v[194:197], v[8:11]
	v_mfma_f32_16x16x32_bf16 v[60:63], v[148:151], v[164:167], v[60:63]
	v_mfma_f32_16x16x32_bf16 v[56:59], v[156:159], v[164:167], v[56:59]
	v_mfma_f32_16x16x32_bf16 v[44:47], v[148:151], v[182:185], v[44:47]
	v_mfma_f32_16x16x32_bf16 v[40:43], v[156:159], v[182:185], v[40:43]
	v_mfma_f32_16x16x32_bf16 v[32:35], v[148:151], v[190:193], v[32:35]
	v_mfma_f32_16x16x32_bf16 v[24:27], v[156:159], v[190:193], v[24:27]
	v_mfma_f32_16x16x32_bf16 v[16:19], v[148:151], v[198:201], v[16:19]
	v_mfma_f32_16x16x32_bf16 v[8:11], v[156:159], v[198:201], v[8:11]
	s_barrier
	s_setprio 0
	s_add_u32 s34, s34, 0x100080
	s_addc_u32 s35, s35, 0
	s_add_i32 s36, s36, s40
	v_lshl_add_u64 v[144:145], s[34:35], 0, v[130:131]
	s_mov_b32 m0, s36
	s_nop 0
	global_load_lds_dwordx4 v[144:145], off
	v_lshl_add_u64 v[144:145], s[34:35], 0, v[134:135]
	s_add_i32 m0, s36, 0x2000
	s_nop 0
	global_load_lds_dwordx4 v[144:145], off
	s_waitcnt vmcnt(6)
	s_setprio 1
	s_barrier
	v_mfma_f32_16x16x32_bf16 v[52:55], v[202:205], v[160:163], v[52:55]
	v_mfma_f32_16x16x32_bf16 v[48:51], v[212:215], v[160:163], v[48:51]
	v_mfma_f32_16x16x32_bf16 v[36:39], v[202:205], v[168:171], v[36:39]
	v_mfma_f32_16x16x32_bf16 v[28:31], v[212:215], v[168:171], v[28:31]
	v_mfma_f32_16x16x32_bf16 v[20:23], v[202:205], v[186:189], v[20:23]
	v_mfma_f32_16x16x32_bf16 v[12:15], v[212:215], v[186:189], v[12:15]
	v_mfma_f32_16x16x32_bf16 v[4:7], v[202:205], v[194:197], v[4:7]
	v_mfma_f32_16x16x32_bf16 v[0:3], v[212:215], v[194:197], v[0:3]
	v_mfma_f32_16x16x32_bf16 v[52:55], v[206:209], v[164:167], v[52:55]
	v_mfma_f32_16x16x32_bf16 v[48:51], v[216:219], v[164:167], v[48:51]
	v_mfma_f32_16x16x32_bf16 v[36:39], v[206:209], v[182:185], v[36:39]
	v_mfma_f32_16x16x32_bf16 v[28:31], v[216:219], v[182:185], v[28:31]
	v_mfma_f32_16x16x32_bf16 v[20:23], v[206:209], v[190:193], v[20:23]
	v_mfma_f32_16x16x32_bf16 v[12:15], v[216:219], v[190:193], v[12:15]
	v_mfma_f32_16x16x32_bf16 v[4:7], v[206:209], v[198:201], v[4:7]
	v_mfma_f32_16x16x32_bf16 v[0:3], v[216:219], v[198:201], v[0:3]
	s_barrier
	s_setprio 0
	s_add_i32 s58, s58, 2
	s_add_u32 s30, s30, 0x100
	s_addc_u32 s31, s31, 0
	s_add_u32 s56, s56, 0x100
	s_addc_u32 s57, s57, 0
	s_cmp_gt_u32 s58, 61
	s_cbranch_scc0 .LBB0_1264
	v_lshl_or_b32 v144, s28, 8, v177
	v_lshl_add_u32 v150, s26, 8, v175
	v_ashrrev_i32_e32 v145, 31, v144
	v_ashrrev_i32_e32 v151, 31, v150
	v_lshlrev_b64 v[144:145], 1, v[144:145]
	v_lshl_add_u64 v[146:147], s[90:91], 0, v[144:145]
	v_lshlrev_b64 v[148:149], 11, v[150:151]
	v_lshl_add_u64 v[152:153], v[146:147], 0, v[148:149]
	global_load_dwordx4 v[156:159], v[152:153], off
	global_load_dwordx4 v[160:163], v[152:153], off offset:256
	v_or_b32_e32 v152, 16, v150
	v_ashrrev_i32_e32 v153, 31, v152
	v_lshlrev_b64 v[170:171], 11, v[152:153]
	v_lshl_add_u64 v[152:153], v[146:147], 0, v[170:171]
	global_load_dwordx4 v[164:167], v[152:153], off
	global_load_dwordx4 v[182:185], v[152:153], off offset:256
	v_or_b32_e32 v152, 32, v150
	v_ashrrev_i32_e32 v153, 31, v152
	v_lshlrev_b64 v[154:155], 11, v[152:153]
	v_lshl_add_u64 v[152:153], v[146:147], 0, v[154:155]
	global_load_dwordx4 v[186:189], v[152:153], off
	global_load_dwordx4 v[190:193], v[152:153], off offset:256
	v_or_b32_e32 v152, 48, v150
	v_ashrrev_i32_e32 v153, 31, v152
	v_lshlrev_b64 v[152:153], 11, v[152:153]
	v_lshl_add_u64 v[168:169], v[146:147], 0, v[152:153]
	global_load_dwordx4 v[194:197], v[168:169], off
	global_load_dwordx4 v[198:201], v[168:169], off offset:256
	s_waitcnt vmcnt(0)
	v_lshlrev_b32_e32 v202, 16, v156
	v_and_b32_e32 v203, 0xffff0000, v156
	v_lshlrev_b32_e32 v204, 16, v157
	v_and_b32_e32 v205, 0xffff0000, v157
	v_lshlrev_b32_e32 v206, 16, v158
	v_and_b32_e32 v207, 0xffff0000, v158
	v_lshlrev_b32_e32 v208, 16, v159
	v_and_b32_e32 v209, 0xffff0000, v159
	v_pk_add_f32 v[126:127], v[126:127], v[204:205]
	v_pk_add_f32 v[124:125], v[124:125], v[202:203]
	v_lshlrev_b32_e32 v224, 16, v166
	v_and_b32_e32 v225, 0xffff0000, v166
	v_lshlrev_b32_e32 v226, 16, v167
	v_and_b32_e32 v227, 0xffff0000, v167
	v_lshlrev_b32_e32 v212, 16, v160
	v_lshlrev_b32_e32 v166, 16, v194
	v_and_b32_e32 v167, 0xffff0000, v194
	v_lshlrev_b32_e32 v172, 16, v195
	v_and_b32_e32 v173, 0xffff0000, v195
	v_pk_add_f32 v[194:195], v[122:123], v[208:209]
	v_pk_add_f32 v[122:123], v[120:121], v[206:207]
	v_mul_f32_e32 v120, v125, v125
	v_mul_f32_e32 v121, v127, v127
	v_fmac_f32_e32 v120, v124, v124
	v_fmac_f32_e32 v121, v126, v126
	v_add_f32_e32 v120, v120, v121
	v_mul_f32_e32 v121, v123, v123
	v_fmac_f32_e32 v121, v122, v122
	v_add_f32_e32 v120, v121, v120
	v_mul_f32_e32 v121, v195, v195
	v_fmac_f32_e32 v121, v194, v194
	v_and_b32_e32 v213, 0xffff0000, v160
	v_lshlrev_b32_e32 v214, 16, v161
	v_and_b32_e32 v215, 0xffff0000, v161
	v_add_f32_e32 v181, v121, v120
	v_cvt_pk_bf16_f32 v120, v124, v125
	v_lshl_add_u64 v[124:125], s[10:11], 0, v[148:149]
	v_lshlrev_b32_e32 v216, 16, v162
	v_and_b32_e32 v217, 0xffff0000, v162
	v_lshlrev_b32_e32 v218, 16, v163
	v_and_b32_e32 v219, 0xffff0000, v163
	v_cvt_pk_bf16_f32 v121, v126, v127
	v_lshl_add_u64 v[124:125], v[124:125], 0, v[144:145]
	v_pk_add_f32 v[118:119], v[118:119], v[214:215]
	v_pk_add_f32 v[116:117], v[116:117], v[212:213]
	v_cvt_pk_bf16_f32 v122, v122, v123
	v_cvt_pk_bf16_f32 v123, v194, v195
	global_store_dwordx4 v[124:125], v[120:123], off
	v_lshlrev_b32_e32 v220, 16, v164
	v_and_b32_e32 v221, 0xffff0000, v164
	v_pk_add_f32 v[120:121], v[114:115], v[218:219]
	v_pk_add_f32 v[114:115], v[112:113], v[216:217]
	v_mul_f32_e32 v112, v117, v117
	v_mul_f32_e32 v113, v119, v119
	v_fmac_f32_e32 v112, v116, v116
	v_fmac_f32_e32 v113, v118, v118
	v_add_f32_e32 v112, v112, v113
	v_mul_f32_e32 v113, v115, v115
	v_fmac_f32_e32 v113, v114, v114
	v_add_f32_e32 v112, v113, v112
	v_mul_f32_e32 v113, v121, v121
	v_fmac_f32_e32 v113, v120, v120
	v_add_f32_e32 v112, v113, v112
	v_lshlrev_b32_e32 v222, 16, v165
	v_and_b32_e32 v223, 0xffff0000, v165
	v_add_f32_e32 v126, v181, v112
	v_cvt_pk_bf16_f32 v112, v116, v117
	v_cvt_pk_bf16_f32 v113, v118, v119
	v_lshl_add_u64 v[116:117], s[10:11], 0, v[170:171]
	v_lshlrev_b32_e32 v230, 16, v184
	v_and_b32_e32 v231, 0xffff0000, v184
	v_lshlrev_b32_e32 v232, 16, v186
	v_and_b32_e32 v233, 0xffff0000, v186
	v_lshlrev_b32_e32 v186, 16, v187
	v_and_b32_e32 v187, 0xffff0000, v187
	v_cvt_pk_bf16_f32 v114, v114, v115
	v_cvt_pk_bf16_f32 v115, v120, v121
	global_store_dwordx4 v[124:125], v[112:115], off offset:256
	v_pk_add_f32 v[110:111], v[110:111], v[222:223]
	v_pk_add_f32 v[108:109], v[108:109], v[220:221]
	v_lshl_add_u64 v[118:119], v[116:117], 0, v[144:145]
	v_cvt_pk_bf16_f32 v112, v108, v109
	v_cvt_pk_bf16_f32 v113, v110, v111
	v_lshlrev_b32_e32 v228, 16, v182
	v_and_b32_e32 v229, 0xffff0000, v182
	v_lshlrev_b32_e32 v182, 16, v183
	v_and_b32_e32 v183, 0xffff0000, v183
	v_lshlrev_b32_e32 v184, 16, v185
	v_and_b32_e32 v185, 0xffff0000, v185
	v_lshlrev_b32_e32 v238, 16, v192
	v_and_b32_e32 v239, 0xffff0000, v192
	v_pk_add_f32 v[106:107], v[106:107], v[226:227]
	v_pk_add_f32 v[104:105], v[104:105], v[224:225]
	v_lshlrev_b32_e32 v156, 16, v200
	v_cvt_pk_bf16_f32 v114, v104, v105
	v_cvt_pk_bf16_f32 v115, v106, v107
	global_store_dwordx4 v[118:119], v[112:115], off
	v_and_b32_e32 v157, 0xffff0000, v200
	v_pk_add_f32 v[102:103], v[102:103], v[182:183]
	v_pk_add_f32 v[112:113], v[92:93], v[230:231]
	v_pk_add_f32 v[92:93], v[98:99], v[186:187]
	v_lshl_add_u64 v[98:99], s[10:11], 0, v[154:155]
	v_pk_add_f32 v[100:101], v[100:101], v[228:229]
	v_pk_add_f32 v[94:95], v[94:95], v[184:185]
	v_cvt_pk_bf16_f32 v114, v100, v101
	v_cvt_pk_bf16_f32 v115, v102, v103
	v_cvt_pk_bf16_f32 v116, v112, v113
	v_lshlrev_b32_e32 v234, 16, v188
	v_cvt_pk_bf16_f32 v117, v94, v95
	global_store_dwordx4 v[118:119], v[114:117], off offset:256
	v_lshl_add_u64 v[118:119], v[98:99], 0, v[144:145]
	v_pk_add_f32 v[98:99], v[76:77], v[238:239]
	v_pk_add_f32 v[76:77], v[82:83], v[172:173]
	v_lshl_add_u64 v[82:83], s[10:11], 0, v[152:153]
	v_lshl_add_u64 v[122:123], v[82:83], 0, v[144:145]
	v_pk_add_f32 v[82:83], v[64:65], v[156:157]
	v_and_b32_e32 v65, 64, v174
	v_and_b32_e32 v235, 0xffff0000, v188
	v_lshlrev_b32_e32 v188, 16, v189
	v_and_b32_e32 v189, 0xffff0000, v189
	v_lshlrev_b32_e32 v236, 16, v190
	v_and_b32_e32 v237, 0xffff0000, v190
	v_pk_add_f32 v[96:97], v[96:97], v[232:233]
	v_xor_b32_e32 v64, 16, v174
	v_cvt_pk_bf16_f32 v114, v96, v97
	v_add_u32_e32 v65, 64, v65
	v_lshlrev_b32_e32 v190, 16, v191
	v_and_b32_e32 v191, 0xffff0000, v191
	v_lshlrev_b32_e32 v192, 16, v193
	v_and_b32_e32 v193, 0xffff0000, v193
	v_pk_add_f32 v[90:91], v[90:91], v[188:189]
	v_pk_add_f32 v[88:89], v[88:89], v[234:235]
	v_cvt_pk_bf16_f32 v115, v92, v93
	v_pk_add_f32 v[84:85], v[84:85], v[236:237]
	v_cvt_pk_bf16_f32 v116, v88, v89
	v_cvt_pk_bf16_f32 v117, v90, v91
	global_store_dwordx4 v[118:119], v[114:117], off
	v_cmp_lt_i32_e32 vcc, v64, v65
	v_lshlrev_b32_e32 v164, 16, v196
	v_cvt_pk_bf16_f32 v114, v84, v85
	v_and_b32_e32 v165, 0xffff0000, v196
	v_lshlrev_b32_e32 v168, 16, v197
	v_and_b32_e32 v169, 0xffff0000, v197
	v_pk_add_f32 v[86:87], v[86:87], v[190:191]
	v_pk_add_f32 v[78:79], v[78:79], v[192:193]
	v_cvt_pk_bf16_f32 v115, v86, v87
	v_cvt_pk_bf16_f32 v116, v98, v99
	v_pk_add_f32 v[80:81], v[80:81], v[166:167]
	v_cvt_pk_bf16_f32 v117, v78, v79
	global_store_dwordx4 v[118:119], v[114:117], off offset:256
	v_cndmask_b32_e32 v64, v174, v64, vcc
	v_pk_add_f32 v[74:75], v[74:75], v[168:169]
	v_cvt_pk_bf16_f32 v114, v80, v81
	v_pk_add_f32 v[72:73], v[72:73], v[164:165]
	v_cvt_pk_bf16_f32 v115, v76, v77
	v_lshlrev_b32_e32 v158, 16, v198
	v_cvt_pk_bf16_f32 v116, v72, v73
	v_cvt_pk_bf16_f32 v117, v74, v75
	global_store_dwordx4 v[122:123], v[114:117], off
	v_and_b32_e32 v159, 0xffff0000, v198
	v_lshlrev_b32_e32 v162, 16, v199
	v_lshlrev_b32_e32 v114, 2, v64
	ds_bpermute_b32 v64, v114, v126
	v_xor_b32_e32 v115, 32, v174
	v_cmp_lt_i32_e32 vcc, v115, v65
	v_and_b32_e32 v163, 0xffff0000, v199
	v_lshlrev_b32_e32 v160, 16, v201
	v_cndmask_b32_e32 v65, v174, v115, vcc
	v_lshlrev_b32_e32 v115, 2, v65
	s_waitcnt lgkmcnt(0)
	v_add_f32_e32 v116, v126, v64
	ds_bpermute_b32 v117, v115, v116
	v_and_b32_e32 v161, 0xffff0000, v201
	v_pk_add_f32 v[70:71], v[70:71], v[162:163]
	v_pk_add_f32 v[68:69], v[68:69], v[158:159]
	v_pk_add_f32 v[66:67], v[66:67], v[160:161]
	v_lshl_add_u64 v[64:65], v[150:151], 2, s[6:7]
	v_cvt_pk_bf16_f32 v118, v68, v69
	v_cvt_pk_bf16_f32 v119, v70, v71
	v_cvt_pk_bf16_f32 v120, v82, v83
	v_cvt_pk_bf16_f32 v121, v66, v67
	global_store_dwordx4 v[122:123], v[118:121], off offset:256
	s_and_saveexec_b64 s[26:27], s[2:3]
	s_cbranch_execz .LBB0_1267
	s_waitcnt lgkmcnt(0)
	v_add_f32_e32 v116, v116, v117
	global_atomic_add_f32 v[64:65], v116, off
